# GEMM tile boundary: first epilogue loads issued before the stagger barrier (9 GEMM instances)
# speedup vs baseline: 1.0594x; 1.0071x over previous
; #define PG8_STAGE(bufoff, gbase, voff) do { _Pragma("unroll") for (int _i = 0; _i < 2; ++_i) \
;     __builtin_amdgcn_global_load_lds((const unsigned*)((const char*)(gbase) + (voff)[_i]), (PG8_LAS unsigned*)(lds + (bufoff) + ldsw + _i * 8192), 16, 0, 0); } while (0)
; #define PG8_LDA(dst, b, h) do { _Pragma("unroll") for (int m = 0; m < 4; ++m) _Pragma("unroll") for (int k = 0; k < 2; ++k) dst[m][k] = *(const PG8_LAS bf16x8*)(lds + PG8_SA(b, h) + aoff + m * 2048 + k * 1024); } while (0)
; #define PG8_LDB(dst, b, h) do { _Pragma("unroll") for (int n = 0; n < 2; ++n) _Pragma("unroll") for (int k = 0; k < 2; ++k) dst[n][k] = *(const PG8_LAS bf16x8*)(lds + PG8_SB(b, h) + boff + n * 2048 + k * 1024); } while (0)
; #define PG8_MMA(ai, bj, At, Bt) do { __builtin_amdgcn_s_setprio(1); _Pragma("unroll") for (int m = 0; m < 4; ++m) _Pragma("unroll") for (int n = 0; n < 2; ++n) _Pragma("unroll") for (int k = 0; k < 2; ++k) \
;     acc[ai][bj][m][n] = __builtin_amdgcn_mfma_f32_16x16x32_bf16(Bt[n][k], At[m][k], acc[ai][bj][m][n], 0, 0, 0); __builtin_amdgcn_s_setprio(0); } while (0)
; #define PG8_WAIT_V(n) asm volatile("s_waitcnt vmcnt(" #n ")" ::: "memory")
; #define PG8_WAIT_L(n) asm volatile("s_waitcnt lgkmcnt(" #n ")" ::: "memory")
; #define PG8_BAR __builtin_amdgcn_s_barrier()
; #define PG8_SCHED __builtin_amdgcn_sched_barrier(0)
; template <class Epi, class Sched>
; DI void gemm_phase(PG8_LAS unsigned char* lds, const Gemm g, const Sched& S, const Epi& E) {
;     ...
;       PG8_LDB(B0, 0, 0); PG8_LDB(B1, 0, 1); PG8_SCHED; PG8_LDA(At, 0, 0); PG8_STAGE(PG8_SA(1, 1), a1 + hstepA, voffA);
;       PG8_WAIT_V(8); PG8_WAIT_L(0); PG8_BAR; PG8_MMA(0, 0, At, B0); PG8_MMA(0, 1, At, B1); PG8_BAR; PG8_SCHED;
;       PG8_LDA(At, 0, 1); PG8_STAGE(PG8_SB(0, 0), b2, voffB); PG8_STAGE(PG8_SB(0, 1), b2 + hstepB, voffB); PG8_STAGE(PG8_SA(0, 0), a2, voffA);
;       PG8_WAIT_V(8); PG8_WAIT_L(0); PG8_BAR; PG8_MMA(1, 0, At, B0); PG8_MMA(1, 1, At, B1); PG8_BAR; PG8_SCHED;
.LBB0_286:
	ds_read_b128 v[146:149], v180
	ds_read_b128 v[150:153], v180 offset:1024
	ds_read_b128 v[154:157], v180 offset:2048
	ds_read_b128 v[158:161], v180 offset:3072
	ds_read_b128 v[162:165], v181
	ds_read_b128 v[166:169], v181 offset:1024
	ds_read_b128 v[170:173], v181 offset:2048
	ds_read_b128 v[174:177], v181 offset:3072
	s_add_u32 s16, s6, 0xfffc0080
	s_addc_u32 s30, s7, -1
	s_cmp_eq_u32 s69, 12
	s_cselect_b32 s35, s1, s30
	s_cselect_b32 s34, s5, s16
	s_cselect_b32 s31, s21, s68
	s_cselect_b32 s30, s23, s67
	v_lshl_add_u64 v[178:179], s[6:7], 0, v[140:141]
	s_add_i32 m0, s3, 0xc000
	ds_read_b128 v[186:189], v182
	ds_read_b128 v[190:193], v182 offset:1024
	ds_read_b128 v[194:197], v182 offset:2048
	ds_read_b128 v[198:201], v182 offset:3072
	ds_read_b128 v[202:205], v182 offset:4096
	ds_read_b128 v[206:209], v182 offset:5120
	ds_read_b128 v[214:217], v182 offset:6144
	ds_read_b128 v[218:221], v182 offset:7168
	global_load_lds_dwordx4 v[178:179], off
	v_lshl_add_u64 v[178:179], s[6:7], 0, v[142:143]
	s_add_i32 m0, s3, 0xe000
	s_nop 0
	global_load_lds_dwordx4 v[178:179], off
	s_waitcnt vmcnt(8)
	s_waitcnt lgkmcnt(0)
	s_barrier
	s_setprio 1
	s_waitcnt lgkmcnt(0)
	v_mfma_f32_16x16x32_bf16 v[122:125], v[146:149], v[186:189], v[122:125]
	v_mfma_f32_16x16x32_bf16 v[126:129], v[154:157], v[186:189], v[126:129]
	v_mfma_f32_16x16x32_bf16 v[106:109], v[146:149], v[194:197], v[106:109]
	v_mfma_f32_16x16x32_bf16 v[110:113], v[154:157], v[194:197], v[110:113]
	v_mfma_f32_16x16x32_bf16 v[90:93], v[146:149], v[202:205], v[90:93]
	v_mfma_f32_16x16x32_bf16 v[94:97], v[154:157], v[202:205], v[94:97]
	v_mfma_f32_16x16x32_bf16 v[74:77], v[146:149], v[214:217], v[74:77]
	v_mfma_f32_16x16x32_bf16 v[78:81], v[154:157], v[214:217], v[78:81]
	v_mfma_f32_16x16x32_bf16 v[122:125], v[150:153], v[190:193], v[122:125]
	v_mfma_f32_16x16x32_bf16 v[126:129], v[158:161], v[190:193], v[126:129]
	v_mfma_f32_16x16x32_bf16 v[106:109], v[150:153], v[198:201], v[106:109]
	v_mfma_f32_16x16x32_bf16 v[110:113], v[158:161], v[198:201], v[110:113]
	v_mfma_f32_16x16x32_bf16 v[90:93], v[150:153], v[206:209], v[90:93]
	v_mfma_f32_16x16x32_bf16 v[94:97], v[158:161], v[206:209], v[94:97]
	v_mfma_f32_16x16x32_bf16 v[74:77], v[150:153], v[218:221], v[74:77]
	v_mfma_f32_16x16x32_bf16 v[78:81], v[158:161], v[218:221], v[78:81]
	s_setprio 0
	s_setprio 1
	v_mfma_f32_16x16x32_bf16 v[114:117], v[162:165], v[186:189], v[114:117]
	v_mfma_f32_16x16x32_bf16 v[118:121], v[170:173], v[186:189], v[118:121]
	v_mfma_f32_16x16x32_bf16 v[98:101], v[162:165], v[194:197], v[98:101]
	v_mfma_f32_16x16x32_bf16 v[102:105], v[170:173], v[194:197], v[102:105]
	v_mfma_f32_16x16x32_bf16 v[82:85], v[162:165], v[202:205], v[82:85]
	v_mfma_f32_16x16x32_bf16 v[86:89], v[170:173], v[202:205], v[86:89]
	v_mfma_f32_16x16x32_bf16 v[66:69], v[162:165], v[214:217], v[66:69]
	v_mfma_f32_16x16x32_bf16 v[70:73], v[170:173], v[214:217], v[70:73]
	v_mfma_f32_16x16x32_bf16 v[114:117], v[166:169], v[190:193], v[114:117]
	v_mfma_f32_16x16x32_bf16 v[118:121], v[174:177], v[190:193], v[118:121]
	v_mfma_f32_16x16x32_bf16 v[98:101], v[166:169], v[198:201], v[98:101]
	v_mfma_f32_16x16x32_bf16 v[102:105], v[174:177], v[198:201], v[102:105]
	v_mfma_f32_16x16x32_bf16 v[82:85], v[166:169], v[206:209], v[82:85]
	v_mfma_f32_16x16x32_bf16 v[86:89], v[174:177], v[206:209], v[86:89]
	v_mfma_f32_16x16x32_bf16 v[66:69], v[166:169], v[218:221], v[66:69]
	v_mfma_f32_16x16x32_bf16 v[70:73], v[174:177], v[218:221], v[70:73]
	s_setprio 0
	s_barrier
	s_add_i32 s16, s40, s2
	v_lshl_add_u64 v[178:179], s[30:31], 0, v[132:133]
	s_mov_b32 m0, s16
	ds_read_b128 v[186:189], v182 offset:16384
	ds_read_b128 v[190:193], v182 offset:17408
	ds_read_b128 v[194:197], v182 offset:18432
	ds_read_b128 v[198:201], v182 offset:19456
	ds_read_b128 v[202:205], v182 offset:20480
	ds_read_b128 v[206:209], v182 offset:21504
	ds_read_b128 v[214:217], v182 offset:22528
	ds_read_b128 v[218:221], v182 offset:23552
	global_load_lds_dwordx4 v[178:179], off
	s_add_i32 m0, s16, 0x2000
	s_add_u32 s56, s30, 0x40000
	v_lshl_add_u64 v[210:211], s[30:31], 0, v[136:137]
	s_addc_u32 s57, s31, 0
	s_add_i32 s16, s41, s2
	global_load_lds_dwordx4 v[210:211], off
	v_lshl_add_u64 v[222:223], s[56:57], 0, v[132:133]
	s_mov_b32 m0, s16
	v_lshl_add_u64 v[224:225], s[34:35], 0, v[134:135]
	global_load_lds_dwordx4 v[222:223], off
	v_lshl_add_u64 v[222:223], s[56:57], 0, v[136:137]
	s_add_i32 m0, s16, 0x2000
	s_nop 0
	global_load_lds_dwordx4 v[222:223], off
	v_lshl_add_u64 v[222:223], s[34:35], 0, v[130:131]
	s_mov_b32 m0, s3
	s_nop 0
	global_load_lds_dwordx4 v[222:223], off
	s_mov_b32 m0, s17
	s_nop 0
	global_load_lds_dwordx4 v[224:225], off
	s_waitcnt vmcnt(8)
	s_waitcnt lgkmcnt(0)
	s_barrier
; #define PG8_STAGE(bufoff, gbase, voff) do { _Pragma("unroll") for (int _i = 0; _i < 2; ++_i) \
;     __builtin_amdgcn_global_load_lds((const unsigned*)((const char*)(gbase) + (voff)[_i]), (PG8_LAS unsigned*)(lds + (bufoff) + ldsw + _i * 8192), 16, 0, 0); } while (0)
; #define PG8_LDA(dst, b, h) do { _Pragma("unroll") for (int m = 0; m < 4; ++m) _Pragma("unroll") for (int k = 0; k < 2; ++k) dst[m][k] = *(const PG8_LAS bf16x8*)(lds + PG8_SA(b, h) + aoff + m * 2048 + k * 1024); } while (0)
; #define PG8_LDB(dst, b, h) do { _Pragma("unroll") for (int n = 0; n < 2; ++n) _Pragma("unroll") for (int k = 0; k < 2; ++k) dst[n][k] = *(const PG8_LAS bf16x8*)(lds + PG8_SB(b, h) + boff + n * 2048 + k * 1024); } while (0)
; #define PG8_MMA(ai, bj, At, Bt) do { __builtin_amdgcn_s_setprio(1); _Pragma("unroll") for (int m = 0; m < 4; ++m) _Pragma("unroll") for (int n = 0; n < 2; ++n) _Pragma("unroll") for (int k = 0; k < 2; ++k) \
;     acc[ai][bj][m][n] = __builtin_amdgcn_mfma_f32_16x16x32_bf16(Bt[n][k], At[m][k], acc[ai][bj][m][n], 0, 0, 0); __builtin_amdgcn_s_setprio(0); } while (0)
; #define PG8_WAIT_V(n) asm volatile("s_waitcnt vmcnt(" #n ")" ::: "memory")
; #define PG8_WAIT_L(n) asm volatile("s_waitcnt lgkmcnt(" #n ")" ::: "memory")
; #define PG8_BAR __builtin_amdgcn_s_barrier()
; #define PG8_SCHED __builtin_amdgcn_sched_barrier(0)
; template <class Epi, class Sched>
; DI void gemm_phase(PG8_LAS unsigned char* lds, const Gemm g, const Sched& S, const Epi& E) {
;     ...
;       PG8_WAIT_V(8); PG8_WAIT_L(0); PG8_BAR; PG8_MMA(1, 0, At, B0); PG8_MMA(1, 1, At, B1); PG8_BAR; PG8_SCHED;
;       PG8_LDB(B0, 1, 0); PG8_LDB(B1, 1, 1); PG8_SCHED; PG8_LDA(At, 1, 0); PG8_STAGE(PG8_SA(0, 1), a2 + hstepA, voffA);
;       PG8_WAIT_V(8); PG8_WAIT_L(0); PG8_BAR; PG8_MMA(0, 0, At, B0); PG8_MMA(0, 1, At, B1); PG8_BAR; PG8_SCHED;
;       PG8_LDA(At, 1, 1); PG8_STAGE(PG8_SB(1, 0), b3, voffB); PG8_STAGE(PG8_SB(1, 1), b3 + hstepB, voffB); PG8_STAGE(PG8_SA(1, 0), a3, voffA);
;       PG8_WAIT_V(8); PG8_WAIT_L(0); PG8_BAR; PG8_MMA(1, 0, At, B0); PG8_MMA(1, 1, At, B1); PG8_BAR; PG8_SCHED;
	s_setprio 1
	s_waitcnt lgkmcnt(0)
	v_mfma_f32_16x16x32_bf16 v[58:61], v[146:149], v[186:189], v[58:61]
	v_mfma_f32_16x16x32_bf16 v[62:65], v[154:157], v[186:189], v[62:65]
	v_mfma_f32_16x16x32_bf16 v[42:45], v[146:149], v[194:197], v[42:45]
	v_mfma_f32_16x16x32_bf16 v[46:49], v[154:157], v[194:197], v[46:49]
	v_mfma_f32_16x16x32_bf16 v[26:29], v[146:149], v[202:205], v[26:29]
	v_mfma_f32_16x16x32_bf16 v[30:33], v[154:157], v[202:205], v[30:33]
	v_mfma_f32_16x16x32_bf16 v[10:13], v[146:149], v[214:217], v[10:13]
	v_mfma_f32_16x16x32_bf16 v[14:17], v[154:157], v[214:217], v[14:17]
	v_mfma_f32_16x16x32_bf16 v[58:61], v[150:153], v[190:193], v[58:61]
	v_mfma_f32_16x16x32_bf16 v[62:65], v[158:161], v[190:193], v[62:65]
	v_mfma_f32_16x16x32_bf16 v[42:45], v[150:153], v[198:201], v[42:45]
	v_mfma_f32_16x16x32_bf16 v[46:49], v[158:161], v[198:201], v[46:49]
	v_mfma_f32_16x16x32_bf16 v[26:29], v[150:153], v[206:209], v[26:29]
	v_mfma_f32_16x16x32_bf16 v[30:33], v[158:161], v[206:209], v[30:33]
	v_mfma_f32_16x16x32_bf16 v[10:13], v[150:153], v[218:221], v[10:13]
	v_mfma_f32_16x16x32_bf16 v[14:17], v[158:161], v[218:221], v[14:17]
	s_setprio 0
	s_setprio 1
	v_mfma_f32_16x16x32_bf16 v[50:53], v[162:165], v[186:189], v[50:53]
	v_mfma_f32_16x16x32_bf16 v[54:57], v[170:173], v[186:189], v[54:57]
	v_mfma_f32_16x16x32_bf16 v[34:37], v[162:165], v[194:197], v[34:37]
	v_mfma_f32_16x16x32_bf16 v[38:41], v[170:173], v[194:197], v[38:41]
	v_mfma_f32_16x16x32_bf16 v[18:21], v[162:165], v[202:205], v[18:21]
	v_mfma_f32_16x16x32_bf16 v[22:25], v[170:173], v[202:205], v[22:25]
	v_mfma_f32_16x16x32_bf16 v[6:9], v[162:165], v[214:217], v[6:9]
	v_mfma_f32_16x16x32_bf16 v[2:5], v[170:173], v[214:217], v[2:5]
	v_mfma_f32_16x16x32_bf16 v[50:53], v[166:169], v[190:193], v[50:53]
	v_mfma_f32_16x16x32_bf16 v[54:57], v[174:177], v[190:193], v[54:57]
	v_mfma_f32_16x16x32_bf16 v[34:37], v[166:169], v[198:201], v[34:37]
	v_mfma_f32_16x16x32_bf16 v[38:41], v[174:177], v[198:201], v[38:41]
	v_mfma_f32_16x16x32_bf16 v[18:21], v[166:169], v[206:209], v[18:21]
	v_mfma_f32_16x16x32_bf16 v[22:25], v[174:177], v[206:209], v[22:25]
	v_mfma_f32_16x16x32_bf16 v[6:9], v[166:169], v[218:221], v[6:9]
	v_mfma_f32_16x16x32_bf16 v[2:5], v[174:177], v[218:221], v[2:5]
	s_setprio 0
	s_barrier
	ds_read_b128 v[146:149], v184
	ds_read_b128 v[150:153], v184 offset:1024
	ds_read_b128 v[154:157], v184 offset:2048
	ds_read_b128 v[158:161], v184 offset:3072
	ds_read_b128 v[162:165], v185
	ds_read_b128 v[166:169], v185 offset:1024
	ds_read_b128 v[170:173], v185 offset:2048
	ds_read_b128 v[174:177], v185 offset:3072
	s_add_u32 s34, s34, 0x40000
	s_addc_u32 s35, s35, 0
	s_mov_b32 m0, s19
	v_lshl_add_u64 v[226:227], s[34:35], 0, v[130:131]
	ds_read_b128 v[186:189], v182 offset:32768
	ds_read_b128 v[190:193], v182 offset:33792
	ds_read_b128 v[194:197], v182 offset:34816
	ds_read_b128 v[198:201], v182 offset:35840
	ds_read_b128 v[202:205], v182 offset:36864
	ds_read_b128 v[206:209], v182 offset:37888
	ds_read_b128 v[214:217], v182 offset:38912
	ds_read_b128 v[218:221], v182 offset:39936
	global_load_lds_dwordx4 v[226:227], off
	v_lshl_add_u64 v[226:227], s[34:35], 0, v[134:135]
	s_mov_b32 m0, s33
	s_nop 0
	global_load_lds_dwordx4 v[226:227], off
	s_waitcnt vmcnt(8)
	s_waitcnt lgkmcnt(0)
	s_barrier
	s_setprio 1
	s_waitcnt lgkmcnt(0)
	v_mfma_f32_16x16x32_bf16 v[122:125], v[146:149], v[186:189], v[122:125]
	v_mfma_f32_16x16x32_bf16 v[126:129], v[154:157], v[186:189], v[126:129]
	v_mfma_f32_16x16x32_bf16 v[106:109], v[146:149], v[194:197], v[106:109]
	v_mfma_f32_16x16x32_bf16 v[110:113], v[154:157], v[194:197], v[110:113]
	v_mfma_f32_16x16x32_bf16 v[90:93], v[146:149], v[202:205], v[90:93]
	v_mfma_f32_16x16x32_bf16 v[94:97], v[154:157], v[202:205], v[94:97]
	v_mfma_f32_16x16x32_bf16 v[74:77], v[146:149], v[214:217], v[74:77]
	v_mfma_f32_16x16x32_bf16 v[78:81], v[154:157], v[214:217], v[78:81]
	v_mfma_f32_16x16x32_bf16 v[122:125], v[150:153], v[190:193], v[122:125]
	v_mfma_f32_16x16x32_bf16 v[126:129], v[158:161], v[190:193], v[126:129]
	v_mfma_f32_16x16x32_bf16 v[106:109], v[150:153], v[198:201], v[106:109]
	v_mfma_f32_16x16x32_bf16 v[110:113], v[158:161], v[198:201], v[110:113]
	v_mfma_f32_16x16x32_bf16 v[90:93], v[150:153], v[206:209], v[90:93]
	v_mfma_f32_16x16x32_bf16 v[94:97], v[158:161], v[206:209], v[94:97]
	v_mfma_f32_16x16x32_bf16 v[74:77], v[150:153], v[218:221], v[74:77]
	v_mfma_f32_16x16x32_bf16 v[78:81], v[158:161], v[218:221], v[78:81]
	s_setprio 0
	s_setprio 1
	v_mfma_f32_16x16x32_bf16 v[114:117], v[162:165], v[186:189], v[114:117]
	v_mfma_f32_16x16x32_bf16 v[118:121], v[170:173], v[186:189], v[118:121]
	v_mfma_f32_16x16x32_bf16 v[98:101], v[162:165], v[194:197], v[98:101]
	v_mfma_f32_16x16x32_bf16 v[102:105], v[170:173], v[194:197], v[102:105]
	v_mfma_f32_16x16x32_bf16 v[82:85], v[162:165], v[202:205], v[82:85]
	v_mfma_f32_16x16x32_bf16 v[86:89], v[170:173], v[202:205], v[86:89]
	v_mfma_f32_16x16x32_bf16 v[66:69], v[162:165], v[214:217], v[66:69]
	v_mfma_f32_16x16x32_bf16 v[70:73], v[170:173], v[214:217], v[70:73]
	v_mfma_f32_16x16x32_bf16 v[114:117], v[166:169], v[190:193], v[114:117]
	v_mfma_f32_16x16x32_bf16 v[118:121], v[174:177], v[190:193], v[118:121]
	v_mfma_f32_16x16x32_bf16 v[98:101], v[166:169], v[198:201], v[98:101]
	v_mfma_f32_16x16x32_bf16 v[102:105], v[174:177], v[198:201], v[102:105]
	v_mfma_f32_16x16x32_bf16 v[82:85], v[166:169], v[206:209], v[82:85]
	v_mfma_f32_16x16x32_bf16 v[86:89], v[174:177], v[206:209], v[86:89]
	v_mfma_f32_16x16x32_bf16 v[66:69], v[166:169], v[218:221], v[66:69]
	v_mfma_f32_16x16x32_bf16 v[70:73], v[174:177], v[218:221], v[70:73]
	s_setprio 0
	s_barrier
; #define PG8_STAGE(bufoff, gbase, voff) do { _Pragma("unroll") for (int _i = 0; _i < 2; ++_i) \
;     __builtin_amdgcn_global_load_lds((const unsigned*)((const char*)(gbase) + (voff)[_i]), (PG8_LAS unsigned*)(lds + (bufoff) + ldsw + _i * 8192), 16, 0, 0); } while (0)
; #define PG8_LDA(dst, b, h) do { _Pragma("unroll") for (int m = 0; m < 4; ++m) _Pragma("unroll") for (int k = 0; k < 2; ++k) dst[m][k] = *(const PG8_LAS bf16x8*)(lds + PG8_SA(b, h) + aoff + m * 2048 + k * 1024); } while (0)
; #define PG8_MMA(ai, bj, At, Bt) do { __builtin_amdgcn_s_setprio(1); _Pragma("unroll") for (int m = 0; m < 4; ++m) _Pragma("unroll") for (int n = 0; n < 2; ++n) _Pragma("unroll") for (int k = 0; k < 2; ++k) \
;     acc[ai][bj][m][n] = __builtin_amdgcn_mfma_f32_16x16x32_bf16(Bt[n][k], At[m][k], acc[ai][bj][m][n], 0, 0, 0); __builtin_amdgcn_s_setprio(0); } while (0)
; #define PG8_WAIT_V(n) asm volatile("s_waitcnt vmcnt(" #n ")" ::: "memory")
; #define PG8_WAIT_L(n) asm volatile("s_waitcnt lgkmcnt(" #n ")" ::: "memory")
; #define PG8_BAR __builtin_amdgcn_s_barrier()
; #define PG8_SCHED __builtin_amdgcn_sched_barrier(0)
; DI void rows_rstd(float (&rs)[2][4], const float* ps, const Unit& u, int wr, int fr, int fq, int p_lo, int p_hi, float inv_dim) {
;   f32x4 pv[2][4];
; #pragma unroll
;   for (int ai = 0; ai < 2; ++ai)
; #pragma unroll
;     for (int m = 0; m < 4; ++m) pv[ai][m] = *(const f32x4*)(ps + (size_t)(u.pm * BM + ai * HALF + wr * 64 + m * 16 + fr) * 16 + 4 * fq);
; template <class Epi, class Sched>
; DI void gemm_phase(PG8_LAS unsigned char* lds, const Gemm g, const Sched& S, const Epi& E) {
;     ...
;       PG8_LDA(At, 1, 1); PG8_STAGE(PG8_SB(1, 0), b3, voffB); PG8_STAGE(PG8_SB(1, 1), b3 + hstepB, voffB); PG8_STAGE(PG8_SA(1, 0), a3, voffA);
;       PG8_WAIT_V(8); PG8_WAIT_L(0); PG8_BAR; PG8_MMA(1, 0, At, B0); PG8_MMA(1, 1, At, B1); PG8_BAR; PG8_SCHED;
;     }
;     if (wr == 0) PG8_BAR;
	s_add_i32 s16, s65, s2
	v_lshl_add_u64 v[178:179], v[178:179], 0, s[12:13]
	s_mov_b32 m0, s16
	ds_read_b128 v[186:189], v182 offset:49152
	ds_read_b128 v[190:193], v182 offset:50176
	ds_read_b128 v[194:197], v182 offset:51200
	ds_read_b128 v[198:201], v182 offset:52224
	ds_read_b128 v[202:205], v182 offset:53248
	ds_read_b128 v[206:209], v182 offset:54272
	ds_read_b128 v[214:217], v182 offset:55296
	ds_read_b128 v[218:221], v182 offset:56320
	global_load_lds_dwordx4 v[178:179], off
	s_add_i32 m0, s16, 0x2000
	s_add_u32 s30, s30, 0x40080
	v_lshl_add_u64 v[178:179], v[210:211], 0, s[12:13]
	s_addc_u32 s31, s31, 0
	s_add_i32 s16, s66, s2
	global_load_lds_dwordx4 v[178:179], off
	v_lshl_add_u64 v[178:179], s[30:31], 0, v[132:133]
	s_mov_b32 m0, s16
	s_nop 0
	global_load_lds_dwordx4 v[178:179], off
	v_lshl_add_u64 v[178:179], s[30:31], 0, v[136:137]
	s_add_i32 m0, s16, 0x2000
	s_nop 0
	global_load_lds_dwordx4 v[178:179], off
	v_lshl_add_u64 v[178:179], v[222:223], 0, s[12:13]
	s_mov_b32 m0, s36
	s_nop 0
	global_load_lds_dwordx4 v[178:179], off
	v_lshl_add_u64 v[178:179], v[224:225], 0, s[12:13]
	s_mov_b32 m0, s37
	s_nop 0
	global_load_lds_dwordx4 v[178:179], off
	s_waitcnt vmcnt(8)
	s_waitcnt lgkmcnt(0)
	s_barrier
	s_setprio 1
	s_waitcnt lgkmcnt(0)
	v_mfma_f32_16x16x32_bf16 v[58:61], v[146:149], v[186:189], v[58:61]
	v_mfma_f32_16x16x32_bf16 v[62:65], v[154:157], v[186:189], v[62:65]
	v_mfma_f32_16x16x32_bf16 v[42:45], v[146:149], v[194:197], v[42:45]
	v_mfma_f32_16x16x32_bf16 v[46:49], v[154:157], v[194:197], v[46:49]
	v_mfma_f32_16x16x32_bf16 v[26:29], v[146:149], v[202:205], v[26:29]
	v_mfma_f32_16x16x32_bf16 v[30:33], v[154:157], v[202:205], v[30:33]
	v_mfma_f32_16x16x32_bf16 v[10:13], v[146:149], v[214:217], v[10:13]
	v_mfma_f32_16x16x32_bf16 v[14:17], v[154:157], v[214:217], v[14:17]
	v_mfma_f32_16x16x32_bf16 v[58:61], v[150:153], v[190:193], v[58:61]
	v_mfma_f32_16x16x32_bf16 v[62:65], v[158:161], v[190:193], v[62:65]
	v_mfma_f32_16x16x32_bf16 v[42:45], v[150:153], v[198:201], v[42:45]
	v_mfma_f32_16x16x32_bf16 v[46:49], v[158:161], v[198:201], v[46:49]
	v_mfma_f32_16x16x32_bf16 v[26:29], v[150:153], v[206:209], v[26:29]
	v_mfma_f32_16x16x32_bf16 v[30:33], v[158:161], v[206:209], v[30:33]
	v_mfma_f32_16x16x32_bf16 v[10:13], v[150:153], v[218:221], v[10:13]
	v_mfma_f32_16x16x32_bf16 v[14:17], v[158:161], v[218:221], v[14:17]
	s_setprio 0
	s_setprio 1
	v_mfma_f32_16x16x32_bf16 v[50:53], v[162:165], v[186:189], v[50:53]
	v_mfma_f32_16x16x32_bf16 v[54:57], v[170:173], v[186:189], v[54:57]
	v_mfma_f32_16x16x32_bf16 v[34:37], v[162:165], v[194:197], v[34:37]
	v_mfma_f32_16x16x32_bf16 v[38:41], v[170:173], v[194:197], v[38:41]
	v_mfma_f32_16x16x32_bf16 v[18:21], v[162:165], v[202:205], v[18:21]
	v_mfma_f32_16x16x32_bf16 v[22:25], v[170:173], v[202:205], v[22:25]
	v_mfma_f32_16x16x32_bf16 v[6:9], v[162:165], v[214:217], v[6:9]
	v_mfma_f32_16x16x32_bf16 v[2:5], v[170:173], v[214:217], v[2:5]
	v_mfma_f32_16x16x32_bf16 v[50:53], v[166:169], v[190:193], v[50:53]
	v_mfma_f32_16x16x32_bf16 v[54:57], v[174:177], v[190:193], v[54:57]
	v_mfma_f32_16x16x32_bf16 v[34:37], v[166:169], v[198:201], v[34:37]
	v_mfma_f32_16x16x32_bf16 v[38:41], v[174:177], v[198:201], v[38:41]
	v_mfma_f32_16x16x32_bf16 v[18:21], v[166:169], v[206:209], v[18:21]
	v_mfma_f32_16x16x32_bf16 v[22:25], v[174:177], v[206:209], v[22:25]
	v_mfma_f32_16x16x32_bf16 v[6:9], v[166:169], v[218:221], v[6:9]
	v_mfma_f32_16x16x32_bf16 v[2:5], v[174:177], v[218:221], v[2:5]
	s_setprio 0
	s_barrier
	s_add_i32 s69, s69, 2
	s_add_u32 s6, s6, 0x100
	s_addc_u32 s7, s7, 0
	s_add_u32 s67, s67, 0x100
	s_addc_u32 s68, s68, 0
	s_cmp_gt_u32 s69, 13
	s_cbranch_scc0 .LBB0_286
	v_lshl_add_u32 v166, s4, 8, v1
	v_or_b32_e32 v164, 16, v166
	v_ashrrev_i32_e32 v165, 31, v164
	v_or_b32_e32 v158, 32, v166
	v_lshlrev_b64 v[146:147], 6, v[164:165]
	v_ashrrev_i32_e32 v159, 31, v158
	v_lshl_add_u64 v[146:147], v[138:139], 0, v[146:147]
	v_lshlrev_b64 v[148:149], 6, v[158:159]
	v_ashrrev_i32_e32 v167, 31, v166
	v_lshl_add_u64 v[148:149], v[138:139], 0, v[148:149]
	global_load_dwordx4 v[160:163], v[146:147], off
	global_load_dwordx4 v[168:171], v[148:149], off
	v_lshlrev_b64 v[146:147], 6, v[166:167]
	v_lshl_add_u64 v[146:147], v[138:139], 0, v[146:147]
	global_load_dwordx4 v[172:175], v[146:147], off
	v_or_b32_e32 v156, 48, v166
	v_ashrrev_i32_e32 v157, 31, v156
	v_add_u32_e32 v154, 0x80, v166
	v_lshlrev_b64 v[146:147], 6, v[156:157]
	v_ashrrev_i32_e32 v155, 31, v154
	v_add_u32_e32 v150, 0x90, v166
	v_lshl_add_u64 v[146:147], v[138:139], 0, v[146:147]
	v_lshlrev_b64 v[148:149], 6, v[154:155]
	v_ashrrev_i32_e32 v151, 31, v150
	v_lshl_add_u64 v[148:149], v[138:139], 0, v[148:149]
	global_load_dwordx4 v[176:179], v[146:147], off
	global_load_dwordx4 v[186:189], v[148:149], off
	v_lshlrev_b64 v[146:147], 6, v[150:151]
	v_lshl_add_u64 v[146:147], v[138:139], 0, v[146:147]
	global_load_dwordx4 v[190:193], v[146:147], off
	v_add_u32_e32 v148, 0xa0, v166
	v_ashrrev_i32_e32 v149, 31, v148
	v_lshlrev_b64 v[146:147], 6, v[148:149]
	v_lshl_add_u64 v[146:147], v[138:139], 0, v[146:147]
	global_load_dwordx4 v[194:197], v[146:147], off
	v_add_u32_e32 v146, 0xb0, v166
	v_ashrrev_i32_e32 v147, 31, v146
	v_lshlrev_b64 v[152:153], 6, v[146:147]
	v_lshl_add_u64 v[152:153], v[138:139], 0, v[152:153]
	global_load_dwordx4 v[198:201], v[152:153], off
	s_and_b64 vcc, exec, s[14:15]
	s_cbranch_vccz .LBB0_289
	s_barrier
; DI unsigned pack2(float a, float b) { bf2_t v = __builtin_convertvector((f32x2){a, b}, bf2_t); return __builtin_bit_cast(unsigned, v); }
; DI void rows_rstd(float (&rs)[2][4], const float* ps, const Unit& u, int wr, int fr, int fq, int p_lo, int p_hi, float inv_dim) {
;     ...
;   const bool use = (4 * fq >= p_lo) && (4 * fq < p_hi);
; #pragma unroll
;   for (int ai = 0; ai < 2; ++ai)
; #pragma unroll
;     for (int m = 0; m < 4; ++m) {
;       float s = use ? (pv[ai][m][0] + pv[ai][m][1]) + (pv[ai][m][2] + pv[ai][m][3]) : 0.f;
;       s += __shfl_xor(s, 16); s += __shfl_xor(s, 32);
;       rs[ai][m] = rsqrtf(s * inv_dim + EPS);
;     }
; }
;   DI void operator()(const f32x4 (&acc)[2][2][4][2], const Unit& u, int wr, int wc, int fr, int fq) const {
;     float rsv[2][4];
;     if (ps_in) rows_rstd(rsv, ps_in, u, wr, fr, fq, p_lo, p_hi, inv_dim);
; #pragma unroll
;     for (int ai = 0; ai < 2; ++ai)
; #pragma unroll
;       for (int m = 0; m < 4; ++m) {
;         const int row = u.pm * BM + ai * HALF + wr * 64 + m * 16 + fr;
;         const float rs = ps_in ? rsv[ai][m] : 1.f;
;         float ssum = 0.f;
; #pragma unroll
;         for (int bj = 0; bj < 2; ++bj) {
;           const int c0 = u.pn * BM + bj * HALF + wc * 32 + 8 * fq;
;           const f32x4 v0 = acc[ai][bj][m][0] * rs, v1 = acc[ai][bj][m][1] * rs;
;           if (PSOUT) ssum += (v0[0] * v0[0] + v0[1] * v0[1]) + (v0[2] * v0[2] + v0[3] * v0[3]) + (v1[0] * v1[0] + v1[1] * v1[1]) + (v1[2] * v1[2] + v1[3] * v1[3]);
;           u32x4 w; w.x = pack2(v0[0], v0[1]); w.y = pack2(v0[2], v0[3]); w.z = pack2(v1[0], v1[1]); w.w = pack2(v1[2], v1[3]);
;           if (EMODE == EM_KVUP) {
;             const int hh = c0 >> 7, j = c0 & 127;
;             if (j < 64) *(u32x4*)(O + (size_t)row * 1152 + hh * 96 + j) = w; else *(u32x4*)(O2 + (size_t)row * 768 + hh * 64 + (j - 64)) = w;
;           } else {
;             if (c0 < ncols) *(u32x4*)(O + (size_t)row * ldo + c0) = w;
.LBB0_289:
	v_and_b32_e32 v149, 64, v183
	v_xor_b32_e32 v147, 32, v183
	v_add_u32_e32 v149, 64, v149
	v_xor_b32_e32 v151, 16, v183
	v_cmp_lt_i32_e32 vcc, v147, v149
	s_waitcnt vmcnt(0)
	v_mov_b32_e32 v152, v173
	v_mov_b32_e32 v153, v174
	v_mov_b32_e32 v173, v175
	v_mov_b32_e32 v174, v161
	v_mov_b32_e32 v175, v162
	v_mov_b32_e32 v161, v163
	v_cndmask_b32_e32 v147, v183, v147, vcc
	v_cmp_lt_i32_e32 vcc, v151, v149
	v_pk_add_f32 v[152:153], v[152:153], v[172:173]
	v_pk_add_f32 v[160:161], v[174:175], v[160:161]
	v_cndmask_b32_e32 v149, v183, v151, vcc
	v_mov_b32_e32 v174, v160
	v_mov_b32_e32 v175, v152
	v_mov_b32_e32 v152, v161
	v_lshlrev_b32_e32 v149, 2, v149
	v_pk_add_f32 v[152:153], v[174:175], v[152:153]
	ds_bpermute_b32 v175, v149, v153
	ds_bpermute_b32 v174, v149, v152
	v_mov_b32_e32 v162, v169
	v_mov_b32_e32 v163, v170
	v_mov_b32_e32 v169, v171
	v_mov_b32_e32 v170, v177
	v_mov_b32_e32 v171, v178
	v_mov_b32_e32 v177, v179
	v_mov_b32_e32 v178, v187
	v_mov_b32_e32 v179, v188
	v_mov_b32_e32 v187, v189
	v_mov_b32_e32 v188, v191
	v_mov_b32_e32 v189, v192
	v_mov_b32_e32 v191, v193
	v_pk_add_f32 v[162:163], v[162:163], v[168:169]
	v_pk_add_f32 v[168:169], v[170:171], v[176:177]
	v_pk_add_f32 v[170:171], v[178:179], v[186:187]
	v_pk_add_f32 v[172:173], v[188:189], v[190:191]
	v_lshlrev_b32_e32 v147, 2, v147
	v_mov_b32_e32 v160, v168
	v_mov_b32_e32 v161, v162
	v_mov_b32_e32 v162, v169
	v_mov_b32_e32 v168, v172
	v_mov_b32_e32 v169, v170
	v_mov_b32_e32 v170, v173
	s_waitcnt lgkmcnt(0)
	v_pk_add_f32 v[152:153], v[152:153], v[174:175]
	v_pk_add_f32 v[160:161], v[160:161], v[162:163]
	v_pk_add_f32 v[162:163], v[168:169], v[170:171]
	ds_bpermute_b32 v169, v147, v153
	ds_bpermute_b32 v168, v147, v152
	ds_bpermute_b32 v171, v149, v161
	ds_bpermute_b32 v170, v149, v160
	v_mov_b32_e32 v192, v195
	v_mov_b32_e32 v193, v196
	s_waitcnt lgkmcnt(2)
	v_pk_add_f32 v[152:153], v[152:153], v[168:169]
	v_mov_b32_e32 v195, v197
	v_pk_fma_f32 v[176:177], v[152:153], s[18:19], v[144:145] op_sel_hi:[1,0,0]
	v_mov_b32_e32 v153, v200
	v_mul_f32_e32 v151, 0x4b800000, v177
	v_cmp_gt_f32_e32 vcc, s53, v177
	v_pk_add_f32 v[186:187], v[192:193], v[194:195]
	s_waitcnt lgkmcnt(0)
	v_pk_add_f32 v[172:173], v[160:161], v[170:171]
	v_cndmask_b32_e32 v151, v177, v151, vcc
	v_rsq_f32_e32 v151, v151
	v_mov_b32_e32 v161, v186
	ds_bpermute_b32 v189, v149, v163
	ds_bpermute_b32 v188, v149, v162
	v_mul_f32_e32 v152, 0x45800000, v151
	v_cndmask_b32_e32 v178, v151, v152, vcc
	v_mov_b32_e32 v152, v199
	v_mov_b32_e32 v199, v201
	v_pk_add_f32 v[152:153], v[152:153], v[198:199]
	s_waitcnt lgkmcnt(0)
	v_pk_add_f32 v[168:169], v[162:163], v[188:189]
	v_mov_b32_e32 v160, v152
	v_mov_b32_e32 v186, v153
	v_pk_add_f32 v[152:153], v[160:161], v[186:187]
	ds_bpermute_b32 v161, v149, v153
	ds_bpermute_b32 v160, v149, v152
	ds_bpermute_b32 v175, v147, v173
	ds_bpermute_b32 v174, v147, v172
	ds_bpermute_b32 v171, v147, v169
	ds_bpermute_b32 v170, v147, v168
	s_waitcnt lgkmcnt(4)
	v_pk_add_f32 v[160:161], v[152:153], v[160:161]
	ds_bpermute_b32 v163, v147, v161
	ds_bpermute_b32 v162, v147, v160
	v_lshl_or_b32 v152, s0, 8, v145
	v_cmp_gt_f32_e64 s[6:7], s53, v176
	v_mov_b32_e32 v179, v178
	v_cmp_gt_i32_e32 vcc, s55, v152
	v_ashrrev_i32_e32 v153, 31, v152
	s_and_saveexec_b64 s[0:1], vcc
	s_cbranch_execz .LBB0_291
	v_mov_b32_e32 v186, v178
	v_mov_b32_e32 v187, v178
	v_pk_mul_f32 v[124:125], v[124:125], v[186:187]
	v_pk_mul_f32 v[122:123], v[122:123], v[178:179]
	v_cvt_pk_bf16_f32 v125, v124, v125
	v_cvt_pk_bf16_f32 v124, v122, v123
	v_mov_b64_e32 v[122:123], s[46:47]
	v_pk_mul_f32 v[128:129], v[128:129], v[186:187]
	v_pk_mul_f32 v[188:189], v[126:127], v[178:179]
	v_mad_i64_i32 v[122:123], s[4:5], v166, s64, v[122:123]
	v_cvt_pk_bf16_f32 v127, v128, v129
	v_cvt_pk_bf16_f32 v126, v188, v189
	v_lshl_add_u64 v[122:123], v[152:153], 1, v[122:123]
	global_store_dwordx4 v[122:123], v[124:127], off

; #define PG8_STAGE(bufoff, gbase, voff) do { _Pragma("unroll") for (int _i = 0; _i < 2; ++_i) \
;     __builtin_amdgcn_global_load_lds((const unsigned*)((const char*)(gbase) + (voff)[_i]), (PG8_LAS unsigned*)(lds + (bufoff) + ldsw + _i * 8192), 16, 0, 0); } while (0)
; #define PG8_LDA(dst, b, h) do { _Pragma("unroll") for (int m = 0; m < 4; ++m) _Pragma("unroll") for (int k = 0; k < 2; ++k) dst[m][k] = *(const PG8_LAS bf16x8*)(lds + PG8_SA(b, h) + aoff + m * 2048 + k * 1024); } while (0)
; #define PG8_LDB(dst, b, h) do { _Pragma("unroll") for (int n = 0; n < 2; ++n) _Pragma("unroll") for (int k = 0; k < 2; ++k) dst[n][k] = *(const PG8_LAS bf16x8*)(lds + PG8_SB(b, h) + boff + n * 2048 + k * 1024); } while (0)
; #define PG8_MMA(ai, bj, At, Bt) do { __builtin_amdgcn_s_setprio(1); _Pragma("unroll") for (int m = 0; m < 4; ++m) _Pragma("unroll") for (int n = 0; n < 2; ++n) _Pragma("unroll") for (int k = 0; k < 2; ++k) \
;     acc[ai][bj][m][n] = __builtin_amdgcn_mfma_f32_16x16x32_bf16(Bt[n][k], At[m][k], acc[ai][bj][m][n], 0, 0, 0); __builtin_amdgcn_s_setprio(0); } while (0)
; #define PG8_WAIT_V(n) asm volatile("s_waitcnt vmcnt(" #n ")" ::: "memory")
; #define PG8_WAIT_L(n) asm volatile("s_waitcnt lgkmcnt(" #n ")" ::: "memory")
; #define PG8_BAR __builtin_amdgcn_s_barrier()
; #define PG8_SCHED __builtin_amdgcn_sched_barrier(0)
; template <class Epi, class Sched>
; DI void gemm_phase(PG8_LAS unsigned char* lds, const Gemm g, const Sched& S, const Epi& E) {
;     ...
;       const char* a1 = cA + (size_t)(t + 1) * kstep;
;       const char* a2 = last ? nA : cA + (size_t)(t + 2) * kstep; const char* b2 = last ? nB : cB + (size_t)(t + 2) * kstep;
;       const char* a3 = a2 + kstep; const char* b3 = b2 + kstep;
;       PG8_LDB(B0, 0, 0); PG8_LDB(B1, 0, 1); PG8_SCHED; PG8_LDA(At, 0, 0); PG8_STAGE(PG8_SA(1, 1), a1 + hstepA, voffA);
;       PG8_WAIT_V(8); PG8_WAIT_L(0); PG8_BAR; PG8_MMA(0, 0, At, B0); PG8_MMA(0, 1, At, B1); PG8_BAR; PG8_SCHED;
;       PG8_LDA(At, 0, 1); PG8_STAGE(PG8_SB(0, 0), b2, voffB); PG8_STAGE(PG8_SB(0, 1), b2 + hstepB, voffB); PG8_STAGE(PG8_SA(0, 0), a2, voffA);
;       PG8_WAIT_V(8); PG8_WAIT_L(0); PG8_BAR; PG8_MMA(1, 0, At, B0); PG8_MMA(1, 1, At, B1); PG8_BAR; PG8_SCHED;
;       PG8_LDB(B0, 1, 0); PG8_LDB(B1, 1, 1); PG8_SCHED; PG8_LDA(At, 1, 0); PG8_STAGE(PG8_SA(0, 1), a2 + hstepA, voffA);
.LBB0_563:
	ds_read_b128 v[128:131], v167
	ds_read_b128 v[132:135], v167 offset:1024
	ds_read_b128 v[136:139], v167 offset:2048
	ds_read_b128 v[140:143], v167 offset:3072
	ds_read_b128 v[158:161], v168
	ds_read_b128 v[162:165], v168 offset:1024
	ds_read_b128 v[172:175], v168 offset:2048
	ds_read_b128 v[176:179], v168 offset:3072
	s_add_u32 s16, s28, 0xfffc0080
	s_addc_u32 s17, s29, -1
	s_cmp_eq_u32 s70, 12
	s_cselect_b32 s35, s19, s17
	s_cselect_b32 s34, s27, s16
	s_cselect_b32 s31, s15, s69
	s_cselect_b32 s30, s67, s68
	v_lshl_add_u64 v[214:215], s[28:29], 0, v[154:155]
	s_add_i32 m0, s3, 0xc000
	ds_read_b128 v[180:183], v169
	ds_read_b128 v[184:187], v169 offset:1024
	ds_read_b128 v[188:191], v169 offset:2048
	ds_read_b128 v[192:195], v169 offset:3072
	ds_read_b128 v[196:199], v169 offset:4096
	ds_read_b128 v[200:203], v169 offset:5120
	ds_read_b128 v[204:207], v169 offset:6144
	ds_read_b128 v[208:211], v169 offset:7168
	global_load_lds_dwordx4 v[214:215], off
	v_lshl_add_u64 v[214:215], s[28:29], 0, v[156:157]
	s_add_i32 m0, s3, 0xe000
	s_nop 0
	global_load_lds_dwordx4 v[214:215], off
	s_waitcnt vmcnt(8)
	s_waitcnt lgkmcnt(0)
	s_barrier
	s_setprio 1
	s_waitcnt lgkmcnt(0)
	v_mfma_f32_16x16x32_bf16 v[124:127], v[128:131], v[180:183], v[124:127]
	v_mfma_f32_16x16x32_bf16 v[120:123], v[136:139], v[180:183], v[120:123]
	v_mfma_f32_16x16x32_bf16 v[108:111], v[128:131], v[188:191], v[108:111]
	v_mfma_f32_16x16x32_bf16 v[104:107], v[136:139], v[188:191], v[104:107]
	v_mfma_f32_16x16x32_bf16 v[92:95], v[128:131], v[196:199], v[92:95]
	v_mfma_f32_16x16x32_bf16 v[88:91], v[136:139], v[196:199], v[88:91]
	v_mfma_f32_16x16x32_bf16 v[76:79], v[128:131], v[204:207], v[76:79]
	v_mfma_f32_16x16x32_bf16 v[72:75], v[136:139], v[204:207], v[72:75]
	v_mfma_f32_16x16x32_bf16 v[124:127], v[132:135], v[184:187], v[124:127]
	v_mfma_f32_16x16x32_bf16 v[120:123], v[140:143], v[184:187], v[120:123]
	v_mfma_f32_16x16x32_bf16 v[108:111], v[132:135], v[192:195], v[108:111]
	v_mfma_f32_16x16x32_bf16 v[104:107], v[140:143], v[192:195], v[104:107]
	v_mfma_f32_16x16x32_bf16 v[92:95], v[132:135], v[200:203], v[92:95]
	v_mfma_f32_16x16x32_bf16 v[88:91], v[140:143], v[200:203], v[88:91]
	v_mfma_f32_16x16x32_bf16 v[76:79], v[132:135], v[208:211], v[76:79]
	v_mfma_f32_16x16x32_bf16 v[72:75], v[140:143], v[208:211], v[72:75]
	s_setprio 0
	s_setprio 1
	v_mfma_f32_16x16x32_bf16 v[116:119], v[158:161], v[180:183], v[116:119]
	v_mfma_f32_16x16x32_bf16 v[112:115], v[172:175], v[180:183], v[112:115]
	v_mfma_f32_16x16x32_bf16 v[100:103], v[158:161], v[188:191], v[100:103]
	v_mfma_f32_16x16x32_bf16 v[96:99], v[172:175], v[188:191], v[96:99]
	v_mfma_f32_16x16x32_bf16 v[84:87], v[158:161], v[196:199], v[84:87]
	v_mfma_f32_16x16x32_bf16 v[80:83], v[172:175], v[196:199], v[80:83]
	v_mfma_f32_16x16x32_bf16 v[68:71], v[158:161], v[204:207], v[68:71]
	v_mfma_f32_16x16x32_bf16 v[64:67], v[172:175], v[204:207], v[64:67]
	v_mfma_f32_16x16x32_bf16 v[116:119], v[162:165], v[184:187], v[116:119]
	v_mfma_f32_16x16x32_bf16 v[112:115], v[176:179], v[184:187], v[112:115]
	v_mfma_f32_16x16x32_bf16 v[100:103], v[162:165], v[192:195], v[100:103]
	v_mfma_f32_16x16x32_bf16 v[96:99], v[176:179], v[192:195], v[96:99]
	v_mfma_f32_16x16x32_bf16 v[84:87], v[162:165], v[200:203], v[84:87]
	v_mfma_f32_16x16x32_bf16 v[80:83], v[176:179], v[200:203], v[80:83]
	v_mfma_f32_16x16x32_bf16 v[68:71], v[162:165], v[208:211], v[68:71]
	v_mfma_f32_16x16x32_bf16 v[64:67], v[176:179], v[208:211], v[64:67]
	s_setprio 0
	s_barrier
	s_add_i32 s16, s55, s2
	v_lshl_add_u64 v[214:215], s[30:31], 0, v[146:147]
	s_mov_b32 m0, s16
	ds_read_b128 v[180:183], v169 offset:16384
	ds_read_b128 v[184:187], v169 offset:17408
	ds_read_b128 v[188:191], v169 offset:18432
	ds_read_b128 v[192:195], v169 offset:19456
	ds_read_b128 v[196:199], v169 offset:20480
	ds_read_b128 v[200:203], v169 offset:21504
	ds_read_b128 v[204:207], v169 offset:22528
	ds_read_b128 v[208:211], v169 offset:23552
	global_load_lds_dwordx4 v[214:215], off
	s_add_i32 m0, s16, 0x2000
	s_add_u32 s16, s30, 0x40000
	v_lshl_add_u64 v[216:217], s[30:31], 0, v[150:151]
	s_addc_u32 s17, s31, 0
	s_add_i32 s33, s64, s2
	global_load_lds_dwordx4 v[216:217], off
	v_lshl_add_u64 v[218:219], s[16:17], 0, v[146:147]
	s_mov_b32 m0, s33
	v_lshl_add_u64 v[220:221], s[34:35], 0, v[148:149]
	global_load_lds_dwordx4 v[218:219], off
	v_lshl_add_u64 v[218:219], s[16:17], 0, v[150:151]
	s_add_i32 m0, s33, 0x2000
	s_nop 0
	global_load_lds_dwordx4 v[218:219], off
	v_lshl_add_u64 v[218:219], s[34:35], 0, v[144:145]
	s_mov_b32 m0, s3
	s_nop 0
	global_load_lds_dwordx4 v[218:219], off
	s_mov_b32 m0, s36
	s_nop 0
	global_load_lds_dwordx4 v[220:221], off
	s_waitcnt vmcnt(8)
	s_waitcnt lgkmcnt(0)
	s_barrier
; #define PG8_STAGE(bufoff, gbase, voff) do { _Pragma("unroll") for (int _i = 0; _i < 2; ++_i) \
;     __builtin_amdgcn_global_load_lds((const unsigned*)((const char*)(gbase) + (voff)[_i]), (PG8_LAS unsigned*)(lds + (bufoff) + ldsw + _i * 8192), 16, 0, 0); } while (0)
; #define PG8_LDA(dst, b, h) do { _Pragma("unroll") for (int m = 0; m < 4; ++m) _Pragma("unroll") for (int k = 0; k < 2; ++k) dst[m][k] = *(const PG8_LAS bf16x8*)(lds + PG8_SA(b, h) + aoff + m * 2048 + k * 1024); } while (0)
; #define PG8_LDB(dst, b, h) do { _Pragma("unroll") for (int n = 0; n < 2; ++n) _Pragma("unroll") for (int k = 0; k < 2; ++k) dst[n][k] = *(const PG8_LAS bf16x8*)(lds + PG8_SB(b, h) + boff + n * 2048 + k * 1024); } while (0)
; #define PG8_MMA(ai, bj, At, Bt) do { __builtin_amdgcn_s_setprio(1); _Pragma("unroll") for (int m = 0; m < 4; ++m) _Pragma("unroll") for (int n = 0; n < 2; ++n) _Pragma("unroll") for (int k = 0; k < 2; ++k) \
;     acc[ai][bj][m][n] = __builtin_amdgcn_mfma_f32_16x16x32_bf16(Bt[n][k], At[m][k], acc[ai][bj][m][n], 0, 0, 0); __builtin_amdgcn_s_setprio(0); } while (0)
; #define PG8_WAIT_V(n) asm volatile("s_waitcnt vmcnt(" #n ")" ::: "memory")
; #define PG8_WAIT_L(n) asm volatile("s_waitcnt lgkmcnt(" #n ")" ::: "memory")
; #define PG8_BAR __builtin_amdgcn_s_barrier()
; #define PG8_SCHED __builtin_amdgcn_sched_barrier(0)
; template <class Epi, class Sched>
; DI void gemm_phase(PG8_LAS unsigned char* lds, const Gemm g, const Sched& S, const Epi& E) {
;     ...
;       PG8_WAIT_V(8); PG8_WAIT_L(0); PG8_BAR; PG8_MMA(1, 0, At, B0); PG8_MMA(1, 1, At, B1); PG8_BAR; PG8_SCHED;
;       PG8_LDB(B0, 1, 0); PG8_LDB(B1, 1, 1); PG8_SCHED; PG8_LDA(At, 1, 0); PG8_STAGE(PG8_SA(0, 1), a2 + hstepA, voffA);
;       PG8_WAIT_V(8); PG8_WAIT_L(0); PG8_BAR; PG8_MMA(0, 0, At, B0); PG8_MMA(0, 1, At, B1); PG8_BAR; PG8_SCHED;
;       PG8_LDA(At, 1, 1); PG8_STAGE(PG8_SB(1, 0), b3, voffB); PG8_STAGE(PG8_SB(1, 1), b3 + hstepB, voffB); PG8_STAGE(PG8_SA(1, 0), a3, voffA);
	s_setprio 1
	s_waitcnt lgkmcnt(0)
	v_mfma_f32_16x16x32_bf16 v[60:63], v[128:131], v[180:183], v[60:63]
	v_mfma_f32_16x16x32_bf16 v[56:59], v[136:139], v[180:183], v[56:59]
	v_mfma_f32_16x16x32_bf16 v[44:47], v[128:131], v[188:191], v[44:47]
	v_mfma_f32_16x16x32_bf16 v[40:43], v[136:139], v[188:191], v[40:43]
	v_mfma_f32_16x16x32_bf16 v[28:31], v[128:131], v[196:199], v[28:31]
	v_mfma_f32_16x16x32_bf16 v[24:27], v[136:139], v[196:199], v[24:27]
	v_mfma_f32_16x16x32_bf16 v[12:15], v[128:131], v[204:207], v[12:15]
	v_mfma_f32_16x16x32_bf16 v[8:11], v[136:139], v[204:207], v[8:11]
	v_mfma_f32_16x16x32_bf16 v[60:63], v[132:135], v[184:187], v[60:63]
	v_mfma_f32_16x16x32_bf16 v[56:59], v[140:143], v[184:187], v[56:59]
	v_mfma_f32_16x16x32_bf16 v[44:47], v[132:135], v[192:195], v[44:47]
	v_mfma_f32_16x16x32_bf16 v[40:43], v[140:143], v[192:195], v[40:43]
	v_mfma_f32_16x16x32_bf16 v[28:31], v[132:135], v[200:203], v[28:31]
	v_mfma_f32_16x16x32_bf16 v[24:27], v[140:143], v[200:203], v[24:27]
	v_mfma_f32_16x16x32_bf16 v[12:15], v[132:135], v[208:211], v[12:15]
	v_mfma_f32_16x16x32_bf16 v[8:11], v[140:143], v[208:211], v[8:11]
	s_setprio 0
	s_setprio 1
	v_mfma_f32_16x16x32_bf16 v[52:55], v[158:161], v[180:183], v[52:55]
	v_mfma_f32_16x16x32_bf16 v[48:51], v[172:175], v[180:183], v[48:51]
	v_mfma_f32_16x16x32_bf16 v[36:39], v[158:161], v[188:191], v[36:39]
	v_mfma_f32_16x16x32_bf16 v[32:35], v[172:175], v[188:191], v[32:35]
	v_mfma_f32_16x16x32_bf16 v[20:23], v[158:161], v[196:199], v[20:23]
	v_mfma_f32_16x16x32_bf16 v[16:19], v[172:175], v[196:199], v[16:19]
	v_mfma_f32_16x16x32_bf16 v[4:7], v[158:161], v[204:207], v[4:7]
	v_mfma_f32_16x16x32_bf16 v[0:3], v[172:175], v[204:207], v[0:3]
	v_mfma_f32_16x16x32_bf16 v[52:55], v[162:165], v[184:187], v[52:55]
	v_mfma_f32_16x16x32_bf16 v[48:51], v[176:179], v[184:187], v[48:51]
	v_mfma_f32_16x16x32_bf16 v[36:39], v[162:165], v[192:195], v[36:39]
	v_mfma_f32_16x16x32_bf16 v[32:35], v[176:179], v[192:195], v[32:35]
	v_mfma_f32_16x16x32_bf16 v[20:23], v[162:165], v[200:203], v[20:23]
	v_mfma_f32_16x16x32_bf16 v[16:19], v[176:179], v[200:203], v[16:19]
	v_mfma_f32_16x16x32_bf16 v[4:7], v[162:165], v[208:211], v[4:7]
	v_mfma_f32_16x16x32_bf16 v[0:3], v[176:179], v[208:211], v[0:3]
	s_setprio 0
	s_barrier
	s_add_i32 s33, s41, 0x110
	v_add_u32_e32 v140, s33, v166
	ds_read_b128 v[128:131], v140
	ds_read_b128 v[132:135], v140 offset:1024
	ds_read_b128 v[136:139], v140 offset:2048
	ds_read_b128 v[140:143], v140 offset:3072
	ds_read_b128 v[158:161], v171
	ds_read_b128 v[162:165], v171 offset:1024
	ds_read_b128 v[172:175], v171 offset:2048
	ds_read_b128 v[176:179], v171 offset:3072
	s_add_u32 s16, s34, 0x40000
	s_addc_u32 s17, s35, 0
	s_mov_b32 m0, s37
	v_lshl_add_u64 v[222:223], s[16:17], 0, v[144:145]
	ds_read_b128 v[180:183], v169 offset:32768
	ds_read_b128 v[184:187], v169 offset:33792
	ds_read_b128 v[188:191], v169 offset:34816
	ds_read_b128 v[192:195], v169 offset:35840
	ds_read_b128 v[196:199], v169 offset:36864
	ds_read_b128 v[200:203], v169 offset:37888
	ds_read_b128 v[204:207], v169 offset:38912
	ds_read_b128 v[208:211], v169 offset:39936
	global_load_lds_dwordx4 v[222:223], off
	v_lshl_add_u64 v[222:223], s[16:17], 0, v[148:149]
	s_mov_b32 m0, s38
	s_nop 0
	global_load_lds_dwordx4 v[222:223], off
	s_waitcnt vmcnt(8)
	s_waitcnt lgkmcnt(0)
	s_barrier
	s_setprio 1
	s_waitcnt lgkmcnt(0)
	v_mfma_f32_16x16x32_bf16 v[124:127], v[128:131], v[180:183], v[124:127]
	v_mfma_f32_16x16x32_bf16 v[120:123], v[136:139], v[180:183], v[120:123]
	v_mfma_f32_16x16x32_bf16 v[108:111], v[128:131], v[188:191], v[108:111]
	v_mfma_f32_16x16x32_bf16 v[104:107], v[136:139], v[188:191], v[104:107]
	v_mfma_f32_16x16x32_bf16 v[92:95], v[128:131], v[196:199], v[92:95]
	v_mfma_f32_16x16x32_bf16 v[88:91], v[136:139], v[196:199], v[88:91]
	v_mfma_f32_16x16x32_bf16 v[76:79], v[128:131], v[204:207], v[76:79]
	v_mfma_f32_16x16x32_bf16 v[72:75], v[136:139], v[204:207], v[72:75]
	v_mfma_f32_16x16x32_bf16 v[124:127], v[132:135], v[184:187], v[124:127]
	v_mfma_f32_16x16x32_bf16 v[120:123], v[140:143], v[184:187], v[120:123]
	v_mfma_f32_16x16x32_bf16 v[108:111], v[132:135], v[192:195], v[108:111]
	v_mfma_f32_16x16x32_bf16 v[104:107], v[140:143], v[192:195], v[104:107]
	v_mfma_f32_16x16x32_bf16 v[92:95], v[132:135], v[200:203], v[92:95]
	v_mfma_f32_16x16x32_bf16 v[88:91], v[140:143], v[200:203], v[88:91]
	v_mfma_f32_16x16x32_bf16 v[76:79], v[132:135], v[208:211], v[76:79]
	v_mfma_f32_16x16x32_bf16 v[72:75], v[140:143], v[208:211], v[72:75]
	s_setprio 0
	s_setprio 1
	v_mfma_f32_16x16x32_bf16 v[116:119], v[158:161], v[180:183], v[116:119]
	v_mfma_f32_16x16x32_bf16 v[112:115], v[172:175], v[180:183], v[112:115]
	v_mfma_f32_16x16x32_bf16 v[100:103], v[158:161], v[188:191], v[100:103]
	v_mfma_f32_16x16x32_bf16 v[96:99], v[172:175], v[188:191], v[96:99]
	v_mfma_f32_16x16x32_bf16 v[84:87], v[158:161], v[196:199], v[84:87]
	v_mfma_f32_16x16x32_bf16 v[80:83], v[172:175], v[196:199], v[80:83]
	v_mfma_f32_16x16x32_bf16 v[68:71], v[158:161], v[204:207], v[68:71]
	v_mfma_f32_16x16x32_bf16 v[64:67], v[172:175], v[204:207], v[64:67]
	v_mfma_f32_16x16x32_bf16 v[116:119], v[162:165], v[184:187], v[116:119]
	v_mfma_f32_16x16x32_bf16 v[112:115], v[176:179], v[184:187], v[112:115]
	v_mfma_f32_16x16x32_bf16 v[100:103], v[162:165], v[192:195], v[100:103]
	v_mfma_f32_16x16x32_bf16 v[96:99], v[176:179], v[192:195], v[96:99]
	v_mfma_f32_16x16x32_bf16 v[84:87], v[162:165], v[200:203], v[84:87]
	v_mfma_f32_16x16x32_bf16 v[80:83], v[176:179], v[200:203], v[80:83]
	v_mfma_f32_16x16x32_bf16 v[68:71], v[162:165], v[208:211], v[68:71]
	v_mfma_f32_16x16x32_bf16 v[64:67], v[176:179], v[208:211], v[64:67]
	s_setprio 0
	s_barrier
; #define PG8_STAGE(bufoff, gbase, voff) do { _Pragma("unroll") for (int _i = 0; _i < 2; ++_i) \
;     __builtin_amdgcn_global_load_lds((const unsigned*)((const char*)(gbase) + (voff)[_i]), (PG8_LAS unsigned*)(lds + (bufoff) + ldsw + _i * 8192), 16, 0, 0); } while (0)
; #define PG8_LDA(dst, b, h) do { _Pragma("unroll") for (int m = 0; m < 4; ++m) _Pragma("unroll") for (int k = 0; k < 2; ++k) dst[m][k] = *(const PG8_LAS bf16x8*)(lds + PG8_SA(b, h) + aoff + m * 2048 + k * 1024); } while (0)
; #define PG8_MMA(ai, bj, At, Bt) do { __builtin_amdgcn_s_setprio(1); _Pragma("unroll") for (int m = 0; m < 4; ++m) _Pragma("unroll") for (int n = 0; n < 2; ++n) _Pragma("unroll") for (int k = 0; k < 2; ++k) \
;     acc[ai][bj][m][n] = __builtin_amdgcn_mfma_f32_16x16x32_bf16(Bt[n][k], At[m][k], acc[ai][bj][m][n], 0, 0, 0); __builtin_amdgcn_s_setprio(0); } while (0)
; #define PG8_WAIT_V(n) asm volatile("s_waitcnt vmcnt(" #n ")" ::: "memory")
; #define PG8_WAIT_L(n) asm volatile("s_waitcnt lgkmcnt(" #n ")" ::: "memory")
; #define PG8_BAR __builtin_amdgcn_s_barrier()
; #define PG8_SCHED __builtin_amdgcn_sched_barrier(0)
;   DI void operator()(const f32x4 (&acc)[2][2][4][2], const Unit& u, int wr, int wc, int fr, int fq) const {
;     ...
;     RES_LD(0)
; #pragma unroll
;     for (int i = 0; i < 8; ++i) {
;       const int ai = i >> 2, m = i & 3;
;       if (i + 1 < 8) RES_LD(i + 1)
; template <class Epi, class Sched>
; DI void gemm_phase(PG8_LAS unsigned char* lds, const Gemm g, const Sched& S, const Epi& E) {
;     ...
;       PG8_LDA(At, 1, 1); PG8_STAGE(PG8_SB(1, 0), b3, voffB); PG8_STAGE(PG8_SB(1, 1), b3 + hstepB, voffB); PG8_STAGE(PG8_SA(1, 0), a3, voffA);
;       PG8_WAIT_V(8); PG8_WAIT_L(0); PG8_BAR; PG8_MMA(1, 0, At, B0); PG8_MMA(1, 1, At, B1); PG8_BAR; PG8_SCHED;
;     }
;     if (wr == 0) PG8_BAR;
	s_add_i32 s16, s33, s2
	v_lshl_add_u64 v[214:215], v[214:215], 0, s[8:9]
	s_mov_b32 m0, s16
	ds_read_b128 v[180:183], v169 offset:49152
	ds_read_b128 v[184:187], v169 offset:50176
	ds_read_b128 v[188:191], v169 offset:51200
	ds_read_b128 v[192:195], v169 offset:52224
	ds_read_b128 v[196:199], v169 offset:53248
	ds_read_b128 v[200:203], v169 offset:54272
	ds_read_b128 v[204:207], v169 offset:55296
	ds_read_b128 v[208:211], v169 offset:56320
	global_load_lds_dwordx4 v[214:215], off
	s_add_i32 m0, s16, 0x2000
	s_add_u32 s16, s30, 0x40080
	v_lshl_add_u64 v[214:215], v[216:217], 0, s[8:9]
	s_addc_u32 s17, s31, 0
	s_add_i32 s30, s65, s2
	global_load_lds_dwordx4 v[214:215], off
	v_lshl_add_u64 v[214:215], s[16:17], 0, v[146:147]
	s_mov_b32 m0, s30
	s_nop 0
	global_load_lds_dwordx4 v[214:215], off
	v_lshl_add_u64 v[214:215], s[16:17], 0, v[150:151]
	s_add_i32 m0, s30, 0x2000
	s_nop 0
	global_load_lds_dwordx4 v[214:215], off
	v_lshl_add_u64 v[214:215], v[218:219], 0, s[8:9]
	s_mov_b32 m0, s4
	s_nop 0
	global_load_lds_dwordx4 v[214:215], off
	v_lshl_add_u64 v[214:215], v[220:221], 0, s[8:9]
	s_mov_b32 m0, s5
	s_nop 0
	global_load_lds_dwordx4 v[214:215], off
	s_waitcnt vmcnt(8)
	s_waitcnt lgkmcnt(0)
	s_barrier
	s_setprio 1
	s_waitcnt lgkmcnt(0)
	v_mfma_f32_16x16x32_bf16 v[60:63], v[128:131], v[180:183], v[60:63]
	v_mfma_f32_16x16x32_bf16 v[56:59], v[136:139], v[180:183], v[56:59]
	v_mfma_f32_16x16x32_bf16 v[44:47], v[128:131], v[188:191], v[44:47]
	v_mfma_f32_16x16x32_bf16 v[40:43], v[136:139], v[188:191], v[40:43]
	v_mfma_f32_16x16x32_bf16 v[28:31], v[128:131], v[196:199], v[28:31]
	v_mfma_f32_16x16x32_bf16 v[24:27], v[136:139], v[196:199], v[24:27]
	v_mfma_f32_16x16x32_bf16 v[12:15], v[128:131], v[204:207], v[12:15]
	v_mfma_f32_16x16x32_bf16 v[8:11], v[136:139], v[204:207], v[8:11]
	v_mfma_f32_16x16x32_bf16 v[60:63], v[132:135], v[184:187], v[60:63]
	v_mfma_f32_16x16x32_bf16 v[56:59], v[140:143], v[184:187], v[56:59]
	v_mfma_f32_16x16x32_bf16 v[44:47], v[132:135], v[192:195], v[44:47]
	v_mfma_f32_16x16x32_bf16 v[40:43], v[140:143], v[192:195], v[40:43]
	v_mfma_f32_16x16x32_bf16 v[28:31], v[132:135], v[200:203], v[28:31]
	v_mfma_f32_16x16x32_bf16 v[24:27], v[140:143], v[200:203], v[24:27]
	v_mfma_f32_16x16x32_bf16 v[12:15], v[132:135], v[208:211], v[12:15]
	v_mfma_f32_16x16x32_bf16 v[8:11], v[140:143], v[208:211], v[8:11]
	s_setprio 0
	s_setprio 1
	v_mfma_f32_16x16x32_bf16 v[52:55], v[158:161], v[180:183], v[52:55]
	v_mfma_f32_16x16x32_bf16 v[48:51], v[172:175], v[180:183], v[48:51]
	v_mfma_f32_16x16x32_bf16 v[36:39], v[158:161], v[188:191], v[36:39]
	v_mfma_f32_16x16x32_bf16 v[32:35], v[172:175], v[188:191], v[32:35]
	v_mfma_f32_16x16x32_bf16 v[20:23], v[158:161], v[196:199], v[20:23]
	v_mfma_f32_16x16x32_bf16 v[16:19], v[172:175], v[196:199], v[16:19]
	v_mfma_f32_16x16x32_bf16 v[4:7], v[158:161], v[204:207], v[4:7]
	v_mfma_f32_16x16x32_bf16 v[0:3], v[172:175], v[204:207], v[0:3]
	v_mfma_f32_16x16x32_bf16 v[52:55], v[162:165], v[184:187], v[52:55]
	v_mfma_f32_16x16x32_bf16 v[48:51], v[176:179], v[184:187], v[48:51]
	v_mfma_f32_16x16x32_bf16 v[36:39], v[162:165], v[192:195], v[36:39]
	v_mfma_f32_16x16x32_bf16 v[32:35], v[176:179], v[192:195], v[32:35]
	v_mfma_f32_16x16x32_bf16 v[20:23], v[162:165], v[200:203], v[20:23]
	v_mfma_f32_16x16x32_bf16 v[16:19], v[176:179], v[200:203], v[16:19]
	v_mfma_f32_16x16x32_bf16 v[4:7], v[162:165], v[208:211], v[4:7]
	v_mfma_f32_16x16x32_bf16 v[0:3], v[176:179], v[208:211], v[0:3]
	s_setprio 0
	s_barrier
	s_add_i32 s70, s70, 2
	s_add_u32 s28, s28, 0x100
	s_addc_u32 s29, s29, 0
	s_add_u32 s68, s68, 0x100
	s_addc_u32 s69, s69, 0
	s_cmp_gt_u32 s70, 13
	s_cbranch_scc0 .LBB0_563
	v_lshl_add_u32 v164, s26, 8, v153
	v_ashrrev_i32_e32 v165, 31, v164
	s_lshl_b32 s16, s12, 8
	v_lshlrev_b64 v[128:129], 10, v[164:165]
	s_ashr_i32 s17, s16, 31
	v_lshl_add_u64 v[186:187], v[128:129], 0, s[16:17]
	v_or_b32_e32 v186, v186, v152
	v_lshl_add_u64 v[162:163], v[186:187], 2, s[44:45]
	s_mov_b64 s[16:17], 0x10000
	v_add_co_u32_e32 v130, vcc, s39, v162
	global_load_dwordx4 v[158:161], v[162:163], off offset:16
	global_load_dwordx4 v[174:177], v[162:163], off
	global_load_dwordx4 v[178:181], v[162:163], off offset:528
	global_load_dwordx4 v[182:185], v[162:163], off offset:512
	v_lshl_add_u64 v[128:129], v[162:163], 0, s[16:17]
	v_addc_co_u32_e32 v131, vcc, 0, v163, vcc
	s_mov_b64 s[16:17], 0x10200
	global_load_dwordx4 v[140:143], v[130:131], off
	global_load_dwordx4 v[136:139], v[128:129], off offset:16
	v_lshl_add_u64 v[128:129], v[162:163], 0, s[16:17]
	global_load_dwordx4 v[132:135], v[130:131], off offset:512
	s_nop 0
	global_load_dwordx4 v[128:131], v[128:129], off offset:16
	s_and_b64 vcc, exec, s[10:11]
	s_cbranch_vccz .LBB0_566
	s_barrier
; DI unsigned pack2(float a, float b) { bf2_t v = __builtin_convertvector((f32x2){a, b}, bf2_t); return __builtin_bit_cast(unsigned, v); }
;   DI void operator()(const f32x4 (&acc)[2][2][4][2], const Unit& u, int wr, int wc, int fr, int fq) const {
;     ...
;     for (int i = 0; i < 8; ++i) {
;       const int ai = i >> 2, m = i & 3;
;       if (i + 1 < 8) RES_LD(i + 1)
;       __builtin_amdgcn_sched_barrier(0);
;       const size_t idx = base + (size_t)(ai * HALF + m * 16) * DM;
;       float ssum = 0.f;
; #pragma unroll
;       for (int bj = 0; bj < 2; ++bj) {
;         f32x4 x0, x1;
;         if (FIRST) { x0 = xv[i & 1][2 * bj]; x1 = xv[i & 1][2 * bj + 1]; }
;         else {
;           const u32x4 hw = xh[i & 1][bj];
;           x0 = (f32x4){__uint_as_float(hw.x << 16), __uint_as_float(hw.x & 0xffff0000u), __uint_as_float(hw.y << 16), __uint_as_float(hw.y & 0xffff0000u)};
;           x1 = (f32x4){__uint_as_float(hw.z << 16), __uint_as_float(hw.z & 0xffff0000u), __uint_as_float(hw.w << 16), __uint_as_float(hw.w & 0xffff0000u)};
;         }
;         const f32x4 v0 = x0 + acc[ai][bj][m][0], v1 = x1 + acc[ai][bj][m][1];
;         if (LAST) { *(f32x4*)(xout32 + idx + bj * HALF) = v0; *(f32x4*)(xout32 + idx + bj * HALF + 4) = v1; }
;         else {
;           ssum += (v0[0] * v0[0] + v0[1] * v0[1]) + (v0[2] * v0[2] + v0[3] * v0[3]) + (v1[0] * v1[0] + v1[1] * v1[1]) + (v1[2] * v1[2] + v1[3] * v1[3]);
;           u32x4 w; w.x = pack2(v0[0], v0[1]); w.y = pack2(v0[2], v0[3]); w.z = pack2(v1[0], v1[1]); w.w = pack2(v1[2], v1[3]);
;           *(u32x4*)(xb + idx + bj * HALF) = w;
;         }
;       }
;       if (!LAST) {
;         ssum += __shfl_xor(ssum, 16); ssum += __shfl_xor(ssum, 32);
;         if (fq == 0) ps_out[(size_t)(row0 + ai * HALF + m * 16) * 16 + u.pn * 4 + wc] = ssum;
.LBB0_566:
	v_and_b32_e32 v173, 64, v170
	v_xor_b32_e32 v172, 16, v170
	v_add_u32_e32 v188, 64, v173
	v_cmp_lt_i32_e32 vcc, v172, v188
	s_lshl_b32 s26, s12, 2
	s_ashr_i32 s27, s26, 31
	v_cndmask_b32_e32 v172, v170, v172, vcc
	v_lshlrev_b32_e32 v173, 2, v172
	v_xor_b32_e32 v172, 32, v170
	v_cmp_lt_i32_e32 vcc, v172, v188
	s_nop 1
	v_cndmask_b32_e32 v172, v170, v172, vcc
	v_lshlrev_b32_e32 v172, 2, v172
	s_waitcnt vmcnt(0)
	v_pk_add_f32 v[126:127], v[126:127], v[176:177]
	v_pk_add_f32 v[124:125], v[124:125], v[174:175]
	v_pk_add_f32 v[160:161], v[122:123], v[160:161]
	v_pk_add_f32 v[122:123], v[120:121], v[158:159]
	v_mul_f32_e32 v120, v125, v125
	v_mul_f32_e32 v121, v127, v127
	v_fmac_f32_e32 v120, v124, v124
	v_fmac_f32_e32 v121, v126, v126
	v_add_f32_e32 v120, v120, v121
	v_mul_f32_e32 v121, v123, v123
	v_fmac_f32_e32 v121, v122, v122
	v_add_f32_e32 v120, v120, v121
	v_mul_f32_e32 v121, v161, v161
	v_fmac_f32_e32 v121, v160, v160
	v_pk_add_f32 v[118:119], v[118:119], v[184:185]
	v_pk_add_f32 v[116:117], v[116:117], v[182:183]
	v_add_f32_e32 v174, v121, v120
	v_cvt_pk_bf16_f32 v120, v124, v125
	v_pk_add_f32 v[124:125], v[114:115], v[180:181]
	v_mul_f32_e32 v114, v117, v117
	v_mul_f32_e32 v115, v119, v119
	v_pk_add_f32 v[112:113], v[112:113], v[178:179]
	v_fmac_f32_e32 v114, v116, v116
	v_fmac_f32_e32 v115, v118, v118
	v_add_f32_e32 v114, v114, v115
	v_mul_f32_e32 v115, v113, v113
	v_fmac_f32_e32 v115, v112, v112
	v_add_f32_e32 v114, v114, v115
	v_mul_f32_e32 v115, v125, v125
	v_fmac_f32_e32 v115, v124, v124
	v_add_f32_e32 v114, v115, v114
	v_cvt_pk_bf16_f32 v121, v126, v127
	v_add_f32_e32 v126, v174, v114
	ds_bpermute_b32 v127, v173, v126
	v_cvt_pk_bf16_f32 v114, v116, v117
	v_cvt_pk_bf16_f32 v116, v112, v113
	v_lshl_add_u64 v[158:159], v[186:187], 1, s[50:51]
	v_cvt_pk_bf16_f32 v115, v118, v119
	s_waitcnt lgkmcnt(0)
	v_add_f32_e32 v112, v126, v127
	ds_bpermute_b32 v113, v172, v112
	v_cvt_pk_bf16_f32 v117, v124, v125
	v_readlane_b32 s16, v254, 18
	global_store_dwordx4 v[158:159], v[114:117], off offset:256
	v_readlane_b32 s17, v254, 19
	v_cvt_pk_bf16_f32 v122, v122, v123
	v_lshlrev_b64 v[114:115], 6, v[164:165]
	v_cvt_pk_bf16_f32 v123, v160, v161
	v_lshl_add_u64 v[160:161], s[16:17], 0, v[114:115]
	global_store_dwordx4 v[158:159], v[120:123], off
	s_and_saveexec_b64 s[28:29], s[6:7]
	s_cbranch_execz .LBB0_568
	v_lshl_add_u64 v[114:115], s[26:27], 2, v[160:161]
	s_lshl_b32 s12, s40, 2
	v_lshl_add_u64 v[114:115], v[114:115], 0, s[12:13]
	s_waitcnt lgkmcnt(0)
	v_add_f32_e32 v112, v112, v113
	global_store_dword v[114:115], v112, off

; #define PG8_STAGE(bufoff, gbase, voff) do { _Pragma("unroll") for (int _i = 0; _i < 2; ++_i) \
;     __builtin_amdgcn_global_load_lds((const unsigned*)((const char*)(gbase) + (voff)[_i]), (PG8_LAS unsigned*)(lds + (bufoff) + ldsw + _i * 8192), 16, 0, 0); } while (0)
; #define PG8_LDA(dst, b, h) do { _Pragma("unroll") for (int m = 0; m < 4; ++m) _Pragma("unroll") for (int k = 0; k < 2; ++k) dst[m][k] = *(const PG8_LAS bf16x8*)(lds + PG8_SA(b, h) + aoff + m * 2048 + k * 1024); } while (0)
; #define PG8_LDB(dst, b, h) do { _Pragma("unroll") for (int n = 0; n < 2; ++n) _Pragma("unroll") for (int k = 0; k < 2; ++k) dst[n][k] = *(const PG8_LAS bf16x8*)(lds + PG8_SB(b, h) + boff + n * 2048 + k * 1024); } while (0)
; #define PG8_MMA(ai, bj, At, Bt) do { __builtin_amdgcn_s_setprio(1); _Pragma("unroll") for (int m = 0; m < 4; ++m) _Pragma("unroll") for (int n = 0; n < 2; ++n) _Pragma("unroll") for (int k = 0; k < 2; ++k) \
;     acc[ai][bj][m][n] = __builtin_amdgcn_mfma_f32_16x16x32_bf16(Bt[n][k], At[m][k], acc[ai][bj][m][n], 0, 0, 0); __builtin_amdgcn_s_setprio(0); } while (0)
; #define PG8_WAIT_V(n) asm volatile("s_waitcnt vmcnt(" #n ")" ::: "memory")
; #define PG8_WAIT_L(n) asm volatile("s_waitcnt lgkmcnt(" #n ")" ::: "memory")
; #define PG8_BAR __builtin_amdgcn_s_barrier()
; #define PG8_SCHED __builtin_amdgcn_sched_barrier(0)
; template <class Epi, class Sched>
; DI void gemm_phase(PG8_LAS unsigned char* lds, const Gemm g, const Sched& S, const Epi& E) {
;     ...
;       const char* a1 = cA + (size_t)(t + 1) * kstep;
;       const char* a2 = last ? nA : cA + (size_t)(t + 2) * kstep; const char* b2 = last ? nB : cB + (size_t)(t + 2) * kstep;
;       const char* a3 = a2 + kstep; const char* b3 = b2 + kstep;
;       PG8_LDB(B0, 0, 0); PG8_LDB(B1, 0, 1); PG8_SCHED; PG8_LDA(At, 0, 0); PG8_STAGE(PG8_SA(1, 1), a1 + hstepA, voffA);
;       PG8_WAIT_V(8); PG8_WAIT_L(0); PG8_BAR; PG8_MMA(0, 0, At, B0); PG8_MMA(0, 1, At, B1); PG8_BAR; PG8_SCHED;
;       PG8_LDA(At, 0, 1); PG8_STAGE(PG8_SB(0, 0), b2, voffB); PG8_STAGE(PG8_SB(0, 1), b2 + hstepB, voffB); PG8_STAGE(PG8_SA(0, 0), a2, voffA);
;       PG8_WAIT_V(8); PG8_WAIT_L(0); PG8_BAR; PG8_MMA(1, 0, At, B0); PG8_MMA(1, 1, At, B1); PG8_BAR; PG8_SCHED;
;       PG8_LDB(B0, 1, 0); PG8_LDB(B1, 1, 1); PG8_SCHED; PG8_LDA(At, 1, 0); PG8_STAGE(PG8_SA(0, 1), a2 + hstepA, voffA);
.LBB0_647:
	ds_read_b128 v[144:147], v157
	ds_read_b128 v[148:151], v157 offset:1024
	ds_read_b128 v[174:177], v157 offset:2048
	ds_read_b128 v[178:181], v157 offset:3072
	ds_read_b128 v[182:185], v161
	ds_read_b128 v[186:189], v161 offset:1024
	ds_read_b128 v[190:193], v161 offset:2048
	ds_read_b128 v[194:197], v161 offset:3072
	s_add_u32 s16, s6, 0xfffc0080
	s_addc_u32 s17, s7, -1
	s_cmp_eq_u32 s68, 12
	s_cselect_b32 s37, s1, s17
	s_cselect_b32 s36, s25, s16
	s_cselect_b32 s35, s23, s67
	s_cselect_b32 s34, s65, s66
	v_lshl_add_u64 v[154:155], s[6:7], 0, v[140:141]
	s_add_i32 m0, s21, 0xc000
	ds_read_b128 v[198:201], v165
	ds_read_b128 v[202:205], v165 offset:1024
	ds_read_b128 v[206:209], v165 offset:2048
	ds_read_b128 v[214:217], v165 offset:3072
	ds_read_b128 v[218:221], v165 offset:4096
	ds_read_b128 v[222:225], v165 offset:5120
	ds_read_b128 v[226:229], v165 offset:6144
	ds_read_b128 v[230:233], v165 offset:7168
	global_load_lds_dwordx4 v[154:155], off
	v_lshl_add_u64 v[154:155], s[6:7], 0, v[142:143]
	s_add_i32 m0, s21, 0xe000
	s_nop 0
	global_load_lds_dwordx4 v[154:155], off
	s_waitcnt vmcnt(8)
	s_waitcnt lgkmcnt(0)
	s_barrier
	s_setprio 1
	s_waitcnt lgkmcnt(0)
	v_mfma_f32_16x16x32_bf16 v[124:127], v[144:147], v[198:201], v[124:127]
	v_mfma_f32_16x16x32_bf16 v[120:123], v[174:177], v[198:201], v[120:123]
	v_mfma_f32_16x16x32_bf16 v[108:111], v[144:147], v[206:209], v[108:111]
	v_mfma_f32_16x16x32_bf16 v[104:107], v[174:177], v[206:209], v[104:107]
	v_mfma_f32_16x16x32_bf16 v[92:95], v[144:147], v[218:221], v[92:95]
	v_mfma_f32_16x16x32_bf16 v[88:91], v[174:177], v[218:221], v[88:91]
	v_mfma_f32_16x16x32_bf16 v[76:79], v[144:147], v[226:229], v[76:79]
	v_mfma_f32_16x16x32_bf16 v[72:75], v[174:177], v[226:229], v[72:75]
	v_mfma_f32_16x16x32_bf16 v[124:127], v[148:151], v[202:205], v[124:127]
	v_mfma_f32_16x16x32_bf16 v[120:123], v[178:181], v[202:205], v[120:123]
	v_mfma_f32_16x16x32_bf16 v[108:111], v[148:151], v[214:217], v[108:111]
	v_mfma_f32_16x16x32_bf16 v[104:107], v[178:181], v[214:217], v[104:107]
	v_mfma_f32_16x16x32_bf16 v[92:95], v[148:151], v[222:225], v[92:95]
	v_mfma_f32_16x16x32_bf16 v[88:91], v[178:181], v[222:225], v[88:91]
	v_mfma_f32_16x16x32_bf16 v[76:79], v[148:151], v[230:233], v[76:79]
	v_mfma_f32_16x16x32_bf16 v[72:75], v[178:181], v[230:233], v[72:75]
	s_setprio 0
	s_setprio 1
	v_mfma_f32_16x16x32_bf16 v[116:119], v[182:185], v[198:201], v[116:119]
	v_mfma_f32_16x16x32_bf16 v[112:115], v[190:193], v[198:201], v[112:115]
	v_mfma_f32_16x16x32_bf16 v[100:103], v[182:185], v[206:209], v[100:103]
	v_mfma_f32_16x16x32_bf16 v[96:99], v[190:193], v[206:209], v[96:99]
	v_mfma_f32_16x16x32_bf16 v[84:87], v[182:185], v[218:221], v[84:87]
	v_mfma_f32_16x16x32_bf16 v[80:83], v[190:193], v[218:221], v[80:83]
	v_mfma_f32_16x16x32_bf16 v[68:71], v[182:185], v[226:229], v[68:71]
	v_mfma_f32_16x16x32_bf16 v[64:67], v[190:193], v[226:229], v[64:67]
	v_mfma_f32_16x16x32_bf16 v[116:119], v[186:189], v[202:205], v[116:119]
	v_mfma_f32_16x16x32_bf16 v[112:115], v[194:197], v[202:205], v[112:115]
	v_mfma_f32_16x16x32_bf16 v[100:103], v[186:189], v[214:217], v[100:103]
	v_mfma_f32_16x16x32_bf16 v[96:99], v[194:197], v[214:217], v[96:99]
	v_mfma_f32_16x16x32_bf16 v[84:87], v[186:189], v[222:225], v[84:87]
	v_mfma_f32_16x16x32_bf16 v[80:83], v[194:197], v[222:225], v[80:83]
	v_mfma_f32_16x16x32_bf16 v[68:71], v[186:189], v[230:233], v[68:71]
	v_mfma_f32_16x16x32_bf16 v[64:67], v[194:197], v[230:233], v[64:67]
	s_setprio 0
	s_barrier
	s_add_i32 s16, s39, s2
	v_lshl_add_u64 v[154:155], s[34:35], 0, v[132:133]
	s_mov_b32 m0, s16
	ds_read_b128 v[198:201], v165 offset:16384
	ds_read_b128 v[202:205], v165 offset:17408
	ds_read_b128 v[206:209], v165 offset:18432
	ds_read_b128 v[214:217], v165 offset:19456
	ds_read_b128 v[218:221], v165 offset:20480
	ds_read_b128 v[222:225], v165 offset:21504
	ds_read_b128 v[226:229], v165 offset:22528
	ds_read_b128 v[230:233], v165 offset:23552
	global_load_lds_dwordx4 v[154:155], off
	s_add_i32 m0, s16, 0x2000
	s_add_u32 s16, s34, 0x40000
	v_lshl_add_u64 v[158:159], s[34:35], 0, v[128:129]
	s_addc_u32 s17, s35, 0
	s_add_i32 s33, s40, s2
	global_load_lds_dwordx4 v[158:159], off
	v_lshl_add_u64 v[162:163], s[16:17], 0, v[132:133]
	s_mov_b32 m0, s33
	v_lshl_add_u64 v[166:167], s[36:37], 0, v[130:131]
	global_load_lds_dwordx4 v[162:163], off
	v_lshl_add_u64 v[162:163], s[16:17], 0, v[128:129]
	s_add_i32 m0, s33, 0x2000
	s_nop 0
	global_load_lds_dwordx4 v[162:163], off
	v_lshl_add_u64 v[162:163], s[36:37], 0, v[134:135]
	s_mov_b32 m0, s21
	s_nop 0
	global_load_lds_dwordx4 v[162:163], off
	s_mov_b32 m0, s4
	s_nop 0
	global_load_lds_dwordx4 v[166:167], off
	s_waitcnt vmcnt(8)
	s_waitcnt lgkmcnt(0)
	s_barrier
; #define PG8_STAGE(bufoff, gbase, voff) do { _Pragma("unroll") for (int _i = 0; _i < 2; ++_i) \
;     __builtin_amdgcn_global_load_lds((const unsigned*)((const char*)(gbase) + (voff)[_i]), (PG8_LAS unsigned*)(lds + (bufoff) + ldsw + _i * 8192), 16, 0, 0); } while (0)
; #define PG8_LDA(dst, b, h) do { _Pragma("unroll") for (int m = 0; m < 4; ++m) _Pragma("unroll") for (int k = 0; k < 2; ++k) dst[m][k] = *(const PG8_LAS bf16x8*)(lds + PG8_SA(b, h) + aoff + m * 2048 + k * 1024); } while (0)
; #define PG8_LDB(dst, b, h) do { _Pragma("unroll") for (int n = 0; n < 2; ++n) _Pragma("unroll") for (int k = 0; k < 2; ++k) dst[n][k] = *(const PG8_LAS bf16x8*)(lds + PG8_SB(b, h) + boff + n * 2048 + k * 1024); } while (0)
; #define PG8_MMA(ai, bj, At, Bt) do { __builtin_amdgcn_s_setprio(1); _Pragma("unroll") for (int m = 0; m < 4; ++m) _Pragma("unroll") for (int n = 0; n < 2; ++n) _Pragma("unroll") for (int k = 0; k < 2; ++k) \
;     acc[ai][bj][m][n] = __builtin_amdgcn_mfma_f32_16x16x32_bf16(Bt[n][k], At[m][k], acc[ai][bj][m][n], 0, 0, 0); __builtin_amdgcn_s_setprio(0); } while (0)
; #define PG8_WAIT_V(n) asm volatile("s_waitcnt vmcnt(" #n ")" ::: "memory")
; #define PG8_WAIT_L(n) asm volatile("s_waitcnt lgkmcnt(" #n ")" ::: "memory")
; #define PG8_BAR __builtin_amdgcn_s_barrier()
; #define PG8_SCHED __builtin_amdgcn_sched_barrier(0)
; template <class Epi, class Sched>
; DI void gemm_phase(PG8_LAS unsigned char* lds, const Gemm g, const Sched& S, const Epi& E) {
;     ...
;       PG8_WAIT_V(8); PG8_WAIT_L(0); PG8_BAR; PG8_MMA(1, 0, At, B0); PG8_MMA(1, 1, At, B1); PG8_BAR; PG8_SCHED;
;       PG8_LDB(B0, 1, 0); PG8_LDB(B1, 1, 1); PG8_SCHED; PG8_LDA(At, 1, 0); PG8_STAGE(PG8_SA(0, 1), a2 + hstepA, voffA);
;       PG8_WAIT_V(8); PG8_WAIT_L(0); PG8_BAR; PG8_MMA(0, 0, At, B0); PG8_MMA(0, 1, At, B1); PG8_BAR; PG8_SCHED;
;       PG8_LDA(At, 1, 1); PG8_STAGE(PG8_SB(1, 0), b3, voffB); PG8_STAGE(PG8_SB(1, 1), b3 + hstepB, voffB); PG8_STAGE(PG8_SA(1, 0), a3, voffA);
	s_setprio 1
	s_waitcnt lgkmcnt(0)
	v_mfma_f32_16x16x32_bf16 v[60:63], v[144:147], v[198:201], v[60:63]
	v_mfma_f32_16x16x32_bf16 v[56:59], v[174:177], v[198:201], v[56:59]
	v_mfma_f32_16x16x32_bf16 v[44:47], v[144:147], v[206:209], v[44:47]
	v_mfma_f32_16x16x32_bf16 v[40:43], v[174:177], v[206:209], v[40:43]
	v_mfma_f32_16x16x32_bf16 v[28:31], v[144:147], v[218:221], v[28:31]
	v_mfma_f32_16x16x32_bf16 v[24:27], v[174:177], v[218:221], v[24:27]
	v_mfma_f32_16x16x32_bf16 v[12:15], v[144:147], v[226:229], v[12:15]
	v_mfma_f32_16x16x32_bf16 v[8:11], v[174:177], v[226:229], v[8:11]
	v_mfma_f32_16x16x32_bf16 v[60:63], v[148:151], v[202:205], v[60:63]
	v_mfma_f32_16x16x32_bf16 v[56:59], v[178:181], v[202:205], v[56:59]
	v_mfma_f32_16x16x32_bf16 v[44:47], v[148:151], v[214:217], v[44:47]
	v_mfma_f32_16x16x32_bf16 v[40:43], v[178:181], v[214:217], v[40:43]
	v_mfma_f32_16x16x32_bf16 v[28:31], v[148:151], v[222:225], v[28:31]
	v_mfma_f32_16x16x32_bf16 v[24:27], v[178:181], v[222:225], v[24:27]
	v_mfma_f32_16x16x32_bf16 v[12:15], v[148:151], v[230:233], v[12:15]
	v_mfma_f32_16x16x32_bf16 v[8:11], v[178:181], v[230:233], v[8:11]
	s_setprio 0
	s_setprio 1
	v_mfma_f32_16x16x32_bf16 v[52:55], v[182:185], v[198:201], v[52:55]
	v_mfma_f32_16x16x32_bf16 v[48:51], v[190:193], v[198:201], v[48:51]
	v_mfma_f32_16x16x32_bf16 v[36:39], v[182:185], v[206:209], v[36:39]
	v_mfma_f32_16x16x32_bf16 v[32:35], v[190:193], v[206:209], v[32:35]
	v_mfma_f32_16x16x32_bf16 v[20:23], v[182:185], v[218:221], v[20:23]
	v_mfma_f32_16x16x32_bf16 v[16:19], v[190:193], v[218:221], v[16:19]
	v_mfma_f32_16x16x32_bf16 v[4:7], v[182:185], v[226:229], v[4:7]
	v_mfma_f32_16x16x32_bf16 v[0:3], v[190:193], v[226:229], v[0:3]
	v_mfma_f32_16x16x32_bf16 v[52:55], v[186:189], v[202:205], v[52:55]
	v_mfma_f32_16x16x32_bf16 v[48:51], v[194:197], v[202:205], v[48:51]
	v_mfma_f32_16x16x32_bf16 v[36:39], v[186:189], v[214:217], v[36:39]
	v_mfma_f32_16x16x32_bf16 v[32:35], v[194:197], v[214:217], v[32:35]
	v_mfma_f32_16x16x32_bf16 v[20:23], v[186:189], v[222:225], v[20:23]
	v_mfma_f32_16x16x32_bf16 v[16:19], v[194:197], v[222:225], v[16:19]
	v_mfma_f32_16x16x32_bf16 v[4:7], v[186:189], v[230:233], v[4:7]
	v_mfma_f32_16x16x32_bf16 v[0:3], v[194:197], v[230:233], v[0:3]
	s_setprio 0
	s_barrier
	ds_read_b128 v[144:147], v171
	ds_read_b128 v[148:151], v171 offset:1024
	ds_read_b128 v[174:177], v171 offset:2048
	ds_read_b128 v[178:181], v171 offset:3072
	ds_read_b128 v[182:185], v173
	ds_read_b128 v[186:189], v173 offset:1024
	ds_read_b128 v[190:193], v173 offset:2048
	ds_read_b128 v[194:197], v173 offset:3072
	s_add_u32 s16, s36, 0x40000
	s_addc_u32 s17, s37, 0
	s_mov_b32 m0, s5
	v_lshl_add_u64 v[210:211], s[16:17], 0, v[134:135]
	ds_read_b128 v[198:201], v165 offset:32768
	ds_read_b128 v[202:205], v165 offset:33792
	ds_read_b128 v[206:209], v165 offset:34816
	ds_read_b128 v[214:217], v165 offset:35840
	ds_read_b128 v[218:221], v165 offset:36864
	ds_read_b128 v[222:225], v165 offset:37888
	ds_read_b128 v[226:229], v165 offset:38912
	ds_read_b128 v[230:233], v165 offset:39936
	global_load_lds_dwordx4 v[210:211], off
	v_lshl_add_u64 v[210:211], s[16:17], 0, v[130:131]
	s_mov_b32 m0, s18
	s_nop 0
	global_load_lds_dwordx4 v[210:211], off
	s_waitcnt vmcnt(8)
	s_waitcnt lgkmcnt(0)
	s_barrier
	s_setprio 1
	s_waitcnt lgkmcnt(0)
	v_mfma_f32_16x16x32_bf16 v[124:127], v[144:147], v[198:201], v[124:127]
	v_mfma_f32_16x16x32_bf16 v[120:123], v[174:177], v[198:201], v[120:123]
	v_mfma_f32_16x16x32_bf16 v[108:111], v[144:147], v[206:209], v[108:111]
	v_mfma_f32_16x16x32_bf16 v[104:107], v[174:177], v[206:209], v[104:107]
	v_mfma_f32_16x16x32_bf16 v[92:95], v[144:147], v[218:221], v[92:95]
	v_mfma_f32_16x16x32_bf16 v[88:91], v[174:177], v[218:221], v[88:91]
	v_mfma_f32_16x16x32_bf16 v[76:79], v[144:147], v[226:229], v[76:79]
	v_mfma_f32_16x16x32_bf16 v[72:75], v[174:177], v[226:229], v[72:75]
	v_mfma_f32_16x16x32_bf16 v[124:127], v[148:151], v[202:205], v[124:127]
	v_mfma_f32_16x16x32_bf16 v[120:123], v[178:181], v[202:205], v[120:123]
	v_mfma_f32_16x16x32_bf16 v[108:111], v[148:151], v[214:217], v[108:111]
	v_mfma_f32_16x16x32_bf16 v[104:107], v[178:181], v[214:217], v[104:107]
	v_mfma_f32_16x16x32_bf16 v[92:95], v[148:151], v[222:225], v[92:95]
	v_mfma_f32_16x16x32_bf16 v[88:91], v[178:181], v[222:225], v[88:91]
	v_mfma_f32_16x16x32_bf16 v[76:79], v[148:151], v[230:233], v[76:79]
	v_mfma_f32_16x16x32_bf16 v[72:75], v[178:181], v[230:233], v[72:75]
	s_setprio 0
	s_setprio 1
	v_mfma_f32_16x16x32_bf16 v[116:119], v[182:185], v[198:201], v[116:119]
	v_mfma_f32_16x16x32_bf16 v[112:115], v[190:193], v[198:201], v[112:115]
	v_mfma_f32_16x16x32_bf16 v[100:103], v[182:185], v[206:209], v[100:103]
	v_mfma_f32_16x16x32_bf16 v[96:99], v[190:193], v[206:209], v[96:99]
	v_mfma_f32_16x16x32_bf16 v[84:87], v[182:185], v[218:221], v[84:87]
	v_mfma_f32_16x16x32_bf16 v[80:83], v[190:193], v[218:221], v[80:83]
	v_mfma_f32_16x16x32_bf16 v[68:71], v[182:185], v[226:229], v[68:71]
	v_mfma_f32_16x16x32_bf16 v[64:67], v[190:193], v[226:229], v[64:67]
	v_mfma_f32_16x16x32_bf16 v[116:119], v[186:189], v[202:205], v[116:119]
	v_mfma_f32_16x16x32_bf16 v[112:115], v[194:197], v[202:205], v[112:115]
	v_mfma_f32_16x16x32_bf16 v[100:103], v[186:189], v[214:217], v[100:103]
	v_mfma_f32_16x16x32_bf16 v[96:99], v[194:197], v[214:217], v[96:99]
	v_mfma_f32_16x16x32_bf16 v[84:87], v[186:189], v[222:225], v[84:87]
	v_mfma_f32_16x16x32_bf16 v[80:83], v[194:197], v[222:225], v[80:83]
	v_mfma_f32_16x16x32_bf16 v[68:71], v[186:189], v[230:233], v[68:71]
	v_mfma_f32_16x16x32_bf16 v[64:67], v[194:197], v[230:233], v[64:67]
	s_setprio 0
	s_barrier
; #define PG8_STAGE(bufoff, gbase, voff) do { _Pragma("unroll") for (int _i = 0; _i < 2; ++_i) \
;     __builtin_amdgcn_global_load_lds((const unsigned*)((const char*)(gbase) + (voff)[_i]), (PG8_LAS unsigned*)(lds + (bufoff) + ldsw + _i * 8192), 16, 0, 0); } while (0)
; #define PG8_LDA(dst, b, h) do { _Pragma("unroll") for (int m = 0; m < 4; ++m) _Pragma("unroll") for (int k = 0; k < 2; ++k) dst[m][k] = *(const PG8_LAS bf16x8*)(lds + PG8_SA(b, h) + aoff + m * 2048 + k * 1024); } while (0)
; #define PG8_MMA(ai, bj, At, Bt) do { __builtin_amdgcn_s_setprio(1); _Pragma("unroll") for (int m = 0; m < 4; ++m) _Pragma("unroll") for (int n = 0; n < 2; ++n) _Pragma("unroll") for (int k = 0; k < 2; ++k) \
;     acc[ai][bj][m][n] = __builtin_amdgcn_mfma_f32_16x16x32_bf16(Bt[n][k], At[m][k], acc[ai][bj][m][n], 0, 0, 0); __builtin_amdgcn_s_setprio(0); } while (0)
; #define PG8_WAIT_V(n) asm volatile("s_waitcnt vmcnt(" #n ")" ::: "memory")
; #define PG8_WAIT_L(n) asm volatile("s_waitcnt lgkmcnt(" #n ")" ::: "memory")
; #define PG8_BAR __builtin_amdgcn_s_barrier()
; #define PG8_SCHED __builtin_amdgcn_sched_barrier(0)
; DI void rows_rstd(float (&rs)[2][4], const float* ps, const Unit& u, int wr, int fr, int fq, int p_lo, int p_hi, float inv_dim) {
;   f32x4 pv[2][4];
; #pragma unroll
;   for (int ai = 0; ai < 2; ++ai)
; #pragma unroll
;     for (int m = 0; m < 4; ++m) pv[ai][m] = *(const f32x4*)(ps + (size_t)(u.pm * BM + ai * HALF + wr * 64 + m * 16 + fr) * 16 + 4 * fq);
; template <class Epi, class Sched>
; DI void gemm_phase(PG8_LAS unsigned char* lds, const Gemm g, const Sched& S, const Epi& E) {
;     ...
;       PG8_LDA(At, 1, 1); PG8_STAGE(PG8_SB(1, 0), b3, voffB); PG8_STAGE(PG8_SB(1, 1), b3 + hstepB, voffB); PG8_STAGE(PG8_SA(1, 0), a3, voffA);
;       PG8_WAIT_V(8); PG8_WAIT_L(0); PG8_BAR; PG8_MMA(1, 0, At, B0); PG8_MMA(1, 1, At, B1); PG8_BAR; PG8_SCHED;
;     }
;     if (wr == 0) PG8_BAR;
	s_add_i32 s16, s45, s2
	v_lshl_add_u64 v[154:155], v[154:155], 0, s[10:11]
	s_mov_b32 m0, s16
	ds_read_b128 v[198:201], v165 offset:49152
	ds_read_b128 v[202:205], v165 offset:50176
	ds_read_b128 v[206:209], v165 offset:51200
	ds_read_b128 v[214:217], v165 offset:52224
	ds_read_b128 v[218:221], v165 offset:53248
	ds_read_b128 v[222:225], v165 offset:54272
	ds_read_b128 v[226:229], v165 offset:55296
	ds_read_b128 v[230:233], v165 offset:56320
	global_load_lds_dwordx4 v[154:155], off
	s_add_i32 m0, s16, 0x2000
	s_add_u32 s16, s34, 0x40080
	v_lshl_add_u64 v[154:155], v[158:159], 0, s[10:11]
	s_addc_u32 s17, s35, 0
	s_add_i32 s33, s53, s2
	global_load_lds_dwordx4 v[154:155], off
	v_lshl_add_u64 v[154:155], s[16:17], 0, v[132:133]
	s_mov_b32 m0, s33
	s_nop 0
	global_load_lds_dwordx4 v[154:155], off
	v_lshl_add_u64 v[154:155], s[16:17], 0, v[128:129]
	s_add_i32 m0, s33, 0x2000
	s_nop 0
	global_load_lds_dwordx4 v[154:155], off
	v_lshl_add_u64 v[154:155], v[162:163], 0, s[10:11]
	s_mov_b32 m0, s19
	s_nop 0
	global_load_lds_dwordx4 v[154:155], off
	v_lshl_add_u64 v[154:155], v[166:167], 0, s[10:11]
	s_mov_b32 m0, s38
	s_nop 0
	global_load_lds_dwordx4 v[154:155], off
	s_waitcnt vmcnt(8)
	s_waitcnt lgkmcnt(0)
	s_barrier
	s_setprio 1
	s_waitcnt lgkmcnt(0)
	v_mfma_f32_16x16x32_bf16 v[60:63], v[144:147], v[198:201], v[60:63]
	v_mfma_f32_16x16x32_bf16 v[56:59], v[174:177], v[198:201], v[56:59]
	v_mfma_f32_16x16x32_bf16 v[44:47], v[144:147], v[206:209], v[44:47]
	v_mfma_f32_16x16x32_bf16 v[40:43], v[174:177], v[206:209], v[40:43]
	v_mfma_f32_16x16x32_bf16 v[28:31], v[144:147], v[218:221], v[28:31]
	v_mfma_f32_16x16x32_bf16 v[24:27], v[174:177], v[218:221], v[24:27]
	v_mfma_f32_16x16x32_bf16 v[12:15], v[144:147], v[226:229], v[12:15]
	v_mfma_f32_16x16x32_bf16 v[8:11], v[174:177], v[226:229], v[8:11]
	v_mfma_f32_16x16x32_bf16 v[60:63], v[148:151], v[202:205], v[60:63]
	v_mfma_f32_16x16x32_bf16 v[56:59], v[178:181], v[202:205], v[56:59]
	v_mfma_f32_16x16x32_bf16 v[44:47], v[148:151], v[214:217], v[44:47]
	v_mfma_f32_16x16x32_bf16 v[40:43], v[178:181], v[214:217], v[40:43]
	v_mfma_f32_16x16x32_bf16 v[28:31], v[148:151], v[222:225], v[28:31]
	v_mfma_f32_16x16x32_bf16 v[24:27], v[178:181], v[222:225], v[24:27]
	v_mfma_f32_16x16x32_bf16 v[12:15], v[148:151], v[230:233], v[12:15]
	v_mfma_f32_16x16x32_bf16 v[8:11], v[178:181], v[230:233], v[8:11]
	s_setprio 0
	s_setprio 1
	v_mfma_f32_16x16x32_bf16 v[52:55], v[182:185], v[198:201], v[52:55]
	v_mfma_f32_16x16x32_bf16 v[48:51], v[190:193], v[198:201], v[48:51]
	v_mfma_f32_16x16x32_bf16 v[36:39], v[182:185], v[206:209], v[36:39]
	v_mfma_f32_16x16x32_bf16 v[32:35], v[190:193], v[206:209], v[32:35]
	v_mfma_f32_16x16x32_bf16 v[20:23], v[182:185], v[218:221], v[20:23]
	v_mfma_f32_16x16x32_bf16 v[16:19], v[190:193], v[218:221], v[16:19]
	v_mfma_f32_16x16x32_bf16 v[4:7], v[182:185], v[226:229], v[4:7]
	v_mfma_f32_16x16x32_bf16 v[0:3], v[190:193], v[226:229], v[0:3]
	v_mfma_f32_16x16x32_bf16 v[52:55], v[186:189], v[202:205], v[52:55]
	v_mfma_f32_16x16x32_bf16 v[48:51], v[194:197], v[202:205], v[48:51]
	v_mfma_f32_16x16x32_bf16 v[36:39], v[186:189], v[214:217], v[36:39]
	v_mfma_f32_16x16x32_bf16 v[32:35], v[194:197], v[214:217], v[32:35]
	v_mfma_f32_16x16x32_bf16 v[20:23], v[186:189], v[222:225], v[20:23]
	v_mfma_f32_16x16x32_bf16 v[16:19], v[194:197], v[222:225], v[16:19]
	v_mfma_f32_16x16x32_bf16 v[4:7], v[186:189], v[230:233], v[4:7]
	v_mfma_f32_16x16x32_bf16 v[0:3], v[194:197], v[230:233], v[0:3]
	s_setprio 0
	s_barrier
	s_add_i32 s68, s68, 2
	s_add_u32 s6, s6, 0x100
	s_addc_u32 s7, s7, 0
	s_add_u32 s66, s66, 0x100
	s_addc_u32 s67, s67, 0
	s_cmp_gt_u32 s68, 13
	s_cbranch_scc0 .LBB0_647
	v_lshl_add_u32 v166, s0, 8, v153
	v_or_b32_e32 v162, 16, v166
	v_ashrrev_i32_e32 v167, 31, v166
	v_ashrrev_i32_e32 v163, 31, v162
	v_or_b32_e32 v158, 32, v166
	v_lshlrev_b64 v[146:147], 6, v[166:167]
	v_lshlrev_b64 v[144:145], 6, v[162:163]
	v_ashrrev_i32_e32 v159, 31, v158
	v_lshl_add_u64 v[146:147], v[138:139], 0, v[146:147]
	v_or_b32_e32 v154, 48, v166
	v_lshl_add_u64 v[144:145], v[138:139], 0, v[144:145]
	global_load_dwordx4 v[174:177], v[146:147], off
	v_lshlrev_b64 v[146:147], 6, v[158:159]
	v_ashrrev_i32_e32 v155, 31, v154
	v_lshl_add_u64 v[146:147], v[138:139], 0, v[146:147]
	global_load_dwordx4 v[178:181], v[144:145], off
	global_load_dwordx4 v[182:185], v[146:147], off
	v_lshlrev_b64 v[144:145], 6, v[154:155]
	v_lshl_add_u64 v[144:145], v[138:139], 0, v[144:145]
	global_load_dwordx4 v[186:189], v[144:145], off
	v_add_u32_e32 v150, 0x80, v166
	v_ashrrev_i32_e32 v151, 31, v150
	v_lshlrev_b64 v[144:145], 6, v[150:151]
	v_add_u32_e32 v148, 0x90, v166
	v_lshl_add_u64 v[144:145], v[138:139], 0, v[144:145]
	v_ashrrev_i32_e32 v149, 31, v148
	global_load_dwordx4 v[190:193], v[144:145], off
	v_lshlrev_b64 v[144:145], 6, v[148:149]
	v_lshl_add_u64 v[144:145], v[138:139], 0, v[144:145]
	global_load_dwordx4 v[194:197], v[144:145], off
	v_and_b32_e32 v145, 64, v169
	v_add_u32_e32 v144, 0xb0, v166
	v_add_u32_e32 v146, 0xa0, v166
	v_add_u32_e32 v152, 64, v145
	v_ashrrev_i32_e32 v145, 31, v144
	v_ashrrev_i32_e32 v147, 31, v146
	v_lshlrev_b64 v[198:199], 6, v[144:145]
	v_lshlrev_b64 v[200:201], 6, v[146:147]
	v_lshl_add_u64 v[198:199], v[138:139], 0, v[198:199]
	v_lshl_add_u64 v[202:203], v[138:139], 0, v[200:201]
	global_load_dwordx4 v[198:201], v[198:199], off
	s_nop 0
	global_load_dwordx4 v[202:205], v[202:203], off
	s_and_b64 vcc, exec, s[12:13]
	s_cbranch_vccz .LBB0_650
	s_barrier
; DI void rows_rstd(float (&rs)[2][4], const float* ps, const Unit& u, int wr, int fr, int fq, int p_lo, int p_hi, float inv_dim) {
;   f32x4 pv[2][4];
; #pragma unroll
;   for (int ai = 0; ai < 2; ++ai)
; #pragma unroll
;     for (int m = 0; m < 4; ++m) pv[ai][m] = *(const f32x4*)(ps + (size_t)(u.pm * BM + ai * HALF + wr * 64 + m * 16 + fr) * 16 + 4 * fq);
;   const bool use = (4 * fq >= p_lo) && (4 * fq < p_hi);
; #pragma unroll
;   for (int ai = 0; ai < 2; ++ai)
; #pragma unroll
;     for (int m = 0; m < 4; ++m) {
;       float s = use ? (pv[ai][m][0] + pv[ai][m][1]) + (pv[ai][m][2] + pv[ai][m][3]) : 0.f;
;       s += __shfl_xor(s, 16); s += __shfl_xor(s, 32);
;       rs[ai][m] = rsqrtf(s * inv_dim + EPS);
;     }
.LBB0_650:
	v_xor_b32_e32 v149, 32, v169
	v_xor_b32_e32 v151, 16, v169
	v_cmp_lt_i32_e32 vcc, v149, v152
	s_mov_b32 s0, 0x358637bd
	v_mov_b64_e32 v[206:207], s[0:1]
	v_cndmask_b32_e32 v149, v169, v149, vcc
	v_cmp_lt_i32_e32 vcc, v151, v152
	v_lshlrev_b32_e32 v145, 2, v149
	s_waitcnt vmcnt(0)
	v_mov_b32_e32 v208, v175
	v_mov_b32_e32 v209, v176
	v_mov_b32_e32 v175, v177
	v_mov_b32_e32 v176, v179
	v_mov_b32_e32 v177, v180
	v_mov_b32_e32 v179, v181
	v_mov_b32_e32 v180, v183
	v_mov_b32_e32 v181, v184
	v_mov_b32_e32 v183, v185
	v_mov_b32_e32 v184, v187
	v_mov_b32_e32 v185, v188
	v_mov_b32_e32 v187, v189
	v_pk_add_f32 v[174:175], v[208:209], v[174:175]
	v_pk_add_f32 v[176:177], v[176:177], v[178:179]
	v_cndmask_b32_e32 v151, v169, v151, vcc
	v_pk_add_f32 v[178:179], v[180:181], v[182:183]
	v_pk_add_f32 v[180:181], v[184:185], v[186:187]
	v_mov_b32_e32 v183, v174
	v_mov_b32_e32 v182, v176
	v_mov_b32_e32 v174, v177
	v_lshlrev_b32_e32 v147, 2, v151
	v_mov_b32_e32 v176, v180
	v_mov_b32_e32 v177, v178
	v_mov_b32_e32 v178, v181
	v_pk_add_f32 v[174:175], v[182:183], v[174:175]
	v_pk_add_f32 v[176:177], v[176:177], v[178:179]
	ds_bpermute_b32 v179, v147, v175
	ds_bpermute_b32 v178, v147, v174
	ds_bpermute_b32 v181, v147, v177
	ds_bpermute_b32 v180, v147, v176
	v_mov_b32_e32 v182, v191
	v_mov_b32_e32 v183, v192
	s_waitcnt lgkmcnt(2)
	v_pk_add_f32 v[174:175], v[174:175], v[178:179]
	ds_bpermute_b32 v179, v145, v175
	ds_bpermute_b32 v178, v145, v174
	s_waitcnt lgkmcnt(2)
	v_pk_add_f32 v[176:177], v[176:177], v[180:181]
	ds_bpermute_b32 v181, v145, v177
	ds_bpermute_b32 v180, v145, v176
	v_mov_b32_e32 v191, v193
	s_waitcnt lgkmcnt(2)
	v_pk_add_f32 v[174:175], v[174:175], v[178:179]
	v_mov_b32_e32 v184, v195
	v_mov_b32_e32 v185, v196
	v_pk_fma_f32 v[174:175], v[174:175], s[20:21], v[206:207] op_sel_hi:[1,0,0]
	v_mov_b32_e32 v195, v197
	v_pk_add_f32 v[182:183], v[182:183], v[190:191]
	v_mul_f32_e32 v149, 0x4b800000, v175
	v_cmp_gt_f32_e32 vcc, s41, v175
	v_pk_add_f32 v[178:179], v[184:185], v[194:195]
	s_waitcnt lgkmcnt(0)
	v_pk_add_f32 v[176:177], v[176:177], v[180:181]
	v_cndmask_b32_e32 v149, v175, v149, vcc
	v_mov_b32_e32 v180, v178
	v_mov_b32_e32 v181, v182
	v_mov_b32_e32 v182, v179
	v_rsq_f32_e32 v149, v149
	v_pk_add_f32 v[178:179], v[180:181], v[182:183]
	ds_bpermute_b32 v181, v147, v179
	ds_bpermute_b32 v180, v147, v178
	v_pk_fma_f32 v[176:177], v[176:177], s[20:21], v[206:207] op_sel_hi:[1,0,0]
	v_mul_f32_e32 v151, 0x4b800000, v174
	v_cmp_gt_f32_e64 s[0:1], s41, v174
	v_mul_f32_e32 v155, 0x45800000, v149
	v_mul_f32_e32 v152, 0x4b800000, v177
	v_cndmask_b32_e64 v151, v174, v151, s[0:1]
	v_cmp_gt_f32_e64 s[6:7], s41, v177
	v_cndmask_b32_e32 v174, v149, v155, vcc
	v_mul_f32_e32 v149, 0x4b800000, v176
	v_cmp_gt_f32_e32 vcc, s41, v176
	v_cndmask_b32_e64 v152, v177, v152, s[6:7]
	v_rsq_f32_e32 v151, v151
	v_cndmask_b32_e32 v149, v176, v149, vcc
	s_waitcnt lgkmcnt(0)
	v_pk_add_f32 v[176:177], v[178:179], v[180:181]
	ds_bpermute_b32 v179, v145, v177
	ds_bpermute_b32 v178, v145, v176
	v_mov_b32_e32 v180, v199
	v_mov_b32_e32 v181, v200
	v_mov_b32_e32 v199, v201
	v_pk_add_f32 v[180:181], v[180:181], v[198:199]
	s_waitcnt lgkmcnt(0)
	v_pk_add_f32 v[176:177], v[176:177], v[178:179]
	v_mov_b32_e32 v178, v203
	v_mov_b32_e32 v179, v204
	v_mov_b32_e32 v203, v205
	v_pk_add_f32 v[178:179], v[178:179], v[202:203]
	v_mov_b32_e32 v182, v180
	v_mov_b32_e32 v183, v178
	v_mov_b32_e32 v178, v181
	v_rsq_f32_e32 v152, v152
	v_pk_add_f32 v[178:179], v[182:183], v[178:179]
	ds_bpermute_b32 v181, v147, v179
	ds_bpermute_b32 v180, v147, v178
	v_mul_f32_e32 v156, 0x45800000, v151
	v_cndmask_b32_e64 v172, v151, v156, s[0:1]
	v_mul_f32_e32 v151, 0x45800000, v152
	v_pk_fma_f32 v[176:177], v[176:177], s[20:21], v[206:207] op_sel_hi:[1,0,0]
	v_cndmask_b32_e64 v170, v152, v151, s[6:7]
	v_mul_f32_e32 v152, 0x4b800000, v177
	v_cmp_gt_f32_e64 s[0:1], s41, v177
	v_mul_f32_e32 v147, 0x4b800000, v176
	v_cmp_gt_f32_e64 s[6:7], s41, v176
	v_cndmask_b32_e64 v152, v177, v152, s[0:1]
	v_rsq_f32_e32 v149, v149
	v_cndmask_b32_e64 v147, v176, v147, s[6:7]
	s_waitcnt lgkmcnt(0)
	v_pk_add_f32 v[176:177], v[178:179], v[180:181]
	ds_bpermute_b32 v179, v145, v177
	ds_bpermute_b32 v178, v145, v176
	v_rsq_f32_e32 v152, v152
	v_mul_f32_e32 v151, 0x45800000, v149
	v_cndmask_b32_e32 v168, v149, v151, vcc
	v_rsq_f32_e32 v147, v147
	s_waitcnt lgkmcnt(0)
; DI unsigned pack2(float a, float b) { bf2_t v = __builtin_convertvector((f32x2){a, b}, bf2_t); return __builtin_bit_cast(unsigned, v); }
;   DI void operator()(const f32x4 (&acc)[2][2][4][2], const Unit& u, int wr, int wc, int fr, int fq) const {
;     float rsv[2][4];
;     rows_rstd(rsv, ps_in, u, wr, fr, fq, 0, 16, 1.f / 1024.f);
; #pragma unroll
;     for (int ai = 0; ai < 2; ++ai)
; #pragma unroll
;       for (int m = 0; m < 4; ++m) {
;         const int row = u.pm * BM + ai * HALF + wr * 64 + m * 16 + fr;
;         const float rs = rsv[ai][m];
;         float o[8];
; #pragma unroll
;         for (int n = 0; n < 2; ++n)
; #pragma unroll
;           for (int c = 0; c < 4; ++c) {
;             const float gv = acc[ai][0][m][n][c] * rs, uv = acc[ai][1][m][n][c] * rs;
;             o[4 * n + c] = gv * __builtin_amdgcn_rcpf(1.f + __expf(-gv)) * uv;
;           }
;         u32x4 w; w.x = pack2(o[0], o[1]); w.y = pack2(o[2], o[3]); w.z = pack2(o[4], o[5]); w.w = pack2(o[6], o[7]);
;         *(u32x4*)(O + (size_t)row * DFF + u.pn * HALF + wc * 32 + 8 * fq) = w;
	v_pk_add_f32 v[176:177], v[176:177], v[178:179]
	v_mul_f32_e32 v145, 0x45800000, v152
	v_pk_fma_f32 v[176:177], v[176:177], s[20:21], v[206:207] op_sel_hi:[1,0,0]
	v_cndmask_b32_e64 v164, v152, v145, s[0:1]
	v_mul_f32_e32 v149, 0x4b800000, v177
	v_cmp_gt_f32_e32 vcc, s41, v177
	v_mul_f32_e32 v151, 0x4b800000, v176
	v_cmp_gt_f32_e64 s[0:1], s41, v176
	v_cndmask_b32_e32 v149, v177, v149, vcc
	v_rsq_f32_e32 v149, v149
	v_cndmask_b32_e64 v151, v176, v151, s[0:1]
	v_rsq_f32_e32 v151, v151
	v_mul_f32_e32 v145, 0x45800000, v147
	v_cndmask_b32_e64 v160, v147, v145, s[6:7]
	v_mul_f32_e32 v145, 0x45800000, v149
	v_cndmask_b32_e32 v156, v149, v145, vcc
	v_mul_f32_e32 v145, 0x45800000, v151
	v_pk_mul_f32 v[124:125], v[124:125], v[174:175] op_sel_hi:[1,0]
	v_cndmask_b32_e64 v152, v151, v145, s[0:1]
	v_mul_f32_e32 v145, 0xbfb8aa3b, v124
	v_exp_f32_e32 v145, v145
	v_mul_f32_e32 v147, 0xbfb8aa3b, v125
	v_exp_f32_e32 v147, v147
	v_pk_mul_f32 v[126:127], v[126:127], v[174:175] op_sel_hi:[1,0]
	v_add_f32_e32 v145, 1.0, v145
	v_rcp_f32_e32 v176, v145
	v_add_f32_e32 v145, 1.0, v147
	v_mul_f32_e32 v147, 0xbfb8aa3b, v126
	v_exp_f32_e32 v147, v147
	v_mul_f32_e32 v149, 0xbfb8aa3b, v127
	v_exp_f32_e32 v149, v149
	v_rcp_f32_e32 v177, v145
	v_add_f32_e32 v145, 1.0, v147
	v_rcp_f32_e32 v178, v145
	v_add_f32_e32 v145, 1.0, v149
	v_rcp_f32_e32 v179, v145
	v_pk_mul_f32 v[116:117], v[116:117], v[174:175] op_sel_hi:[1,0]
	v_pk_mul_f32 v[124:125], v[124:125], v[176:177]
	v_pk_mul_f32 v[120:121], v[120:121], v[174:175] op_sel_hi:[1,0]
	v_pk_mul_f32 v[116:117], v[116:117], v[124:125]
	v_pk_mul_f32 v[124:125], v[126:127], v[178:179]
	v_mul_f32_e32 v126, 0xbfb8aa3b, v120
	v_exp_f32_e32 v126, v126
	v_pk_mul_f32 v[118:119], v[118:119], v[174:175] op_sel_hi:[1,0]
	v_pk_mul_f32 v[122:123], v[122:123], v[174:175] op_sel_hi:[1,0]
	v_pk_mul_f32 v[118:119], v[118:119], v[124:125]
	v_mul_f32_e32 v124, 0xbfb8aa3b, v121
	v_exp_f32_e32 v125, v124
	v_add_f32_e32 v124, 1.0, v126
	v_mul_f32_e32 v126, 0xbfb8aa3b, v122
	v_mul_f32_e32 v127, 0xbfb8aa3b, v123
	v_exp_f32_e32 v126, v126
	v_exp_f32_e32 v127, v127
	v_add_f32_e32 v125, 1.0, v125
	v_rcp_f32_e32 v124, v124
	v_rcp_f32_e32 v125, v125
	v_add_f32_e32 v126, 1.0, v126
	v_add_f32_e32 v127, 1.0, v127
	v_rcp_f32_e32 v126, v126
	v_rcp_f32_e32 v127, v127
	v_pk_mul_f32 v[112:113], v[112:113], v[174:175] op_sel_hi:[1,0]
	v_pk_mul_f32 v[120:121], v[120:121], v[124:125]
	s_lshl_b32 s0, s64, 7
	v_pk_mul_f32 v[112:113], v[112:113], v[120:121]
	v_pk_mul_f32 v[114:115], v[114:115], v[174:175] op_sel_hi:[1,0]
	v_pk_mul_f32 v[120:121], v[122:123], v[126:127]
	s_ashr_i32 s1, s0, 31
	v_pk_mul_f32 v[120:121], v[114:115], v[120:121]
	v_cvt_pk_bf16_f32 v114, v116, v117
	v_cvt_pk_bf16_f32 v116, v112, v113
	v_mov_b64_e32 v[112:113], s[46:47]
	v_cvt_pk_bf16_f32 v115, v118, v119
	v_mad_i64_i32 v[118:119], s[6:7], v166, s44, v[112:113]
	s_lshl_b64 s[0:1], s[0:1], 1
	v_lshl_add_u64 v[118:119], v[118:119], 0, s[0:1]
	v_lshl_add_u64 v[118:119], v[118:119], 0, s[14:15]
	v_cvt_pk_bf16_f32 v117, v120, v121
	v_lshl_add_u64 v[118:119], v[118:119], 0, v[136:137]
	v_pk_mul_f32 v[108:109], v[108:109], v[172:173] op_sel_hi:[1,0]
	global_store_dwordx4 v[118:119], v[114:117], off
	v_mul_f32_e32 v120, 0xbfb8aa3b, v108
	v_pk_mul_f32 v[110:111], v[110:111], v[172:173] op_sel_hi:[1,0]
	v_mul_f32_e32 v114, 0xbfb8aa3b, v109
	v_exp_f32_e32 v120, v120
	v_exp_f32_e32 v115, v114
	v_mul_f32_e32 v116, 0xbfb8aa3b, v110
	v_mul_f32_e32 v117, 0xbfb8aa3b, v111
	v_exp_f32_e32 v116, v116
	v_exp_f32_e32 v117, v117
	v_add_f32_e32 v114, 1.0, v120
	v_add_f32_e32 v115, 1.0, v115
	v_rcp_f32_e32 v114, v114
	v_rcp_f32_e32 v115, v115
	v_add_f32_e32 v116, 1.0, v116
	v_add_f32_e32 v117, 1.0, v117
	v_rcp_f32_e32 v116, v116
	v_rcp_f32_e32 v117, v117
	v_pk_mul_f32 v[100:101], v[100:101], v[172:173] op_sel_hi:[1,0]
	v_pk_mul_f32 v[108:109], v[108:109], v[114:115]
	v_pk_mul_f32 v[104:105], v[104:105], v[172:173] op_sel_hi:[1,0]
	v_pk_mul_f32 v[100:101], v[100:101], v[108:109]
	v_pk_mul_f32 v[108:109], v[110:111], v[116:117]
	v_mul_f32_e32 v110, 0xbfb8aa3b, v104
	v_exp_f32_e32 v110, v110
	v_pk_mul_f32 v[102:103], v[102:103], v[172:173] op_sel_hi:[1,0]
	v_pk_mul_f32 v[106:107], v[106:107], v[172:173] op_sel_hi:[1,0]
	v_pk_mul_f32 v[102:103], v[102:103], v[108:109]
	v_mul_f32_e32 v108, 0xbfb8aa3b, v105
	v_exp_f32_e32 v109, v108
	v_add_f32_e32 v108, 1.0, v110
	v_mul_f32_e32 v110, 0xbfb8aa3b, v106
	v_mul_f32_e32 v111, 0xbfb8aa3b, v107
	v_exp_f32_e32 v110, v110
	v_exp_f32_e32 v111, v111
	v_add_f32_e32 v109, 1.0, v109
	v_rcp_f32_e32 v108, v108
	v_rcp_f32_e32 v109, v109
	v_add_f32_e32 v110, 1.0, v110
	v_add_f32_e32 v111, 1.0, v111
	v_rcp_f32_e32 v110, v110
	v_rcp_f32_e32 v111, v111
	v_pk_mul_f32 v[96:97], v[96:97], v[172:173] op_sel_hi:[1,0]
	v_pk_mul_f32 v[104:105], v[104:105], v[108:109]
	v_pk_mul_f32 v[92:93], v[92:93], v[170:171] op_sel_hi:[1,0]
	v_pk_mul_f32 v[104:105], v[96:97], v[104:105]
	v_pk_mul_f32 v[96:97], v[98:99], v[172:173] op_sel_hi:[1,0]
	v_pk_mul_f32 v[98:99], v[106:107], v[110:111]
	v_pk_mul_f32 v[94:95], v[94:95], v[170:171] op_sel_hi:[1,0]
	v_pk_mul_f32 v[106:107], v[96:97], v[98:99]
	v_cvt_pk_bf16_f32 v96, v100, v101
	v_mad_i64_i32 v[100:101], s[6:7], v162, s44, v[112:113]
	v_lshl_add_u64 v[100:101], v[100:101], 0, s[0:1]
	v_lshl_add_u64 v[100:101], v[100:101], 0, s[14:15]
	v_cvt_pk_bf16_f32 v97, v102, v103
	v_cvt_pk_bf16_f32 v98, v104, v105
	v_cvt_pk_bf16_f32 v99, v106, v107
	v_lshl_add_u64 v[100:101], v[100:101], 0, v[136:137]
	v_mul_f32_e32 v102, 0xbfb8aa3b, v92
	global_store_dwordx4 v[100:101], v[96:99], off
	v_exp_f32_e32 v102, v102
	v_pk_mul_f32 v[84:85], v[84:85], v[170:171] op_sel_hi:[1,0]
; DI unsigned pack2(float a, float b) { bf2_t v = __builtin_convertvector((f32x2){a, b}, bf2_t); return __builtin_bit_cast(unsigned, v); }
;   DI void operator()(const f32x4 (&acc)[2][2][4][2], const Unit& u, int wr, int wc, int fr, int fq) const {
;     ...
; #pragma unroll
;     for (int ai = 0; ai < 2; ++ai)
; #pragma unroll
;       for (int m = 0; m < 4; ++m) {
;         const int row = u.pm * BM + ai * HALF + wr * 64 + m * 16 + fr;
;         const float rs = rsv[ai][m];
;         float o[8];
; #pragma unroll
;         for (int n = 0; n < 2; ++n)
; #pragma unroll
;           for (int c = 0; c < 4; ++c) {
;             const float gv = acc[ai][0][m][n][c] * rs, uv = acc[ai][1][m][n][c] * rs;
;             o[4 * n + c] = gv * __builtin_amdgcn_rcpf(1.f + __expf(-gv)) * uv;
;           }
;         u32x4 w; w.x = pack2(o[0], o[1]); w.y = pack2(o[2], o[3]); w.z = pack2(o[4], o[5]); w.w = pack2(o[6], o[7]);
;         *(u32x4*)(O + (size_t)row * DFF + u.pn * HALF + wc * 32 + 8 * fq) = w;
	v_mul_f32_e32 v96, 0xbfb8aa3b, v93
	v_exp_f32_e32 v97, v96
	v_mul_f32_e32 v98, 0xbfb8aa3b, v94
	v_mul_f32_e32 v99, 0xbfb8aa3b, v95
	v_exp_f32_e32 v98, v98
	v_exp_f32_e32 v99, v99
	v_add_f32_e32 v96, 1.0, v102
	v_add_f32_e32 v97, 1.0, v97
	v_rcp_f32_e32 v96, v96
	v_rcp_f32_e32 v97, v97
	v_add_f32_e32 v98, 1.0, v98
	v_add_f32_e32 v99, 1.0, v99
	v_rcp_f32_e32 v98, v98
	v_rcp_f32_e32 v99, v99
	v_pk_mul_f32 v[92:93], v[92:93], v[96:97]
	v_pk_mul_f32 v[88:89], v[88:89], v[170:171] op_sel_hi:[1,0]
	v_pk_mul_f32 v[84:85], v[84:85], v[92:93]
	v_pk_mul_f32 v[92:93], v[94:95], v[98:99]
	v_mul_f32_e32 v94, 0xbfb8aa3b, v88
	v_exp_f32_e32 v94, v94
	v_pk_mul_f32 v[86:87], v[86:87], v[170:171] op_sel_hi:[1,0]
	v_pk_mul_f32 v[90:91], v[90:91], v[170:171] op_sel_hi:[1,0]
	v_pk_mul_f32 v[86:87], v[86:87], v[92:93]
	v_mul_f32_e32 v92, 0xbfb8aa3b, v89
	v_exp_f32_e32 v93, v92
	v_add_f32_e32 v92, 1.0, v94
	v_mul_f32_e32 v94, 0xbfb8aa3b, v90
	v_mul_f32_e32 v95, 0xbfb8aa3b, v91
	v_exp_f32_e32 v94, v94
	v_exp_f32_e32 v95, v95
	v_add_f32_e32 v93, 1.0, v93
	v_rcp_f32_e32 v92, v92
	v_rcp_f32_e32 v93, v93
	v_add_f32_e32 v94, 1.0, v94
	v_add_f32_e32 v95, 1.0, v95
	v_rcp_f32_e32 v94, v94
	v_rcp_f32_e32 v95, v95
	v_pk_mul_f32 v[80:81], v[80:81], v[170:171] op_sel_hi:[1,0]
	v_pk_mul_f32 v[88:89], v[88:89], v[92:93]
	v_pk_mul_f32 v[76:77], v[76:77], v[168:169] op_sel_hi:[1,0]
	v_pk_mul_f32 v[88:89], v[80:81], v[88:89]
	v_pk_mul_f32 v[80:81], v[82:83], v[170:171] op_sel_hi:[1,0]
	v_pk_mul_f32 v[82:83], v[90:91], v[94:95]
	v_pk_mul_f32 v[78:79], v[78:79], v[168:169] op_sel_hi:[1,0]
	v_pk_mul_f32 v[90:91], v[80:81], v[82:83]
	v_cvt_pk_bf16_f32 v80, v84, v85
	v_mad_i64_i32 v[84:85], s[6:7], v158, s44, v[112:113]
	v_lshl_add_u64 v[84:85], v[84:85], 0, s[0:1]
	v_lshl_add_u64 v[84:85], v[84:85], 0, s[14:15]
	v_cvt_pk_bf16_f32 v81, v86, v87
	v_cvt_pk_bf16_f32 v82, v88, v89
	v_cvt_pk_bf16_f32 v83, v90, v91
	v_lshl_add_u64 v[84:85], v[84:85], 0, v[136:137]
	v_mul_f32_e32 v86, 0xbfb8aa3b, v76
	global_store_dwordx4 v[84:85], v[80:83], off
	v_exp_f32_e32 v86, v86
	v_pk_mul_f32 v[68:69], v[68:69], v[168:169] op_sel_hi:[1,0]
	v_mul_f32_e32 v80, 0xbfb8aa3b, v77
	v_exp_f32_e32 v81, v80
	v_mul_f32_e32 v82, 0xbfb8aa3b, v78
	v_mul_f32_e32 v83, 0xbfb8aa3b, v79
	v_exp_f32_e32 v82, v82
	v_exp_f32_e32 v83, v83
	v_add_f32_e32 v80, 1.0, v86
	v_add_f32_e32 v81, 1.0, v81
	v_rcp_f32_e32 v80, v80
	v_rcp_f32_e32 v81, v81
	v_add_f32_e32 v82, 1.0, v82
	v_add_f32_e32 v83, 1.0, v83
	v_rcp_f32_e32 v82, v82
	v_rcp_f32_e32 v83, v83
	v_pk_mul_f32 v[76:77], v[76:77], v[80:81]
	v_pk_mul_f32 v[72:73], v[72:73], v[168:169] op_sel_hi:[1,0]
	v_pk_mul_f32 v[68:69], v[68:69], v[76:77]
	v_pk_mul_f32 v[76:77], v[78:79], v[82:83]
	v_mul_f32_e32 v78, 0xbfb8aa3b, v72
	v_exp_f32_e32 v78, v78
	v_pk_mul_f32 v[70:71], v[70:71], v[168:169] op_sel_hi:[1,0]
	v_pk_mul_f32 v[74:75], v[74:75], v[168:169] op_sel_hi:[1,0]
	v_pk_mul_f32 v[70:71], v[70:71], v[76:77]
	v_mul_f32_e32 v76, 0xbfb8aa3b, v73
	v_exp_f32_e32 v77, v76
	v_add_f32_e32 v76, 1.0, v78
	v_mul_f32_e32 v78, 0xbfb8aa3b, v74
	v_mul_f32_e32 v79, 0xbfb8aa3b, v75
	v_exp_f32_e32 v78, v78
	v_exp_f32_e32 v79, v79
	v_add_f32_e32 v77, 1.0, v77
	v_rcp_f32_e32 v76, v76
	v_rcp_f32_e32 v77, v77
	v_add_f32_e32 v78, 1.0, v78
	v_add_f32_e32 v79, 1.0, v79
	v_rcp_f32_e32 v78, v78
	v_rcp_f32_e32 v79, v79
	v_pk_mul_f32 v[64:65], v[64:65], v[168:169] op_sel_hi:[1,0]
	v_pk_mul_f32 v[72:73], v[72:73], v[76:77]
	v_pk_mul_f32 v[60:61], v[60:61], v[164:165] op_sel_hi:[1,0]
	v_pk_mul_f32 v[72:73], v[64:65], v[72:73]
	v_pk_mul_f32 v[64:65], v[66:67], v[168:169] op_sel_hi:[1,0]
	v_pk_mul_f32 v[66:67], v[74:75], v[78:79]
	v_pk_mul_f32 v[62:63], v[62:63], v[164:165] op_sel_hi:[1,0]
	v_pk_mul_f32 v[74:75], v[64:65], v[66:67]
	v_cvt_pk_bf16_f32 v64, v68, v69
	v_mad_i64_i32 v[68:69], s[6:7], v154, s44, v[112:113]
	v_lshl_add_u64 v[68:69], v[68:69], 0, s[0:1]
	v_lshl_add_u64 v[68:69], v[68:69], 0, s[14:15]
	v_cvt_pk_bf16_f32 v65, v70, v71
	v_cvt_pk_bf16_f32 v66, v72, v73
	v_cvt_pk_bf16_f32 v67, v74, v75
	v_lshl_add_u64 v[68:69], v[68:69], 0, v[136:137]
	v_mul_f32_e32 v70, 0xbfb8aa3b, v60
	global_store_dwordx4 v[68:69], v[64:67], off
	v_exp_f32_e32 v70, v70
	v_pk_mul_f32 v[52:53], v[52:53], v[164:165] op_sel_hi:[1,0]
	v_mul_f32_e32 v64, 0xbfb8aa3b, v61
	v_exp_f32_e32 v65, v64
	v_mul_f32_e32 v66, 0xbfb8aa3b, v62
	v_mul_f32_e32 v67, 0xbfb8aa3b, v63
	v_exp_f32_e32 v66, v66
	v_exp_f32_e32 v67, v67
	v_add_f32_e32 v64, 1.0, v70
	v_add_f32_e32 v65, 1.0, v65
	v_rcp_f32_e32 v64, v64
	v_rcp_f32_e32 v65, v65
	v_add_f32_e32 v66, 1.0, v66
	v_add_f32_e32 v67, 1.0, v67
	v_rcp_f32_e32 v66, v66
	v_rcp_f32_e32 v67, v67
	v_pk_mul_f32 v[60:61], v[60:61], v[64:65]
	v_pk_mul_f32 v[56:57], v[56:57], v[164:165] op_sel_hi:[1,0]
	v_pk_mul_f32 v[52:53], v[52:53], v[60:61]
	v_pk_mul_f32 v[60:61], v[62:63], v[66:67]
	v_mul_f32_e32 v62, 0xbfb8aa3b, v56
	v_exp_f32_e32 v62, v62
	v_pk_mul_f32 v[54:55], v[54:55], v[164:165] op_sel_hi:[1,0]
	v_pk_mul_f32 v[58:59], v[58:59], v[164:165] op_sel_hi:[1,0]
	v_pk_mul_f32 v[54:55], v[54:55], v[60:61]
	v_mul_f32_e32 v60, 0xbfb8aa3b, v57
	v_exp_f32_e32 v61, v60
	v_add_f32_e32 v60, 1.0, v62
	v_mul_f32_e32 v62, 0xbfb8aa3b, v58
	v_mul_f32_e32 v63, 0xbfb8aa3b, v59
	v_exp_f32_e32 v62, v62
	v_exp_f32_e32 v63, v63
	v_add_f32_e32 v61, 1.0, v61
	v_rcp_f32_e32 v60, v60
	v_rcp_f32_e32 v61, v61
	v_add_f32_e32 v62, 1.0, v62
	v_add_f32_e32 v63, 1.0, v63
	v_rcp_f32_e32 v62, v62
	v_rcp_f32_e32 v63, v63
	v_pk_mul_f32 v[48:49], v[48:49], v[164:165] op_sel_hi:[1,0]
	v_pk_mul_f32 v[56:57], v[56:57], v[60:61]
	v_pk_mul_f32 v[44:45], v[44:45], v[160:161] op_sel_hi:[1,0]
	v_pk_mul_f32 v[56:57], v[48:49], v[56:57]
; DI unsigned pack2(float a, float b) { bf2_t v = __builtin_convertvector((f32x2){a, b}, bf2_t); return __builtin_bit_cast(unsigned, v); }
; #define PG8_BAR __builtin_amdgcn_s_barrier()
;   DI void operator()(const f32x4 (&acc)[2][2][4][2], const Unit& u, int wr, int wc, int fr, int fq) const {
;     ...
; #pragma unroll
;     for (int ai = 0; ai < 2; ++ai)
; #pragma unroll
;       for (int m = 0; m < 4; ++m) {
;         const int row = u.pm * BM + ai * HALF + wr * 64 + m * 16 + fr;
;         const float rs = rsv[ai][m];
;         float o[8];
; #pragma unroll
;         for (int n = 0; n < 2; ++n)
; #pragma unroll
;           for (int c = 0; c < 4; ++c) {
;             const float gv = acc[ai][0][m][n][c] * rs, uv = acc[ai][1][m][n][c] * rs;
;             o[4 * n + c] = gv * __builtin_amdgcn_rcpf(1.f + __expf(-gv)) * uv;
;           }
;         u32x4 w; w.x = pack2(o[0], o[1]); w.y = pack2(o[2], o[3]); w.z = pack2(o[4], o[5]); w.w = pack2(o[6], o[7]);
;         *(u32x4*)(O + (size_t)row * DFF + u.pn * HALF + wc * 32 + 8 * fq) = w;
; template <class Epi, class Sched>
; DI void gemm_phase(PG8_LAS unsigned char* lds, const Gemm g, const Sched& S, const Epi& E) {
;     ...
;     if (!has_next) break;
; #pragma unroll
;     for (int a = 0; a < 2; ++a)
; #pragma unroll
;       for (int b = 0; b < 2; ++b)
; #pragma unroll
;         for (int m = 0; m < 4; ++m)
; #pragma unroll
;           for (int n = 0; n < 2; ++n) acc[a][b][m][n] = (f32x4){0.f, 0.f, 0.f, 0.f};
;     cur = nxt; cA = nA; cB = nB; ++ui;
;     if (wr == 1) PG8_BAR;
	v_pk_mul_f32 v[48:49], v[50:51], v[164:165] op_sel_hi:[1,0]
	v_pk_mul_f32 v[50:51], v[58:59], v[62:63]
	v_pk_mul_f32 v[46:47], v[46:47], v[160:161] op_sel_hi:[1,0]
	v_pk_mul_f32 v[58:59], v[48:49], v[50:51]
	v_cvt_pk_bf16_f32 v48, v52, v53
	v_mad_i64_i32 v[52:53], s[6:7], v150, s44, v[112:113]
	v_lshl_add_u64 v[52:53], v[52:53], 0, s[0:1]
	v_lshl_add_u64 v[52:53], v[52:53], 0, s[14:15]
	v_cvt_pk_bf16_f32 v49, v54, v55
	v_cvt_pk_bf16_f32 v50, v56, v57
	v_cvt_pk_bf16_f32 v51, v58, v59
	v_lshl_add_u64 v[52:53], v[52:53], 0, v[136:137]
	v_mul_f32_e32 v54, 0xbfb8aa3b, v44
	global_store_dwordx4 v[52:53], v[48:51], off
	v_exp_f32_e32 v54, v54
	v_pk_mul_f32 v[36:37], v[36:37], v[160:161] op_sel_hi:[1,0]
	v_mul_f32_e32 v48, 0xbfb8aa3b, v45
	v_exp_f32_e32 v49, v48
	v_mul_f32_e32 v50, 0xbfb8aa3b, v46
	v_mul_f32_e32 v51, 0xbfb8aa3b, v47
	v_exp_f32_e32 v50, v50
	v_exp_f32_e32 v51, v51
	v_add_f32_e32 v48, 1.0, v54
	v_add_f32_e32 v49, 1.0, v49
	v_rcp_f32_e32 v48, v48
	v_rcp_f32_e32 v49, v49
	v_add_f32_e32 v50, 1.0, v50
	v_add_f32_e32 v51, 1.0, v51
	v_rcp_f32_e32 v50, v50
	v_rcp_f32_e32 v51, v51
	v_pk_mul_f32 v[44:45], v[44:45], v[48:49]
	v_pk_mul_f32 v[40:41], v[40:41], v[160:161] op_sel_hi:[1,0]
	v_pk_mul_f32 v[36:37], v[36:37], v[44:45]
	v_pk_mul_f32 v[44:45], v[46:47], v[50:51]
	v_mul_f32_e32 v46, 0xbfb8aa3b, v40
	v_exp_f32_e32 v46, v46
	v_pk_mul_f32 v[38:39], v[38:39], v[160:161] op_sel_hi:[1,0]
	v_pk_mul_f32 v[42:43], v[42:43], v[160:161] op_sel_hi:[1,0]
	v_pk_mul_f32 v[38:39], v[38:39], v[44:45]
	v_mul_f32_e32 v44, 0xbfb8aa3b, v41
	v_exp_f32_e32 v45, v44
	v_add_f32_e32 v44, 1.0, v46
	v_mul_f32_e32 v46, 0xbfb8aa3b, v42
	v_mul_f32_e32 v47, 0xbfb8aa3b, v43
	v_exp_f32_e32 v46, v46
	v_exp_f32_e32 v47, v47
	v_add_f32_e32 v45, 1.0, v45
	v_rcp_f32_e32 v44, v44
	v_rcp_f32_e32 v45, v45
	v_add_f32_e32 v46, 1.0, v46
	v_add_f32_e32 v47, 1.0, v47
	v_rcp_f32_e32 v46, v46
	v_rcp_f32_e32 v47, v47
	v_pk_mul_f32 v[32:33], v[32:33], v[160:161] op_sel_hi:[1,0]
	v_pk_mul_f32 v[40:41], v[40:41], v[44:45]
	v_pk_mul_f32 v[28:29], v[28:29], v[156:157] op_sel_hi:[1,0]
	v_pk_mul_f32 v[40:41], v[32:33], v[40:41]
	v_pk_mul_f32 v[32:33], v[34:35], v[160:161] op_sel_hi:[1,0]
	v_pk_mul_f32 v[34:35], v[42:43], v[46:47]
	v_pk_mul_f32 v[30:31], v[30:31], v[156:157] op_sel_hi:[1,0]
	v_pk_mul_f32 v[42:43], v[32:33], v[34:35]
	v_cvt_pk_bf16_f32 v32, v36, v37
	v_mad_i64_i32 v[36:37], s[6:7], v148, s44, v[112:113]
	v_lshl_add_u64 v[36:37], v[36:37], 0, s[0:1]
	v_lshl_add_u64 v[36:37], v[36:37], 0, s[14:15]
	v_cvt_pk_bf16_f32 v33, v38, v39
	v_cvt_pk_bf16_f32 v34, v40, v41
	v_cvt_pk_bf16_f32 v35, v42, v43
	v_lshl_add_u64 v[36:37], v[36:37], 0, v[136:137]
	v_mul_f32_e32 v38, 0xbfb8aa3b, v28
	global_store_dwordx4 v[36:37], v[32:35], off
	v_exp_f32_e32 v38, v38
	v_pk_mul_f32 v[20:21], v[20:21], v[156:157] op_sel_hi:[1,0]
	v_mul_f32_e32 v32, 0xbfb8aa3b, v29
	v_exp_f32_e32 v33, v32
	v_mul_f32_e32 v34, 0xbfb8aa3b, v30
	v_mul_f32_e32 v35, 0xbfb8aa3b, v31
	v_exp_f32_e32 v34, v34
	v_exp_f32_e32 v35, v35
	v_add_f32_e32 v32, 1.0, v38
	v_add_f32_e32 v33, 1.0, v33
	v_rcp_f32_e32 v32, v32
	v_rcp_f32_e32 v33, v33
	v_add_f32_e32 v34, 1.0, v34
	v_add_f32_e32 v35, 1.0, v35
	v_rcp_f32_e32 v34, v34
	v_rcp_f32_e32 v35, v35
	v_pk_mul_f32 v[28:29], v[28:29], v[32:33]
	v_pk_mul_f32 v[24:25], v[24:25], v[156:157] op_sel_hi:[1,0]
	v_pk_mul_f32 v[20:21], v[20:21], v[28:29]
	v_pk_mul_f32 v[28:29], v[30:31], v[34:35]
	v_mul_f32_e32 v30, 0xbfb8aa3b, v24
	v_exp_f32_e32 v30, v30
	v_pk_mul_f32 v[22:23], v[22:23], v[156:157] op_sel_hi:[1,0]
	v_pk_mul_f32 v[26:27], v[26:27], v[156:157] op_sel_hi:[1,0]
	v_pk_mul_f32 v[22:23], v[22:23], v[28:29]
	v_mul_f32_e32 v28, 0xbfb8aa3b, v25
	v_exp_f32_e32 v29, v28
	v_add_f32_e32 v28, 1.0, v30
	v_mul_f32_e32 v30, 0xbfb8aa3b, v26
	v_mul_f32_e32 v31, 0xbfb8aa3b, v27
	v_exp_f32_e32 v30, v30
	v_exp_f32_e32 v31, v31
	v_add_f32_e32 v29, 1.0, v29
	v_rcp_f32_e32 v28, v28
	v_rcp_f32_e32 v29, v29
	v_add_f32_e32 v30, 1.0, v30
	v_add_f32_e32 v31, 1.0, v31
	v_rcp_f32_e32 v30, v30
	v_rcp_f32_e32 v31, v31
	v_pk_mul_f32 v[16:17], v[16:17], v[156:157] op_sel_hi:[1,0]
	v_pk_mul_f32 v[24:25], v[24:25], v[28:29]
	v_pk_mul_f32 v[12:13], v[12:13], v[152:153] op_sel_hi:[1,0]
	v_pk_mul_f32 v[24:25], v[16:17], v[24:25]
	v_pk_mul_f32 v[16:17], v[18:19], v[156:157] op_sel_hi:[1,0]
	v_pk_mul_f32 v[18:19], v[26:27], v[30:31]
	v_pk_mul_f32 v[14:15], v[14:15], v[152:153] op_sel_hi:[1,0]
	v_pk_mul_f32 v[26:27], v[16:17], v[18:19]
	v_cvt_pk_bf16_f32 v16, v20, v21
	v_mad_i64_i32 v[20:21], s[6:7], v146, s44, v[112:113]
	v_lshl_add_u64 v[20:21], v[20:21], 0, s[0:1]
	v_lshl_add_u64 v[20:21], v[20:21], 0, s[14:15]
	v_cvt_pk_bf16_f32 v17, v22, v23
	v_cvt_pk_bf16_f32 v18, v24, v25
	v_cvt_pk_bf16_f32 v19, v26, v27
	v_lshl_add_u64 v[20:21], v[20:21], 0, v[136:137]
	v_mul_f32_e32 v22, 0xbfb8aa3b, v12
	global_store_dwordx4 v[20:21], v[16:19], off
	v_exp_f32_e32 v22, v22
	v_pk_mul_f32 v[4:5], v[4:5], v[152:153] op_sel_hi:[1,0]
	v_mul_f32_e32 v16, 0xbfb8aa3b, v13
	v_exp_f32_e32 v17, v16
	v_mul_f32_e32 v18, 0xbfb8aa3b, v14
	v_mul_f32_e32 v19, 0xbfb8aa3b, v15
	v_exp_f32_e32 v18, v18
	v_exp_f32_e32 v19, v19
	v_add_f32_e32 v16, 1.0, v22
	v_add_f32_e32 v17, 1.0, v17
	v_rcp_f32_e32 v16, v16
	v_rcp_f32_e32 v17, v17
	v_add_f32_e32 v18, 1.0, v18
	v_add_f32_e32 v19, 1.0, v19
	v_rcp_f32_e32 v18, v18
	v_rcp_f32_e32 v19, v19
	v_pk_mul_f32 v[12:13], v[12:13], v[16:17]
	v_pk_mul_f32 v[8:9], v[8:9], v[152:153] op_sel_hi:[1,0]
	v_pk_mul_f32 v[4:5], v[4:5], v[12:13]
	v_pk_mul_f32 v[12:13], v[14:15], v[18:19]
	v_mul_f32_e32 v14, 0xbfb8aa3b, v8
	v_exp_f32_e32 v14, v14
	v_pk_mul_f32 v[6:7], v[6:7], v[152:153] op_sel_hi:[1,0]
	v_pk_mul_f32 v[10:11], v[10:11], v[152:153] op_sel_hi:[1,0]
	v_pk_mul_f32 v[6:7], v[6:7], v[12:13]
	v_mul_f32_e32 v12, 0xbfb8aa3b, v9
	v_exp_f32_e32 v13, v12
	v_add_f32_e32 v12, 1.0, v14
	v_mul_f32_e32 v14, 0xbfb8aa3b, v10
	v_mul_f32_e32 v15, 0xbfb8aa3b, v11
	v_exp_f32_e32 v14, v14
	v_exp_f32_e32 v15, v15
	v_add_f32_e32 v13, 1.0, v13
	v_rcp_f32_e32 v12, v12
	v_rcp_f32_e32 v13, v13
	v_add_f32_e32 v14, 1.0, v14
	v_add_f32_e32 v15, 1.0, v15
	v_rcp_f32_e32 v14, v14
	v_rcp_f32_e32 v15, v15
	v_pk_mul_f32 v[0:1], v[0:1], v[152:153] op_sel_hi:[1,0]
	v_pk_mul_f32 v[8:9], v[8:9], v[12:13]
	s_andn2_b64 vcc, exec, s[26:27]
	v_pk_mul_f32 v[8:9], v[0:1], v[8:9]
	v_pk_mul_f32 v[0:1], v[2:3], v[152:153] op_sel_hi:[1,0]
	v_pk_mul_f32 v[2:3], v[10:11], v[14:15]
	s_nop 0
	v_pk_mul_f32 v[10:11], v[0:1], v[2:3]
	v_cvt_pk_bf16_f32 v0, v4, v5
	v_mad_i64_i32 v[4:5], s[6:7], v144, s44, v[112:113]
	v_lshl_add_u64 v[4:5], v[4:5], 0, s[0:1]
	v_lshl_add_u64 v[4:5], v[4:5], 0, s[14:15]
	v_cvt_pk_bf16_f32 v1, v6, v7
	v_cvt_pk_bf16_f32 v2, v8, v9
	v_cvt_pk_bf16_f32 v3, v10, v11
	v_lshl_add_u64 v[4:5], v[4:5], 0, v[136:137]
	s_mov_b64 s[0:1], -1
	global_store_dwordx4 v[4:5], v[0:3], off
	s_cbranch_vccnz .LBB0_643
	s_andn2_b64 vcc, exec, s[8:9]
	s_cbranch_vccnz .LBB0_642
	s_barrier
	s_branch .LBB0_642

; #define PG8_STAGE(bufoff, gbase, voff) do { _Pragma("unroll") for (int _i = 0; _i < 2; ++_i) \
;     __builtin_amdgcn_global_load_lds((const unsigned*)((const char*)(gbase) + (voff)[_i]), (PG8_LAS unsigned*)(lds + (bufoff) + ldsw + _i * 8192), 16, 0, 0); } while (0)
; #define PG8_LDA(dst, b, h) do { _Pragma("unroll") for (int m = 0; m < 4; ++m) _Pragma("unroll") for (int k = 0; k < 2; ++k) dst[m][k] = *(const PG8_LAS bf16x8*)(lds + PG8_SA(b, h) + aoff + m * 2048 + k * 1024); } while (0)
; #define PG8_LDB(dst, b, h) do { _Pragma("unroll") for (int n = 0; n < 2; ++n) _Pragma("unroll") for (int k = 0; k < 2; ++k) dst[n][k] = *(const PG8_LAS bf16x8*)(lds + PG8_SB(b, h) + boff + n * 2048 + k * 1024); } while (0)
; #define PG8_MMA(ai, bj, At, Bt) do { __builtin_amdgcn_s_setprio(1); _Pragma("unroll") for (int m = 0; m < 4; ++m) _Pragma("unroll") for (int n = 0; n < 2; ++n) _Pragma("unroll") for (int k = 0; k < 2; ++k) \
;     acc[ai][bj][m][n] = __builtin_amdgcn_mfma_f32_16x16x32_bf16(Bt[n][k], At[m][k], acc[ai][bj][m][n], 0, 0, 0); __builtin_amdgcn_s_setprio(0); } while (0)
; #define PG8_WAIT_V(n) asm volatile("s_waitcnt vmcnt(" #n ")" ::: "memory")
; #define PG8_WAIT_L(n) asm volatile("s_waitcnt lgkmcnt(" #n ")" ::: "memory")
; #define PG8_BAR __builtin_amdgcn_s_barrier()
; #define PG8_SCHED __builtin_amdgcn_sched_barrier(0)
; template <class Epi, class Sched>
; DI void gemm_phase(PG8_LAS unsigned char* lds, const Gemm g, const Sched& S, const Epi& E) {
;     ...
;       const char* a1 = cA + (size_t)(t + 1) * kstep;
;       const char* a2 = last ? nA : cA + (size_t)(t + 2) * kstep; const char* b2 = last ? nB : cB + (size_t)(t + 2) * kstep;
;       const char* a3 = a2 + kstep; const char* b3 = b2 + kstep;
;       PG8_LDB(B0, 0, 0); PG8_LDB(B1, 0, 1); PG8_SCHED; PG8_LDA(At, 0, 0); PG8_STAGE(PG8_SA(1, 1), a1 + hstepA, voffA);
;       PG8_WAIT_V(8); PG8_WAIT_L(0); PG8_BAR; PG8_MMA(0, 0, At, B0); PG8_MMA(0, 1, At, B1); PG8_BAR; PG8_SCHED;
;       PG8_LDA(At, 0, 1); PG8_STAGE(PG8_SB(0, 0), b2, voffB); PG8_STAGE(PG8_SB(0, 1), b2 + hstepB, voffB); PG8_STAGE(PG8_SA(0, 0), a2, voffA);
;       PG8_WAIT_V(8); PG8_WAIT_L(0); PG8_BAR; PG8_MMA(1, 0, At, B0); PG8_MMA(1, 1, At, B1); PG8_BAR; PG8_SCHED;
;       PG8_LDB(B0, 1, 0); PG8_LDB(B1, 1, 1); PG8_SCHED; PG8_LDA(At, 1, 0); PG8_STAGE(PG8_SA(0, 1), a2 + hstepA, voffA);
.LBB0_721:
	ds_read_b128 v[128:131], v156
	ds_read_b128 v[132:135], v156 offset:1024
	ds_read_b128 v[150:153], v156 offset:2048
	ds_read_b128 v[162:165], v156 offset:3072
	ds_read_b128 v[166:169], v157
	ds_read_b128 v[170:173], v157 offset:1024
	ds_read_b128 v[174:177], v157 offset:2048
	ds_read_b128 v[178:181], v157 offset:3072
	s_add_u32 s26, s24, 0x100
	s_addc_u32 s27, s25, 0
	s_cmp_eq_u32 s65, 40
	s_cselect_b32 s31, s21, s27
	s_cselect_b32 s30, s20, s26
	s_cselect_b32 s29, s23, s64
	s_cselect_b32 s28, s22, s55
	v_lshl_add_u64 v[210:211], s[24:25], 0, v[146:147]
	s_add_i32 m0, s3, 0xc000
	ds_read_b128 v[182:185], v158
	ds_read_b128 v[186:189], v158 offset:1024
	ds_read_b128 v[190:193], v158 offset:2048
	ds_read_b128 v[194:197], v158 offset:3072
	ds_read_b128 v[198:201], v158 offset:4096
	ds_read_b128 v[202:205], v158 offset:5120
	ds_read_b128 v[206:209], v158 offset:6144
	ds_read_b128 v[214:217], v158 offset:7168
	global_load_lds_dwordx4 v[210:211], off
	v_lshl_add_u64 v[210:211], s[24:25], 0, v[148:149]
	s_add_i32 m0, s3, 0xe000
	s_nop 0
	global_load_lds_dwordx4 v[210:211], off
	s_waitcnt vmcnt(8)
	s_waitcnt lgkmcnt(0)
	s_barrier
	s_setprio 1
	s_waitcnt lgkmcnt(0)
	v_mfma_f32_16x16x32_bf16 v[124:127], v[128:131], v[182:185], v[124:127]
	v_mfma_f32_16x16x32_bf16 v[120:123], v[150:153], v[182:185], v[120:123]
	v_mfma_f32_16x16x32_bf16 v[108:111], v[128:131], v[190:193], v[108:111]
	v_mfma_f32_16x16x32_bf16 v[104:107], v[150:153], v[190:193], v[104:107]
	v_mfma_f32_16x16x32_bf16 v[92:95], v[128:131], v[198:201], v[92:95]
	v_mfma_f32_16x16x32_bf16 v[88:91], v[150:153], v[198:201], v[88:91]
	v_mfma_f32_16x16x32_bf16 v[76:79], v[128:131], v[206:209], v[76:79]
	v_mfma_f32_16x16x32_bf16 v[72:75], v[150:153], v[206:209], v[72:75]
	v_mfma_f32_16x16x32_bf16 v[124:127], v[132:135], v[186:189], v[124:127]
	v_mfma_f32_16x16x32_bf16 v[120:123], v[162:165], v[186:189], v[120:123]
	v_mfma_f32_16x16x32_bf16 v[108:111], v[132:135], v[194:197], v[108:111]
	v_mfma_f32_16x16x32_bf16 v[104:107], v[162:165], v[194:197], v[104:107]
	v_mfma_f32_16x16x32_bf16 v[92:95], v[132:135], v[202:205], v[92:95]
	v_mfma_f32_16x16x32_bf16 v[88:91], v[162:165], v[202:205], v[88:91]
	v_mfma_f32_16x16x32_bf16 v[76:79], v[132:135], v[214:217], v[76:79]
	v_mfma_f32_16x16x32_bf16 v[72:75], v[162:165], v[214:217], v[72:75]
	s_setprio 0
	s_setprio 1
	v_mfma_f32_16x16x32_bf16 v[116:119], v[166:169], v[182:185], v[116:119]
	v_mfma_f32_16x16x32_bf16 v[112:115], v[174:177], v[182:185], v[112:115]
	v_mfma_f32_16x16x32_bf16 v[100:103], v[166:169], v[190:193], v[100:103]
	v_mfma_f32_16x16x32_bf16 v[96:99], v[174:177], v[190:193], v[96:99]
	v_mfma_f32_16x16x32_bf16 v[84:87], v[166:169], v[198:201], v[84:87]
	v_mfma_f32_16x16x32_bf16 v[80:83], v[174:177], v[198:201], v[80:83]
	v_mfma_f32_16x16x32_bf16 v[68:71], v[166:169], v[206:209], v[68:71]
	v_mfma_f32_16x16x32_bf16 v[64:67], v[174:177], v[206:209], v[64:67]
	v_mfma_f32_16x16x32_bf16 v[116:119], v[170:173], v[186:189], v[116:119]
	v_mfma_f32_16x16x32_bf16 v[112:115], v[178:181], v[186:189], v[112:115]
	v_mfma_f32_16x16x32_bf16 v[100:103], v[170:173], v[194:197], v[100:103]
	v_mfma_f32_16x16x32_bf16 v[96:99], v[178:181], v[194:197], v[96:99]
	v_mfma_f32_16x16x32_bf16 v[84:87], v[170:173], v[202:205], v[84:87]
	v_mfma_f32_16x16x32_bf16 v[80:83], v[178:181], v[202:205], v[80:83]
	v_mfma_f32_16x16x32_bf16 v[68:71], v[170:173], v[214:217], v[68:71]
	v_mfma_f32_16x16x32_bf16 v[64:67], v[178:181], v[214:217], v[64:67]
	s_setprio 0
	s_barrier
	s_add_i32 s16, s37, s2
	v_lshl_add_u64 v[210:211], s[28:29], 0, v[138:139]
	s_mov_b32 m0, s16
	ds_read_b128 v[182:185], v158 offset:16384
	ds_read_b128 v[186:189], v158 offset:17408
	ds_read_b128 v[190:193], v158 offset:18432
	ds_read_b128 v[194:197], v158 offset:19456
	ds_read_b128 v[198:201], v158 offset:20480
	ds_read_b128 v[202:205], v158 offset:21504
	ds_read_b128 v[206:209], v158 offset:22528
	ds_read_b128 v[214:217], v158 offset:23552
	global_load_lds_dwordx4 v[210:211], off
	s_add_i32 m0, s16, 0x2000
	s_add_u32 s16, s28, 0xb0000
	v_lshl_add_u64 v[218:219], s[28:29], 0, v[142:143]
	s_addc_u32 s17, s29, 0
	s_add_i32 s24, s38, s2
	global_load_lds_dwordx4 v[218:219], off
	v_lshl_add_u64 v[220:221], s[16:17], 0, v[138:139]
	s_mov_b32 m0, s24
	v_lshl_add_u64 v[222:223], s[30:31], 0, v[140:141]
	global_load_lds_dwordx4 v[220:221], off
	v_lshl_add_u64 v[220:221], s[16:17], 0, v[142:143]
	s_add_i32 m0, s24, 0x2000
	s_nop 0
	global_load_lds_dwordx4 v[220:221], off
	v_lshl_add_u64 v[220:221], s[30:31], 0, v[136:137]
	s_mov_b32 m0, s3
	s_nop 0
	global_load_lds_dwordx4 v[220:221], off
	s_mov_b32 m0, s34
	s_nop 0
	global_load_lds_dwordx4 v[222:223], off
	s_waitcnt vmcnt(8)
	s_waitcnt lgkmcnt(0)
	s_barrier
; #define PG8_STAGE(bufoff, gbase, voff) do { _Pragma("unroll") for (int _i = 0; _i < 2; ++_i) \
;     __builtin_amdgcn_global_load_lds((const unsigned*)((const char*)(gbase) + (voff)[_i]), (PG8_LAS unsigned*)(lds + (bufoff) + ldsw + _i * 8192), 16, 0, 0); } while (0)
; #define PG8_LDA(dst, b, h) do { _Pragma("unroll") for (int m = 0; m < 4; ++m) _Pragma("unroll") for (int k = 0; k < 2; ++k) dst[m][k] = *(const PG8_LAS bf16x8*)(lds + PG8_SA(b, h) + aoff + m * 2048 + k * 1024); } while (0)
; #define PG8_LDB(dst, b, h) do { _Pragma("unroll") for (int n = 0; n < 2; ++n) _Pragma("unroll") for (int k = 0; k < 2; ++k) dst[n][k] = *(const PG8_LAS bf16x8*)(lds + PG8_SB(b, h) + boff + n * 2048 + k * 1024); } while (0)
; #define PG8_MMA(ai, bj, At, Bt) do { __builtin_amdgcn_s_setprio(1); _Pragma("unroll") for (int m = 0; m < 4; ++m) _Pragma("unroll") for (int n = 0; n < 2; ++n) _Pragma("unroll") for (int k = 0; k < 2; ++k) \
;     acc[ai][bj][m][n] = __builtin_amdgcn_mfma_f32_16x16x32_bf16(Bt[n][k], At[m][k], acc[ai][bj][m][n], 0, 0, 0); __builtin_amdgcn_s_setprio(0); } while (0)
; #define PG8_WAIT_V(n) asm volatile("s_waitcnt vmcnt(" #n ")" ::: "memory")
; #define PG8_WAIT_L(n) asm volatile("s_waitcnt lgkmcnt(" #n ")" ::: "memory")
; #define PG8_BAR __builtin_amdgcn_s_barrier()
; #define PG8_SCHED __builtin_amdgcn_sched_barrier(0)
; template <class Epi, class Sched>
; DI void gemm_phase(PG8_LAS unsigned char* lds, const Gemm g, const Sched& S, const Epi& E) {
;     ...
;       PG8_WAIT_V(8); PG8_WAIT_L(0); PG8_BAR; PG8_MMA(1, 0, At, B0); PG8_MMA(1, 1, At, B1); PG8_BAR; PG8_SCHED;
;       PG8_LDB(B0, 1, 0); PG8_LDB(B1, 1, 1); PG8_SCHED; PG8_LDA(At, 1, 0); PG8_STAGE(PG8_SA(0, 1), a2 + hstepA, voffA);
;       PG8_WAIT_V(8); PG8_WAIT_L(0); PG8_BAR; PG8_MMA(0, 0, At, B0); PG8_MMA(0, 1, At, B1); PG8_BAR; PG8_SCHED;
;       PG8_LDA(At, 1, 1); PG8_STAGE(PG8_SB(1, 0), b3, voffB); PG8_STAGE(PG8_SB(1, 1), b3 + hstepB, voffB); PG8_STAGE(PG8_SA(1, 0), a3, voffA);
	s_setprio 1
	s_waitcnt lgkmcnt(0)
	v_mfma_f32_16x16x32_bf16 v[60:63], v[128:131], v[182:185], v[60:63]
	v_mfma_f32_16x16x32_bf16 v[56:59], v[150:153], v[182:185], v[56:59]
	v_mfma_f32_16x16x32_bf16 v[44:47], v[128:131], v[190:193], v[44:47]
	v_mfma_f32_16x16x32_bf16 v[40:43], v[150:153], v[190:193], v[40:43]
	v_mfma_f32_16x16x32_bf16 v[28:31], v[128:131], v[198:201], v[28:31]
	v_mfma_f32_16x16x32_bf16 v[24:27], v[150:153], v[198:201], v[24:27]
	v_mfma_f32_16x16x32_bf16 v[12:15], v[128:131], v[206:209], v[12:15]
	v_mfma_f32_16x16x32_bf16 v[8:11], v[150:153], v[206:209], v[8:11]
	v_mfma_f32_16x16x32_bf16 v[60:63], v[132:135], v[186:189], v[60:63]
	v_mfma_f32_16x16x32_bf16 v[56:59], v[162:165], v[186:189], v[56:59]
	v_mfma_f32_16x16x32_bf16 v[44:47], v[132:135], v[194:197], v[44:47]
	v_mfma_f32_16x16x32_bf16 v[40:43], v[162:165], v[194:197], v[40:43]
	v_mfma_f32_16x16x32_bf16 v[28:31], v[132:135], v[202:205], v[28:31]
	v_mfma_f32_16x16x32_bf16 v[24:27], v[162:165], v[202:205], v[24:27]
	v_mfma_f32_16x16x32_bf16 v[12:15], v[132:135], v[214:217], v[12:15]
	v_mfma_f32_16x16x32_bf16 v[8:11], v[162:165], v[214:217], v[8:11]
	s_setprio 0
	s_setprio 1
	v_mfma_f32_16x16x32_bf16 v[52:55], v[166:169], v[182:185], v[52:55]
	v_mfma_f32_16x16x32_bf16 v[48:51], v[174:177], v[182:185], v[48:51]
	v_mfma_f32_16x16x32_bf16 v[36:39], v[166:169], v[190:193], v[36:39]
	v_mfma_f32_16x16x32_bf16 v[32:35], v[174:177], v[190:193], v[32:35]
	v_mfma_f32_16x16x32_bf16 v[20:23], v[166:169], v[198:201], v[20:23]
	v_mfma_f32_16x16x32_bf16 v[16:19], v[174:177], v[198:201], v[16:19]
	v_mfma_f32_16x16x32_bf16 v[4:7], v[166:169], v[206:209], v[4:7]
	v_mfma_f32_16x16x32_bf16 v[0:3], v[174:177], v[206:209], v[0:3]
	v_mfma_f32_16x16x32_bf16 v[52:55], v[170:173], v[186:189], v[52:55]
	v_mfma_f32_16x16x32_bf16 v[48:51], v[178:181], v[186:189], v[48:51]
	v_mfma_f32_16x16x32_bf16 v[36:39], v[170:173], v[194:197], v[36:39]
	v_mfma_f32_16x16x32_bf16 v[32:35], v[178:181], v[194:197], v[32:35]
	v_mfma_f32_16x16x32_bf16 v[20:23], v[170:173], v[202:205], v[20:23]
	v_mfma_f32_16x16x32_bf16 v[16:19], v[178:181], v[202:205], v[16:19]
	v_mfma_f32_16x16x32_bf16 v[4:7], v[170:173], v[214:217], v[4:7]
	v_mfma_f32_16x16x32_bf16 v[0:3], v[178:181], v[214:217], v[0:3]
	s_setprio 0
	s_barrier
	s_mov_b32 s16, 0x18000
	s_add_i32 s24, s16, 0x110
	v_add_u32_e32 v161, s24, v155
	ds_read_b128 v[128:131], v161
	ds_read_b128 v[132:135], v161 offset:1024
	ds_read_b128 v[150:153], v161 offset:2048
	ds_read_b128 v[162:165], v161 offset:3072
	ds_read_b128 v[166:169], v160
	ds_read_b128 v[170:173], v160 offset:1024
	ds_read_b128 v[174:177], v160 offset:2048
	ds_read_b128 v[178:181], v160 offset:3072
	s_add_u32 s16, s30, 0xb0000
	s_addc_u32 s17, s31, 0
	s_mov_b32 m0, s18
	v_lshl_add_u64 v[224:225], s[16:17], 0, v[136:137]
	ds_read_b128 v[182:185], v158 offset:32768
	ds_read_b128 v[186:189], v158 offset:33792
	ds_read_b128 v[190:193], v158 offset:34816
	ds_read_b128 v[194:197], v158 offset:35840
	ds_read_b128 v[198:201], v158 offset:36864
	ds_read_b128 v[202:205], v158 offset:37888
	ds_read_b128 v[206:209], v158 offset:38912
	ds_read_b128 v[214:217], v158 offset:39936
	global_load_lds_dwordx4 v[224:225], off
	v_lshl_add_u64 v[224:225], s[16:17], 0, v[140:141]
	s_mov_b32 m0, s19
	s_nop 0
	global_load_lds_dwordx4 v[224:225], off
	s_waitcnt vmcnt(8)
	s_waitcnt lgkmcnt(0)
	s_barrier
	s_setprio 1
	s_waitcnt lgkmcnt(0)
	v_mfma_f32_16x16x32_bf16 v[124:127], v[128:131], v[182:185], v[124:127]
	v_mfma_f32_16x16x32_bf16 v[120:123], v[150:153], v[182:185], v[120:123]
	v_mfma_f32_16x16x32_bf16 v[108:111], v[128:131], v[190:193], v[108:111]
	v_mfma_f32_16x16x32_bf16 v[104:107], v[150:153], v[190:193], v[104:107]
	v_mfma_f32_16x16x32_bf16 v[92:95], v[128:131], v[198:201], v[92:95]
	v_mfma_f32_16x16x32_bf16 v[88:91], v[150:153], v[198:201], v[88:91]
	v_mfma_f32_16x16x32_bf16 v[76:79], v[128:131], v[206:209], v[76:79]
	v_mfma_f32_16x16x32_bf16 v[72:75], v[150:153], v[206:209], v[72:75]
	v_mfma_f32_16x16x32_bf16 v[124:127], v[132:135], v[186:189], v[124:127]
	v_mfma_f32_16x16x32_bf16 v[120:123], v[162:165], v[186:189], v[120:123]
	v_mfma_f32_16x16x32_bf16 v[108:111], v[132:135], v[194:197], v[108:111]
	v_mfma_f32_16x16x32_bf16 v[104:107], v[162:165], v[194:197], v[104:107]
	v_mfma_f32_16x16x32_bf16 v[92:95], v[132:135], v[202:205], v[92:95]
	v_mfma_f32_16x16x32_bf16 v[88:91], v[162:165], v[202:205], v[88:91]
	v_mfma_f32_16x16x32_bf16 v[76:79], v[132:135], v[214:217], v[76:79]
	v_mfma_f32_16x16x32_bf16 v[72:75], v[162:165], v[214:217], v[72:75]
	s_setprio 0
	s_setprio 1
	v_mfma_f32_16x16x32_bf16 v[116:119], v[166:169], v[182:185], v[116:119]
	v_mfma_f32_16x16x32_bf16 v[112:115], v[174:177], v[182:185], v[112:115]
	v_mfma_f32_16x16x32_bf16 v[100:103], v[166:169], v[190:193], v[100:103]
	v_mfma_f32_16x16x32_bf16 v[96:99], v[174:177], v[190:193], v[96:99]
	v_mfma_f32_16x16x32_bf16 v[84:87], v[166:169], v[198:201], v[84:87]
	v_mfma_f32_16x16x32_bf16 v[80:83], v[174:177], v[198:201], v[80:83]
	v_mfma_f32_16x16x32_bf16 v[68:71], v[166:169], v[206:209], v[68:71]
	v_mfma_f32_16x16x32_bf16 v[64:67], v[174:177], v[206:209], v[64:67]
	v_mfma_f32_16x16x32_bf16 v[116:119], v[170:173], v[186:189], v[116:119]
	v_mfma_f32_16x16x32_bf16 v[112:115], v[178:181], v[186:189], v[112:115]
	v_mfma_f32_16x16x32_bf16 v[100:103], v[170:173], v[194:197], v[100:103]
	v_mfma_f32_16x16x32_bf16 v[96:99], v[178:181], v[194:197], v[96:99]
	v_mfma_f32_16x16x32_bf16 v[84:87], v[170:173], v[202:205], v[84:87]
	v_mfma_f32_16x16x32_bf16 v[80:83], v[178:181], v[202:205], v[80:83]
	v_mfma_f32_16x16x32_bf16 v[68:71], v[170:173], v[214:217], v[68:71]
	v_mfma_f32_16x16x32_bf16 v[64:67], v[178:181], v[214:217], v[64:67]
	s_setprio 0
	s_barrier
; #define PG8_STAGE(bufoff, gbase, voff) do { _Pragma("unroll") for (int _i = 0; _i < 2; ++_i) \
;     __builtin_amdgcn_global_load_lds((const unsigned*)((const char*)(gbase) + (voff)[_i]), (PG8_LAS unsigned*)(lds + (bufoff) + ldsw + _i * 8192), 16, 0, 0); } while (0)
; #define PG8_LDA(dst, b, h) do { _Pragma("unroll") for (int m = 0; m < 4; ++m) _Pragma("unroll") for (int k = 0; k < 2; ++k) dst[m][k] = *(const PG8_LAS bf16x8*)(lds + PG8_SA(b, h) + aoff + m * 2048 + k * 1024); } while (0)
; #define PG8_MMA(ai, bj, At, Bt) do { __builtin_amdgcn_s_setprio(1); _Pragma("unroll") for (int m = 0; m < 4; ++m) _Pragma("unroll") for (int n = 0; n < 2; ++n) _Pragma("unroll") for (int k = 0; k < 2; ++k) \
;     acc[ai][bj][m][n] = __builtin_amdgcn_mfma_f32_16x16x32_bf16(Bt[n][k], At[m][k], acc[ai][bj][m][n], 0, 0, 0); __builtin_amdgcn_s_setprio(0); } while (0)
; #define PG8_WAIT_V(n) asm volatile("s_waitcnt vmcnt(" #n ")" ::: "memory")
; #define PG8_WAIT_L(n) asm volatile("s_waitcnt lgkmcnt(" #n ")" ::: "memory")
; #define PG8_BAR __builtin_amdgcn_s_barrier()
; #define PG8_SCHED __builtin_amdgcn_sched_barrier(0)
;   DI void operator()(const f32x4 (&acc)[2][2][4][2], const Unit& u, int wr, int wc, int fr, int fq) const {
;     ...
;     RES_LD(0)
; #pragma unroll
;     for (int i = 0; i < 8; ++i) {
;       const int ai = i >> 2, m = i & 3;
;       if (i + 1 < 8) RES_LD(i + 1)
; template <class Epi, class Sched>
; DI void gemm_phase(PG8_LAS unsigned char* lds, const Gemm g, const Sched& S, const Epi& E) {
;     ...
;       PG8_LDA(At, 1, 1); PG8_STAGE(PG8_SB(1, 0), b3, voffB); PG8_STAGE(PG8_SB(1, 1), b3 + hstepB, voffB); PG8_STAGE(PG8_SA(1, 0), a3, voffA);
;       PG8_WAIT_V(8); PG8_WAIT_L(0); PG8_BAR; PG8_MMA(1, 0, At, B0); PG8_MMA(1, 1, At, B1); PG8_BAR; PG8_SCHED;
;     }
;     if (wr == 0) PG8_BAR;
	s_add_i32 s16, s24, s2
	v_lshl_add_u64 v[210:211], v[210:211], 0, s[10:11]
	s_mov_b32 m0, s16
	ds_read_b128 v[182:185], v158 offset:49152
	ds_read_b128 v[186:189], v158 offset:50176
	ds_read_b128 v[190:193], v158 offset:51200
	ds_read_b128 v[194:197], v158 offset:52224
	ds_read_b128 v[198:201], v158 offset:53248
	ds_read_b128 v[202:205], v158 offset:54272
	ds_read_b128 v[206:209], v158 offset:55296
	ds_read_b128 v[214:217], v158 offset:56320
	global_load_lds_dwordx4 v[210:211], off
	s_add_i32 m0, s16, 0x2000
	s_add_u32 s16, s28, 0xb0080
	v_lshl_add_u64 v[210:211], v[218:219], 0, s[10:11]
	s_addc_u32 s17, s29, 0
	s_add_i32 s24, s39, s2
	global_load_lds_dwordx4 v[210:211], off
	v_lshl_add_u64 v[210:211], s[16:17], 0, v[138:139]
	s_mov_b32 m0, s24
	s_nop 0
	global_load_lds_dwordx4 v[210:211], off
	v_lshl_add_u64 v[210:211], s[16:17], 0, v[142:143]
	s_add_i32 m0, s24, 0x2000
	s_nop 0
	global_load_lds_dwordx4 v[210:211], off
	v_lshl_add_u64 v[210:211], v[220:221], 0, s[10:11]
	s_mov_b32 m0, s5
	s_nop 0
	global_load_lds_dwordx4 v[210:211], off
	v_lshl_add_u64 v[210:211], v[222:223], 0, s[10:11]
	s_mov_b32 m0, s35
	s_nop 0
	global_load_lds_dwordx4 v[210:211], off
	s_waitcnt vmcnt(8)
	s_waitcnt lgkmcnt(0)
	s_barrier
	s_setprio 1
	s_waitcnt lgkmcnt(0)
	v_mfma_f32_16x16x32_bf16 v[60:63], v[128:131], v[182:185], v[60:63]
	v_mfma_f32_16x16x32_bf16 v[56:59], v[150:153], v[182:185], v[56:59]
	v_mfma_f32_16x16x32_bf16 v[44:47], v[128:131], v[190:193], v[44:47]
	v_mfma_f32_16x16x32_bf16 v[40:43], v[150:153], v[190:193], v[40:43]
	v_mfma_f32_16x16x32_bf16 v[28:31], v[128:131], v[198:201], v[28:31]
	v_mfma_f32_16x16x32_bf16 v[24:27], v[150:153], v[198:201], v[24:27]
	v_mfma_f32_16x16x32_bf16 v[12:15], v[128:131], v[206:209], v[12:15]
	v_mfma_f32_16x16x32_bf16 v[8:11], v[150:153], v[206:209], v[8:11]
	v_mfma_f32_16x16x32_bf16 v[60:63], v[132:135], v[186:189], v[60:63]
	v_mfma_f32_16x16x32_bf16 v[56:59], v[162:165], v[186:189], v[56:59]
	v_mfma_f32_16x16x32_bf16 v[44:47], v[132:135], v[194:197], v[44:47]
	v_mfma_f32_16x16x32_bf16 v[40:43], v[162:165], v[194:197], v[40:43]
	v_mfma_f32_16x16x32_bf16 v[28:31], v[132:135], v[202:205], v[28:31]
	v_mfma_f32_16x16x32_bf16 v[24:27], v[162:165], v[202:205], v[24:27]
	v_mfma_f32_16x16x32_bf16 v[12:15], v[132:135], v[214:217], v[12:15]
	v_mfma_f32_16x16x32_bf16 v[8:11], v[162:165], v[214:217], v[8:11]
	s_setprio 0
	s_setprio 1
	v_mfma_f32_16x16x32_bf16 v[52:55], v[166:169], v[182:185], v[52:55]
	v_mfma_f32_16x16x32_bf16 v[48:51], v[174:177], v[182:185], v[48:51]
	v_mfma_f32_16x16x32_bf16 v[36:39], v[166:169], v[190:193], v[36:39]
	v_mfma_f32_16x16x32_bf16 v[32:35], v[174:177], v[190:193], v[32:35]
	v_mfma_f32_16x16x32_bf16 v[20:23], v[166:169], v[198:201], v[20:23]
	v_mfma_f32_16x16x32_bf16 v[16:19], v[174:177], v[198:201], v[16:19]
	v_mfma_f32_16x16x32_bf16 v[4:7], v[166:169], v[206:209], v[4:7]
	v_mfma_f32_16x16x32_bf16 v[0:3], v[174:177], v[206:209], v[0:3]
	v_mfma_f32_16x16x32_bf16 v[52:55], v[170:173], v[186:189], v[52:55]
	v_mfma_f32_16x16x32_bf16 v[48:51], v[178:181], v[186:189], v[48:51]
	v_mfma_f32_16x16x32_bf16 v[36:39], v[170:173], v[194:197], v[36:39]
	v_mfma_f32_16x16x32_bf16 v[32:35], v[178:181], v[194:197], v[32:35]
	v_mfma_f32_16x16x32_bf16 v[20:23], v[170:173], v[202:205], v[20:23]
	v_mfma_f32_16x16x32_bf16 v[16:19], v[178:181], v[202:205], v[16:19]
	v_mfma_f32_16x16x32_bf16 v[4:7], v[170:173], v[214:217], v[4:7]
	v_mfma_f32_16x16x32_bf16 v[0:3], v[178:181], v[214:217], v[0:3]
	s_setprio 0
	s_barrier
	s_add_i32 s65, s65, 2
	s_add_u32 s55, s55, 0x100
	s_addc_u32 s64, s64, 0
	s_cmp_gt_u32 s65, 41
	s_mov_b64 s[24:25], s[26:27]
	s_cbranch_scc0 .LBB0_721
	v_lshl_add_u32 v152, s53, 8, v154
	v_ashrrev_i32_e32 v153, 31, v152
	s_lshl_b32 s16, s45, 8
	v_lshlrev_b64 v[128:129], 11, v[152:153]
	s_ashr_i32 s17, s16, 31
	v_lshl_add_u64 v[128:129], s[50:51], 0, v[128:129]
	v_lshl_add_u64 v[128:129], s[16:17], 1, v[128:129]
	v_lshl_add_u64 v[128:129], v[128:129], 0, s[14:15]
	v_lshl_add_u64 v[150:151], v[128:129], 0, v[144:145]
	s_mov_b32 s16, 0x8000
	v_add_co_u32_e32 v128, vcc, s16, v150
	global_load_dwordx4 v[164:167], v[150:151], off
	global_load_dwordx4 v[168:171], v[150:151], off offset:256
	v_addc_co_u32_e32 v129, vcc, 0, v151, vcc
	global_load_dwordx4 v[132:135], v[128:129], off
	s_nop 0
	global_load_dwordx4 v[128:131], v[128:129], off offset:256
	s_and_b64 vcc, exec, s[12:13]
	s_cbranch_vccz .LBB0_724
	s_barrier
; DI unsigned pack2(float a, float b) { bf2_t v = __builtin_convertvector((f32x2){a, b}, bf2_t); return __builtin_bit_cast(unsigned, v); }
;   DI void operator()(const f32x4 (&acc)[2][2][4][2], const Unit& u, int wr, int wc, int fr, int fq) const {
;     ...
;     for (int i = 0; i < 8; ++i) {
;       const int ai = i >> 2, m = i & 3;
;       if (i + 1 < 8) RES_LD(i + 1)
;       __builtin_amdgcn_sched_barrier(0);
;       const size_t idx = base + (size_t)(ai * HALF + m * 16) * DM;
;       float ssum = 0.f;
; #pragma unroll
;       for (int bj = 0; bj < 2; ++bj) {
;         f32x4 x0, x1;
;         if (FIRST) { x0 = xv[i & 1][2 * bj]; x1 = xv[i & 1][2 * bj + 1]; }
;         else {
;           const u32x4 hw = xh[i & 1][bj];
;           x0 = (f32x4){__uint_as_float(hw.x << 16), __uint_as_float(hw.x & 0xffff0000u), __uint_as_float(hw.y << 16), __uint_as_float(hw.y & 0xffff0000u)};
;           x1 = (f32x4){__uint_as_float(hw.z << 16), __uint_as_float(hw.z & 0xffff0000u), __uint_as_float(hw.w << 16), __uint_as_float(hw.w & 0xffff0000u)};
;         }
;         const f32x4 v0 = x0 + acc[ai][bj][m][0], v1 = x1 + acc[ai][bj][m][1];
;         if (LAST) { *(f32x4*)(xout32 + idx + bj * HALF) = v0; *(f32x4*)(xout32 + idx + bj * HALF + 4) = v1; }
;         else {
;           ssum += (v0[0] * v0[0] + v0[1] * v0[1]) + (v0[2] * v0[2] + v0[3] * v0[3]) + (v1[0] * v1[0] + v1[1] * v1[1]) + (v1[2] * v1[2] + v1[3] * v1[3]);
;           u32x4 w; w.x = pack2(v0[0], v0[1]); w.y = pack2(v0[2], v0[3]); w.z = pack2(v1[0], v1[1]); w.w = pack2(v1[2], v1[3]);
;           *(u32x4*)(xb + idx + bj * HALF) = w;
;         }
;       }
;       if (!LAST) {
;         ssum += __shfl_xor(ssum, 16); ssum += __shfl_xor(ssum, 32);
;         if (fq == 0) ps_out[(size_t)(row0 + ai * HALF + m * 16) * 16 + u.pn * 4 + wc] = ssum;
.LBB0_724:
	v_and_b32_e32 v162, 64, v159
	v_xor_b32_e32 v161, 16, v159
	v_add_u32_e32 v163, 64, v162
	v_cmp_lt_i32_e32 vcc, v161, v163
	s_lshl_b32 s24, s45, 2
	s_ashr_i32 s25, s24, 31
	v_cndmask_b32_e32 v161, v159, v161, vcc
	v_lshlrev_b32_e32 v162, 2, v161
	v_xor_b32_e32 v161, 32, v159
	v_cmp_lt_i32_e32 vcc, v161, v163
	s_nop 1
	v_cndmask_b32_e32 v161, v159, v161, vcc
	v_lshlrev_b32_e32 v161, 2, v161
	s_waitcnt vmcnt(0)
	v_lshlrev_b32_e32 v172, 16, v164
	v_and_b32_e32 v173, 0xffff0000, v164
	v_lshlrev_b32_e32 v164, 16, v165
	v_and_b32_e32 v165, 0xffff0000, v165
	v_lshlrev_b32_e32 v174, 16, v166
	v_and_b32_e32 v175, 0xffff0000, v166
	v_lshlrev_b32_e32 v166, 16, v167
	v_and_b32_e32 v167, 0xffff0000, v167
	v_pk_add_f32 v[126:127], v[126:127], v[164:165]
	v_pk_add_f32 v[124:125], v[124:125], v[172:173]
	v_pk_add_f32 v[164:165], v[122:123], v[166:167]
	v_pk_add_f32 v[122:123], v[120:121], v[174:175]
	v_mul_f32_e32 v120, v125, v125
	v_mul_f32_e32 v121, v127, v127
	v_fmac_f32_e32 v120, v124, v124
	v_fmac_f32_e32 v121, v126, v126
	v_add_f32_e32 v120, v120, v121
	v_mul_f32_e32 v121, v123, v123
	v_fmac_f32_e32 v121, v122, v122
	v_add_f32_e32 v120, v121, v120
	v_mul_f32_e32 v121, v165, v165
	v_fmac_f32_e32 v121, v164, v164
	v_add_f32_e32 v163, v121, v120
	v_cvt_pk_bf16_f32 v120, v124, v125
	v_cvt_pk_bf16_f32 v121, v126, v127
	v_lshlrev_b32_e32 v124, 16, v168
	v_and_b32_e32 v125, 0xffff0000, v168
	v_lshlrev_b32_e32 v126, 16, v169
	v_and_b32_e32 v127, 0xffff0000, v169
	v_lshlrev_b32_e32 v166, 16, v171
	v_and_b32_e32 v167, 0xffff0000, v171
	v_pk_add_f32 v[118:119], v[118:119], v[126:127]
	v_pk_add_f32 v[116:117], v[116:117], v[124:125]
	v_cvt_pk_bf16_f32 v122, v122, v123
	v_cvt_pk_bf16_f32 v123, v164, v165
	v_lshlrev_b32_e32 v164, 16, v170
	v_and_b32_e32 v165, 0xffff0000, v170
	v_pk_add_f32 v[124:125], v[114:115], v[166:167]
	v_mul_f32_e32 v114, v117, v117
	v_mul_f32_e32 v115, v119, v119
	v_pk_add_f32 v[112:113], v[112:113], v[164:165]
	v_fmac_f32_e32 v114, v116, v116
	v_fmac_f32_e32 v115, v118, v118
	v_add_f32_e32 v114, v114, v115
	v_mul_f32_e32 v115, v113, v113
	v_fmac_f32_e32 v115, v112, v112
	v_add_f32_e32 v114, v115, v114
	v_mul_f32_e32 v115, v125, v125
	v_fmac_f32_e32 v115, v124, v124
	v_add_f32_e32 v114, v115, v114
	v_add_f32_e32 v126, v163, v114
	ds_bpermute_b32 v127, v162, v126
	v_cvt_pk_bf16_f32 v114, v116, v117
	v_cvt_pk_bf16_f32 v116, v112, v113
	v_cvt_pk_bf16_f32 v115, v118, v119
	v_cvt_pk_bf16_f32 v117, v124, v125
	s_waitcnt lgkmcnt(0)
	v_add_f32_e32 v112, v126, v127
	ds_bpermute_b32 v113, v161, v112
	global_store_dwordx4 v[150:151], v[114:117], off offset:256
	global_store_dwordx4 v[150:151], v[120:123], off
	s_nop 0
	v_lshlrev_b64 v[114:115], 6, v[152:153]
	v_lshl_add_u64 v[120:121], s[96:97], 0, v[114:115]
	s_and_saveexec_b64 s[26:27], s[6:7]
	s_cbranch_execz .LBB0_726
	s_waitcnt lgkmcnt(0)
	v_add_f32_e32 v114, v112, v113
	v_lshl_add_u64 v[112:113], s[24:25], 2, v[120:121]
	s_lshl_b32 s16, s4, 2
	s_mov_b32 s17, s15
	v_lshl_add_u64 v[112:113], v[112:113], 0, s[16:17]
	global_store_dword v[112:113], v114, off

; #define PG8_STAGE(bufoff, gbase, voff) do { _Pragma("unroll") for (int _i = 0; _i < 2; ++_i) \
;     __builtin_amdgcn_global_load_lds((const unsigned*)((const char*)(gbase) + (voff)[_i]), (PG8_LAS unsigned*)(lds + (bufoff) + ldsw + _i * 8192), 16, 0, 0); } while (0)
; #define PG8_LDA(dst, b, h) do { _Pragma("unroll") for (int m = 0; m < 4; ++m) _Pragma("unroll") for (int k = 0; k < 2; ++k) dst[m][k] = *(const PG8_LAS bf16x8*)(lds + PG8_SA(b, h) + aoff + m * 2048 + k * 1024); } while (0)
; #define PG8_LDB(dst, b, h) do { _Pragma("unroll") for (int n = 0; n < 2; ++n) _Pragma("unroll") for (int k = 0; k < 2; ++k) dst[n][k] = *(const PG8_LAS bf16x8*)(lds + PG8_SB(b, h) + boff + n * 2048 + k * 1024); } while (0)
; #define PG8_MMA(ai, bj, At, Bt) do { __builtin_amdgcn_s_setprio(1); _Pragma("unroll") for (int m = 0; m < 4; ++m) _Pragma("unroll") for (int n = 0; n < 2; ++n) _Pragma("unroll") for (int k = 0; k < 2; ++k) \
;     acc[ai][bj][m][n] = __builtin_amdgcn_mfma_f32_16x16x32_bf16(Bt[n][k], At[m][k], acc[ai][bj][m][n], 0, 0, 0); __builtin_amdgcn_s_setprio(0); } while (0)
; #define PG8_WAIT_V(n) asm volatile("s_waitcnt vmcnt(" #n ")" ::: "memory")
; #define PG8_WAIT_L(n) asm volatile("s_waitcnt lgkmcnt(" #n ")" ::: "memory")
; #define PG8_BAR __builtin_amdgcn_s_barrier()
; #define PG8_SCHED __builtin_amdgcn_sched_barrier(0)
; template <class Epi, class Sched>
; DI void gemm_phase(PG8_LAS unsigned char* lds, const Gemm g, const Sched& S, const Epi& E) {
;     ...
;       const char* a1 = cA + (size_t)(t + 1) * kstep;
;       const char* a2 = last ? nA : cA + (size_t)(t + 2) * kstep; const char* b2 = last ? nB : cB + (size_t)(t + 2) * kstep;
;       const char* a3 = a2 + kstep; const char* b3 = b2 + kstep;
;       PG8_LDB(B0, 0, 0); PG8_LDB(B1, 0, 1); PG8_SCHED; PG8_LDA(At, 0, 0); PG8_STAGE(PG8_SA(1, 1), a1 + hstepA, voffA);
;       PG8_WAIT_V(8); PG8_WAIT_L(0); PG8_BAR; PG8_MMA(0, 0, At, B0); PG8_MMA(0, 1, At, B1); PG8_BAR; PG8_SCHED;
;       PG8_LDA(At, 0, 1); PG8_STAGE(PG8_SB(0, 0), b2, voffB); PG8_STAGE(PG8_SB(0, 1), b2 + hstepB, voffB); PG8_STAGE(PG8_SA(0, 0), a2, voffA);
;       PG8_WAIT_V(8); PG8_WAIT_L(0); PG8_BAR; PG8_MMA(1, 0, At, B0); PG8_MMA(1, 1, At, B1); PG8_BAR; PG8_SCHED;
;       PG8_LDB(B0, 1, 0); PG8_LDB(B1, 1, 1); PG8_SCHED; PG8_LDA(At, 1, 0); PG8_STAGE(PG8_SA(0, 1), a2 + hstepA, voffA);
.LBB0_807:
	ds_read_b128 v[144:147], v195
	ds_read_b128 v[148:151], v195 offset:1024
	ds_read_b128 v[152:155], v195 offset:2048
	ds_read_b128 v[156:159], v195 offset:3072
	ds_read_b128 v[160:163], v196
	ds_read_b128 v[164:167], v196 offset:1024
	ds_read_b128 v[168:171], v196 offset:2048
	ds_read_b128 v[172:175], v196 offset:3072
	s_add_u32 s16, s10, 0xfffc0080
	s_addc_u32 s17, s11, -1
	s_cmp_eq_u32 s73, 12
	s_cselect_b32 s45, s1, s17
	s_cselect_b32 s44, s9, s16
	s_cselect_b32 s41, s22, s72
	s_cselect_b32 s40, s29, s31
	v_lshl_add_u64 v[192:193], s[10:11], 0, v[138:139]
	s_add_i32 m0, s3, 0xc000
	ds_read_b128 v[176:179], v197
	ds_read_b128 v[180:183], v197 offset:1024
	ds_read_b128 v[184:187], v197 offset:2048
	ds_read_b128 v[188:191], v197 offset:3072
	ds_read_b128 v[202:205], v197 offset:4096
	ds_read_b128 v[206:209], v197 offset:5120
	ds_read_b128 v[214:217], v197 offset:6144
	ds_read_b128 v[218:221], v197 offset:7168
	global_load_lds_dwordx4 v[192:193], off
	v_lshl_add_u64 v[192:193], s[10:11], 0, v[140:141]
	s_add_i32 m0, s3, 0xe000
	s_nop 0
	global_load_lds_dwordx4 v[192:193], off
	s_waitcnt vmcnt(8)
	s_waitcnt lgkmcnt(0)
	s_barrier
	s_setprio 1
	s_waitcnt lgkmcnt(0)
	v_mfma_f32_16x16x32_bf16 v[124:127], v[144:147], v[176:179], v[124:127]
	v_mfma_f32_16x16x32_bf16 v[120:123], v[152:155], v[176:179], v[120:123]
	v_mfma_f32_16x16x32_bf16 v[108:111], v[144:147], v[184:187], v[108:111]
	v_mfma_f32_16x16x32_bf16 v[104:107], v[152:155], v[184:187], v[104:107]
	v_mfma_f32_16x16x32_bf16 v[92:95], v[144:147], v[202:205], v[92:95]
	v_mfma_f32_16x16x32_bf16 v[88:91], v[152:155], v[202:205], v[88:91]
	v_mfma_f32_16x16x32_bf16 v[76:79], v[144:147], v[214:217], v[76:79]
	v_mfma_f32_16x16x32_bf16 v[72:75], v[152:155], v[214:217], v[72:75]
	v_mfma_f32_16x16x32_bf16 v[124:127], v[148:151], v[180:183], v[124:127]
	v_mfma_f32_16x16x32_bf16 v[120:123], v[156:159], v[180:183], v[120:123]
	v_mfma_f32_16x16x32_bf16 v[108:111], v[148:151], v[188:191], v[108:111]
	v_mfma_f32_16x16x32_bf16 v[104:107], v[156:159], v[188:191], v[104:107]
	v_mfma_f32_16x16x32_bf16 v[92:95], v[148:151], v[206:209], v[92:95]
	v_mfma_f32_16x16x32_bf16 v[88:91], v[156:159], v[206:209], v[88:91]
	v_mfma_f32_16x16x32_bf16 v[76:79], v[148:151], v[218:221], v[76:79]
	v_mfma_f32_16x16x32_bf16 v[72:75], v[156:159], v[218:221], v[72:75]
	s_setprio 0
	s_setprio 1
	v_mfma_f32_16x16x32_bf16 v[116:119], v[160:163], v[176:179], v[116:119]
	v_mfma_f32_16x16x32_bf16 v[112:115], v[168:171], v[176:179], v[112:115]
	v_mfma_f32_16x16x32_bf16 v[100:103], v[160:163], v[184:187], v[100:103]
	v_mfma_f32_16x16x32_bf16 v[96:99], v[168:171], v[184:187], v[96:99]
	v_mfma_f32_16x16x32_bf16 v[84:87], v[160:163], v[202:205], v[84:87]
	v_mfma_f32_16x16x32_bf16 v[80:83], v[168:171], v[202:205], v[80:83]
	v_mfma_f32_16x16x32_bf16 v[68:71], v[160:163], v[214:217], v[68:71]
	v_mfma_f32_16x16x32_bf16 v[64:67], v[168:171], v[214:217], v[64:67]
	v_mfma_f32_16x16x32_bf16 v[116:119], v[164:167], v[180:183], v[116:119]
	v_mfma_f32_16x16x32_bf16 v[112:115], v[172:175], v[180:183], v[112:115]
	v_mfma_f32_16x16x32_bf16 v[100:103], v[164:167], v[188:191], v[100:103]
	v_mfma_f32_16x16x32_bf16 v[96:99], v[172:175], v[188:191], v[96:99]
	v_mfma_f32_16x16x32_bf16 v[84:87], v[164:167], v[206:209], v[84:87]
	v_mfma_f32_16x16x32_bf16 v[80:83], v[172:175], v[206:209], v[80:83]
	v_mfma_f32_16x16x32_bf16 v[68:71], v[164:167], v[218:221], v[68:71]
	v_mfma_f32_16x16x32_bf16 v[64:67], v[172:175], v[218:221], v[64:67]
	s_setprio 0
	s_barrier
	s_add_i32 s16, s4, s2
	v_lshl_add_u64 v[192:193], s[40:41], 0, v[130:131]
	s_mov_b32 m0, s16
	ds_read_b128 v[176:179], v197 offset:16384
	ds_read_b128 v[180:183], v197 offset:17408
	ds_read_b128 v[184:187], v197 offset:18432
	ds_read_b128 v[188:191], v197 offset:19456
	ds_read_b128 v[202:205], v197 offset:20480
	ds_read_b128 v[206:209], v197 offset:21504
	ds_read_b128 v[214:217], v197 offset:22528
	ds_read_b128 v[218:221], v197 offset:23552
	global_load_lds_dwordx4 v[192:193], off
	s_add_i32 m0, s16, 0x2000
	s_add_u32 s16, s40, 0x40000
	v_lshl_add_u64 v[210:211], s[40:41], 0, v[134:135]
	s_addc_u32 s17, s41, 0
	s_add_i32 s33, s5, s2
	global_load_lds_dwordx4 v[210:211], off
	v_lshl_add_u64 v[222:223], s[16:17], 0, v[130:131]
	s_mov_b32 m0, s33
	v_lshl_add_u64 v[224:225], s[44:45], 0, v[132:133]
	global_load_lds_dwordx4 v[222:223], off
	v_lshl_add_u64 v[222:223], s[16:17], 0, v[134:135]
	s_add_i32 m0, s33, 0x2000
	s_nop 0
	global_load_lds_dwordx4 v[222:223], off
	v_lshl_add_u64 v[222:223], s[44:45], 0, v[128:129]
	s_mov_b32 m0, s3
	s_nop 0
	global_load_lds_dwordx4 v[222:223], off
	s_mov_b32 m0, s27
	s_nop 0
	global_load_lds_dwordx4 v[224:225], off
	s_waitcnt vmcnt(8)
	s_waitcnt lgkmcnt(0)
	s_barrier
; #define PG8_STAGE(bufoff, gbase, voff) do { _Pragma("unroll") for (int _i = 0; _i < 2; ++_i) \
;     __builtin_amdgcn_global_load_lds((const unsigned*)((const char*)(gbase) + (voff)[_i]), (PG8_LAS unsigned*)(lds + (bufoff) + ldsw + _i * 8192), 16, 0, 0); } while (0)
; #define PG8_LDA(dst, b, h) do { _Pragma("unroll") for (int m = 0; m < 4; ++m) _Pragma("unroll") for (int k = 0; k < 2; ++k) dst[m][k] = *(const PG8_LAS bf16x8*)(lds + PG8_SA(b, h) + aoff + m * 2048 + k * 1024); } while (0)
; #define PG8_LDB(dst, b, h) do { _Pragma("unroll") for (int n = 0; n < 2; ++n) _Pragma("unroll") for (int k = 0; k < 2; ++k) dst[n][k] = *(const PG8_LAS bf16x8*)(lds + PG8_SB(b, h) + boff + n * 2048 + k * 1024); } while (0)
; #define PG8_MMA(ai, bj, At, Bt) do { __builtin_amdgcn_s_setprio(1); _Pragma("unroll") for (int m = 0; m < 4; ++m) _Pragma("unroll") for (int n = 0; n < 2; ++n) _Pragma("unroll") for (int k = 0; k < 2; ++k) \
;     acc[ai][bj][m][n] = __builtin_amdgcn_mfma_f32_16x16x32_bf16(Bt[n][k], At[m][k], acc[ai][bj][m][n], 0, 0, 0); __builtin_amdgcn_s_setprio(0); } while (0)
; #define PG8_WAIT_V(n) asm volatile("s_waitcnt vmcnt(" #n ")" ::: "memory")
; #define PG8_WAIT_L(n) asm volatile("s_waitcnt lgkmcnt(" #n ")" ::: "memory")
; #define PG8_BAR __builtin_amdgcn_s_barrier()
; #define PG8_SCHED __builtin_amdgcn_sched_barrier(0)
; template <class Epi, class Sched>
; DI void gemm_phase(PG8_LAS unsigned char* lds, const Gemm g, const Sched& S, const Epi& E) {
;     ...
;       PG8_WAIT_V(8); PG8_WAIT_L(0); PG8_BAR; PG8_MMA(1, 0, At, B0); PG8_MMA(1, 1, At, B1); PG8_BAR; PG8_SCHED;
;       PG8_LDB(B0, 1, 0); PG8_LDB(B1, 1, 1); PG8_SCHED; PG8_LDA(At, 1, 0); PG8_STAGE(PG8_SA(0, 1), a2 + hstepA, voffA);
;       PG8_WAIT_V(8); PG8_WAIT_L(0); PG8_BAR; PG8_MMA(0, 0, At, B0); PG8_MMA(0, 1, At, B1); PG8_BAR; PG8_SCHED;
;       PG8_LDA(At, 1, 1); PG8_STAGE(PG8_SB(1, 0), b3, voffB); PG8_STAGE(PG8_SB(1, 1), b3 + hstepB, voffB); PG8_STAGE(PG8_SA(1, 0), a3, voffA);
	s_setprio 1
	s_waitcnt lgkmcnt(0)
	v_mfma_f32_16x16x32_bf16 v[60:63], v[144:147], v[176:179], v[60:63]
	v_mfma_f32_16x16x32_bf16 v[56:59], v[152:155], v[176:179], v[56:59]
	v_mfma_f32_16x16x32_bf16 v[44:47], v[144:147], v[184:187], v[44:47]
	v_mfma_f32_16x16x32_bf16 v[40:43], v[152:155], v[184:187], v[40:43]
	v_mfma_f32_16x16x32_bf16 v[28:31], v[144:147], v[202:205], v[28:31]
	v_mfma_f32_16x16x32_bf16 v[24:27], v[152:155], v[202:205], v[24:27]
	v_mfma_f32_16x16x32_bf16 v[12:15], v[144:147], v[214:217], v[12:15]
	v_mfma_f32_16x16x32_bf16 v[8:11], v[152:155], v[214:217], v[8:11]
	v_mfma_f32_16x16x32_bf16 v[60:63], v[148:151], v[180:183], v[60:63]
	v_mfma_f32_16x16x32_bf16 v[56:59], v[156:159], v[180:183], v[56:59]
	v_mfma_f32_16x16x32_bf16 v[44:47], v[148:151], v[188:191], v[44:47]
	v_mfma_f32_16x16x32_bf16 v[40:43], v[156:159], v[188:191], v[40:43]
	v_mfma_f32_16x16x32_bf16 v[28:31], v[148:151], v[206:209], v[28:31]
	v_mfma_f32_16x16x32_bf16 v[24:27], v[156:159], v[206:209], v[24:27]
	v_mfma_f32_16x16x32_bf16 v[12:15], v[148:151], v[218:221], v[12:15]
	v_mfma_f32_16x16x32_bf16 v[8:11], v[156:159], v[218:221], v[8:11]
	s_setprio 0
	s_setprio 1
	v_mfma_f32_16x16x32_bf16 v[52:55], v[160:163], v[176:179], v[52:55]
	v_mfma_f32_16x16x32_bf16 v[48:51], v[168:171], v[176:179], v[48:51]
	v_mfma_f32_16x16x32_bf16 v[36:39], v[160:163], v[184:187], v[36:39]
	v_mfma_f32_16x16x32_bf16 v[32:35], v[168:171], v[184:187], v[32:35]
	v_mfma_f32_16x16x32_bf16 v[20:23], v[160:163], v[202:205], v[20:23]
	v_mfma_f32_16x16x32_bf16 v[16:19], v[168:171], v[202:205], v[16:19]
	v_mfma_f32_16x16x32_bf16 v[4:7], v[160:163], v[214:217], v[4:7]
	v_mfma_f32_16x16x32_bf16 v[0:3], v[168:171], v[214:217], v[0:3]
	v_mfma_f32_16x16x32_bf16 v[52:55], v[164:167], v[180:183], v[52:55]
	v_mfma_f32_16x16x32_bf16 v[48:51], v[172:175], v[180:183], v[48:51]
	v_mfma_f32_16x16x32_bf16 v[36:39], v[164:167], v[188:191], v[36:39]
	v_mfma_f32_16x16x32_bf16 v[32:35], v[172:175], v[188:191], v[32:35]
	v_mfma_f32_16x16x32_bf16 v[20:23], v[164:167], v[206:209], v[20:23]
	v_mfma_f32_16x16x32_bf16 v[16:19], v[172:175], v[206:209], v[16:19]
	v_mfma_f32_16x16x32_bf16 v[4:7], v[164:167], v[218:221], v[4:7]
	v_mfma_f32_16x16x32_bf16 v[0:3], v[172:175], v[218:221], v[0:3]
	s_setprio 0
	s_barrier
	ds_read_b128 v[144:147], v199
	ds_read_b128 v[148:151], v199 offset:1024
	ds_read_b128 v[152:155], v199 offset:2048
	ds_read_b128 v[156:159], v199 offset:3072
	ds_read_b128 v[160:163], v200
	ds_read_b128 v[164:167], v200 offset:1024
	ds_read_b128 v[168:171], v200 offset:2048
	ds_read_b128 v[172:175], v200 offset:3072
	s_add_u32 s16, s44, 0x40000
	s_addc_u32 s17, s45, 0
	s_mov_b32 m0, s53
	v_lshl_add_u64 v[226:227], s[16:17], 0, v[128:129]
	ds_read_b128 v[176:179], v197 offset:32768
	ds_read_b128 v[180:183], v197 offset:33792
	ds_read_b128 v[184:187], v197 offset:34816
	ds_read_b128 v[188:191], v197 offset:35840
	ds_read_b128 v[202:205], v197 offset:36864
	ds_read_b128 v[206:209], v197 offset:37888
	ds_read_b128 v[214:217], v197 offset:38912
	ds_read_b128 v[218:221], v197 offset:39936
	global_load_lds_dwordx4 v[226:227], off
	v_lshl_add_u64 v[226:227], s[16:17], 0, v[132:133]
	s_mov_b32 m0, s55
	s_nop 0
	global_load_lds_dwordx4 v[226:227], off
	s_waitcnt vmcnt(8)
	s_waitcnt lgkmcnt(0)
	s_barrier
	s_setprio 1
	s_waitcnt lgkmcnt(0)
	v_mfma_f32_16x16x32_bf16 v[124:127], v[144:147], v[176:179], v[124:127]
	v_mfma_f32_16x16x32_bf16 v[120:123], v[152:155], v[176:179], v[120:123]
	v_mfma_f32_16x16x32_bf16 v[108:111], v[144:147], v[184:187], v[108:111]
	v_mfma_f32_16x16x32_bf16 v[104:107], v[152:155], v[184:187], v[104:107]
	v_mfma_f32_16x16x32_bf16 v[92:95], v[144:147], v[202:205], v[92:95]
	v_mfma_f32_16x16x32_bf16 v[88:91], v[152:155], v[202:205], v[88:91]
	v_mfma_f32_16x16x32_bf16 v[76:79], v[144:147], v[214:217], v[76:79]
	v_mfma_f32_16x16x32_bf16 v[72:75], v[152:155], v[214:217], v[72:75]
	v_mfma_f32_16x16x32_bf16 v[124:127], v[148:151], v[180:183], v[124:127]
	v_mfma_f32_16x16x32_bf16 v[120:123], v[156:159], v[180:183], v[120:123]
	v_mfma_f32_16x16x32_bf16 v[108:111], v[148:151], v[188:191], v[108:111]
	v_mfma_f32_16x16x32_bf16 v[104:107], v[156:159], v[188:191], v[104:107]
	v_mfma_f32_16x16x32_bf16 v[92:95], v[148:151], v[206:209], v[92:95]
	v_mfma_f32_16x16x32_bf16 v[88:91], v[156:159], v[206:209], v[88:91]
	v_mfma_f32_16x16x32_bf16 v[76:79], v[148:151], v[218:221], v[76:79]
	v_mfma_f32_16x16x32_bf16 v[72:75], v[156:159], v[218:221], v[72:75]
	s_setprio 0
	s_setprio 1
	v_mfma_f32_16x16x32_bf16 v[116:119], v[160:163], v[176:179], v[116:119]
	v_mfma_f32_16x16x32_bf16 v[112:115], v[168:171], v[176:179], v[112:115]
	v_mfma_f32_16x16x32_bf16 v[100:103], v[160:163], v[184:187], v[100:103]
	v_mfma_f32_16x16x32_bf16 v[96:99], v[168:171], v[184:187], v[96:99]
	v_mfma_f32_16x16x32_bf16 v[84:87], v[160:163], v[202:205], v[84:87]
	v_mfma_f32_16x16x32_bf16 v[80:83], v[168:171], v[202:205], v[80:83]
	v_mfma_f32_16x16x32_bf16 v[68:71], v[160:163], v[214:217], v[68:71]
	v_mfma_f32_16x16x32_bf16 v[64:67], v[168:171], v[214:217], v[64:67]
	v_mfma_f32_16x16x32_bf16 v[116:119], v[164:167], v[180:183], v[116:119]
	v_mfma_f32_16x16x32_bf16 v[112:115], v[172:175], v[180:183], v[112:115]
	v_mfma_f32_16x16x32_bf16 v[100:103], v[164:167], v[188:191], v[100:103]
	v_mfma_f32_16x16x32_bf16 v[96:99], v[172:175], v[188:191], v[96:99]
	v_mfma_f32_16x16x32_bf16 v[84:87], v[164:167], v[206:209], v[84:87]
	v_mfma_f32_16x16x32_bf16 v[80:83], v[172:175], v[206:209], v[80:83]
	v_mfma_f32_16x16x32_bf16 v[68:71], v[164:167], v[218:221], v[68:71]
	v_mfma_f32_16x16x32_bf16 v[64:67], v[172:175], v[218:221], v[64:67]
	s_setprio 0
	s_barrier
; #define PG8_STAGE(bufoff, gbase, voff) do { _Pragma("unroll") for (int _i = 0; _i < 2; ++_i) \
;     __builtin_amdgcn_global_load_lds((const unsigned*)((const char*)(gbase) + (voff)[_i]), (PG8_LAS unsigned*)(lds + (bufoff) + ldsw + _i * 8192), 16, 0, 0); } while (0)
; #define PG8_LDA(dst, b, h) do { _Pragma("unroll") for (int m = 0; m < 4; ++m) _Pragma("unroll") for (int k = 0; k < 2; ++k) dst[m][k] = *(const PG8_LAS bf16x8*)(lds + PG8_SA(b, h) + aoff + m * 2048 + k * 1024); } while (0)
; #define PG8_MMA(ai, bj, At, Bt) do { __builtin_amdgcn_s_setprio(1); _Pragma("unroll") for (int m = 0; m < 4; ++m) _Pragma("unroll") for (int n = 0; n < 2; ++n) _Pragma("unroll") for (int k = 0; k < 2; ++k) \
;     acc[ai][bj][m][n] = __builtin_amdgcn_mfma_f32_16x16x32_bf16(Bt[n][k], At[m][k], acc[ai][bj][m][n], 0, 0, 0); __builtin_amdgcn_s_setprio(0); } while (0)
; #define PG8_WAIT_V(n) asm volatile("s_waitcnt vmcnt(" #n ")" ::: "memory")
; #define PG8_WAIT_L(n) asm volatile("s_waitcnt lgkmcnt(" #n ")" ::: "memory")
; #define PG8_BAR __builtin_amdgcn_s_barrier()
; #define PG8_SCHED __builtin_amdgcn_sched_barrier(0)
; DI void rows_rstd(float (&rs)[2][4], const float* ps, const Unit& u, int wr, int fr, int fq, int p_lo, int p_hi, float inv_dim) {
;   f32x4 pv[2][4];
; #pragma unroll
;   for (int ai = 0; ai < 2; ++ai)
; #pragma unroll
;     for (int m = 0; m < 4; ++m) pv[ai][m] = *(const f32x4*)(ps + (size_t)(u.pm * BM + ai * HALF + wr * 64 + m * 16 + fr) * 16 + 4 * fq);
; template <class Epi, class Sched>
; DI void gemm_phase(PG8_LAS unsigned char* lds, const Gemm g, const Sched& S, const Epi& E) {
;     ...
;       PG8_LDA(At, 1, 1); PG8_STAGE(PG8_SB(1, 0), b3, voffB); PG8_STAGE(PG8_SB(1, 1), b3 + hstepB, voffB); PG8_STAGE(PG8_SA(1, 0), a3, voffA);
;       PG8_WAIT_V(8); PG8_WAIT_L(0); PG8_BAR; PG8_MMA(1, 0, At, B0); PG8_MMA(1, 1, At, B1); PG8_BAR; PG8_SCHED;
;     }
;     if (wr == 0) PG8_BAR;
	s_add_i32 s16, s69, s2
	v_lshl_add_u64 v[192:193], v[192:193], 0, s[14:15]
	s_mov_b32 m0, s16
	ds_read_b128 v[176:179], v197 offset:49152
	ds_read_b128 v[180:183], v197 offset:50176
	ds_read_b128 v[184:187], v197 offset:51200
	ds_read_b128 v[188:191], v197 offset:52224
	ds_read_b128 v[202:205], v197 offset:53248
	ds_read_b128 v[206:209], v197 offset:54272
	ds_read_b128 v[214:217], v197 offset:55296
	ds_read_b128 v[218:221], v197 offset:56320
	global_load_lds_dwordx4 v[192:193], off
	s_add_i32 m0, s16, 0x2000
	s_add_u32 s16, s40, 0x40080
	v_lshl_add_u64 v[192:193], v[210:211], 0, s[14:15]
	s_addc_u32 s17, s41, 0
	s_add_i32 s33, s70, s2
	global_load_lds_dwordx4 v[192:193], off
	v_lshl_add_u64 v[192:193], s[16:17], 0, v[130:131]
	s_mov_b32 m0, s33
	s_nop 0
	global_load_lds_dwordx4 v[192:193], off
	v_lshl_add_u64 v[192:193], s[16:17], 0, v[134:135]
	s_add_i32 m0, s33, 0x2000
	s_nop 0
	global_load_lds_dwordx4 v[192:193], off
	v_lshl_add_u64 v[192:193], v[222:223], 0, s[14:15]
	s_mov_b32 m0, s65
	s_nop 0
	global_load_lds_dwordx4 v[192:193], off
	v_lshl_add_u64 v[192:193], v[224:225], 0, s[14:15]
	s_mov_b32 m0, s66
	s_nop 0
	global_load_lds_dwordx4 v[192:193], off
	s_waitcnt vmcnt(8)
	s_waitcnt lgkmcnt(0)
	s_barrier
	s_setprio 1
	s_waitcnt lgkmcnt(0)
	v_mfma_f32_16x16x32_bf16 v[60:63], v[144:147], v[176:179], v[60:63]
	v_mfma_f32_16x16x32_bf16 v[56:59], v[152:155], v[176:179], v[56:59]
	v_mfma_f32_16x16x32_bf16 v[44:47], v[144:147], v[184:187], v[44:47]
	v_mfma_f32_16x16x32_bf16 v[40:43], v[152:155], v[184:187], v[40:43]
	v_mfma_f32_16x16x32_bf16 v[28:31], v[144:147], v[202:205], v[28:31]
	v_mfma_f32_16x16x32_bf16 v[24:27], v[152:155], v[202:205], v[24:27]
	v_mfma_f32_16x16x32_bf16 v[12:15], v[144:147], v[214:217], v[12:15]
	v_mfma_f32_16x16x32_bf16 v[8:11], v[152:155], v[214:217], v[8:11]
	v_mfma_f32_16x16x32_bf16 v[60:63], v[148:151], v[180:183], v[60:63]
	v_mfma_f32_16x16x32_bf16 v[56:59], v[156:159], v[180:183], v[56:59]
	v_mfma_f32_16x16x32_bf16 v[44:47], v[148:151], v[188:191], v[44:47]
	v_mfma_f32_16x16x32_bf16 v[40:43], v[156:159], v[188:191], v[40:43]
	v_mfma_f32_16x16x32_bf16 v[28:31], v[148:151], v[206:209], v[28:31]
	v_mfma_f32_16x16x32_bf16 v[24:27], v[156:159], v[206:209], v[24:27]
	v_mfma_f32_16x16x32_bf16 v[12:15], v[148:151], v[218:221], v[12:15]
	v_mfma_f32_16x16x32_bf16 v[8:11], v[156:159], v[218:221], v[8:11]
	s_setprio 0
	s_setprio 1
	v_mfma_f32_16x16x32_bf16 v[52:55], v[160:163], v[176:179], v[52:55]
	v_mfma_f32_16x16x32_bf16 v[48:51], v[168:171], v[176:179], v[48:51]
	v_mfma_f32_16x16x32_bf16 v[36:39], v[160:163], v[184:187], v[36:39]
	v_mfma_f32_16x16x32_bf16 v[32:35], v[168:171], v[184:187], v[32:35]
	v_mfma_f32_16x16x32_bf16 v[20:23], v[160:163], v[202:205], v[20:23]
	v_mfma_f32_16x16x32_bf16 v[16:19], v[168:171], v[202:205], v[16:19]
	v_mfma_f32_16x16x32_bf16 v[4:7], v[160:163], v[214:217], v[4:7]
	v_mfma_f32_16x16x32_bf16 v[0:3], v[168:171], v[214:217], v[0:3]
	v_mfma_f32_16x16x32_bf16 v[52:55], v[164:167], v[180:183], v[52:55]
	v_mfma_f32_16x16x32_bf16 v[48:51], v[172:175], v[180:183], v[48:51]
	v_mfma_f32_16x16x32_bf16 v[36:39], v[164:167], v[188:191], v[36:39]
	v_mfma_f32_16x16x32_bf16 v[32:35], v[172:175], v[188:191], v[32:35]
	v_mfma_f32_16x16x32_bf16 v[20:23], v[164:167], v[206:209], v[20:23]
	v_mfma_f32_16x16x32_bf16 v[16:19], v[172:175], v[206:209], v[16:19]
	v_mfma_f32_16x16x32_bf16 v[4:7], v[164:167], v[218:221], v[4:7]
	v_mfma_f32_16x16x32_bf16 v[0:3], v[172:175], v[218:221], v[0:3]
	s_setprio 0
	s_barrier
	s_add_i32 s73, s73, 2
	s_add_u32 s10, s10, 0x100
	s_addc_u32 s11, s11, 0
	s_add_u32 s31, s31, 0x100
	s_addc_u32 s72, s72, 0
	s_cmp_gt_u32 s73, 13
	s_cbranch_scc0 .LBB0_807
	v_lshl_add_u32 v184, s8, 8, v143
	v_or_b32_e32 v180, 16, v184
	v_ashrrev_i32_e32 v181, 31, v180
	v_or_b32_e32 v172, 32, v184
	v_lshlrev_b64 v[178:179], 6, v[180:181]
	v_ashrrev_i32_e32 v173, 31, v172
	v_ashrrev_i32_e32 v185, 31, v184
	v_lshl_add_u64 v[144:145], v[136:137], 0, v[178:179]
	v_lshlrev_b64 v[170:171], 6, v[172:173]
	v_lshlrev_b64 v[182:183], 6, v[184:185]
	v_lshl_add_u64 v[146:147], v[136:137], 0, v[170:171]
	global_load_dwordx4 v[162:165], v[144:145], off
	global_load_dwordx4 v[174:177], v[146:147], off
	v_lshl_add_u64 v[144:145], v[136:137], 0, v[182:183]
	global_load_dwordx4 v[186:189], v[144:145], off
	v_or_b32_e32 v168, 48, v184
	v_ashrrev_i32_e32 v169, 31, v168
	v_add_u32_e32 v160, 0x80, v184
	v_add_u32_e32 v156, 0x90, v184
	v_lshlrev_b64 v[166:167], 6, v[168:169]
	v_ashrrev_i32_e32 v161, 31, v160
	v_ashrrev_i32_e32 v157, 31, v156
	v_lshl_add_u64 v[144:145], v[136:137], 0, v[166:167]
	v_lshlrev_b64 v[158:159], 6, v[160:161]
	v_lshlrev_b64 v[154:155], 6, v[156:157]
	v_lshl_add_u64 v[146:147], v[136:137], 0, v[158:159]
	global_load_dwordx4 v[190:193], v[144:145], off
	global_load_dwordx4 v[202:205], v[146:147], off
	v_lshl_add_u64 v[144:145], v[136:137], 0, v[154:155]
	global_load_dwordx4 v[206:209], v[144:145], off
	v_add_u32_e32 v150, 0xa0, v184
	v_ashrrev_i32_e32 v151, 31, v150
	v_lshlrev_b64 v[148:149], 6, v[150:151]
	v_add_u32_e32 v146, 0xb0, v184
	v_lshl_add_u64 v[144:145], v[136:137], 0, v[148:149]
	v_ashrrev_i32_e32 v147, 31, v146
	global_load_dwordx4 v[214:217], v[144:145], off
	v_lshlrev_b64 v[144:145], 6, v[146:147]
	v_lshl_add_u64 v[152:153], v[136:137], 0, v[144:145]
	global_load_dwordx4 v[218:221], v[152:153], off
	s_and_b64 vcc, exec, s[20:21]
	s_cbranch_vccz .LBB0_810
	s_barrier
; DI unsigned pack2(float a, float b) { bf2_t v = __builtin_convertvector((f32x2){a, b}, bf2_t); return __builtin_bit_cast(unsigned, v); }
; DI void rows_rstd(float (&rs)[2][4], const float* ps, const Unit& u, int wr, int fr, int fq, int p_lo, int p_hi, float inv_dim) {
;     ...
;   const bool use = (4 * fq >= p_lo) && (4 * fq < p_hi);
; #pragma unroll
;   for (int ai = 0; ai < 2; ++ai)
; #pragma unroll
;     for (int m = 0; m < 4; ++m) {
;       float s = use ? (pv[ai][m][0] + pv[ai][m][1]) + (pv[ai][m][2] + pv[ai][m][3]) : 0.f;
;       s += __shfl_xor(s, 16); s += __shfl_xor(s, 32);
;       rs[ai][m] = rsqrtf(s * inv_dim + EPS);
;     }
; }
;   DI void operator()(const f32x4 (&acc)[2][2][4][2], const Unit& u, int wr, int wc, int fr, int fq) const {
;     float rsv[2][4];
;     if (ps_in) rows_rstd(rsv, ps_in, u, wr, fr, fq, p_lo, p_hi, inv_dim);
; #pragma unroll
;     for (int ai = 0; ai < 2; ++ai)
; #pragma unroll
;       for (int m = 0; m < 4; ++m) {
;         const int row = u.pm * BM + ai * HALF + wr * 64 + m * 16 + fr;
;         const float rs = ps_in ? rsv[ai][m] : 1.f;
;         float ssum = 0.f;
; #pragma unroll
;         for (int bj = 0; bj < 2; ++bj) {
;           const int c0 = u.pn * BM + bj * HALF + wc * 32 + 8 * fq;
;           const f32x4 v0 = acc[ai][bj][m][0] * rs, v1 = acc[ai][bj][m][1] * rs;
;           if (PSOUT) ssum += (v0[0] * v0[0] + v0[1] * v0[1]) + (v0[2] * v0[2] + v0[3] * v0[3]) + (v1[0] * v1[0] + v1[1] * v1[1]) + (v1[2] * v1[2] + v1[3] * v1[3]);
;           u32x4 w; w.x = pack2(v0[0], v0[1]); w.y = pack2(v0[2], v0[3]); w.z = pack2(v1[0], v1[1]); w.w = pack2(v1[2], v1[3]);
;           if (EMODE == EM_KVUP) {
;             const int hh = c0 >> 7, j = c0 & 127;
;             if (j < 64) *(u32x4*)(O + (size_t)row * 1152 + hh * 96 + j) = w; else *(u32x4*)(O2 + (size_t)row * 768 + hh * 64 + (j - 64)) = w;
;           } else {
;             if (c0 < ncols) *(u32x4*)(O + (size_t)row * ldo + c0) = w;
.LBB0_810:
	v_and_b32_e32 v151, 64, v198
	v_xor_b32_e32 v147, 32, v198
	v_add_u32_e32 v151, 64, v151
	v_xor_b32_e32 v152, 16, v198
	v_cmp_lt_i32_e32 vcc, v147, v151
	s_waitcnt vmcnt(0)
	v_mov_b32_e32 v153, v188
	v_cndmask_b32_e32 v147, v198, v147, vcc
	v_cmp_lt_i32_e32 vcc, v152, v151
	v_mov_b32_e32 v188, v163
	v_mov_b32_e32 v163, v165
	v_cndmask_b32_e32 v151, v198, v152, vcc
	v_mov_b32_e32 v152, v187
	v_mov_b32_e32 v187, v189
	v_mov_b32_e32 v189, v164
	v_pk_add_f32 v[152:153], v[152:153], v[186:187]
	v_pk_add_f32 v[162:163], v[188:189], v[162:163]
	v_mov_b32_e32 v189, v152
	v_mov_b32_e32 v188, v162
	v_mov_b32_e32 v152, v163
	v_lshlrev_b32_e32 v151, 2, v151
	v_pk_add_f32 v[152:153], v[188:189], v[152:153]
	ds_bpermute_b32 v189, v151, v153
	ds_bpermute_b32 v188, v151, v152
	v_mov_b32_e32 v164, v175
	v_mov_b32_e32 v165, v176
	v_mov_b32_e32 v175, v177
	v_mov_b32_e32 v176, v191
	v_mov_b32_e32 v177, v192
	v_mov_b32_e32 v191, v193
	v_mov_b32_e32 v192, v203
	v_mov_b32_e32 v193, v204
	v_mov_b32_e32 v203, v205
	v_mov_b32_e32 v204, v207
	v_mov_b32_e32 v205, v208
	v_mov_b32_e32 v207, v209
	v_pk_add_f32 v[164:165], v[164:165], v[174:175]
	v_pk_add_f32 v[174:175], v[176:177], v[190:191]
	v_pk_add_f32 v[176:177], v[192:193], v[202:203]
	v_pk_add_f32 v[186:187], v[204:205], v[206:207]
	v_lshlrev_b32_e32 v147, 2, v147
	v_mov_b32_e32 v162, v174
	v_mov_b32_e32 v163, v164
	v_mov_b32_e32 v164, v175
	v_mov_b32_e32 v174, v186
	v_mov_b32_e32 v175, v176
	v_mov_b32_e32 v176, v187
	s_waitcnt lgkmcnt(0)
	v_pk_add_f32 v[152:153], v[152:153], v[188:189]
	v_pk_add_f32 v[162:163], v[162:163], v[164:165]
	v_pk_add_f32 v[164:165], v[174:175], v[176:177]
	ds_bpermute_b32 v175, v147, v153
	ds_bpermute_b32 v174, v147, v152
	ds_bpermute_b32 v177, v151, v163
	ds_bpermute_b32 v176, v151, v162
	v_mov_b32_e32 v208, v215
	v_mov_b32_e32 v209, v216
	s_waitcnt lgkmcnt(2)
	v_pk_add_f32 v[152:153], v[152:153], v[174:175]
	v_mov_b32_e32 v215, v217
	v_pk_fma_f32 v[190:191], v[152:153], s[26:27], v[142:143] op_sel_hi:[1,0,0]
	v_pk_add_f32 v[202:203], v[208:209], v[214:215]
	v_mul_f32_e32 v152, 0x4b800000, v191
	v_cmp_gt_f32_e32 vcc, s19, v191
	s_waitcnt lgkmcnt(0)
	v_pk_add_f32 v[186:187], v[162:163], v[176:177]
	v_mov_b32_e32 v163, v202
	v_cndmask_b32_e32 v152, v191, v152, vcc
	v_rsq_f32_e32 v152, v152
	ds_bpermute_b32 v205, v151, v165
	ds_bpermute_b32 v204, v151, v164
	ds_bpermute_b32 v189, v147, v187
	v_mul_f32_e32 v153, 0x45800000, v152
	v_cndmask_b32_e32 v192, v152, v153, vcc
	v_mov_b32_e32 v152, v219
	v_mov_b32_e32 v153, v220
	v_mov_b32_e32 v219, v221
	v_pk_add_f32 v[152:153], v[152:153], v[218:219]
	s_waitcnt lgkmcnt(1)
	v_pk_add_f32 v[174:175], v[164:165], v[204:205]
	v_mov_b32_e32 v162, v152
	v_mov_b32_e32 v202, v153
	v_pk_add_f32 v[152:153], v[162:163], v[202:203]
	ds_bpermute_b32 v163, v151, v153
	ds_bpermute_b32 v162, v151, v152
	ds_bpermute_b32 v188, v147, v186
	ds_bpermute_b32 v177, v147, v175
	ds_bpermute_b32 v176, v147, v174
	v_cmp_gt_f32_e64 s[10:11], s19, v190
	s_waitcnt lgkmcnt(3)
	v_pk_add_f32 v[162:163], v[152:153], v[162:163]
	ds_bpermute_b32 v165, v147, v163
	ds_bpermute_b32 v164, v147, v162
	v_lshl_or_b32 v152, s0, 8, v194
	v_pk_mul_f32 v[126:127], v[126:127], v[192:193] op_sel_hi:[1,0]
	v_pk_mul_f32 v[124:125], v[124:125], v[192:193] op_sel_hi:[1,0]
	v_pk_mul_f32 v[122:123], v[122:123], v[192:193] op_sel_hi:[1,0]
	v_pk_mul_f32 v[120:121], v[120:121], v[192:193] op_sel_hi:[1,0]
	v_cmp_gt_i32_e32 vcc, s67, v152
	v_ashrrev_i32_e32 v153, 31, v152
	s_and_saveexec_b64 s[8:9], vcc
	s_cbranch_execz .LBB0_812
	v_mov_b64_e32 v[206:207], s[98:99]
	v_mad_i64_i32 v[206:207], s[16:17], v184, s68, v[206:207]
	v_cvt_pk_bf16_f32 v205, v122, v123
	v_cvt_pk_bf16_f32 v204, v120, v121
	v_cvt_pk_bf16_f32 v203, v126, v127
	v_cvt_pk_bf16_f32 v202, v124, v125
	v_lshl_add_u64 v[206:207], v[152:153], 1, v[206:207]
	global_store_dwordx4 v[206:207], v[202:205], off

; #define PG8_STAGE(bufoff, gbase, voff) do { _Pragma("unroll") for (int _i = 0; _i < 2; ++_i) \
;     __builtin_amdgcn_global_load_lds((const unsigned*)((const char*)(gbase) + (voff)[_i]), (PG8_LAS unsigned*)(lds + (bufoff) + ldsw + _i * 8192), 16, 0, 0); } while (0)
; #define PG8_LDA(dst, b, h) do { _Pragma("unroll") for (int m = 0; m < 4; ++m) _Pragma("unroll") for (int k = 0; k < 2; ++k) dst[m][k] = *(const PG8_LAS bf16x8*)(lds + PG8_SA(b, h) + aoff + m * 2048 + k * 1024); } while (0)
; #define PG8_LDB(dst, b, h) do { _Pragma("unroll") for (int n = 0; n < 2; ++n) _Pragma("unroll") for (int k = 0; k < 2; ++k) dst[n][k] = *(const PG8_LAS bf16x8*)(lds + PG8_SB(b, h) + boff + n * 2048 + k * 1024); } while (0)
; #define PG8_MMA(ai, bj, At, Bt) do { __builtin_amdgcn_s_setprio(1); _Pragma("unroll") for (int m = 0; m < 4; ++m) _Pragma("unroll") for (int n = 0; n < 2; ++n) _Pragma("unroll") for (int k = 0; k < 2; ++k) \
;     acc[ai][bj][m][n] = __builtin_amdgcn_mfma_f32_16x16x32_bf16(Bt[n][k], At[m][k], acc[ai][bj][m][n], 0, 0, 0); __builtin_amdgcn_s_setprio(0); } while (0)
; #define PG8_WAIT_V(n) asm volatile("s_waitcnt vmcnt(" #n ")" ::: "memory")
; #define PG8_WAIT_L(n) asm volatile("s_waitcnt lgkmcnt(" #n ")" ::: "memory")
; #define PG8_BAR __builtin_amdgcn_s_barrier()
; #define PG8_SCHED __builtin_amdgcn_sched_barrier(0)
; template <class Epi, class Sched>
; DI void gemm_phase(PG8_LAS unsigned char* lds, const Gemm g, const Sched& S, const Epi& E) {
;     ...
;       const char* a1 = cA + (size_t)(t + 1) * kstep;
;       const char* a2 = last ? nA : cA + (size_t)(t + 2) * kstep; const char* b2 = last ? nB : cB + (size_t)(t + 2) * kstep;
;       const char* a3 = a2 + kstep; const char* b3 = b2 + kstep;
;       PG8_LDB(B0, 0, 0); PG8_LDB(B1, 0, 1); PG8_SCHED; PG8_LDA(At, 0, 0); PG8_STAGE(PG8_SA(1, 1), a1 + hstepA, voffA);
;       PG8_WAIT_V(8); PG8_WAIT_L(0); PG8_BAR; PG8_MMA(0, 0, At, B0); PG8_MMA(0, 1, At, B1); PG8_BAR; PG8_SCHED;
;       PG8_LDA(At, 0, 1); PG8_STAGE(PG8_SB(0, 0), b2, voffB); PG8_STAGE(PG8_SB(0, 1), b2 + hstepB, voffB); PG8_STAGE(PG8_SA(0, 0), a2, voffA);
;       PG8_WAIT_V(8); PG8_WAIT_L(0); PG8_BAR; PG8_MMA(1, 0, At, B0); PG8_MMA(1, 1, At, B1); PG8_BAR; PG8_SCHED;
;       PG8_LDB(B0, 1, 0); PG8_LDB(B1, 1, 1); PG8_SCHED; PG8_LDA(At, 1, 0); PG8_STAGE(PG8_SA(0, 1), a2 + hstepA, voffA);
.LBB0_1300:
	ds_read_b128 v[128:131], v156
	ds_read_b128 v[132:135], v156 offset:1024
	ds_read_b128 v[150:153], v156 offset:2048
	ds_read_b128 v[162:165], v156 offset:3072
	ds_read_b128 v[166:169], v157
	ds_read_b128 v[170:173], v157 offset:1024
	ds_read_b128 v[174:177], v157 offset:2048
	ds_read_b128 v[178:181], v157 offset:3072
	s_add_u32 s17, s62, 0xfffc0080
	s_addc_u32 s33, s63, -1
	s_cmp_eq_u32 s75, 12
	s_cselect_b32 s67, s39, s33
	s_cselect_b32 s66, s59, s17
	s_cselect_b32 s65, s37, s74
	s_cselect_b32 s64, s61, s73
	v_lshl_add_u64 v[210:211], s[62:63], 0, v[146:147]
	s_add_i32 m0, s53, 0xc000
	ds_read_b128 v[182:185], v158
	ds_read_b128 v[186:189], v158 offset:1024
	ds_read_b128 v[190:193], v158 offset:2048
	ds_read_b128 v[194:197], v158 offset:3072
	ds_read_b128 v[198:201], v158 offset:4096
	ds_read_b128 v[202:205], v158 offset:5120
	ds_read_b128 v[206:209], v158 offset:6144
	ds_read_b128 v[214:217], v158 offset:7168
	global_load_lds_dwordx4 v[210:211], off
	v_lshl_add_u64 v[210:211], s[62:63], 0, v[148:149]
	s_add_i32 m0, s53, 0xe000
	s_nop 0
	global_load_lds_dwordx4 v[210:211], off
	s_waitcnt vmcnt(8)
	s_waitcnt lgkmcnt(0)
	s_barrier
	s_setprio 1
	s_waitcnt lgkmcnt(0)
	v_mfma_f32_16x16x32_bf16 v[124:127], v[128:131], v[182:185], v[124:127]
	v_mfma_f32_16x16x32_bf16 v[120:123], v[150:153], v[182:185], v[120:123]
	v_mfma_f32_16x16x32_bf16 v[108:111], v[128:131], v[190:193], v[108:111]
	v_mfma_f32_16x16x32_bf16 v[104:107], v[150:153], v[190:193], v[104:107]
	v_mfma_f32_16x16x32_bf16 v[92:95], v[128:131], v[198:201], v[92:95]
	v_mfma_f32_16x16x32_bf16 v[88:91], v[150:153], v[198:201], v[88:91]
	v_mfma_f32_16x16x32_bf16 v[76:79], v[128:131], v[206:209], v[76:79]
	v_mfma_f32_16x16x32_bf16 v[72:75], v[150:153], v[206:209], v[72:75]
	v_mfma_f32_16x16x32_bf16 v[124:127], v[132:135], v[186:189], v[124:127]
	v_mfma_f32_16x16x32_bf16 v[120:123], v[162:165], v[186:189], v[120:123]
	v_mfma_f32_16x16x32_bf16 v[108:111], v[132:135], v[194:197], v[108:111]
	v_mfma_f32_16x16x32_bf16 v[104:107], v[162:165], v[194:197], v[104:107]
	v_mfma_f32_16x16x32_bf16 v[92:95], v[132:135], v[202:205], v[92:95]
	v_mfma_f32_16x16x32_bf16 v[88:91], v[162:165], v[202:205], v[88:91]
	v_mfma_f32_16x16x32_bf16 v[76:79], v[132:135], v[214:217], v[76:79]
	v_mfma_f32_16x16x32_bf16 v[72:75], v[162:165], v[214:217], v[72:75]
	s_setprio 0
	s_setprio 1
	v_mfma_f32_16x16x32_bf16 v[116:119], v[166:169], v[182:185], v[116:119]
	v_mfma_f32_16x16x32_bf16 v[112:115], v[174:177], v[182:185], v[112:115]
	v_mfma_f32_16x16x32_bf16 v[100:103], v[166:169], v[190:193], v[100:103]
	v_mfma_f32_16x16x32_bf16 v[96:99], v[174:177], v[190:193], v[96:99]
	v_mfma_f32_16x16x32_bf16 v[84:87], v[166:169], v[198:201], v[84:87]
	v_mfma_f32_16x16x32_bf16 v[80:83], v[174:177], v[198:201], v[80:83]
	v_mfma_f32_16x16x32_bf16 v[68:71], v[166:169], v[206:209], v[68:71]
	v_mfma_f32_16x16x32_bf16 v[64:67], v[174:177], v[206:209], v[64:67]
	v_mfma_f32_16x16x32_bf16 v[116:119], v[170:173], v[186:189], v[116:119]
	v_mfma_f32_16x16x32_bf16 v[112:115], v[178:181], v[186:189], v[112:115]
	v_mfma_f32_16x16x32_bf16 v[100:103], v[170:173], v[194:197], v[100:103]
	v_mfma_f32_16x16x32_bf16 v[96:99], v[178:181], v[194:197], v[96:99]
	v_mfma_f32_16x16x32_bf16 v[84:87], v[170:173], v[202:205], v[84:87]
	v_mfma_f32_16x16x32_bf16 v[80:83], v[178:181], v[202:205], v[80:83]
	v_mfma_f32_16x16x32_bf16 v[68:71], v[170:173], v[214:217], v[68:71]
	v_mfma_f32_16x16x32_bf16 v[64:67], v[178:181], v[214:217], v[64:67]
	s_setprio 0
	s_barrier
	s_add_i32 s17, s69, s16
	v_lshl_add_u64 v[210:211], s[64:65], 0, v[138:139]
	s_mov_b32 m0, s17
	ds_read_b128 v[182:185], v158 offset:16384
	ds_read_b128 v[186:189], v158 offset:17408
	ds_read_b128 v[190:193], v158 offset:18432
	ds_read_b128 v[194:197], v158 offset:19456
	ds_read_b128 v[198:201], v158 offset:20480
	ds_read_b128 v[202:205], v158 offset:21504
	ds_read_b128 v[206:209], v158 offset:22528
	ds_read_b128 v[214:217], v158 offset:23552
	global_load_lds_dwordx4 v[210:211], off
	s_add_i32 m0, s17, 0x2000
	s_add_u32 s56, s64, 0x40000
	v_lshl_add_u64 v[218:219], s[64:65], 0, v[142:143]
	s_addc_u32 s57, s65, 0
	s_add_i32 s17, s70, s16
	global_load_lds_dwordx4 v[218:219], off
	v_lshl_add_u64 v[220:221], s[56:57], 0, v[138:139]
	s_mov_b32 m0, s17
	v_lshl_add_u64 v[222:223], s[66:67], 0, v[140:141]
	global_load_lds_dwordx4 v[220:221], off
	v_lshl_add_u64 v[220:221], s[56:57], 0, v[142:143]
	s_add_i32 m0, s17, 0x2000
	s_nop 0
	global_load_lds_dwordx4 v[220:221], off
	v_lshl_add_u64 v[220:221], s[66:67], 0, v[136:137]
	s_mov_b32 m0, s53
	s_nop 0
	global_load_lds_dwordx4 v[220:221], off
	s_mov_b32 m0, s18
	s_nop 0
	global_load_lds_dwordx4 v[222:223], off
	s_waitcnt vmcnt(8)
	s_waitcnt lgkmcnt(0)
	s_barrier
; #define PG8_STAGE(bufoff, gbase, voff) do { _Pragma("unroll") for (int _i = 0; _i < 2; ++_i) \
;     __builtin_amdgcn_global_load_lds((const unsigned*)((const char*)(gbase) + (voff)[_i]), (PG8_LAS unsigned*)(lds + (bufoff) + ldsw + _i * 8192), 16, 0, 0); } while (0)
; #define PG8_LDA(dst, b, h) do { _Pragma("unroll") for (int m = 0; m < 4; ++m) _Pragma("unroll") for (int k = 0; k < 2; ++k) dst[m][k] = *(const PG8_LAS bf16x8*)(lds + PG8_SA(b, h) + aoff + m * 2048 + k * 1024); } while (0)
; #define PG8_LDB(dst, b, h) do { _Pragma("unroll") for (int n = 0; n < 2; ++n) _Pragma("unroll") for (int k = 0; k < 2; ++k) dst[n][k] = *(const PG8_LAS bf16x8*)(lds + PG8_SB(b, h) + boff + n * 2048 + k * 1024); } while (0)
; #define PG8_MMA(ai, bj, At, Bt) do { __builtin_amdgcn_s_setprio(1); _Pragma("unroll") for (int m = 0; m < 4; ++m) _Pragma("unroll") for (int n = 0; n < 2; ++n) _Pragma("unroll") for (int k = 0; k < 2; ++k) \
;     acc[ai][bj][m][n] = __builtin_amdgcn_mfma_f32_16x16x32_bf16(Bt[n][k], At[m][k], acc[ai][bj][m][n], 0, 0, 0); __builtin_amdgcn_s_setprio(0); } while (0)
; #define PG8_WAIT_V(n) asm volatile("s_waitcnt vmcnt(" #n ")" ::: "memory")
; #define PG8_WAIT_L(n) asm volatile("s_waitcnt lgkmcnt(" #n ")" ::: "memory")
; #define PG8_BAR __builtin_amdgcn_s_barrier()
; #define PG8_SCHED __builtin_amdgcn_sched_barrier(0)
; template <class Epi, class Sched>
; DI void gemm_phase(PG8_LAS unsigned char* lds, const Gemm g, const Sched& S, const Epi& E) {
;     ...
;       PG8_WAIT_V(8); PG8_WAIT_L(0); PG8_BAR; PG8_MMA(1, 0, At, B0); PG8_MMA(1, 1, At, B1); PG8_BAR; PG8_SCHED;
;       PG8_LDB(B0, 1, 0); PG8_LDB(B1, 1, 1); PG8_SCHED; PG8_LDA(At, 1, 0); PG8_STAGE(PG8_SA(0, 1), a2 + hstepA, voffA);
;       PG8_WAIT_V(8); PG8_WAIT_L(0); PG8_BAR; PG8_MMA(0, 0, At, B0); PG8_MMA(0, 1, At, B1); PG8_BAR; PG8_SCHED;
;       PG8_LDA(At, 1, 1); PG8_STAGE(PG8_SB(1, 0), b3, voffB); PG8_STAGE(PG8_SB(1, 1), b3 + hstepB, voffB); PG8_STAGE(PG8_SA(1, 0), a3, voffA);
	s_setprio 1
	s_waitcnt lgkmcnt(0)
	v_mfma_f32_16x16x32_bf16 v[60:63], v[128:131], v[182:185], v[60:63]
	v_mfma_f32_16x16x32_bf16 v[56:59], v[150:153], v[182:185], v[56:59]
	v_mfma_f32_16x16x32_bf16 v[44:47], v[128:131], v[190:193], v[44:47]
	v_mfma_f32_16x16x32_bf16 v[40:43], v[150:153], v[190:193], v[40:43]
	v_mfma_f32_16x16x32_bf16 v[28:31], v[128:131], v[198:201], v[28:31]
	v_mfma_f32_16x16x32_bf16 v[24:27], v[150:153], v[198:201], v[24:27]
	v_mfma_f32_16x16x32_bf16 v[12:15], v[128:131], v[206:209], v[12:15]
	v_mfma_f32_16x16x32_bf16 v[8:11], v[150:153], v[206:209], v[8:11]
	v_mfma_f32_16x16x32_bf16 v[60:63], v[132:135], v[186:189], v[60:63]
	v_mfma_f32_16x16x32_bf16 v[56:59], v[162:165], v[186:189], v[56:59]
	v_mfma_f32_16x16x32_bf16 v[44:47], v[132:135], v[194:197], v[44:47]
	v_mfma_f32_16x16x32_bf16 v[40:43], v[162:165], v[194:197], v[40:43]
	v_mfma_f32_16x16x32_bf16 v[28:31], v[132:135], v[202:205], v[28:31]
	v_mfma_f32_16x16x32_bf16 v[24:27], v[162:165], v[202:205], v[24:27]
	v_mfma_f32_16x16x32_bf16 v[12:15], v[132:135], v[214:217], v[12:15]
	v_mfma_f32_16x16x32_bf16 v[8:11], v[162:165], v[214:217], v[8:11]
	s_setprio 0
	s_setprio 1
	v_mfma_f32_16x16x32_bf16 v[52:55], v[166:169], v[182:185], v[52:55]
	v_mfma_f32_16x16x32_bf16 v[48:51], v[174:177], v[182:185], v[48:51]
	v_mfma_f32_16x16x32_bf16 v[36:39], v[166:169], v[190:193], v[36:39]
	v_mfma_f32_16x16x32_bf16 v[32:35], v[174:177], v[190:193], v[32:35]
	v_mfma_f32_16x16x32_bf16 v[20:23], v[166:169], v[198:201], v[20:23]
	v_mfma_f32_16x16x32_bf16 v[16:19], v[174:177], v[198:201], v[16:19]
	v_mfma_f32_16x16x32_bf16 v[4:7], v[166:169], v[206:209], v[4:7]
	v_mfma_f32_16x16x32_bf16 v[0:3], v[174:177], v[206:209], v[0:3]
	v_mfma_f32_16x16x32_bf16 v[52:55], v[170:173], v[186:189], v[52:55]
	v_mfma_f32_16x16x32_bf16 v[48:51], v[178:181], v[186:189], v[48:51]
	v_mfma_f32_16x16x32_bf16 v[36:39], v[170:173], v[194:197], v[36:39]
	v_mfma_f32_16x16x32_bf16 v[32:35], v[178:181], v[194:197], v[32:35]
	v_mfma_f32_16x16x32_bf16 v[20:23], v[170:173], v[202:205], v[20:23]
	v_mfma_f32_16x16x32_bf16 v[16:19], v[178:181], v[202:205], v[16:19]
	v_mfma_f32_16x16x32_bf16 v[4:7], v[170:173], v[214:217], v[4:7]
	v_mfma_f32_16x16x32_bf16 v[0:3], v[178:181], v[214:217], v[0:3]
	s_setprio 0
	s_barrier
	s_mov_b32 s17, 0x18000
	s_addk_i32 s17, 0x110
	v_add_u32_e32 v161, s17, v155
	ds_read_b128 v[128:131], v161
	ds_read_b128 v[132:135], v161 offset:1024
	ds_read_b128 v[150:153], v161 offset:2048
	ds_read_b128 v[162:165], v161 offset:3072
	ds_read_b128 v[166:169], v160
	ds_read_b128 v[170:173], v160 offset:1024
	ds_read_b128 v[174:177], v160 offset:2048
	ds_read_b128 v[178:181], v160 offset:3072
	s_add_u32 s56, s66, 0x40000
	s_addc_u32 s57, s67, 0
	s_mov_b32 m0, s19
	v_lshl_add_u64 v[224:225], s[56:57], 0, v[136:137]
	ds_read_b128 v[182:185], v158 offset:32768
	ds_read_b128 v[186:189], v158 offset:33792
	ds_read_b128 v[190:193], v158 offset:34816
	ds_read_b128 v[194:197], v158 offset:35840
	ds_read_b128 v[198:201], v158 offset:36864
	ds_read_b128 v[202:205], v158 offset:37888
	ds_read_b128 v[206:209], v158 offset:38912
	ds_read_b128 v[214:217], v158 offset:39936
	global_load_lds_dwordx4 v[224:225], off
	v_lshl_add_u64 v[224:225], s[56:57], 0, v[140:141]
	s_mov_b32 m0, s54
	s_nop 0
	global_load_lds_dwordx4 v[224:225], off
	s_waitcnt vmcnt(8)
	s_waitcnt lgkmcnt(0)
	s_barrier
	s_setprio 1
	s_waitcnt lgkmcnt(0)
	v_mfma_f32_16x16x32_bf16 v[124:127], v[128:131], v[182:185], v[124:127]
	v_mfma_f32_16x16x32_bf16 v[120:123], v[150:153], v[182:185], v[120:123]
	v_mfma_f32_16x16x32_bf16 v[108:111], v[128:131], v[190:193], v[108:111]
	v_mfma_f32_16x16x32_bf16 v[104:107], v[150:153], v[190:193], v[104:107]
	v_mfma_f32_16x16x32_bf16 v[92:95], v[128:131], v[198:201], v[92:95]
	v_mfma_f32_16x16x32_bf16 v[88:91], v[150:153], v[198:201], v[88:91]
	v_mfma_f32_16x16x32_bf16 v[76:79], v[128:131], v[206:209], v[76:79]
	v_mfma_f32_16x16x32_bf16 v[72:75], v[150:153], v[206:209], v[72:75]
	v_mfma_f32_16x16x32_bf16 v[124:127], v[132:135], v[186:189], v[124:127]
	v_mfma_f32_16x16x32_bf16 v[120:123], v[162:165], v[186:189], v[120:123]
	v_mfma_f32_16x16x32_bf16 v[108:111], v[132:135], v[194:197], v[108:111]
	v_mfma_f32_16x16x32_bf16 v[104:107], v[162:165], v[194:197], v[104:107]
	v_mfma_f32_16x16x32_bf16 v[92:95], v[132:135], v[202:205], v[92:95]
	v_mfma_f32_16x16x32_bf16 v[88:91], v[162:165], v[202:205], v[88:91]
	v_mfma_f32_16x16x32_bf16 v[76:79], v[132:135], v[214:217], v[76:79]
	v_mfma_f32_16x16x32_bf16 v[72:75], v[162:165], v[214:217], v[72:75]
	s_setprio 0
	s_setprio 1
	v_mfma_f32_16x16x32_bf16 v[116:119], v[166:169], v[182:185], v[116:119]
	v_mfma_f32_16x16x32_bf16 v[112:115], v[174:177], v[182:185], v[112:115]
	v_mfma_f32_16x16x32_bf16 v[100:103], v[166:169], v[190:193], v[100:103]
	v_mfma_f32_16x16x32_bf16 v[96:99], v[174:177], v[190:193], v[96:99]
	v_mfma_f32_16x16x32_bf16 v[84:87], v[166:169], v[198:201], v[84:87]
	v_mfma_f32_16x16x32_bf16 v[80:83], v[174:177], v[198:201], v[80:83]
	v_mfma_f32_16x16x32_bf16 v[68:71], v[166:169], v[206:209], v[68:71]
	v_mfma_f32_16x16x32_bf16 v[64:67], v[174:177], v[206:209], v[64:67]
	v_mfma_f32_16x16x32_bf16 v[116:119], v[170:173], v[186:189], v[116:119]
	v_mfma_f32_16x16x32_bf16 v[112:115], v[178:181], v[186:189], v[112:115]
	v_mfma_f32_16x16x32_bf16 v[100:103], v[170:173], v[194:197], v[100:103]
	v_mfma_f32_16x16x32_bf16 v[96:99], v[178:181], v[194:197], v[96:99]
	v_mfma_f32_16x16x32_bf16 v[84:87], v[170:173], v[202:205], v[84:87]
	v_mfma_f32_16x16x32_bf16 v[80:83], v[178:181], v[202:205], v[80:83]
	v_mfma_f32_16x16x32_bf16 v[68:71], v[170:173], v[214:217], v[68:71]
	v_mfma_f32_16x16x32_bf16 v[64:67], v[178:181], v[214:217], v[64:67]
	s_setprio 0
	s_barrier
; #define PG8_STAGE(bufoff, gbase, voff) do { _Pragma("unroll") for (int _i = 0; _i < 2; ++_i) \
;     __builtin_amdgcn_global_load_lds((const unsigned*)((const char*)(gbase) + (voff)[_i]), (PG8_LAS unsigned*)(lds + (bufoff) + ldsw + _i * 8192), 16, 0, 0); } while (0)
; #define PG8_LDA(dst, b, h) do { _Pragma("unroll") for (int m = 0; m < 4; ++m) _Pragma("unroll") for (int k = 0; k < 2; ++k) dst[m][k] = *(const PG8_LAS bf16x8*)(lds + PG8_SA(b, h) + aoff + m * 2048 + k * 1024); } while (0)
; #define PG8_MMA(ai, bj, At, Bt) do { __builtin_amdgcn_s_setprio(1); _Pragma("unroll") for (int m = 0; m < 4; ++m) _Pragma("unroll") for (int n = 0; n < 2; ++n) _Pragma("unroll") for (int k = 0; k < 2; ++k) \
;     acc[ai][bj][m][n] = __builtin_amdgcn_mfma_f32_16x16x32_bf16(Bt[n][k], At[m][k], acc[ai][bj][m][n], 0, 0, 0); __builtin_amdgcn_s_setprio(0); } while (0)
; #define PG8_WAIT_V(n) asm volatile("s_waitcnt vmcnt(" #n ")" ::: "memory")
; #define PG8_WAIT_L(n) asm volatile("s_waitcnt lgkmcnt(" #n ")" ::: "memory")
; #define PG8_BAR __builtin_amdgcn_s_barrier()
; #define PG8_SCHED __builtin_amdgcn_sched_barrier(0)
;   DI void operator()(const f32x4 (&acc)[2][2][4][2], const Unit& u, int wr, int wc, int fr, int fq) const {
;     ...
;     RES_LD(0)
; #pragma unroll
;     for (int i = 0; i < 8; ++i) {
;       const int ai = i >> 2, m = i & 3;
;       if (i + 1 < 8) RES_LD(i + 1)
; template <class Epi, class Sched>
; DI void gemm_phase(PG8_LAS unsigned char* lds, const Gemm g, const Sched& S, const Epi& E) {
;     ...
;       PG8_LDA(At, 1, 1); PG8_STAGE(PG8_SB(1, 0), b3, voffB); PG8_STAGE(PG8_SB(1, 1), b3 + hstepB, voffB); PG8_STAGE(PG8_SA(1, 0), a3, voffA);
;       PG8_WAIT_V(8); PG8_WAIT_L(0); PG8_BAR; PG8_MMA(1, 0, At, B0); PG8_MMA(1, 1, At, B1); PG8_BAR; PG8_SCHED;
;     }
;     if (wr == 0) PG8_BAR;
	s_add_i32 s17, s17, s16
	v_lshl_add_u64 v[210:211], v[210:211], 0, s[6:7]
	s_mov_b32 m0, s17
	ds_read_b128 v[182:185], v158 offset:49152
	ds_read_b128 v[186:189], v158 offset:50176
	ds_read_b128 v[190:193], v158 offset:51200
	ds_read_b128 v[194:197], v158 offset:52224
	ds_read_b128 v[198:201], v158 offset:53248
	ds_read_b128 v[202:205], v158 offset:54272
	ds_read_b128 v[206:209], v158 offset:55296
	ds_read_b128 v[214:217], v158 offset:56320
	global_load_lds_dwordx4 v[210:211], off
	s_add_i32 m0, s17, 0x2000
	s_add_u32 s56, s64, 0x40080
	v_lshl_add_u64 v[210:211], v[218:219], 0, s[6:7]
	s_addc_u32 s57, s65, 0
	s_add_i32 s17, s71, s16
	global_load_lds_dwordx4 v[210:211], off
	v_lshl_add_u64 v[210:211], s[56:57], 0, v[138:139]
	s_mov_b32 m0, s17
	s_nop 0
	global_load_lds_dwordx4 v[210:211], off
	v_lshl_add_u64 v[210:211], s[56:57], 0, v[142:143]
	s_add_i32 m0, s17, 0x2000
	s_nop 0
	global_load_lds_dwordx4 v[210:211], off
	v_lshl_add_u64 v[210:211], v[220:221], 0, s[6:7]
	s_mov_b32 m0, s5
	s_nop 0
	global_load_lds_dwordx4 v[210:211], off
	v_lshl_add_u64 v[210:211], v[222:223], 0, s[6:7]
	s_mov_b32 m0, s55
	s_nop 0
	global_load_lds_dwordx4 v[210:211], off
	s_waitcnt vmcnt(8)
	s_waitcnt lgkmcnt(0)
	s_barrier
	s_setprio 1
	s_waitcnt lgkmcnt(0)
	v_mfma_f32_16x16x32_bf16 v[60:63], v[128:131], v[182:185], v[60:63]
	v_mfma_f32_16x16x32_bf16 v[56:59], v[150:153], v[182:185], v[56:59]
	v_mfma_f32_16x16x32_bf16 v[44:47], v[128:131], v[190:193], v[44:47]
	v_mfma_f32_16x16x32_bf16 v[40:43], v[150:153], v[190:193], v[40:43]
	v_mfma_f32_16x16x32_bf16 v[28:31], v[128:131], v[198:201], v[28:31]
	v_mfma_f32_16x16x32_bf16 v[24:27], v[150:153], v[198:201], v[24:27]
	v_mfma_f32_16x16x32_bf16 v[12:15], v[128:131], v[206:209], v[12:15]
	v_mfma_f32_16x16x32_bf16 v[8:11], v[150:153], v[206:209], v[8:11]
	v_mfma_f32_16x16x32_bf16 v[60:63], v[132:135], v[186:189], v[60:63]
	v_mfma_f32_16x16x32_bf16 v[56:59], v[162:165], v[186:189], v[56:59]
	v_mfma_f32_16x16x32_bf16 v[44:47], v[132:135], v[194:197], v[44:47]
	v_mfma_f32_16x16x32_bf16 v[40:43], v[162:165], v[194:197], v[40:43]
	v_mfma_f32_16x16x32_bf16 v[28:31], v[132:135], v[202:205], v[28:31]
	v_mfma_f32_16x16x32_bf16 v[24:27], v[162:165], v[202:205], v[24:27]
	v_mfma_f32_16x16x32_bf16 v[12:15], v[132:135], v[214:217], v[12:15]
	v_mfma_f32_16x16x32_bf16 v[8:11], v[162:165], v[214:217], v[8:11]
	s_setprio 0
	s_setprio 1
	v_mfma_f32_16x16x32_bf16 v[52:55], v[166:169], v[182:185], v[52:55]
	v_mfma_f32_16x16x32_bf16 v[48:51], v[174:177], v[182:185], v[48:51]
	v_mfma_f32_16x16x32_bf16 v[36:39], v[166:169], v[190:193], v[36:39]
	v_mfma_f32_16x16x32_bf16 v[32:35], v[174:177], v[190:193], v[32:35]
	v_mfma_f32_16x16x32_bf16 v[20:23], v[166:169], v[198:201], v[20:23]
	v_mfma_f32_16x16x32_bf16 v[16:19], v[174:177], v[198:201], v[16:19]
	v_mfma_f32_16x16x32_bf16 v[4:7], v[166:169], v[206:209], v[4:7]
	v_mfma_f32_16x16x32_bf16 v[0:3], v[174:177], v[206:209], v[0:3]
	v_mfma_f32_16x16x32_bf16 v[52:55], v[170:173], v[186:189], v[52:55]
	v_mfma_f32_16x16x32_bf16 v[48:51], v[178:181], v[186:189], v[48:51]
	v_mfma_f32_16x16x32_bf16 v[36:39], v[170:173], v[194:197], v[36:39]
	v_mfma_f32_16x16x32_bf16 v[32:35], v[178:181], v[194:197], v[32:35]
	v_mfma_f32_16x16x32_bf16 v[20:23], v[170:173], v[202:205], v[20:23]
	v_mfma_f32_16x16x32_bf16 v[16:19], v[178:181], v[202:205], v[16:19]
	v_mfma_f32_16x16x32_bf16 v[4:7], v[170:173], v[214:217], v[4:7]
	v_mfma_f32_16x16x32_bf16 v[0:3], v[178:181], v[214:217], v[0:3]
	s_setprio 0
	s_barrier
	s_add_i32 s75, s75, 2
	s_add_u32 s62, s62, 0x100
	s_addc_u32 s63, s63, 0
	s_add_u32 s73, s73, 0x100
	s_addc_u32 s74, s74, 0
	s_cmp_gt_u32 s75, 13
	s_cbranch_scc0 .LBB0_1300
	v_lshl_add_u32 v152, s60, 8, v154
	v_ashrrev_i32_e32 v153, 31, v152
	s_lshl_b32 s56, s58, 8
	v_lshlrev_b64 v[128:129], 11, v[152:153]
	s_ashr_i32 s57, s56, 31
	v_lshl_add_u64 v[128:129], s[50:51], 0, v[128:129]
	v_lshl_add_u64 v[128:129], s[56:57], 1, v[128:129]
	v_lshl_add_u64 v[128:129], v[128:129], 0, s[10:11]
	v_lshl_add_u64 v[150:151], v[128:129], 0, v[144:145]
	s_mov_b32 s17, 0x8000
	v_add_co_u32_e32 v128, vcc, s17, v150
	global_load_dwordx4 v[164:167], v[150:151], off
	global_load_dwordx4 v[168:171], v[150:151], off offset:256
	v_addc_co_u32_e32 v129, vcc, 0, v151, vcc
	global_load_dwordx4 v[132:135], v[128:129], off
	s_nop 0
	global_load_dwordx4 v[128:131], v[128:129], off offset:256
	s_and_b64 vcc, exec, s[8:9]
	s_cbranch_vccz .LBB0_1303
	s_barrier
; DI unsigned pack2(float a, float b) { bf2_t v = __builtin_convertvector((f32x2){a, b}, bf2_t); return __builtin_bit_cast(unsigned, v); }
;   DI void operator()(const f32x4 (&acc)[2][2][4][2], const Unit& u, int wr, int wc, int fr, int fq) const {
;     ...
;     for (int i = 0; i < 8; ++i) {
;       const int ai = i >> 2, m = i & 3;
;       if (i + 1 < 8) RES_LD(i + 1)
;       __builtin_amdgcn_sched_barrier(0);
;       const size_t idx = base + (size_t)(ai * HALF + m * 16) * DM;
;       float ssum = 0.f;
; #pragma unroll
;       for (int bj = 0; bj < 2; ++bj) {
;         f32x4 x0, x1;
;         if (FIRST) { x0 = xv[i & 1][2 * bj]; x1 = xv[i & 1][2 * bj + 1]; }
;         else {
;           const u32x4 hw = xh[i & 1][bj];
;           x0 = (f32x4){__uint_as_float(hw.x << 16), __uint_as_float(hw.x & 0xffff0000u), __uint_as_float(hw.y << 16), __uint_as_float(hw.y & 0xffff0000u)};
;           x1 = (f32x4){__uint_as_float(hw.z << 16), __uint_as_float(hw.z & 0xffff0000u), __uint_as_float(hw.w << 16), __uint_as_float(hw.w & 0xffff0000u)};
;         }
;         const f32x4 v0 = x0 + acc[ai][bj][m][0], v1 = x1 + acc[ai][bj][m][1];
;         if (LAST) { *(f32x4*)(xout32 + idx + bj * HALF) = v0; *(f32x4*)(xout32 + idx + bj * HALF + 4) = v1; }
;         else {
;           ssum += (v0[0] * v0[0] + v0[1] * v0[1]) + (v0[2] * v0[2] + v0[3] * v0[3]) + (v1[0] * v1[0] + v1[1] * v1[1]) + (v1[2] * v1[2] + v1[3] * v1[3]);
;           u32x4 w; w.x = pack2(v0[0], v0[1]); w.y = pack2(v0[2], v0[3]); w.z = pack2(v1[0], v1[1]); w.w = pack2(v1[2], v1[3]);
;           *(u32x4*)(xb + idx + bj * HALF) = w;
;         }
;       }
;       if (!LAST) {
;         ssum += __shfl_xor(ssum, 16); ssum += __shfl_xor(ssum, 32);
;         if (fq == 0) ps_out[(size_t)(row0 + ai * HALF + m * 16) * 16 + u.pn * 4 + wc] = ssum;
.LBB0_1303:
	v_and_b32_e32 v162, 64, v159
	v_xor_b32_e32 v161, 16, v159
	v_add_u32_e32 v163, 64, v162
	v_cmp_lt_i32_e32 vcc, v161, v163
	s_lshl_b32 s58, s58, 2
	s_ashr_i32 s59, s58, 31
	v_cndmask_b32_e32 v161, v159, v161, vcc
	v_lshlrev_b32_e32 v162, 2, v161
	v_xor_b32_e32 v161, 32, v159
	v_cmp_lt_i32_e32 vcc, v161, v163
	s_nop 1
	v_cndmask_b32_e32 v161, v159, v161, vcc
	v_lshlrev_b32_e32 v161, 2, v161
	s_waitcnt vmcnt(0)
	v_lshlrev_b32_e32 v172, 16, v164
	v_and_b32_e32 v173, 0xffff0000, v164
	v_lshlrev_b32_e32 v164, 16, v165
	v_and_b32_e32 v165, 0xffff0000, v165
	v_lshlrev_b32_e32 v174, 16, v166
	v_and_b32_e32 v175, 0xffff0000, v166
	v_lshlrev_b32_e32 v166, 16, v167
	v_and_b32_e32 v167, 0xffff0000, v167
	v_pk_add_f32 v[126:127], v[126:127], v[164:165]
	v_pk_add_f32 v[124:125], v[124:125], v[172:173]
	v_pk_add_f32 v[164:165], v[122:123], v[166:167]
	v_pk_add_f32 v[122:123], v[120:121], v[174:175]
	v_mul_f32_e32 v120, v125, v125
	v_mul_f32_e32 v121, v127, v127
	v_fmac_f32_e32 v120, v124, v124
	v_fmac_f32_e32 v121, v126, v126
	v_add_f32_e32 v120, v120, v121
	v_mul_f32_e32 v121, v123, v123
	v_fmac_f32_e32 v121, v122, v122
	v_add_f32_e32 v120, v121, v120
	v_mul_f32_e32 v121, v165, v165
	v_fmac_f32_e32 v121, v164, v164
	v_add_f32_e32 v163, v121, v120
	v_cvt_pk_bf16_f32 v120, v124, v125
	v_cvt_pk_bf16_f32 v121, v126, v127
	v_lshlrev_b32_e32 v124, 16, v168
	v_and_b32_e32 v125, 0xffff0000, v168
	v_lshlrev_b32_e32 v126, 16, v169
	v_and_b32_e32 v127, 0xffff0000, v169
	v_lshlrev_b32_e32 v166, 16, v171
	v_and_b32_e32 v167, 0xffff0000, v171
	v_pk_add_f32 v[118:119], v[118:119], v[126:127]
	v_pk_add_f32 v[116:117], v[116:117], v[124:125]
	v_cvt_pk_bf16_f32 v122, v122, v123
	v_cvt_pk_bf16_f32 v123, v164, v165
	v_lshlrev_b32_e32 v164, 16, v170
	v_and_b32_e32 v165, 0xffff0000, v170
	v_pk_add_f32 v[124:125], v[114:115], v[166:167]
	v_mul_f32_e32 v114, v117, v117
	v_mul_f32_e32 v115, v119, v119
	v_pk_add_f32 v[112:113], v[112:113], v[164:165]
	v_fmac_f32_e32 v114, v116, v116
	v_fmac_f32_e32 v115, v118, v118
	v_add_f32_e32 v114, v114, v115
	v_mul_f32_e32 v115, v113, v113
	v_fmac_f32_e32 v115, v112, v112
	v_add_f32_e32 v114, v115, v114
	v_mul_f32_e32 v115, v125, v125
	v_fmac_f32_e32 v115, v124, v124
	v_add_f32_e32 v114, v115, v114
	v_add_f32_e32 v126, v163, v114
	ds_bpermute_b32 v127, v162, v126
	v_cvt_pk_bf16_f32 v114, v116, v117
	v_cvt_pk_bf16_f32 v116, v112, v113
	v_cvt_pk_bf16_f32 v115, v118, v119
	v_cvt_pk_bf16_f32 v117, v124, v125
	s_waitcnt lgkmcnt(0)
	v_add_f32_e32 v112, v126, v127
	ds_bpermute_b32 v113, v161, v112
	global_store_dwordx4 v[150:151], v[114:117], off offset:256
	global_store_dwordx4 v[150:151], v[120:123], off
	s_nop 0
	v_lshlrev_b64 v[114:115], 6, v[152:153]
	v_lshl_add_u64 v[120:121], s[96:97], 0, v[114:115]
	s_and_saveexec_b64 s[60:61], s[2:3]
	s_cbranch_execz .LBB0_1305
	s_waitcnt lgkmcnt(0)
	v_add_f32_e32 v114, v112, v113
	v_lshl_add_u64 v[112:113], s[58:59], 2, v[120:121]
	s_lshl_b32 s56, s4, 2
	s_mov_b32 s57, s11
	v_lshl_add_u64 v[112:113], v[112:113], 0, s[56:57]
	global_store_dword v[112:113], v114, off

; #define PG8_STAGE(bufoff, gbase, voff) do { _Pragma("unroll") for (int _i = 0; _i < 2; ++_i) \
;     __builtin_amdgcn_global_load_lds((const unsigned*)((const char*)(gbase) + (voff)[_i]), (PG8_LAS unsigned*)(lds + (bufoff) + ldsw + _i * 8192), 16, 0, 0); } while (0)
; #define PG8_LDA(dst, b, h) do { _Pragma("unroll") for (int m = 0; m < 4; ++m) _Pragma("unroll") for (int k = 0; k < 2; ++k) dst[m][k] = *(const PG8_LAS bf16x8*)(lds + PG8_SA(b, h) + aoff + m * 2048 + k * 1024); } while (0)
; #define PG8_LDB(dst, b, h) do { _Pragma("unroll") for (int n = 0; n < 2; ++n) _Pragma("unroll") for (int k = 0; k < 2; ++k) dst[n][k] = *(const PG8_LAS bf16x8*)(lds + PG8_SB(b, h) + boff + n * 2048 + k * 1024); } while (0)
; #define PG8_MMA(ai, bj, At, Bt) do { __builtin_amdgcn_s_setprio(1); _Pragma("unroll") for (int m = 0; m < 4; ++m) _Pragma("unroll") for (int n = 0; n < 2; ++n) _Pragma("unroll") for (int k = 0; k < 2; ++k) \
;     acc[ai][bj][m][n] = __builtin_amdgcn_mfma_f32_16x16x32_bf16(Bt[n][k], At[m][k], acc[ai][bj][m][n], 0, 0, 0); __builtin_amdgcn_s_setprio(0); } while (0)
; #define PG8_WAIT_V(n) asm volatile("s_waitcnt vmcnt(" #n ")" ::: "memory")
; #define PG8_WAIT_L(n) asm volatile("s_waitcnt lgkmcnt(" #n ")" ::: "memory")
; #define PG8_BAR __builtin_amdgcn_s_barrier()
; #define PG8_SCHED __builtin_amdgcn_sched_barrier(0)
; template <class Epi, class Sched>
; DI void gemm_phase(PG8_LAS unsigned char* lds, const Gemm g, const Sched& S, const Epi& E) {
;     ...
;       PG8_LDB(B0, 0, 0); PG8_LDB(B1, 0, 1); PG8_SCHED; PG8_LDA(At, 0, 0); PG8_STAGE(PG8_SA(1, 1), a1 + hstepA, voffA);
;       PG8_WAIT_V(8); PG8_WAIT_L(0); PG8_BAR; PG8_MMA(0, 0, At, B0); PG8_MMA(0, 1, At, B1); PG8_BAR; PG8_SCHED;
;       PG8_LDA(At, 0, 1); PG8_STAGE(PG8_SB(0, 0), b2, voffB); PG8_STAGE(PG8_SB(0, 1), b2 + hstepB, voffB); PG8_STAGE(PG8_SA(0, 0), a2, voffA);
;       PG8_WAIT_V(8); PG8_WAIT_L(0); PG8_BAR; PG8_MMA(1, 0, At, B0); PG8_MMA(1, 1, At, B1); PG8_BAR; PG8_SCHED;
.LBB0_1384:
	ds_read_b128 v[144:147], v155
	ds_read_b128 v[156:159], v155 offset:1024
	ds_read_b128 v[174:177], v155 offset:2048
	ds_read_b128 v[178:181], v155 offset:3072
	ds_read_b128 v[182:185], v161
	ds_read_b128 v[186:189], v161 offset:1024
	ds_read_b128 v[190:193], v161 offset:2048
	ds_read_b128 v[194:197], v161 offset:3072
	s_add_u32 s30, s2, 0xfffc0080
	s_addc_u32 s31, s3, -1
	s_cmp_eq_u32 s55, 12
	s_cselect_b32 s35, s1, s31
	s_cselect_b32 s34, s23, s30
	s_cselect_b32 s31, s21, s54
	s_cselect_b32 s30, s49, s53
	v_lshl_add_u64 v[148:149], s[2:3], 0, v[140:141]
	s_add_i32 m0, s17, 0xc000
	ds_read_b128 v[198:201], v165
	ds_read_b128 v[202:205], v165 offset:1024
	ds_read_b128 v[206:209], v165 offset:2048
	ds_read_b128 v[214:217], v165 offset:3072
	ds_read_b128 v[218:221], v165 offset:4096
	ds_read_b128 v[222:225], v165 offset:5120
	ds_read_b128 v[226:229], v165 offset:6144
	ds_read_b128 v[230:233], v165 offset:7168
	global_load_lds_dwordx4 v[148:149], off
	v_lshl_add_u64 v[148:149], s[2:3], 0, v[142:143]
	s_add_i32 m0, s17, 0xe000
	s_nop 0
	global_load_lds_dwordx4 v[148:149], off
	s_waitcnt vmcnt(8)
	s_waitcnt lgkmcnt(0)
	s_barrier
	s_setprio 1
	s_waitcnt lgkmcnt(0)
	v_mfma_f32_16x16x32_bf16 v[124:127], v[144:147], v[198:201], v[124:127]
	v_mfma_f32_16x16x32_bf16 v[120:123], v[174:177], v[198:201], v[120:123]
	v_mfma_f32_16x16x32_bf16 v[108:111], v[144:147], v[206:209], v[108:111]
	v_mfma_f32_16x16x32_bf16 v[104:107], v[174:177], v[206:209], v[104:107]
	v_mfma_f32_16x16x32_bf16 v[92:95], v[144:147], v[218:221], v[92:95]
	v_mfma_f32_16x16x32_bf16 v[88:91], v[174:177], v[218:221], v[88:91]
	v_mfma_f32_16x16x32_bf16 v[76:79], v[144:147], v[226:229], v[76:79]
	v_mfma_f32_16x16x32_bf16 v[72:75], v[174:177], v[226:229], v[72:75]
	v_mfma_f32_16x16x32_bf16 v[124:127], v[156:159], v[202:205], v[124:127]
	v_mfma_f32_16x16x32_bf16 v[120:123], v[178:181], v[202:205], v[120:123]
	v_mfma_f32_16x16x32_bf16 v[108:111], v[156:159], v[214:217], v[108:111]
	v_mfma_f32_16x16x32_bf16 v[104:107], v[178:181], v[214:217], v[104:107]
	v_mfma_f32_16x16x32_bf16 v[92:95], v[156:159], v[222:225], v[92:95]
	v_mfma_f32_16x16x32_bf16 v[88:91], v[178:181], v[222:225], v[88:91]
	v_mfma_f32_16x16x32_bf16 v[76:79], v[156:159], v[230:233], v[76:79]
	v_mfma_f32_16x16x32_bf16 v[72:75], v[178:181], v[230:233], v[72:75]
	s_setprio 0
	s_setprio 1
	v_mfma_f32_16x16x32_bf16 v[116:119], v[182:185], v[198:201], v[116:119]
	v_mfma_f32_16x16x32_bf16 v[112:115], v[190:193], v[198:201], v[112:115]
	v_mfma_f32_16x16x32_bf16 v[100:103], v[182:185], v[206:209], v[100:103]
	v_mfma_f32_16x16x32_bf16 v[96:99], v[190:193], v[206:209], v[96:99]
	v_mfma_f32_16x16x32_bf16 v[84:87], v[182:185], v[218:221], v[84:87]
	v_mfma_f32_16x16x32_bf16 v[80:83], v[190:193], v[218:221], v[80:83]
	v_mfma_f32_16x16x32_bf16 v[68:71], v[182:185], v[226:229], v[68:71]
	v_mfma_f32_16x16x32_bf16 v[64:67], v[190:193], v[226:229], v[64:67]
	v_mfma_f32_16x16x32_bf16 v[116:119], v[186:189], v[202:205], v[116:119]
	v_mfma_f32_16x16x32_bf16 v[112:115], v[194:197], v[202:205], v[112:115]
	v_mfma_f32_16x16x32_bf16 v[100:103], v[186:189], v[214:217], v[100:103]
	v_mfma_f32_16x16x32_bf16 v[96:99], v[194:197], v[214:217], v[96:99]
	v_mfma_f32_16x16x32_bf16 v[84:87], v[186:189], v[222:225], v[84:87]
	v_mfma_f32_16x16x32_bf16 v[80:83], v[194:197], v[222:225], v[80:83]
	v_mfma_f32_16x16x32_bf16 v[68:71], v[186:189], v[230:233], v[68:71]
	v_mfma_f32_16x16x32_bf16 v[64:67], v[194:197], v[230:233], v[64:67]
	s_setprio 0
	s_barrier
	s_add_i32 s56, s37, s15
	v_lshl_add_u64 v[148:149], s[30:31], 0, v[132:133]
	s_mov_b32 m0, s56
	ds_read_b128 v[198:201], v165 offset:16384
	ds_read_b128 v[202:205], v165 offset:17408
	ds_read_b128 v[206:209], v165 offset:18432
	ds_read_b128 v[214:217], v165 offset:19456
	ds_read_b128 v[218:221], v165 offset:20480
	ds_read_b128 v[222:225], v165 offset:21504
	ds_read_b128 v[226:229], v165 offset:22528
	ds_read_b128 v[230:233], v165 offset:23552
	global_load_lds_dwordx4 v[148:149], off
	s_add_i32 m0, s56, 0x2000
	s_add_u32 s56, s30, 0x40000
	v_lshl_add_u64 v[152:153], s[30:31], 0, v[128:129]
	s_addc_u32 s57, s31, 0
	s_add_i32 s58, s38, s15
	global_load_lds_dwordx4 v[152:153], off
	v_lshl_add_u64 v[162:163], s[56:57], 0, v[132:133]
	s_mov_b32 m0, s58
	v_lshl_add_u64 v[166:167], s[34:35], 0, v[130:131]
	global_load_lds_dwordx4 v[162:163], off
	v_lshl_add_u64 v[162:163], s[56:57], 0, v[128:129]
	s_add_i32 m0, s58, 0x2000
	s_nop 0
	global_load_lds_dwordx4 v[162:163], off
	v_lshl_add_u64 v[162:163], s[34:35], 0, v[134:135]
	s_mov_b32 m0, s17
	s_nop 0
	global_load_lds_dwordx4 v[162:163], off
	s_mov_b32 m0, s4
	s_nop 0
	global_load_lds_dwordx4 v[166:167], off
	s_waitcnt vmcnt(8)
	s_waitcnt lgkmcnt(0)
	s_barrier
; #define PG8_STAGE(bufoff, gbase, voff) do { _Pragma("unroll") for (int _i = 0; _i < 2; ++_i) \
;     __builtin_amdgcn_global_load_lds((const unsigned*)((const char*)(gbase) + (voff)[_i]), (PG8_LAS unsigned*)(lds + (bufoff) + ldsw + _i * 8192), 16, 0, 0); } while (0)
; #define PG8_LDA(dst, b, h) do { _Pragma("unroll") for (int m = 0; m < 4; ++m) _Pragma("unroll") for (int k = 0; k < 2; ++k) dst[m][k] = *(const PG8_LAS bf16x8*)(lds + PG8_SA(b, h) + aoff + m * 2048 + k * 1024); } while (0)
; #define PG8_LDB(dst, b, h) do { _Pragma("unroll") for (int n = 0; n < 2; ++n) _Pragma("unroll") for (int k = 0; k < 2; ++k) dst[n][k] = *(const PG8_LAS bf16x8*)(lds + PG8_SB(b, h) + boff + n * 2048 + k * 1024); } while (0)
; #define PG8_MMA(ai, bj, At, Bt) do { __builtin_amdgcn_s_setprio(1); _Pragma("unroll") for (int m = 0; m < 4; ++m) _Pragma("unroll") for (int n = 0; n < 2; ++n) _Pragma("unroll") for (int k = 0; k < 2; ++k) \
;     acc[ai][bj][m][n] = __builtin_amdgcn_mfma_f32_16x16x32_bf16(Bt[n][k], At[m][k], acc[ai][bj][m][n], 0, 0, 0); __builtin_amdgcn_s_setprio(0); } while (0)
; #define PG8_WAIT_V(n) asm volatile("s_waitcnt vmcnt(" #n ")" ::: "memory")
; #define PG8_WAIT_L(n) asm volatile("s_waitcnt lgkmcnt(" #n ")" ::: "memory")
; #define PG8_BAR __builtin_amdgcn_s_barrier()
; #define PG8_SCHED __builtin_amdgcn_sched_barrier(0)
; template <class Epi, class Sched>
; DI void gemm_phase(PG8_LAS unsigned char* lds, const Gemm g, const Sched& S, const Epi& E) {
;     ...
;       PG8_WAIT_V(8); PG8_WAIT_L(0); PG8_BAR; PG8_MMA(1, 0, At, B0); PG8_MMA(1, 1, At, B1); PG8_BAR; PG8_SCHED;
;       PG8_LDB(B0, 1, 0); PG8_LDB(B1, 1, 1); PG8_SCHED; PG8_LDA(At, 1, 0); PG8_STAGE(PG8_SA(0, 1), a2 + hstepA, voffA);
;       PG8_WAIT_V(8); PG8_WAIT_L(0); PG8_BAR; PG8_MMA(0, 0, At, B0); PG8_MMA(0, 1, At, B1); PG8_BAR; PG8_SCHED;
;       PG8_LDA(At, 1, 1); PG8_STAGE(PG8_SB(1, 0), b3, voffB); PG8_STAGE(PG8_SB(1, 1), b3 + hstepB, voffB); PG8_STAGE(PG8_SA(1, 0), a3, voffA);
;       PG8_WAIT_V(8); PG8_WAIT_L(0); PG8_BAR; PG8_MMA(1, 0, At, B0); PG8_MMA(1, 1, At, B1); PG8_BAR; PG8_SCHED;
	s_setprio 1
	s_waitcnt lgkmcnt(0)
	v_mfma_f32_16x16x32_bf16 v[60:63], v[144:147], v[198:201], v[60:63]
	v_mfma_f32_16x16x32_bf16 v[56:59], v[174:177], v[198:201], v[56:59]
	v_mfma_f32_16x16x32_bf16 v[44:47], v[144:147], v[206:209], v[44:47]
	v_mfma_f32_16x16x32_bf16 v[40:43], v[174:177], v[206:209], v[40:43]
	v_mfma_f32_16x16x32_bf16 v[28:31], v[144:147], v[218:221], v[28:31]
	v_mfma_f32_16x16x32_bf16 v[24:27], v[174:177], v[218:221], v[24:27]
	v_mfma_f32_16x16x32_bf16 v[12:15], v[144:147], v[226:229], v[12:15]
	v_mfma_f32_16x16x32_bf16 v[8:11], v[174:177], v[226:229], v[8:11]
	v_mfma_f32_16x16x32_bf16 v[60:63], v[156:159], v[202:205], v[60:63]
	v_mfma_f32_16x16x32_bf16 v[56:59], v[178:181], v[202:205], v[56:59]
	v_mfma_f32_16x16x32_bf16 v[44:47], v[156:159], v[214:217], v[44:47]
	v_mfma_f32_16x16x32_bf16 v[40:43], v[178:181], v[214:217], v[40:43]
	v_mfma_f32_16x16x32_bf16 v[28:31], v[156:159], v[222:225], v[28:31]
	v_mfma_f32_16x16x32_bf16 v[24:27], v[178:181], v[222:225], v[24:27]
	v_mfma_f32_16x16x32_bf16 v[12:15], v[156:159], v[230:233], v[12:15]
	v_mfma_f32_16x16x32_bf16 v[8:11], v[178:181], v[230:233], v[8:11]
	s_setprio 0
	s_setprio 1
	v_mfma_f32_16x16x32_bf16 v[52:55], v[182:185], v[198:201], v[52:55]
	v_mfma_f32_16x16x32_bf16 v[48:51], v[190:193], v[198:201], v[48:51]
	v_mfma_f32_16x16x32_bf16 v[36:39], v[182:185], v[206:209], v[36:39]
	v_mfma_f32_16x16x32_bf16 v[32:35], v[190:193], v[206:209], v[32:35]
	v_mfma_f32_16x16x32_bf16 v[20:23], v[182:185], v[218:221], v[20:23]
	v_mfma_f32_16x16x32_bf16 v[16:19], v[190:193], v[218:221], v[16:19]
	v_mfma_f32_16x16x32_bf16 v[4:7], v[182:185], v[226:229], v[4:7]
	v_mfma_f32_16x16x32_bf16 v[0:3], v[190:193], v[226:229], v[0:3]
	v_mfma_f32_16x16x32_bf16 v[52:55], v[186:189], v[202:205], v[52:55]
	v_mfma_f32_16x16x32_bf16 v[48:51], v[194:197], v[202:205], v[48:51]
	v_mfma_f32_16x16x32_bf16 v[36:39], v[186:189], v[214:217], v[36:39]
	v_mfma_f32_16x16x32_bf16 v[32:35], v[194:197], v[214:217], v[32:35]
	v_mfma_f32_16x16x32_bf16 v[20:23], v[186:189], v[222:225], v[20:23]
	v_mfma_f32_16x16x32_bf16 v[16:19], v[194:197], v[222:225], v[16:19]
	v_mfma_f32_16x16x32_bf16 v[4:7], v[186:189], v[230:233], v[4:7]
	v_mfma_f32_16x16x32_bf16 v[0:3], v[194:197], v[230:233], v[0:3]
	s_setprio 0
	s_barrier
	ds_read_b128 v[144:147], v171
	ds_read_b128 v[156:159], v171 offset:1024
	ds_read_b128 v[174:177], v171 offset:2048
	ds_read_b128 v[178:181], v171 offset:3072
	ds_read_b128 v[182:185], v173
	ds_read_b128 v[186:189], v173 offset:1024
	ds_read_b128 v[190:193], v173 offset:2048
	ds_read_b128 v[194:197], v173 offset:3072
	s_add_u32 s34, s34, 0x40000
	s_addc_u32 s35, s35, 0
	s_mov_b32 m0, s5
	v_lshl_add_u64 v[210:211], s[34:35], 0, v[134:135]
	ds_read_b128 v[198:201], v165 offset:32768
	ds_read_b128 v[202:205], v165 offset:33792
	ds_read_b128 v[206:209], v165 offset:34816
	ds_read_b128 v[214:217], v165 offset:35840
	ds_read_b128 v[218:221], v165 offset:36864
	ds_read_b128 v[222:225], v165 offset:37888
	ds_read_b128 v[226:229], v165 offset:38912
	ds_read_b128 v[230:233], v165 offset:39936
	global_load_lds_dwordx4 v[210:211], off
	v_lshl_add_u64 v[210:211], s[34:35], 0, v[130:131]
	s_mov_b32 m0, s19
	s_nop 0
	global_load_lds_dwordx4 v[210:211], off
	s_waitcnt vmcnt(8)
	s_waitcnt lgkmcnt(0)
	s_barrier
	s_setprio 1
	s_waitcnt lgkmcnt(0)
	v_mfma_f32_16x16x32_bf16 v[124:127], v[144:147], v[198:201], v[124:127]
	v_mfma_f32_16x16x32_bf16 v[120:123], v[174:177], v[198:201], v[120:123]
	v_mfma_f32_16x16x32_bf16 v[108:111], v[144:147], v[206:209], v[108:111]
	v_mfma_f32_16x16x32_bf16 v[104:107], v[174:177], v[206:209], v[104:107]
	v_mfma_f32_16x16x32_bf16 v[92:95], v[144:147], v[218:221], v[92:95]
	v_mfma_f32_16x16x32_bf16 v[88:91], v[174:177], v[218:221], v[88:91]
	v_mfma_f32_16x16x32_bf16 v[76:79], v[144:147], v[226:229], v[76:79]
	v_mfma_f32_16x16x32_bf16 v[72:75], v[174:177], v[226:229], v[72:75]
	v_mfma_f32_16x16x32_bf16 v[124:127], v[156:159], v[202:205], v[124:127]
	v_mfma_f32_16x16x32_bf16 v[120:123], v[178:181], v[202:205], v[120:123]
	v_mfma_f32_16x16x32_bf16 v[108:111], v[156:159], v[214:217], v[108:111]
	v_mfma_f32_16x16x32_bf16 v[104:107], v[178:181], v[214:217], v[104:107]
	v_mfma_f32_16x16x32_bf16 v[92:95], v[156:159], v[222:225], v[92:95]
	v_mfma_f32_16x16x32_bf16 v[88:91], v[178:181], v[222:225], v[88:91]
	v_mfma_f32_16x16x32_bf16 v[76:79], v[156:159], v[230:233], v[76:79]
	v_mfma_f32_16x16x32_bf16 v[72:75], v[178:181], v[230:233], v[72:75]
	s_setprio 0
	s_setprio 1
	v_mfma_f32_16x16x32_bf16 v[116:119], v[182:185], v[198:201], v[116:119]
	v_mfma_f32_16x16x32_bf16 v[112:115], v[190:193], v[198:201], v[112:115]
	v_mfma_f32_16x16x32_bf16 v[100:103], v[182:185], v[206:209], v[100:103]
	v_mfma_f32_16x16x32_bf16 v[96:99], v[190:193], v[206:209], v[96:99]
	v_mfma_f32_16x16x32_bf16 v[84:87], v[182:185], v[218:221], v[84:87]
	v_mfma_f32_16x16x32_bf16 v[80:83], v[190:193], v[218:221], v[80:83]
	v_mfma_f32_16x16x32_bf16 v[68:71], v[182:185], v[226:229], v[68:71]
	v_mfma_f32_16x16x32_bf16 v[64:67], v[190:193], v[226:229], v[64:67]
	v_mfma_f32_16x16x32_bf16 v[116:119], v[186:189], v[202:205], v[116:119]
	v_mfma_f32_16x16x32_bf16 v[112:115], v[194:197], v[202:205], v[112:115]
	v_mfma_f32_16x16x32_bf16 v[100:103], v[186:189], v[214:217], v[100:103]
	v_mfma_f32_16x16x32_bf16 v[96:99], v[194:197], v[214:217], v[96:99]
	v_mfma_f32_16x16x32_bf16 v[84:87], v[186:189], v[222:225], v[84:87]
	v_mfma_f32_16x16x32_bf16 v[80:83], v[194:197], v[222:225], v[80:83]
	v_mfma_f32_16x16x32_bf16 v[68:71], v[186:189], v[230:233], v[68:71]
	v_mfma_f32_16x16x32_bf16 v[64:67], v[194:197], v[230:233], v[64:67]
	s_setprio 0
	s_barrier
; #define PG8_MMA(ai, bj, At, Bt) do { __builtin_amdgcn_s_setprio(1); _Pragma("unroll") for (int m = 0; m < 4; ++m) _Pragma("unroll") for (int n = 0; n < 2; ++n) _Pragma("unroll") for (int k = 0; k < 2; ++k) \
;     acc[ai][bj][m][n] = __builtin_amdgcn_mfma_f32_16x16x32_bf16(Bt[n][k], At[m][k], acc[ai][bj][m][n], 0, 0, 0); __builtin_amdgcn_s_setprio(0); } while (0)
; #define PG8_WAIT_V(n) asm volatile("s_waitcnt vmcnt(" #n ")" ::: "memory")
; #define PG8_WAIT_L(n) asm volatile("s_waitcnt lgkmcnt(" #n ")" ::: "memory")
; #define PG8_BAR __builtin_amdgcn_s_barrier()
; #define PG8_SCHED __builtin_amdgcn_sched_barrier(0)
; DI void rows_rstd(float (&rs)[2][4], const float* ps, const Unit& u, int wr, int fr, int fq, int p_lo, int p_hi, float inv_dim) {
;   f32x4 pv[2][4];
; #pragma unroll
;   for (int ai = 0; ai < 2; ++ai)
; #pragma unroll
;     for (int m = 0; m < 4; ++m) pv[ai][m] = *(const f32x4*)(ps + (size_t)(u.pm * BM + ai * HALF + wr * 64 + m * 16 + fr) * 16 + 4 * fq);
; template <class Epi, class Sched>
; DI void gemm_phase(PG8_LAS unsigned char* lds, const Gemm g, const Sched& S, const Epi& E) {
;     ...
;       PG8_WAIT_V(8); PG8_WAIT_L(0); PG8_BAR; PG8_MMA(1, 0, At, B0); PG8_MMA(1, 1, At, B1); PG8_BAR; PG8_SCHED;
;     }
;     if (wr == 0) PG8_BAR;
	s_add_i32 s34, s41, s15
	v_lshl_add_u64 v[148:149], v[148:149], 0, s[8:9]
	s_mov_b32 m0, s34
	ds_read_b128 v[198:201], v165 offset:49152
	ds_read_b128 v[202:205], v165 offset:50176
	ds_read_b128 v[206:209], v165 offset:51200
	ds_read_b128 v[214:217], v165 offset:52224
	ds_read_b128 v[218:221], v165 offset:53248
	ds_read_b128 v[222:225], v165 offset:54272
	ds_read_b128 v[226:229], v165 offset:55296
	ds_read_b128 v[230:233], v165 offset:56320
	global_load_lds_dwordx4 v[148:149], off
	s_add_i32 m0, s34, 0x2000
	s_add_u32 s30, s30, 0x40080
	v_lshl_add_u64 v[148:149], v[152:153], 0, s[8:9]
	s_addc_u32 s31, s31, 0
	s_add_i32 s34, s44, s15
	global_load_lds_dwordx4 v[148:149], off
	v_lshl_add_u64 v[148:149], s[30:31], 0, v[132:133]
	s_mov_b32 m0, s34
	s_nop 0
	global_load_lds_dwordx4 v[148:149], off
	v_lshl_add_u64 v[148:149], s[30:31], 0, v[128:129]
	s_add_i32 m0, s34, 0x2000
	s_nop 0
	global_load_lds_dwordx4 v[148:149], off
	v_lshl_add_u64 v[148:149], v[162:163], 0, s[8:9]
	s_mov_b32 m0, s33
	s_nop 0
	global_load_lds_dwordx4 v[148:149], off
	v_lshl_add_u64 v[148:149], v[166:167], 0, s[8:9]
	s_mov_b32 m0, s36
	s_nop 0
	global_load_lds_dwordx4 v[148:149], off
	s_waitcnt vmcnt(8)
	s_waitcnt lgkmcnt(0)
	s_barrier
	s_setprio 1
	s_waitcnt lgkmcnt(0)
	v_mfma_f32_16x16x32_bf16 v[60:63], v[144:147], v[198:201], v[60:63]
	v_mfma_f32_16x16x32_bf16 v[56:59], v[174:177], v[198:201], v[56:59]
	v_mfma_f32_16x16x32_bf16 v[44:47], v[144:147], v[206:209], v[44:47]
	v_mfma_f32_16x16x32_bf16 v[40:43], v[174:177], v[206:209], v[40:43]
	v_mfma_f32_16x16x32_bf16 v[28:31], v[144:147], v[218:221], v[28:31]
	v_mfma_f32_16x16x32_bf16 v[24:27], v[174:177], v[218:221], v[24:27]
	v_mfma_f32_16x16x32_bf16 v[12:15], v[144:147], v[226:229], v[12:15]
	v_mfma_f32_16x16x32_bf16 v[8:11], v[174:177], v[226:229], v[8:11]
	v_mfma_f32_16x16x32_bf16 v[60:63], v[156:159], v[202:205], v[60:63]
	v_mfma_f32_16x16x32_bf16 v[56:59], v[178:181], v[202:205], v[56:59]
	v_mfma_f32_16x16x32_bf16 v[44:47], v[156:159], v[214:217], v[44:47]
	v_mfma_f32_16x16x32_bf16 v[40:43], v[178:181], v[214:217], v[40:43]
	v_mfma_f32_16x16x32_bf16 v[28:31], v[156:159], v[222:225], v[28:31]
	v_mfma_f32_16x16x32_bf16 v[24:27], v[178:181], v[222:225], v[24:27]
	v_mfma_f32_16x16x32_bf16 v[12:15], v[156:159], v[230:233], v[12:15]
	v_mfma_f32_16x16x32_bf16 v[8:11], v[178:181], v[230:233], v[8:11]
	s_setprio 0
	s_setprio 1
	v_mfma_f32_16x16x32_bf16 v[52:55], v[182:185], v[198:201], v[52:55]
	v_mfma_f32_16x16x32_bf16 v[48:51], v[190:193], v[198:201], v[48:51]
	v_mfma_f32_16x16x32_bf16 v[36:39], v[182:185], v[206:209], v[36:39]
	v_mfma_f32_16x16x32_bf16 v[32:35], v[190:193], v[206:209], v[32:35]
	v_mfma_f32_16x16x32_bf16 v[20:23], v[182:185], v[218:221], v[20:23]
	v_mfma_f32_16x16x32_bf16 v[16:19], v[190:193], v[218:221], v[16:19]
	v_mfma_f32_16x16x32_bf16 v[4:7], v[182:185], v[226:229], v[4:7]
	v_mfma_f32_16x16x32_bf16 v[0:3], v[190:193], v[226:229], v[0:3]
	v_mfma_f32_16x16x32_bf16 v[52:55], v[186:189], v[202:205], v[52:55]
	v_mfma_f32_16x16x32_bf16 v[48:51], v[194:197], v[202:205], v[48:51]
	v_mfma_f32_16x16x32_bf16 v[36:39], v[186:189], v[214:217], v[36:39]
	v_mfma_f32_16x16x32_bf16 v[32:35], v[194:197], v[214:217], v[32:35]
	v_mfma_f32_16x16x32_bf16 v[20:23], v[186:189], v[222:225], v[20:23]
	v_mfma_f32_16x16x32_bf16 v[16:19], v[194:197], v[222:225], v[16:19]
	v_mfma_f32_16x16x32_bf16 v[4:7], v[186:189], v[230:233], v[4:7]
	v_mfma_f32_16x16x32_bf16 v[0:3], v[194:197], v[230:233], v[0:3]
	s_setprio 0
	s_barrier
	s_add_i32 s55, s55, 2
	s_add_u32 s2, s2, 0x100
	s_addc_u32 s3, s3, 0
	s_add_u32 s53, s53, 0x100
	s_addc_u32 s54, s54, 0
	s_cmp_gt_u32 s55, 13
	s_cbranch_scc0 .LBB0_1384
	v_lshl_add_u32 v166, s0, 8, v151
	v_or_b32_e32 v162, 16, v166
	v_ashrrev_i32_e32 v167, 31, v166
	v_ashrrev_i32_e32 v163, 31, v162
	v_or_b32_e32 v158, 32, v166
	v_lshlrev_b64 v[146:147], 6, v[166:167]
	v_lshlrev_b64 v[144:145], 6, v[162:163]
	v_ashrrev_i32_e32 v159, 31, v158
	v_lshl_add_u64 v[146:147], v[138:139], 0, v[146:147]
	v_or_b32_e32 v156, 48, v166
	v_lshl_add_u64 v[144:145], v[138:139], 0, v[144:145]
	global_load_dwordx4 v[174:177], v[146:147], off
	v_lshlrev_b64 v[146:147], 6, v[158:159]
	v_ashrrev_i32_e32 v157, 31, v156
	v_lshl_add_u64 v[146:147], v[138:139], 0, v[146:147]
	global_load_dwordx4 v[178:181], v[144:145], off
	global_load_dwordx4 v[182:185], v[146:147], off
	v_lshlrev_b64 v[144:145], 6, v[156:157]
	v_lshl_add_u64 v[144:145], v[138:139], 0, v[144:145]
	global_load_dwordx4 v[186:189], v[144:145], off
	v_add_u32_e32 v152, 0x80, v166
	v_ashrrev_i32_e32 v153, 31, v152
	v_lshlrev_b64 v[144:145], 6, v[152:153]
	v_add_u32_e32 v148, 0x90, v166
	v_lshl_add_u64 v[144:145], v[138:139], 0, v[144:145]
	v_ashrrev_i32_e32 v149, 31, v148
	global_load_dwordx4 v[190:193], v[144:145], off
	v_lshlrev_b64 v[144:145], 6, v[148:149]
	v_lshl_add_u64 v[144:145], v[138:139], 0, v[144:145]
	global_load_dwordx4 v[194:197], v[144:145], off
	v_add_u32_e32 v144, 0xb0, v166
	v_ashrrev_i32_e32 v145, 31, v144
	v_lshlrev_b64 v[146:147], 6, v[144:145]
	v_lshl_add_u64 v[146:147], v[138:139], 0, v[146:147]
	global_load_dwordx4 v[198:201], v[146:147], off
	v_and_b32_e32 v147, 64, v169
	v_add_u32_e32 v146, 0xa0, v166
	v_add_u32_e32 v150, 64, v147
	v_ashrrev_i32_e32 v147, 31, v146
	v_lshlrev_b64 v[202:203], 6, v[146:147]
	v_lshl_add_u64 v[202:203], v[138:139], 0, v[202:203]
	global_load_dwordx4 v[202:205], v[202:203], off
	s_and_b64 vcc, exec, s[10:11]
	s_cbranch_vccz .LBB0_1387
	s_barrier
; DI void rows_rstd(float (&rs)[2][4], const float* ps, const Unit& u, int wr, int fr, int fq, int p_lo, int p_hi, float inv_dim) {
;   f32x4 pv[2][4];
; #pragma unroll
;   for (int ai = 0; ai < 2; ++ai)
; #pragma unroll
;     for (int m = 0; m < 4; ++m) pv[ai][m] = *(const f32x4*)(ps + (size_t)(u.pm * BM + ai * HALF + wr * 64 + m * 16 + fr) * 16 + 4 * fq);
;   const bool use = (4 * fq >= p_lo) && (4 * fq < p_hi);
; #pragma unroll
;   for (int ai = 0; ai < 2; ++ai)
; #pragma unroll
;     for (int m = 0; m < 4; ++m) {
;       float s = use ? (pv[ai][m][0] + pv[ai][m][1]) + (pv[ai][m][2] + pv[ai][m][3]) : 0.f;
;       s += __shfl_xor(s, 16); s += __shfl_xor(s, 32);
;       rs[ai][m] = rsqrtf(s * inv_dim + EPS);
.LBB0_1387:
	v_xor_b32_e32 v145, 32, v169
	v_xor_b32_e32 v149, 16, v169
	v_cmp_lt_i32_e32 vcc, v145, v150
	v_mov_b64_e32 v[206:207], s[18:19]
	s_waitcnt vmcnt(0)
	v_mov_b32_e32 v208, v175
	v_mov_b32_e32 v209, v176
	v_mov_b32_e32 v175, v177
	v_mov_b32_e32 v176, v179
	v_mov_b32_e32 v177, v180
	v_mov_b32_e32 v179, v181
	v_cndmask_b32_e32 v145, v169, v145, vcc
	v_cmp_lt_i32_e32 vcc, v149, v150
	v_mov_b32_e32 v180, v183
	v_mov_b32_e32 v181, v184
	v_mov_b32_e32 v183, v185
	v_mov_b32_e32 v184, v187
	v_mov_b32_e32 v185, v188
	v_mov_b32_e32 v187, v189
	v_pk_add_f32 v[174:175], v[208:209], v[174:175]
	v_pk_add_f32 v[176:177], v[176:177], v[178:179]
	v_cndmask_b32_e32 v149, v169, v149, vcc
	v_pk_add_f32 v[178:179], v[180:181], v[182:183]
	v_pk_add_f32 v[180:181], v[184:185], v[186:187]
	v_mov_b32_e32 v182, v176
	v_mov_b32_e32 v183, v174
	v_mov_b32_e32 v174, v177
	v_lshlrev_b32_e32 v147, 2, v149
	v_mov_b32_e32 v176, v180
	v_mov_b32_e32 v177, v178
	v_mov_b32_e32 v178, v181
	v_pk_add_f32 v[174:175], v[182:183], v[174:175]
	v_pk_add_f32 v[176:177], v[176:177], v[178:179]
	ds_bpermute_b32 v179, v147, v175
	ds_bpermute_b32 v178, v147, v174
	ds_bpermute_b32 v181, v147, v177
	ds_bpermute_b32 v180, v147, v176
	v_lshlrev_b32_e32 v145, 2, v145
	v_mov_b32_e32 v182, v191
	s_waitcnt lgkmcnt(2)
	v_pk_add_f32 v[174:175], v[174:175], v[178:179]
	ds_bpermute_b32 v179, v145, v175
	ds_bpermute_b32 v178, v145, v174
	s_waitcnt lgkmcnt(2)
	v_pk_add_f32 v[176:177], v[176:177], v[180:181]
	ds_bpermute_b32 v181, v145, v177
	ds_bpermute_b32 v180, v145, v176
	v_mov_b32_e32 v183, v192
	s_waitcnt lgkmcnt(2)
	v_pk_add_f32 v[174:175], v[174:175], v[178:179]
	v_mov_b32_e32 v191, v193
	v_mov_b32_e32 v184, v195
	v_mov_b32_e32 v185, v196
	v_pk_fma_f32 v[174:175], v[174:175], s[14:15], v[206:207] op_sel_hi:[1,0,0]
	v_mov_b32_e32 v195, v197
	v_pk_add_f32 v[182:183], v[182:183], v[190:191]
	v_mul_f32_e32 v149, 0x4b800000, v175
	v_cmp_gt_f32_e32 vcc, s39, v175
	v_pk_add_f32 v[178:179], v[184:185], v[194:195]
	s_waitcnt lgkmcnt(0)
	v_pk_add_f32 v[176:177], v[176:177], v[180:181]
	v_cndmask_b32_e32 v149, v175, v149, vcc
	v_mov_b32_e32 v180, v178
	v_mov_b32_e32 v181, v182
	v_mov_b32_e32 v182, v179
	v_rsq_f32_e32 v149, v149
	v_pk_add_f32 v[178:179], v[180:181], v[182:183]
	ds_bpermute_b32 v181, v147, v179
	ds_bpermute_b32 v180, v147, v178
	v_pk_fma_f32 v[176:177], v[176:177], s[14:15], v[206:207] op_sel_hi:[1,0,0]
	v_mul_f32_e32 v150, 0x4b800000, v174
	v_cmp_gt_f32_e64 s[0:1], s39, v174
	v_mul_f32_e32 v154, 0x45800000, v149
	v_mul_f32_e32 v153, 0x4b800000, v177
	v_cndmask_b32_e64 v150, v174, v150, s[0:1]
	v_cmp_gt_f32_e64 s[2:3], s39, v177
	v_cndmask_b32_e32 v174, v149, v154, vcc
	v_mul_f32_e32 v149, 0x4b800000, v176
	v_cmp_gt_f32_e32 vcc, s39, v176
	v_cndmask_b32_e64 v153, v177, v153, s[2:3]
	v_rsq_f32_e32 v150, v150
	v_cndmask_b32_e32 v149, v176, v149, vcc
	s_waitcnt lgkmcnt(0)
	v_pk_add_f32 v[176:177], v[178:179], v[180:181]
	ds_bpermute_b32 v179, v145, v177
	ds_bpermute_b32 v178, v145, v176
	v_mov_b32_e32 v180, v199
	v_mov_b32_e32 v181, v200
	v_mov_b32_e32 v199, v201
	v_pk_add_f32 v[180:181], v[180:181], v[198:199]
	s_waitcnt lgkmcnt(0)
	v_pk_add_f32 v[176:177], v[176:177], v[178:179]
	v_mov_b32_e32 v178, v203
	v_mov_b32_e32 v179, v204
	v_mov_b32_e32 v203, v205
	v_pk_add_f32 v[178:179], v[178:179], v[202:203]
	v_mov_b32_e32 v182, v180
	v_mov_b32_e32 v183, v178
	v_mov_b32_e32 v178, v181
	v_rsq_f32_e32 v153, v153
	v_pk_add_f32 v[178:179], v[182:183], v[178:179]
	ds_bpermute_b32 v181, v147, v179
	ds_bpermute_b32 v180, v147, v178
	v_mul_f32_e32 v157, 0x45800000, v150
	v_cndmask_b32_e64 v172, v150, v157, s[0:1]
	v_mul_f32_e32 v150, 0x45800000, v153
	v_pk_fma_f32 v[176:177], v[176:177], s[14:15], v[206:207] op_sel_hi:[1,0,0]
	v_cndmask_b32_e64 v170, v153, v150, s[2:3]
	v_mul_f32_e32 v153, 0x4b800000, v177
	v_cmp_gt_f32_e64 s[0:1], s39, v177
	v_mul_f32_e32 v147, 0x4b800000, v176
	v_cmp_gt_f32_e64 s[2:3], s39, v176
	v_cndmask_b32_e64 v153, v177, v153, s[0:1]
	v_rsq_f32_e32 v149, v149
	v_cndmask_b32_e64 v147, v176, v147, s[2:3]
	s_waitcnt lgkmcnt(0)
	v_pk_add_f32 v[176:177], v[178:179], v[180:181]
	ds_bpermute_b32 v179, v145, v177
	ds_bpermute_b32 v178, v145, v176
	v_rsq_f32_e32 v153, v153
	v_mul_f32_e32 v150, 0x45800000, v149
	v_cndmask_b32_e32 v168, v149, v150, vcc
	v_rsq_f32_e32 v147, v147
	s_waitcnt lgkmcnt(0)
; DI unsigned pack2(float a, float b) { bf2_t v = __builtin_convertvector((f32x2){a, b}, bf2_t); return __builtin_bit_cast(unsigned, v); }
;   DI void operator()(const f32x4 (&acc)[2][2][4][2], const Unit& u, int wr, int wc, int fr, int fq) const {
;     float rsv[2][4];
;     rows_rstd(rsv, ps_in, u, wr, fr, fq, 0, 16, 1.f / 1024.f);
; #pragma unroll
;     for (int ai = 0; ai < 2; ++ai)
; #pragma unroll
;       for (int m = 0; m < 4; ++m) {
;         const int row = u.pm * BM + ai * HALF + wr * 64 + m * 16 + fr;
;         const float rs = rsv[ai][m];
;         float o[8];
; #pragma unroll
;         for (int n = 0; n < 2; ++n)
; #pragma unroll
;           for (int c = 0; c < 4; ++c) {
;             const float gv = acc[ai][0][m][n][c] * rs, uv = acc[ai][1][m][n][c] * rs;
;             o[4 * n + c] = gv * __builtin_amdgcn_rcpf(1.f + __expf(-gv)) * uv;
;           }
;         u32x4 w; w.x = pack2(o[0], o[1]); w.y = pack2(o[2], o[3]); w.z = pack2(o[4], o[5]); w.w = pack2(o[6], o[7]);
;         *(u32x4*)(O + (size_t)row * DFF + u.pn * HALF + wc * 32 + 8 * fq) = w;
	v_pk_add_f32 v[176:177], v[176:177], v[178:179]
	v_mul_f32_e32 v145, 0x45800000, v153
	v_pk_fma_f32 v[176:177], v[176:177], s[14:15], v[206:207] op_sel_hi:[1,0,0]
	v_cndmask_b32_e64 v164, v153, v145, s[0:1]
	v_mul_f32_e32 v149, 0x4b800000, v177
	v_cmp_gt_f32_e32 vcc, s39, v177
	v_mul_f32_e32 v150, 0x4b800000, v176
	v_cmp_gt_f32_e64 s[0:1], s39, v176
	v_cndmask_b32_e32 v149, v177, v149, vcc
	v_rsq_f32_e32 v149, v149
	v_cndmask_b32_e64 v150, v176, v150, s[0:1]
	v_rsq_f32_e32 v150, v150
	v_mul_f32_e32 v145, 0x45800000, v147
	v_cndmask_b32_e64 v160, v147, v145, s[2:3]
	v_mul_f32_e32 v145, 0x45800000, v149
	v_cndmask_b32_e32 v154, v149, v145, vcc
	v_mul_f32_e32 v145, 0x45800000, v150
	v_pk_mul_f32 v[124:125], v[124:125], v[174:175] op_sel_hi:[1,0]
	v_cndmask_b32_e64 v150, v150, v145, s[0:1]
	v_mul_f32_e32 v145, 0xbfb8aa3b, v124
	v_exp_f32_e32 v145, v145
	v_mul_f32_e32 v147, 0xbfb8aa3b, v125
	v_exp_f32_e32 v147, v147
	v_pk_mul_f32 v[126:127], v[126:127], v[174:175] op_sel_hi:[1,0]
	v_add_f32_e32 v145, 1.0, v145
	v_rcp_f32_e32 v176, v145
	v_add_f32_e32 v145, 1.0, v147
	v_mul_f32_e32 v147, 0xbfb8aa3b, v126
	v_exp_f32_e32 v147, v147
	v_mul_f32_e32 v149, 0xbfb8aa3b, v127
	v_exp_f32_e32 v149, v149
	v_rcp_f32_e32 v177, v145
	v_add_f32_e32 v145, 1.0, v147
	v_rcp_f32_e32 v178, v145
	v_add_f32_e32 v145, 1.0, v149
	v_rcp_f32_e32 v179, v145
	v_pk_mul_f32 v[116:117], v[116:117], v[174:175] op_sel_hi:[1,0]
	v_pk_mul_f32 v[124:125], v[124:125], v[176:177]
	v_pk_mul_f32 v[120:121], v[120:121], v[174:175] op_sel_hi:[1,0]
	v_pk_mul_f32 v[116:117], v[116:117], v[124:125]
	v_pk_mul_f32 v[124:125], v[126:127], v[178:179]
	v_mul_f32_e32 v126, 0xbfb8aa3b, v120
	v_exp_f32_e32 v126, v126
	v_pk_mul_f32 v[118:119], v[118:119], v[174:175] op_sel_hi:[1,0]
	v_pk_mul_f32 v[122:123], v[122:123], v[174:175] op_sel_hi:[1,0]
	v_pk_mul_f32 v[118:119], v[118:119], v[124:125]
	v_mul_f32_e32 v124, 0xbfb8aa3b, v121
	v_exp_f32_e32 v125, v124
	v_add_f32_e32 v124, 1.0, v126
	v_mul_f32_e32 v126, 0xbfb8aa3b, v122
	v_mul_f32_e32 v127, 0xbfb8aa3b, v123
	v_exp_f32_e32 v126, v126
	v_exp_f32_e32 v127, v127
	v_add_f32_e32 v125, 1.0, v125
	v_rcp_f32_e32 v124, v124
	v_rcp_f32_e32 v125, v125
	v_add_f32_e32 v126, 1.0, v126
	v_add_f32_e32 v127, 1.0, v127
	v_rcp_f32_e32 v126, v126
	v_rcp_f32_e32 v127, v127
	v_pk_mul_f32 v[112:113], v[112:113], v[174:175] op_sel_hi:[1,0]
	v_pk_mul_f32 v[120:121], v[120:121], v[124:125]
	s_lshl_b32 s0, s48, 7
	v_pk_mul_f32 v[112:113], v[112:113], v[120:121]
	v_pk_mul_f32 v[114:115], v[114:115], v[174:175] op_sel_hi:[1,0]
	v_pk_mul_f32 v[120:121], v[122:123], v[126:127]
	s_ashr_i32 s1, s0, 31
	v_pk_mul_f32 v[120:121], v[114:115], v[120:121]
	v_cvt_pk_bf16_f32 v114, v116, v117
	v_cvt_pk_bf16_f32 v116, v112, v113
	v_mov_b64_e32 v[112:113], s[46:47]
	v_cvt_pk_bf16_f32 v115, v118, v119
	v_mad_i64_i32 v[118:119], s[2:3], v166, s40, v[112:113]
	s_lshl_b64 s[0:1], s[0:1], 1
	v_lshl_add_u64 v[118:119], v[118:119], 0, s[0:1]
	v_lshl_add_u64 v[118:119], v[118:119], 0, s[12:13]
	v_cvt_pk_bf16_f32 v117, v120, v121
	v_lshl_add_u64 v[118:119], v[118:119], 0, v[136:137]
	v_pk_mul_f32 v[108:109], v[108:109], v[172:173] op_sel_hi:[1,0]
	global_store_dwordx4 v[118:119], v[114:117], off
	v_mul_f32_e32 v120, 0xbfb8aa3b, v108
	v_pk_mul_f32 v[110:111], v[110:111], v[172:173] op_sel_hi:[1,0]
	v_mul_f32_e32 v114, 0xbfb8aa3b, v109
	v_exp_f32_e32 v120, v120
	v_exp_f32_e32 v115, v114
	v_mul_f32_e32 v116, 0xbfb8aa3b, v110
	v_mul_f32_e32 v117, 0xbfb8aa3b, v111
	v_exp_f32_e32 v116, v116
	v_exp_f32_e32 v117, v117
	v_add_f32_e32 v114, 1.0, v120
	v_add_f32_e32 v115, 1.0, v115
	v_rcp_f32_e32 v114, v114
	v_rcp_f32_e32 v115, v115
	v_add_f32_e32 v116, 1.0, v116
	v_add_f32_e32 v117, 1.0, v117
	v_rcp_f32_e32 v116, v116
	v_rcp_f32_e32 v117, v117
	v_pk_mul_f32 v[100:101], v[100:101], v[172:173] op_sel_hi:[1,0]
	v_pk_mul_f32 v[108:109], v[108:109], v[114:115]
	v_pk_mul_f32 v[104:105], v[104:105], v[172:173] op_sel_hi:[1,0]
	v_pk_mul_f32 v[100:101], v[100:101], v[108:109]
	v_pk_mul_f32 v[108:109], v[110:111], v[116:117]
	v_mul_f32_e32 v110, 0xbfb8aa3b, v104
	v_exp_f32_e32 v110, v110
	v_pk_mul_f32 v[102:103], v[102:103], v[172:173] op_sel_hi:[1,0]
	v_pk_mul_f32 v[106:107], v[106:107], v[172:173] op_sel_hi:[1,0]
	v_pk_mul_f32 v[102:103], v[102:103], v[108:109]
	v_mul_f32_e32 v108, 0xbfb8aa3b, v105
	v_exp_f32_e32 v109, v108
	v_add_f32_e32 v108, 1.0, v110
	v_mul_f32_e32 v110, 0xbfb8aa3b, v106
	v_mul_f32_e32 v111, 0xbfb8aa3b, v107
	v_exp_f32_e32 v110, v110
	v_exp_f32_e32 v111, v111
	v_add_f32_e32 v109, 1.0, v109
	v_rcp_f32_e32 v108, v108
	v_rcp_f32_e32 v109, v109
	v_add_f32_e32 v110, 1.0, v110
	v_add_f32_e32 v111, 1.0, v111
	v_rcp_f32_e32 v110, v110
	v_rcp_f32_e32 v111, v111
	v_pk_mul_f32 v[96:97], v[96:97], v[172:173] op_sel_hi:[1,0]
	v_pk_mul_f32 v[104:105], v[104:105], v[108:109]
	v_pk_mul_f32 v[92:93], v[92:93], v[170:171] op_sel_hi:[1,0]
	v_pk_mul_f32 v[104:105], v[96:97], v[104:105]
	v_pk_mul_f32 v[96:97], v[98:99], v[172:173] op_sel_hi:[1,0]
	v_pk_mul_f32 v[98:99], v[106:107], v[110:111]
	v_pk_mul_f32 v[94:95], v[94:95], v[170:171] op_sel_hi:[1,0]
	v_pk_mul_f32 v[106:107], v[96:97], v[98:99]
	v_cvt_pk_bf16_f32 v96, v100, v101
	v_mad_i64_i32 v[100:101], s[2:3], v162, s40, v[112:113]
	v_lshl_add_u64 v[100:101], v[100:101], 0, s[0:1]
	v_lshl_add_u64 v[100:101], v[100:101], 0, s[12:13]
	v_cvt_pk_bf16_f32 v97, v102, v103
	v_cvt_pk_bf16_f32 v98, v104, v105
	v_cvt_pk_bf16_f32 v99, v106, v107
	v_lshl_add_u64 v[100:101], v[100:101], 0, v[136:137]
	v_mul_f32_e32 v102, 0xbfb8aa3b, v92
	global_store_dwordx4 v[100:101], v[96:99], off
	v_exp_f32_e32 v102, v102
	v_pk_mul_f32 v[84:85], v[84:85], v[170:171] op_sel_hi:[1,0]
; DI unsigned pack2(float a, float b) { bf2_t v = __builtin_convertvector((f32x2){a, b}, bf2_t); return __builtin_bit_cast(unsigned, v); }
;   DI void operator()(const f32x4 (&acc)[2][2][4][2], const Unit& u, int wr, int wc, int fr, int fq) const {
;     ...
;     for (int ai = 0; ai < 2; ++ai)
; #pragma unroll
;       for (int m = 0; m < 4; ++m) {
;         const int row = u.pm * BM + ai * HALF + wr * 64 + m * 16 + fr;
;         const float rs = rsv[ai][m];
;         float o[8];
; #pragma unroll
;         for (int n = 0; n < 2; ++n)
; #pragma unroll
;           for (int c = 0; c < 4; ++c) {
;             const float gv = acc[ai][0][m][n][c] * rs, uv = acc[ai][1][m][n][c] * rs;
;             o[4 * n + c] = gv * __builtin_amdgcn_rcpf(1.f + __expf(-gv)) * uv;
;           }
;         u32x4 w; w.x = pack2(o[0], o[1]); w.y = pack2(o[2], o[3]); w.z = pack2(o[4], o[5]); w.w = pack2(o[6], o[7]);
;         *(u32x4*)(O + (size_t)row * DFF + u.pn * HALF + wc * 32 + 8 * fq) = w;
	v_mul_f32_e32 v96, 0xbfb8aa3b, v93
	v_exp_f32_e32 v97, v96
	v_mul_f32_e32 v98, 0xbfb8aa3b, v94
	v_mul_f32_e32 v99, 0xbfb8aa3b, v95
	v_exp_f32_e32 v98, v98
	v_exp_f32_e32 v99, v99
	v_add_f32_e32 v96, 1.0, v102
	v_add_f32_e32 v97, 1.0, v97
	v_rcp_f32_e32 v96, v96
	v_rcp_f32_e32 v97, v97
	v_add_f32_e32 v98, 1.0, v98
	v_add_f32_e32 v99, 1.0, v99
	v_rcp_f32_e32 v98, v98
	v_rcp_f32_e32 v99, v99
	v_pk_mul_f32 v[92:93], v[92:93], v[96:97]
	v_pk_mul_f32 v[88:89], v[88:89], v[170:171] op_sel_hi:[1,0]
	v_pk_mul_f32 v[84:85], v[84:85], v[92:93]
	v_pk_mul_f32 v[92:93], v[94:95], v[98:99]
	v_mul_f32_e32 v94, 0xbfb8aa3b, v88
	v_exp_f32_e32 v94, v94
	v_pk_mul_f32 v[86:87], v[86:87], v[170:171] op_sel_hi:[1,0]
	v_pk_mul_f32 v[90:91], v[90:91], v[170:171] op_sel_hi:[1,0]
	v_pk_mul_f32 v[86:87], v[86:87], v[92:93]
	v_mul_f32_e32 v92, 0xbfb8aa3b, v89
	v_exp_f32_e32 v93, v92
	v_add_f32_e32 v92, 1.0, v94
	v_mul_f32_e32 v94, 0xbfb8aa3b, v90
	v_mul_f32_e32 v95, 0xbfb8aa3b, v91
	v_exp_f32_e32 v94, v94
	v_exp_f32_e32 v95, v95
	v_add_f32_e32 v93, 1.0, v93
	v_rcp_f32_e32 v92, v92
	v_rcp_f32_e32 v93, v93
	v_add_f32_e32 v94, 1.0, v94
	v_add_f32_e32 v95, 1.0, v95
	v_rcp_f32_e32 v94, v94
	v_rcp_f32_e32 v95, v95
	v_pk_mul_f32 v[80:81], v[80:81], v[170:171] op_sel_hi:[1,0]
	v_pk_mul_f32 v[88:89], v[88:89], v[92:93]
	v_pk_mul_f32 v[76:77], v[76:77], v[168:169] op_sel_hi:[1,0]
	v_pk_mul_f32 v[88:89], v[80:81], v[88:89]
	v_pk_mul_f32 v[80:81], v[82:83], v[170:171] op_sel_hi:[1,0]
	v_pk_mul_f32 v[82:83], v[90:91], v[94:95]
	v_pk_mul_f32 v[78:79], v[78:79], v[168:169] op_sel_hi:[1,0]
	v_pk_mul_f32 v[90:91], v[80:81], v[82:83]
	v_cvt_pk_bf16_f32 v80, v84, v85
	v_mad_i64_i32 v[84:85], s[2:3], v158, s40, v[112:113]
	v_lshl_add_u64 v[84:85], v[84:85], 0, s[0:1]
	v_lshl_add_u64 v[84:85], v[84:85], 0, s[12:13]
	v_cvt_pk_bf16_f32 v81, v86, v87
	v_cvt_pk_bf16_f32 v82, v88, v89
	v_cvt_pk_bf16_f32 v83, v90, v91
	v_lshl_add_u64 v[84:85], v[84:85], 0, v[136:137]
	v_mul_f32_e32 v86, 0xbfb8aa3b, v76
	global_store_dwordx4 v[84:85], v[80:83], off
	v_exp_f32_e32 v86, v86
	v_pk_mul_f32 v[68:69], v[68:69], v[168:169] op_sel_hi:[1,0]
	v_mul_f32_e32 v80, 0xbfb8aa3b, v77
	v_exp_f32_e32 v81, v80
	v_mul_f32_e32 v82, 0xbfb8aa3b, v78
	v_mul_f32_e32 v83, 0xbfb8aa3b, v79
	v_exp_f32_e32 v82, v82
	v_exp_f32_e32 v83, v83
	v_add_f32_e32 v80, 1.0, v86
	v_add_f32_e32 v81, 1.0, v81
	v_rcp_f32_e32 v80, v80
	v_rcp_f32_e32 v81, v81
	v_add_f32_e32 v82, 1.0, v82
	v_add_f32_e32 v83, 1.0, v83
	v_rcp_f32_e32 v82, v82
	v_rcp_f32_e32 v83, v83
	v_pk_mul_f32 v[76:77], v[76:77], v[80:81]
	v_pk_mul_f32 v[72:73], v[72:73], v[168:169] op_sel_hi:[1,0]
	v_pk_mul_f32 v[68:69], v[68:69], v[76:77]
	v_pk_mul_f32 v[76:77], v[78:79], v[82:83]
	v_mul_f32_e32 v78, 0xbfb8aa3b, v72
	v_exp_f32_e32 v78, v78
	v_pk_mul_f32 v[70:71], v[70:71], v[168:169] op_sel_hi:[1,0]
	v_pk_mul_f32 v[74:75], v[74:75], v[168:169] op_sel_hi:[1,0]
	v_pk_mul_f32 v[70:71], v[70:71], v[76:77]
	v_mul_f32_e32 v76, 0xbfb8aa3b, v73
	v_exp_f32_e32 v77, v76
	v_add_f32_e32 v76, 1.0, v78
	v_mul_f32_e32 v78, 0xbfb8aa3b, v74
	v_mul_f32_e32 v79, 0xbfb8aa3b, v75
	v_exp_f32_e32 v78, v78
	v_exp_f32_e32 v79, v79
	v_add_f32_e32 v77, 1.0, v77
	v_rcp_f32_e32 v76, v76
	v_rcp_f32_e32 v77, v77
	v_add_f32_e32 v78, 1.0, v78
	v_add_f32_e32 v79, 1.0, v79
	v_rcp_f32_e32 v78, v78
	v_rcp_f32_e32 v79, v79
	v_pk_mul_f32 v[64:65], v[64:65], v[168:169] op_sel_hi:[1,0]
	v_pk_mul_f32 v[72:73], v[72:73], v[76:77]
	v_pk_mul_f32 v[60:61], v[60:61], v[164:165] op_sel_hi:[1,0]
	v_pk_mul_f32 v[72:73], v[64:65], v[72:73]
	v_pk_mul_f32 v[64:65], v[66:67], v[168:169] op_sel_hi:[1,0]
	v_pk_mul_f32 v[66:67], v[74:75], v[78:79]
	v_pk_mul_f32 v[62:63], v[62:63], v[164:165] op_sel_hi:[1,0]
	v_pk_mul_f32 v[74:75], v[64:65], v[66:67]
	v_cvt_pk_bf16_f32 v64, v68, v69
	v_mad_i64_i32 v[68:69], s[2:3], v156, s40, v[112:113]
	v_lshl_add_u64 v[68:69], v[68:69], 0, s[0:1]
	v_lshl_add_u64 v[68:69], v[68:69], 0, s[12:13]
	v_cvt_pk_bf16_f32 v65, v70, v71
	v_cvt_pk_bf16_f32 v66, v72, v73
	v_cvt_pk_bf16_f32 v67, v74, v75
	v_lshl_add_u64 v[68:69], v[68:69], 0, v[136:137]
	v_mul_f32_e32 v70, 0xbfb8aa3b, v60
	global_store_dwordx4 v[68:69], v[64:67], off
	v_exp_f32_e32 v70, v70
	v_pk_mul_f32 v[52:53], v[52:53], v[164:165] op_sel_hi:[1,0]
	v_mul_f32_e32 v64, 0xbfb8aa3b, v61
	v_exp_f32_e32 v65, v64
	v_mul_f32_e32 v66, 0xbfb8aa3b, v62
	v_mul_f32_e32 v67, 0xbfb8aa3b, v63
	v_exp_f32_e32 v66, v66
	v_exp_f32_e32 v67, v67
	v_add_f32_e32 v64, 1.0, v70
	v_add_f32_e32 v65, 1.0, v65
	v_rcp_f32_e32 v64, v64
	v_rcp_f32_e32 v65, v65
	v_add_f32_e32 v66, 1.0, v66
	v_add_f32_e32 v67, 1.0, v67
	v_rcp_f32_e32 v66, v66
	v_rcp_f32_e32 v67, v67
	v_pk_mul_f32 v[60:61], v[60:61], v[64:65]
	v_pk_mul_f32 v[56:57], v[56:57], v[164:165] op_sel_hi:[1,0]
	v_pk_mul_f32 v[52:53], v[52:53], v[60:61]
	v_pk_mul_f32 v[60:61], v[62:63], v[66:67]
	v_mul_f32_e32 v62, 0xbfb8aa3b, v56
	v_exp_f32_e32 v62, v62
	v_pk_mul_f32 v[54:55], v[54:55], v[164:165] op_sel_hi:[1,0]
	v_pk_mul_f32 v[58:59], v[58:59], v[164:165] op_sel_hi:[1,0]
	v_pk_mul_f32 v[54:55], v[54:55], v[60:61]
	v_mul_f32_e32 v60, 0xbfb8aa3b, v57
	v_exp_f32_e32 v61, v60
	v_add_f32_e32 v60, 1.0, v62
	v_mul_f32_e32 v62, 0xbfb8aa3b, v58
	v_mul_f32_e32 v63, 0xbfb8aa3b, v59
	v_exp_f32_e32 v62, v62
	v_exp_f32_e32 v63, v63
	v_add_f32_e32 v61, 1.0, v61
	v_rcp_f32_e32 v60, v60
	v_rcp_f32_e32 v61, v61
	v_add_f32_e32 v62, 1.0, v62
	v_add_f32_e32 v63, 1.0, v63
	v_rcp_f32_e32 v62, v62
	v_rcp_f32_e32 v63, v63
	v_pk_mul_f32 v[48:49], v[48:49], v[164:165] op_sel_hi:[1,0]
	v_pk_mul_f32 v[56:57], v[56:57], v[60:61]
	v_pk_mul_f32 v[44:45], v[44:45], v[160:161] op_sel_hi:[1,0]
	v_pk_mul_f32 v[56:57], v[48:49], v[56:57]
; DI unsigned pack2(float a, float b) { bf2_t v = __builtin_convertvector((f32x2){a, b}, bf2_t); return __builtin_bit_cast(unsigned, v); }
; #define PG8_BAR __builtin_amdgcn_s_barrier()
;   DI void operator()(const f32x4 (&acc)[2][2][4][2], const Unit& u, int wr, int wc, int fr, int fq) const {
;     ...
;     for (int ai = 0; ai < 2; ++ai)
; #pragma unroll
;       for (int m = 0; m < 4; ++m) {
;         const int row = u.pm * BM + ai * HALF + wr * 64 + m * 16 + fr;
;         const float rs = rsv[ai][m];
;         float o[8];
; #pragma unroll
;         for (int n = 0; n < 2; ++n)
; #pragma unroll
;           for (int c = 0; c < 4; ++c) {
;             const float gv = acc[ai][0][m][n][c] * rs, uv = acc[ai][1][m][n][c] * rs;
;             o[4 * n + c] = gv * __builtin_amdgcn_rcpf(1.f + __expf(-gv)) * uv;
;           }
;         u32x4 w; w.x = pack2(o[0], o[1]); w.y = pack2(o[2], o[3]); w.z = pack2(o[4], o[5]); w.w = pack2(o[6], o[7]);
;         *(u32x4*)(O + (size_t)row * DFF + u.pn * HALF + wc * 32 + 8 * fq) = w;
;       }
; template <class Epi, class Sched>
; DI void gemm_phase(PG8_LAS unsigned char* lds, const Gemm g, const Sched& S, const Epi& E) {
;     ...
;     if (!has_next) break;
; #pragma unroll
;     for (int a = 0; a < 2; ++a)
; #pragma unroll
;       for (int b = 0; b < 2; ++b)
; #pragma unroll
;         for (int m = 0; m < 4; ++m)
; #pragma unroll
;           for (int n = 0; n < 2; ++n) acc[a][b][m][n] = (f32x4){0.f, 0.f, 0.f, 0.f};
;     cur = nxt; cA = nA; cB = nB; ++ui;
;     if (wr == 1) PG8_BAR;
	v_pk_mul_f32 v[48:49], v[50:51], v[164:165] op_sel_hi:[1,0]
	v_pk_mul_f32 v[50:51], v[58:59], v[62:63]
	v_pk_mul_f32 v[46:47], v[46:47], v[160:161] op_sel_hi:[1,0]
	v_pk_mul_f32 v[58:59], v[48:49], v[50:51]
	v_cvt_pk_bf16_f32 v48, v52, v53
	v_mad_i64_i32 v[52:53], s[2:3], v152, s40, v[112:113]
	v_lshl_add_u64 v[52:53], v[52:53], 0, s[0:1]
	v_lshl_add_u64 v[52:53], v[52:53], 0, s[12:13]
	v_cvt_pk_bf16_f32 v49, v54, v55
	v_cvt_pk_bf16_f32 v50, v56, v57
	v_cvt_pk_bf16_f32 v51, v58, v59
	v_lshl_add_u64 v[52:53], v[52:53], 0, v[136:137]
	v_mul_f32_e32 v54, 0xbfb8aa3b, v44
	global_store_dwordx4 v[52:53], v[48:51], off
	v_exp_f32_e32 v54, v54
	v_pk_mul_f32 v[36:37], v[36:37], v[160:161] op_sel_hi:[1,0]
	v_mul_f32_e32 v48, 0xbfb8aa3b, v45
	v_exp_f32_e32 v49, v48
	v_mul_f32_e32 v50, 0xbfb8aa3b, v46
	v_mul_f32_e32 v51, 0xbfb8aa3b, v47
	v_exp_f32_e32 v50, v50
	v_exp_f32_e32 v51, v51
	v_add_f32_e32 v48, 1.0, v54
	v_add_f32_e32 v49, 1.0, v49
	v_rcp_f32_e32 v48, v48
	v_rcp_f32_e32 v49, v49
	v_add_f32_e32 v50, 1.0, v50
	v_add_f32_e32 v51, 1.0, v51
	v_rcp_f32_e32 v50, v50
	v_rcp_f32_e32 v51, v51
	v_pk_mul_f32 v[44:45], v[44:45], v[48:49]
	v_pk_mul_f32 v[40:41], v[40:41], v[160:161] op_sel_hi:[1,0]
	v_pk_mul_f32 v[36:37], v[36:37], v[44:45]
	v_pk_mul_f32 v[44:45], v[46:47], v[50:51]
	v_mul_f32_e32 v46, 0xbfb8aa3b, v40
	v_exp_f32_e32 v46, v46
	v_pk_mul_f32 v[38:39], v[38:39], v[160:161] op_sel_hi:[1,0]
	v_pk_mul_f32 v[42:43], v[42:43], v[160:161] op_sel_hi:[1,0]
	v_pk_mul_f32 v[38:39], v[38:39], v[44:45]
	v_mul_f32_e32 v44, 0xbfb8aa3b, v41
	v_exp_f32_e32 v45, v44
	v_add_f32_e32 v44, 1.0, v46
	v_mul_f32_e32 v46, 0xbfb8aa3b, v42
	v_mul_f32_e32 v47, 0xbfb8aa3b, v43
	v_exp_f32_e32 v46, v46
	v_exp_f32_e32 v47, v47
	v_add_f32_e32 v45, 1.0, v45
	v_rcp_f32_e32 v44, v44
	v_rcp_f32_e32 v45, v45
	v_add_f32_e32 v46, 1.0, v46
	v_add_f32_e32 v47, 1.0, v47
	v_rcp_f32_e32 v46, v46
	v_rcp_f32_e32 v47, v47
	v_pk_mul_f32 v[32:33], v[32:33], v[160:161] op_sel_hi:[1,0]
	v_pk_mul_f32 v[40:41], v[40:41], v[44:45]
	v_pk_mul_f32 v[28:29], v[28:29], v[154:155] op_sel_hi:[1,0]
	v_pk_mul_f32 v[40:41], v[32:33], v[40:41]
	v_pk_mul_f32 v[32:33], v[34:35], v[160:161] op_sel_hi:[1,0]
	v_pk_mul_f32 v[34:35], v[42:43], v[46:47]
	v_pk_mul_f32 v[30:31], v[30:31], v[154:155] op_sel_hi:[1,0]
	v_pk_mul_f32 v[42:43], v[32:33], v[34:35]
	v_cvt_pk_bf16_f32 v32, v36, v37
	v_mad_i64_i32 v[36:37], s[2:3], v148, s40, v[112:113]
	v_lshl_add_u64 v[36:37], v[36:37], 0, s[0:1]
	v_lshl_add_u64 v[36:37], v[36:37], 0, s[12:13]
	v_cvt_pk_bf16_f32 v33, v38, v39
	v_cvt_pk_bf16_f32 v34, v40, v41
	v_cvt_pk_bf16_f32 v35, v42, v43
	v_lshl_add_u64 v[36:37], v[36:37], 0, v[136:137]
	v_mul_f32_e32 v38, 0xbfb8aa3b, v28
	global_store_dwordx4 v[36:37], v[32:35], off
	v_exp_f32_e32 v38, v38
	v_pk_mul_f32 v[20:21], v[20:21], v[154:155] op_sel_hi:[1,0]
	v_mul_f32_e32 v32, 0xbfb8aa3b, v29
	v_exp_f32_e32 v33, v32
	v_mul_f32_e32 v34, 0xbfb8aa3b, v30
	v_mul_f32_e32 v35, 0xbfb8aa3b, v31
	v_exp_f32_e32 v34, v34
	v_exp_f32_e32 v35, v35
	v_add_f32_e32 v32, 1.0, v38
	v_add_f32_e32 v33, 1.0, v33
	v_rcp_f32_e32 v32, v32
	v_rcp_f32_e32 v33, v33
	v_add_f32_e32 v34, 1.0, v34
	v_add_f32_e32 v35, 1.0, v35
	v_rcp_f32_e32 v34, v34
	v_rcp_f32_e32 v35, v35
	v_pk_mul_f32 v[28:29], v[28:29], v[32:33]
	v_pk_mul_f32 v[24:25], v[24:25], v[154:155] op_sel_hi:[1,0]
	v_pk_mul_f32 v[20:21], v[20:21], v[28:29]
	v_pk_mul_f32 v[28:29], v[30:31], v[34:35]
	v_mul_f32_e32 v30, 0xbfb8aa3b, v24
	v_exp_f32_e32 v30, v30
	v_pk_mul_f32 v[22:23], v[22:23], v[154:155] op_sel_hi:[1,0]
	v_pk_mul_f32 v[26:27], v[26:27], v[154:155] op_sel_hi:[1,0]
	v_pk_mul_f32 v[22:23], v[22:23], v[28:29]
	v_mul_f32_e32 v28, 0xbfb8aa3b, v25
	v_exp_f32_e32 v29, v28
	v_add_f32_e32 v28, 1.0, v30
	v_mul_f32_e32 v30, 0xbfb8aa3b, v26
	v_mul_f32_e32 v31, 0xbfb8aa3b, v27
	v_exp_f32_e32 v30, v30
	v_exp_f32_e32 v31, v31
	v_add_f32_e32 v29, 1.0, v29
	v_rcp_f32_e32 v28, v28
	v_rcp_f32_e32 v29, v29
	v_add_f32_e32 v30, 1.0, v30
	v_add_f32_e32 v31, 1.0, v31
	v_rcp_f32_e32 v30, v30
	v_rcp_f32_e32 v31, v31
	v_pk_mul_f32 v[16:17], v[16:17], v[154:155] op_sel_hi:[1,0]
	v_pk_mul_f32 v[24:25], v[24:25], v[28:29]
	v_pk_mul_f32 v[12:13], v[12:13], v[150:151] op_sel_hi:[1,0]
	v_pk_mul_f32 v[24:25], v[16:17], v[24:25]
	v_pk_mul_f32 v[16:17], v[18:19], v[154:155] op_sel_hi:[1,0]
	v_pk_mul_f32 v[18:19], v[26:27], v[30:31]
	v_pk_mul_f32 v[14:15], v[14:15], v[150:151] op_sel_hi:[1,0]
	v_pk_mul_f32 v[26:27], v[16:17], v[18:19]
	v_cvt_pk_bf16_f32 v16, v20, v21
	v_mad_i64_i32 v[20:21], s[2:3], v146, s40, v[112:113]
	v_lshl_add_u64 v[20:21], v[20:21], 0, s[0:1]
	v_lshl_add_u64 v[20:21], v[20:21], 0, s[12:13]
	v_cvt_pk_bf16_f32 v17, v22, v23
	v_cvt_pk_bf16_f32 v18, v24, v25
	v_cvt_pk_bf16_f32 v19, v26, v27
	v_lshl_add_u64 v[20:21], v[20:21], 0, v[136:137]
	v_mul_f32_e32 v22, 0xbfb8aa3b, v12
	global_store_dwordx4 v[20:21], v[16:19], off
	v_exp_f32_e32 v22, v22
	v_pk_mul_f32 v[4:5], v[4:5], v[150:151] op_sel_hi:[1,0]
	v_mul_f32_e32 v16, 0xbfb8aa3b, v13
	v_exp_f32_e32 v17, v16
	v_mul_f32_e32 v18, 0xbfb8aa3b, v14
	v_mul_f32_e32 v19, 0xbfb8aa3b, v15
	v_exp_f32_e32 v18, v18
	v_exp_f32_e32 v19, v19
	v_add_f32_e32 v16, 1.0, v22
	v_add_f32_e32 v17, 1.0, v17
	v_rcp_f32_e32 v16, v16
	v_rcp_f32_e32 v17, v17
	v_add_f32_e32 v18, 1.0, v18
	v_add_f32_e32 v19, 1.0, v19
	v_rcp_f32_e32 v18, v18
	v_rcp_f32_e32 v19, v19
	v_pk_mul_f32 v[12:13], v[12:13], v[16:17]
	v_pk_mul_f32 v[8:9], v[8:9], v[150:151] op_sel_hi:[1,0]
	v_pk_mul_f32 v[4:5], v[4:5], v[12:13]
	v_pk_mul_f32 v[12:13], v[14:15], v[18:19]
	v_mul_f32_e32 v14, 0xbfb8aa3b, v8
	v_exp_f32_e32 v14, v14
	v_pk_mul_f32 v[6:7], v[6:7], v[150:151] op_sel_hi:[1,0]
	v_pk_mul_f32 v[10:11], v[10:11], v[150:151] op_sel_hi:[1,0]
	v_pk_mul_f32 v[6:7], v[6:7], v[12:13]
	v_mul_f32_e32 v12, 0xbfb8aa3b, v9
	v_exp_f32_e32 v13, v12
	v_add_f32_e32 v12, 1.0, v14
	v_mul_f32_e32 v14, 0xbfb8aa3b, v10
	v_mul_f32_e32 v15, 0xbfb8aa3b, v11
	v_exp_f32_e32 v14, v14
	v_exp_f32_e32 v15, v15
	v_add_f32_e32 v13, 1.0, v13
	v_rcp_f32_e32 v12, v12
	v_rcp_f32_e32 v13, v13
	v_add_f32_e32 v14, 1.0, v14
	v_add_f32_e32 v15, 1.0, v15
	v_rcp_f32_e32 v14, v14
	v_rcp_f32_e32 v15, v15
	v_pk_mul_f32 v[0:1], v[0:1], v[150:151] op_sel_hi:[1,0]
	v_pk_mul_f32 v[8:9], v[8:9], v[12:13]
	s_andn2_b64 vcc, exec, s[24:25]
	v_pk_mul_f32 v[8:9], v[0:1], v[8:9]
	v_pk_mul_f32 v[0:1], v[2:3], v[150:151] op_sel_hi:[1,0]
	v_pk_mul_f32 v[2:3], v[10:11], v[14:15]
	s_nop 0
	v_pk_mul_f32 v[10:11], v[0:1], v[2:3]
	v_cvt_pk_bf16_f32 v0, v4, v5
	v_mad_i64_i32 v[4:5], s[2:3], v144, s40, v[112:113]
	v_lshl_add_u64 v[4:5], v[4:5], 0, s[0:1]
	v_lshl_add_u64 v[4:5], v[4:5], 0, s[12:13]
	v_cvt_pk_bf16_f32 v1, v6, v7
	v_cvt_pk_bf16_f32 v2, v8, v9
	v_cvt_pk_bf16_f32 v3, v10, v11
	v_lshl_add_u64 v[4:5], v[4:5], 0, v[136:137]
	s_mov_b64 s[0:1], -1
	global_store_dwordx4 v[4:5], v[0:3], off
	s_cbranch_vccnz .LBB0_1380
	s_andn2_b64 vcc, exec, s[6:7]
	s_cbranch_vccnz .LBB0_1379
	s_barrier
	s_branch .LBB0_1379

; #define PG8_STAGE(bufoff, gbase, voff) do { _Pragma("unroll") for (int _i = 0; _i < 2; ++_i) \
;     __builtin_amdgcn_global_load_lds((const unsigned*)((const char*)(gbase) + (voff)[_i]), (PG8_LAS unsigned*)(lds + (bufoff) + ldsw + _i * 8192), 16, 0, 0); } while (0)
; #define PG8_LDA(dst, b, h) do { _Pragma("unroll") for (int m = 0; m < 4; ++m) _Pragma("unroll") for (int k = 0; k < 2; ++k) dst[m][k] = *(const PG8_LAS bf16x8*)(lds + PG8_SA(b, h) + aoff + m * 2048 + k * 1024); } while (0)
; #define PG8_LDB(dst, b, h) do { _Pragma("unroll") for (int n = 0; n < 2; ++n) _Pragma("unroll") for (int k = 0; k < 2; ++k) dst[n][k] = *(const PG8_LAS bf16x8*)(lds + PG8_SB(b, h) + boff + n * 2048 + k * 1024); } while (0)
; #define PG8_MMA(ai, bj, At, Bt) do { __builtin_amdgcn_s_setprio(1); _Pragma("unroll") for (int m = 0; m < 4; ++m) _Pragma("unroll") for (int n = 0; n < 2; ++n) _Pragma("unroll") for (int k = 0; k < 2; ++k) \
;     acc[ai][bj][m][n] = __builtin_amdgcn_mfma_f32_16x16x32_bf16(Bt[n][k], At[m][k], acc[ai][bj][m][n], 0, 0, 0); __builtin_amdgcn_s_setprio(0); } while (0)
; #define PG8_WAIT_V(n) asm volatile("s_waitcnt vmcnt(" #n ")" ::: "memory")
; #define PG8_WAIT_L(n) asm volatile("s_waitcnt lgkmcnt(" #n ")" ::: "memory")
; #define PG8_BAR __builtin_amdgcn_s_barrier()
; #define PG8_SCHED __builtin_amdgcn_sched_barrier(0)
; template <class Epi, class Sched>
; DI void gemm_phase(PG8_LAS unsigned char* lds, const Gemm g, const Sched& S, const Epi& E) {
;     ...
;       PG8_LDB(B0, 0, 0); PG8_LDB(B1, 0, 1); PG8_SCHED; PG8_LDA(At, 0, 0); PG8_STAGE(PG8_SA(1, 1), a1 + hstepA, voffA);
;       PG8_WAIT_V(8); PG8_WAIT_L(0); PG8_BAR; PG8_MMA(0, 0, At, B0); PG8_MMA(0, 1, At, B1); PG8_BAR; PG8_SCHED;
;       PG8_LDA(At, 0, 1); PG8_STAGE(PG8_SB(0, 0), b2, voffB); PG8_STAGE(PG8_SB(0, 1), b2 + hstepB, voffB); PG8_STAGE(PG8_SA(0, 0), a2, voffA);
;       PG8_WAIT_V(8); PG8_WAIT_L(0); PG8_BAR; PG8_MMA(1, 0, At, B0); PG8_MMA(1, 1, At, B1); PG8_BAR; PG8_SCHED;
.LBB0_1456:
	ds_read_b128 v[150:153], v145
	ds_read_b128 v[154:157], v145 offset:1024
	ds_read_b128 v[158:161], v145 offset:2048
	ds_read_b128 v[162:165], v145 offset:3072
	ds_read_b128 v[166:169], v146
	ds_read_b128 v[170:173], v146 offset:1024
	ds_read_b128 v[174:177], v146 offset:2048
	ds_read_b128 v[178:181], v146 offset:3072
	s_add_u32 s14, s12, 0x100
	s_addc_u32 s15, s13, 0
	s_cmp_eq_u32 s60, 40
	s_cselect_b32 s19, s9, s15
	s_cselect_b32 s18, s8, s14
	s_cselect_b32 s17, s11, s59
	s_cselect_b32 s16, s10, s58
	s_mov_b32 m0, s49
	v_lshl_add_u64 v[142:143], s[12:13], 0, v[138:139]
	ds_read_b128 v[182:185], v147
	ds_read_b128 v[186:189], v147 offset:1024
	ds_read_b128 v[190:193], v147 offset:2048
	ds_read_b128 v[194:197], v147 offset:3072
	ds_read_b128 v[198:201], v147 offset:4096
	ds_read_b128 v[202:205], v147 offset:5120
	ds_read_b128 v[206:209], v147 offset:6144
	ds_read_b128 v[210:213], v147 offset:7168
	global_load_lds_dwordx4 v[142:143], off
	v_lshl_add_u64 v[142:143], s[12:13], 0, v[140:141]
	s_mov_b32 m0, s52
	s_nop 0
	global_load_lds_dwordx4 v[142:143], off
	s_waitcnt vmcnt(8)
	s_waitcnt lgkmcnt(0)
	s_barrier
	s_setprio 1
	s_waitcnt lgkmcnt(0)
	v_mfma_f32_16x16x32_bf16 v[124:127], v[150:153], v[182:185], v[124:127]
	v_mfma_f32_16x16x32_bf16 v[120:123], v[158:161], v[182:185], v[120:123]
	v_mfma_f32_16x16x32_bf16 v[108:111], v[150:153], v[190:193], v[108:111]
	v_mfma_f32_16x16x32_bf16 v[104:107], v[158:161], v[190:193], v[104:107]
	v_mfma_f32_16x16x32_bf16 v[92:95], v[150:153], v[198:201], v[92:95]
	v_mfma_f32_16x16x32_bf16 v[88:91], v[158:161], v[198:201], v[88:91]
	v_mfma_f32_16x16x32_bf16 v[76:79], v[150:153], v[206:209], v[76:79]
	v_mfma_f32_16x16x32_bf16 v[72:75], v[158:161], v[206:209], v[72:75]
	v_mfma_f32_16x16x32_bf16 v[124:127], v[154:157], v[186:189], v[124:127]
	v_mfma_f32_16x16x32_bf16 v[120:123], v[162:165], v[186:189], v[120:123]
	v_mfma_f32_16x16x32_bf16 v[108:111], v[154:157], v[194:197], v[108:111]
	v_mfma_f32_16x16x32_bf16 v[104:107], v[162:165], v[194:197], v[104:107]
	v_mfma_f32_16x16x32_bf16 v[92:95], v[154:157], v[202:205], v[92:95]
	v_mfma_f32_16x16x32_bf16 v[88:91], v[162:165], v[202:205], v[88:91]
	v_mfma_f32_16x16x32_bf16 v[76:79], v[154:157], v[210:213], v[76:79]
	v_mfma_f32_16x16x32_bf16 v[72:75], v[162:165], v[210:213], v[72:75]
	s_setprio 0
	s_setprio 1
	v_mfma_f32_16x16x32_bf16 v[116:119], v[166:169], v[182:185], v[116:119]
	v_mfma_f32_16x16x32_bf16 v[112:115], v[174:177], v[182:185], v[112:115]
	v_mfma_f32_16x16x32_bf16 v[100:103], v[166:169], v[190:193], v[100:103]
	v_mfma_f32_16x16x32_bf16 v[96:99], v[174:177], v[190:193], v[96:99]
	v_mfma_f32_16x16x32_bf16 v[84:87], v[166:169], v[198:201], v[84:87]
	v_mfma_f32_16x16x32_bf16 v[80:83], v[174:177], v[198:201], v[80:83]
	v_mfma_f32_16x16x32_bf16 v[68:71], v[166:169], v[206:209], v[68:71]
	v_mfma_f32_16x16x32_bf16 v[64:67], v[174:177], v[206:209], v[64:67]
	v_mfma_f32_16x16x32_bf16 v[116:119], v[170:173], v[186:189], v[116:119]
	v_mfma_f32_16x16x32_bf16 v[112:115], v[178:181], v[186:189], v[112:115]
	v_mfma_f32_16x16x32_bf16 v[100:103], v[170:173], v[194:197], v[100:103]
	v_mfma_f32_16x16x32_bf16 v[96:99], v[178:181], v[194:197], v[96:99]
	v_mfma_f32_16x16x32_bf16 v[84:87], v[170:173], v[202:205], v[84:87]
	v_mfma_f32_16x16x32_bf16 v[80:83], v[178:181], v[202:205], v[80:83]
	v_mfma_f32_16x16x32_bf16 v[68:71], v[170:173], v[210:213], v[68:71]
	v_mfma_f32_16x16x32_bf16 v[64:67], v[178:181], v[210:213], v[64:67]
	s_setprio 0
	s_barrier
	s_add_i32 s12, s33, s20
	v_lshl_add_u64 v[142:143], s[16:17], 0, v[132:133]
	s_mov_b32 m0, s12
	ds_read_b128 v[182:185], v147 offset:16384
	ds_read_b128 v[186:189], v147 offset:17408
	ds_read_b128 v[190:193], v147 offset:18432
	ds_read_b128 v[194:197], v147 offset:19456
	ds_read_b128 v[198:201], v147 offset:20480
	ds_read_b128 v[202:205], v147 offset:21504
	ds_read_b128 v[206:209], v147 offset:22528
	ds_read_b128 v[210:213], v147 offset:23552
	global_load_lds_dwordx4 v[142:143], off
	s_add_i32 m0, s12, 0x2000
	s_add_u32 s12, s16, 0xb0000
	v_lshl_add_u64 v[214:215], s[16:17], 0, v[128:129]
	s_addc_u32 s13, s17, 0
	s_add_i32 s61, s34, s20
	global_load_lds_dwordx4 v[214:215], off
	v_lshl_add_u64 v[216:217], s[12:13], 0, v[132:133]
	s_mov_b32 m0, s61
	v_lshl_add_u64 v[218:219], s[18:19], 0, v[130:131]
	global_load_lds_dwordx4 v[216:217], off
	v_lshl_add_u64 v[216:217], s[12:13], 0, v[128:129]
	s_add_i32 m0, s61, 0x2000
	s_nop 0
	global_load_lds_dwordx4 v[216:217], off
	v_lshl_add_u64 v[216:217], s[18:19], 0, v[134:135]
	s_mov_b32 m0, s22
	s_nop 0
	global_load_lds_dwordx4 v[216:217], off
	s_mov_b32 m0, s23
	s_nop 0
	global_load_lds_dwordx4 v[218:219], off
	s_waitcnt vmcnt(8)
	s_waitcnt lgkmcnt(0)
	s_barrier
; #define PG8_STAGE(bufoff, gbase, voff) do { _Pragma("unroll") for (int _i = 0; _i < 2; ++_i) \
;     __builtin_amdgcn_global_load_lds((const unsigned*)((const char*)(gbase) + (voff)[_i]), (PG8_LAS unsigned*)(lds + (bufoff) + ldsw + _i * 8192), 16, 0, 0); } while (0)
; #define PG8_LDA(dst, b, h) do { _Pragma("unroll") for (int m = 0; m < 4; ++m) _Pragma("unroll") for (int k = 0; k < 2; ++k) dst[m][k] = *(const PG8_LAS bf16x8*)(lds + PG8_SA(b, h) + aoff + m * 2048 + k * 1024); } while (0)
; #define PG8_LDB(dst, b, h) do { _Pragma("unroll") for (int n = 0; n < 2; ++n) _Pragma("unroll") for (int k = 0; k < 2; ++k) dst[n][k] = *(const PG8_LAS bf16x8*)(lds + PG8_SB(b, h) + boff + n * 2048 + k * 1024); } while (0)
; #define PG8_MMA(ai, bj, At, Bt) do { __builtin_amdgcn_s_setprio(1); _Pragma("unroll") for (int m = 0; m < 4; ++m) _Pragma("unroll") for (int n = 0; n < 2; ++n) _Pragma("unroll") for (int k = 0; k < 2; ++k) \
;     acc[ai][bj][m][n] = __builtin_amdgcn_mfma_f32_16x16x32_bf16(Bt[n][k], At[m][k], acc[ai][bj][m][n], 0, 0, 0); __builtin_amdgcn_s_setprio(0); } while (0)
; #define PG8_WAIT_V(n) asm volatile("s_waitcnt vmcnt(" #n ")" ::: "memory")
; #define PG8_WAIT_L(n) asm volatile("s_waitcnt lgkmcnt(" #n ")" ::: "memory")
; #define PG8_BAR __builtin_amdgcn_s_barrier()
; #define PG8_SCHED __builtin_amdgcn_sched_barrier(0)
; template <class Epi, class Sched>
; DI void gemm_phase(PG8_LAS unsigned char* lds, const Gemm g, const Sched& S, const Epi& E) {
;     ...
;       PG8_WAIT_V(8); PG8_WAIT_L(0); PG8_BAR; PG8_MMA(1, 0, At, B0); PG8_MMA(1, 1, At, B1); PG8_BAR; PG8_SCHED;
;       PG8_LDB(B0, 1, 0); PG8_LDB(B1, 1, 1); PG8_SCHED; PG8_LDA(At, 1, 0); PG8_STAGE(PG8_SA(0, 1), a2 + hstepA, voffA);
;       PG8_WAIT_V(8); PG8_WAIT_L(0); PG8_BAR; PG8_MMA(0, 0, At, B0); PG8_MMA(0, 1, At, B1); PG8_BAR; PG8_SCHED;
;       PG8_LDA(At, 1, 1); PG8_STAGE(PG8_SB(1, 0), b3, voffB); PG8_STAGE(PG8_SB(1, 1), b3 + hstepB, voffB); PG8_STAGE(PG8_SA(1, 0), a3, voffA);
;       PG8_WAIT_V(8); PG8_WAIT_L(0); PG8_BAR; PG8_MMA(1, 0, At, B0); PG8_MMA(1, 1, At, B1); PG8_BAR; PG8_SCHED;
	s_setprio 1
	s_waitcnt lgkmcnt(0)
	v_mfma_f32_16x16x32_bf16 v[60:63], v[150:153], v[182:185], v[60:63]
	v_mfma_f32_16x16x32_bf16 v[56:59], v[158:161], v[182:185], v[56:59]
	v_mfma_f32_16x16x32_bf16 v[44:47], v[150:153], v[190:193], v[44:47]
	v_mfma_f32_16x16x32_bf16 v[40:43], v[158:161], v[190:193], v[40:43]
	v_mfma_f32_16x16x32_bf16 v[28:31], v[150:153], v[198:201], v[28:31]
	v_mfma_f32_16x16x32_bf16 v[24:27], v[158:161], v[198:201], v[24:27]
	v_mfma_f32_16x16x32_bf16 v[16:19], v[150:153], v[206:209], v[16:19]
	v_mfma_f32_16x16x32_bf16 v[8:11], v[158:161], v[206:209], v[8:11]
	v_mfma_f32_16x16x32_bf16 v[60:63], v[154:157], v[186:189], v[60:63]
	v_mfma_f32_16x16x32_bf16 v[56:59], v[162:165], v[186:189], v[56:59]
	v_mfma_f32_16x16x32_bf16 v[44:47], v[154:157], v[194:197], v[44:47]
	v_mfma_f32_16x16x32_bf16 v[40:43], v[162:165], v[194:197], v[40:43]
	v_mfma_f32_16x16x32_bf16 v[28:31], v[154:157], v[202:205], v[28:31]
	v_mfma_f32_16x16x32_bf16 v[24:27], v[162:165], v[202:205], v[24:27]
	v_mfma_f32_16x16x32_bf16 v[16:19], v[154:157], v[210:213], v[16:19]
	v_mfma_f32_16x16x32_bf16 v[8:11], v[162:165], v[210:213], v[8:11]
	s_setprio 0
	s_setprio 1
	v_mfma_f32_16x16x32_bf16 v[52:55], v[166:169], v[182:185], v[52:55]
	v_mfma_f32_16x16x32_bf16 v[48:51], v[174:177], v[182:185], v[48:51]
	v_mfma_f32_16x16x32_bf16 v[36:39], v[166:169], v[190:193], v[36:39]
	v_mfma_f32_16x16x32_bf16 v[32:35], v[174:177], v[190:193], v[32:35]
	v_mfma_f32_16x16x32_bf16 v[20:23], v[166:169], v[198:201], v[20:23]
	v_mfma_f32_16x16x32_bf16 v[12:15], v[174:177], v[198:201], v[12:15]
	v_mfma_f32_16x16x32_bf16 v[4:7], v[166:169], v[206:209], v[4:7]
	v_mfma_f32_16x16x32_bf16 v[0:3], v[174:177], v[206:209], v[0:3]
	v_mfma_f32_16x16x32_bf16 v[52:55], v[170:173], v[186:189], v[52:55]
	v_mfma_f32_16x16x32_bf16 v[48:51], v[178:181], v[186:189], v[48:51]
	v_mfma_f32_16x16x32_bf16 v[36:39], v[170:173], v[194:197], v[36:39]
	v_mfma_f32_16x16x32_bf16 v[32:35], v[178:181], v[194:197], v[32:35]
	v_mfma_f32_16x16x32_bf16 v[20:23], v[170:173], v[202:205], v[20:23]
	v_mfma_f32_16x16x32_bf16 v[12:15], v[178:181], v[202:205], v[12:15]
	v_mfma_f32_16x16x32_bf16 v[4:7], v[170:173], v[210:213], v[4:7]
	v_mfma_f32_16x16x32_bf16 v[0:3], v[178:181], v[210:213], v[0:3]
	s_setprio 0
	s_barrier
	s_add_i32 s61, s30, 0x110
	v_add_u32_e32 v149, s61, v144
	ds_read_b128 v[150:153], v149
	ds_read_b128 v[154:157], v149 offset:1024
	ds_read_b128 v[158:161], v149 offset:2048
	ds_read_b128 v[162:165], v149 offset:3072
	ds_read_b128 v[166:169], v148
	ds_read_b128 v[170:173], v148 offset:1024
	ds_read_b128 v[174:177], v148 offset:2048
	ds_read_b128 v[178:181], v148 offset:3072
	s_add_u32 s12, s18, 0xb0000
	s_addc_u32 s13, s19, 0
	s_mov_b32 m0, s24
	v_lshl_add_u64 v[220:221], s[12:13], 0, v[134:135]
	ds_read_b128 v[182:185], v147 offset:32768
	ds_read_b128 v[186:189], v147 offset:33792
	ds_read_b128 v[190:193], v147 offset:34816
	ds_read_b128 v[194:197], v147 offset:35840
	ds_read_b128 v[198:201], v147 offset:36864
	ds_read_b128 v[202:205], v147 offset:37888
	ds_read_b128 v[206:209], v147 offset:38912
	ds_read_b128 v[210:213], v147 offset:39936
	global_load_lds_dwordx4 v[220:221], off
	v_lshl_add_u64 v[220:221], s[12:13], 0, v[130:131]
	s_mov_b32 m0, s25
	s_nop 0
	global_load_lds_dwordx4 v[220:221], off
	s_waitcnt vmcnt(8)
	s_waitcnt lgkmcnt(0)
	s_barrier
	s_setprio 1
	s_waitcnt lgkmcnt(0)
	v_mfma_f32_16x16x32_bf16 v[124:127], v[150:153], v[182:185], v[124:127]
	v_mfma_f32_16x16x32_bf16 v[120:123], v[158:161], v[182:185], v[120:123]
	v_mfma_f32_16x16x32_bf16 v[108:111], v[150:153], v[190:193], v[108:111]
	v_mfma_f32_16x16x32_bf16 v[104:107], v[158:161], v[190:193], v[104:107]
	v_mfma_f32_16x16x32_bf16 v[92:95], v[150:153], v[198:201], v[92:95]
	v_mfma_f32_16x16x32_bf16 v[88:91], v[158:161], v[198:201], v[88:91]
	v_mfma_f32_16x16x32_bf16 v[76:79], v[150:153], v[206:209], v[76:79]
	v_mfma_f32_16x16x32_bf16 v[72:75], v[158:161], v[206:209], v[72:75]
	v_mfma_f32_16x16x32_bf16 v[124:127], v[154:157], v[186:189], v[124:127]
	v_mfma_f32_16x16x32_bf16 v[120:123], v[162:165], v[186:189], v[120:123]
	v_mfma_f32_16x16x32_bf16 v[108:111], v[154:157], v[194:197], v[108:111]
	v_mfma_f32_16x16x32_bf16 v[104:107], v[162:165], v[194:197], v[104:107]
	v_mfma_f32_16x16x32_bf16 v[92:95], v[154:157], v[202:205], v[92:95]
	v_mfma_f32_16x16x32_bf16 v[88:91], v[162:165], v[202:205], v[88:91]
	v_mfma_f32_16x16x32_bf16 v[76:79], v[154:157], v[210:213], v[76:79]
	v_mfma_f32_16x16x32_bf16 v[72:75], v[162:165], v[210:213], v[72:75]
	s_setprio 0
	s_setprio 1
	v_mfma_f32_16x16x32_bf16 v[116:119], v[166:169], v[182:185], v[116:119]
	v_mfma_f32_16x16x32_bf16 v[112:115], v[174:177], v[182:185], v[112:115]
	v_mfma_f32_16x16x32_bf16 v[100:103], v[166:169], v[190:193], v[100:103]
	v_mfma_f32_16x16x32_bf16 v[96:99], v[174:177], v[190:193], v[96:99]
	v_mfma_f32_16x16x32_bf16 v[84:87], v[166:169], v[198:201], v[84:87]
	v_mfma_f32_16x16x32_bf16 v[80:83], v[174:177], v[198:201], v[80:83]
	v_mfma_f32_16x16x32_bf16 v[68:71], v[166:169], v[206:209], v[68:71]
	v_mfma_f32_16x16x32_bf16 v[64:67], v[174:177], v[206:209], v[64:67]
	v_mfma_f32_16x16x32_bf16 v[116:119], v[170:173], v[186:189], v[116:119]
	v_mfma_f32_16x16x32_bf16 v[112:115], v[178:181], v[186:189], v[112:115]
	v_mfma_f32_16x16x32_bf16 v[100:103], v[170:173], v[194:197], v[100:103]
	v_mfma_f32_16x16x32_bf16 v[96:99], v[178:181], v[194:197], v[96:99]
	v_mfma_f32_16x16x32_bf16 v[84:87], v[170:173], v[202:205], v[84:87]
	v_mfma_f32_16x16x32_bf16 v[80:83], v[178:181], v[202:205], v[80:83]
	v_mfma_f32_16x16x32_bf16 v[68:71], v[170:173], v[210:213], v[68:71]
	v_mfma_f32_16x16x32_bf16 v[64:67], v[178:181], v[210:213], v[64:67]
	s_setprio 0
	s_barrier
; #define PG8_MMA(ai, bj, At, Bt) do { __builtin_amdgcn_s_setprio(1); _Pragma("unroll") for (int m = 0; m < 4; ++m) _Pragma("unroll") for (int n = 0; n < 2; ++n) _Pragma("unroll") for (int k = 0; k < 2; ++k) \
;     acc[ai][bj][m][n] = __builtin_amdgcn_mfma_f32_16x16x32_bf16(Bt[n][k], At[m][k], acc[ai][bj][m][n], 0, 0, 0); __builtin_amdgcn_s_setprio(0); } while (0)
; #define PG8_WAIT_V(n) asm volatile("s_waitcnt vmcnt(" #n ")" ::: "memory")
; #define PG8_WAIT_L(n) asm volatile("s_waitcnt lgkmcnt(" #n ")" ::: "memory")
; #define PG8_BAR __builtin_amdgcn_s_barrier()
; #define PG8_SCHED __builtin_amdgcn_sched_barrier(0)
;   DI void operator()(const f32x4 (&acc)[2][2][4][2], const Unit& u, int wr, int wc, int fr, int fq) const {
;     ...
;     RES_LD(0)
; #pragma unroll
;     for (int i = 0; i < 8; ++i) {
;       const int ai = i >> 2, m = i & 3;
;       if (i + 1 < 8) RES_LD(i + 1)
; template <class Epi, class Sched>
; DI void gemm_phase(PG8_LAS unsigned char* lds, const Gemm g, const Sched& S, const Epi& E) {
;     ...
;       PG8_WAIT_V(8); PG8_WAIT_L(0); PG8_BAR; PG8_MMA(1, 0, At, B0); PG8_MMA(1, 1, At, B1); PG8_BAR; PG8_SCHED;
;     }
;     if (wr == 0) PG8_BAR;
	s_add_i32 s12, s61, s20
	v_lshl_add_u64 v[142:143], v[142:143], 0, s[4:5]
	s_mov_b32 m0, s12
	ds_read_b128 v[182:185], v147 offset:49152
	ds_read_b128 v[186:189], v147 offset:50176
	ds_read_b128 v[190:193], v147 offset:51200
	ds_read_b128 v[194:197], v147 offset:52224
	ds_read_b128 v[198:201], v147 offset:53248
	ds_read_b128 v[202:205], v147 offset:54272
	ds_read_b128 v[206:209], v147 offset:55296
	ds_read_b128 v[210:213], v147 offset:56320
	global_load_lds_dwordx4 v[142:143], off
	s_add_i32 m0, s12, 0x2000
	s_add_u32 s12, s16, 0xb0080
	v_lshl_add_u64 v[142:143], v[214:215], 0, s[4:5]
	s_addc_u32 s13, s17, 0
	s_add_i32 s16, s53, s20
	global_load_lds_dwordx4 v[142:143], off
	v_lshl_add_u64 v[142:143], s[12:13], 0, v[132:133]
	s_mov_b32 m0, s16
	s_nop 0
	global_load_lds_dwordx4 v[142:143], off
	v_lshl_add_u64 v[142:143], s[12:13], 0, v[128:129]
	s_add_i32 m0, s16, 0x2000
	s_nop 0
	global_load_lds_dwordx4 v[142:143], off
	v_lshl_add_u64 v[142:143], v[216:217], 0, s[4:5]
	s_mov_b32 m0, s28
	s_nop 0
	global_load_lds_dwordx4 v[142:143], off
	v_lshl_add_u64 v[142:143], v[218:219], 0, s[4:5]
	s_mov_b32 m0, s29
	s_nop 0
	global_load_lds_dwordx4 v[142:143], off
	s_waitcnt vmcnt(8)
	s_waitcnt lgkmcnt(0)
	s_barrier
	s_setprio 1
	s_waitcnt lgkmcnt(0)
	v_mfma_f32_16x16x32_bf16 v[60:63], v[150:153], v[182:185], v[60:63]
	v_mfma_f32_16x16x32_bf16 v[56:59], v[158:161], v[182:185], v[56:59]
	v_mfma_f32_16x16x32_bf16 v[44:47], v[150:153], v[190:193], v[44:47]
	v_mfma_f32_16x16x32_bf16 v[40:43], v[158:161], v[190:193], v[40:43]
	v_mfma_f32_16x16x32_bf16 v[28:31], v[150:153], v[198:201], v[28:31]
	v_mfma_f32_16x16x32_bf16 v[24:27], v[158:161], v[198:201], v[24:27]
	v_mfma_f32_16x16x32_bf16 v[16:19], v[150:153], v[206:209], v[16:19]
	v_mfma_f32_16x16x32_bf16 v[8:11], v[158:161], v[206:209], v[8:11]
	v_mfma_f32_16x16x32_bf16 v[60:63], v[154:157], v[186:189], v[60:63]
	v_mfma_f32_16x16x32_bf16 v[56:59], v[162:165], v[186:189], v[56:59]
	v_mfma_f32_16x16x32_bf16 v[44:47], v[154:157], v[194:197], v[44:47]
	v_mfma_f32_16x16x32_bf16 v[40:43], v[162:165], v[194:197], v[40:43]
	v_mfma_f32_16x16x32_bf16 v[28:31], v[154:157], v[202:205], v[28:31]
	v_mfma_f32_16x16x32_bf16 v[24:27], v[162:165], v[202:205], v[24:27]
	v_mfma_f32_16x16x32_bf16 v[16:19], v[154:157], v[210:213], v[16:19]
	v_mfma_f32_16x16x32_bf16 v[8:11], v[162:165], v[210:213], v[8:11]
	s_setprio 0
	s_setprio 1
	v_mfma_f32_16x16x32_bf16 v[52:55], v[166:169], v[182:185], v[52:55]
	v_mfma_f32_16x16x32_bf16 v[48:51], v[174:177], v[182:185], v[48:51]
	v_mfma_f32_16x16x32_bf16 v[36:39], v[166:169], v[190:193], v[36:39]
	v_mfma_f32_16x16x32_bf16 v[32:35], v[174:177], v[190:193], v[32:35]
	v_mfma_f32_16x16x32_bf16 v[20:23], v[166:169], v[198:201], v[20:23]
	v_mfma_f32_16x16x32_bf16 v[12:15], v[174:177], v[198:201], v[12:15]
	v_mfma_f32_16x16x32_bf16 v[4:7], v[166:169], v[206:209], v[4:7]
	v_mfma_f32_16x16x32_bf16 v[0:3], v[174:177], v[206:209], v[0:3]
	v_mfma_f32_16x16x32_bf16 v[52:55], v[170:173], v[186:189], v[52:55]
	v_mfma_f32_16x16x32_bf16 v[48:51], v[178:181], v[186:189], v[48:51]
	v_mfma_f32_16x16x32_bf16 v[36:39], v[170:173], v[194:197], v[36:39]
	v_mfma_f32_16x16x32_bf16 v[32:35], v[178:181], v[194:197], v[32:35]
	v_mfma_f32_16x16x32_bf16 v[20:23], v[170:173], v[202:205], v[20:23]
	v_mfma_f32_16x16x32_bf16 v[12:15], v[178:181], v[202:205], v[12:15]
	v_mfma_f32_16x16x32_bf16 v[4:7], v[170:173], v[210:213], v[4:7]
	v_mfma_f32_16x16x32_bf16 v[0:3], v[178:181], v[210:213], v[0:3]
	s_setprio 0
	s_barrier
	s_add_i32 s60, s60, 2
	s_add_u32 s58, s58, 0x100
	s_addc_u32 s59, s59, 0
	s_cmp_gt_u32 s60, 41
	s_mov_b64 s[12:13], s[14:15]
	s_cbranch_scc0 .LBB0_1456
	v_lshl_add_u32 v142, s57, 8, v137
	v_ashrrev_i32_e32 v143, 31, v142
	s_lshl_b32 s12, s56, 8
	v_lshlrev_b64 v[142:143], 10, v[142:143]
	s_ashr_i32 s13, s12, 31
	v_lshl_add_u64 v[166:167], v[142:143], 0, s[12:13]
	v_or_b32_e32 v166, v166, v136
	v_lshl_add_u64 v[142:143], v[166:167], 1, s[50:51]
	v_add_co_u32_e32 v162, vcc, s31, v142
	global_load_dwordx4 v[150:153], v[142:143], off
	global_load_dwordx4 v[154:157], v[142:143], off offset:256
	v_addc_co_u32_e32 v163, vcc, 0, v143, vcc
	global_load_dwordx4 v[158:161], v[162:163], off
	s_nop 0
	global_load_dwordx4 v[162:165], v[162:163], off offset:256
	s_and_b64 vcc, exec, s[6:7]
	s_cbranch_vccz .LBB0_1459
	s_barrier
; DI unsigned pack2(float a, float b) { bf2_t v = __builtin_convertvector((f32x2){a, b}, bf2_t); return __builtin_bit_cast(unsigned, v); }
;   DI void operator()(const f32x4 (&acc)[2][2][4][2], const Unit& u, int wr, int wc, int fr, int fq) const {
;     ...
;     RES_LD(0)
; #pragma unroll
;     for (int i = 0; i < 8; ++i) {
;       const int ai = i >> 2, m = i & 3;
;       if (i + 1 < 8) RES_LD(i + 1)
;       __builtin_amdgcn_sched_barrier(0);
;       const size_t idx = base + (size_t)(ai * HALF + m * 16) * DM;
;       float ssum = 0.f;
; #pragma unroll
;       for (int bj = 0; bj < 2; ++bj) {
;         f32x4 x0, x1;
;         if (FIRST) { x0 = xv[i & 1][2 * bj]; x1 = xv[i & 1][2 * bj + 1]; }
;         else {
;           const u32x4 hw = xh[i & 1][bj];
;           x0 = (f32x4){__uint_as_float(hw.x << 16), __uint_as_float(hw.x & 0xffff0000u), __uint_as_float(hw.y << 16), __uint_as_float(hw.y & 0xffff0000u)};
;           x1 = (f32x4){__uint_as_float(hw.z << 16), __uint_as_float(hw.z & 0xffff0000u), __uint_as_float(hw.w << 16), __uint_as_float(hw.w & 0xffff0000u)};
;         }
;         const f32x4 v0 = x0 + acc[ai][bj][m][0], v1 = x1 + acc[ai][bj][m][1];
;         if (LAST) { *(f32x4*)(xout32 + idx + bj * HALF) = v0; *(f32x4*)(xout32 + idx + bj * HALF + 4) = v1; }
;         else {
;           ssum += (v0[0] * v0[0] + v0[1] * v0[1]) + (v0[2] * v0[2] + v0[3] * v0[3]) + (v1[0] * v1[0] + v1[1] * v1[1]) + (v1[2] * v1[2] + v1[3] * v1[3]);
;           u32x4 w; w.x = pack2(v0[0], v0[1]); w.y = pack2(v0[2], v0[3]); w.z = pack2(v1[0], v1[1]); w.w = pack2(v1[2], v1[3]);
;           *(u32x4*)(xb + idx + bj * HALF) = w;
.LBB0_1459:
	s_waitcnt vmcnt(0)
	v_lshlrev_b32_e32 v168, 16, v150
	v_and_b32_e32 v169, 0xffff0000, v150
	v_lshlrev_b32_e32 v150, 16, v151
	v_and_b32_e32 v151, 0xffff0000, v151
	v_lshlrev_b32_e32 v170, 16, v152
	v_and_b32_e32 v171, 0xffff0000, v152
	v_lshlrev_b32_e32 v152, 16, v153
	v_and_b32_e32 v153, 0xffff0000, v153
	v_pk_add_f32 v[126:127], v[126:127], v[150:151]
	v_pk_add_f32 v[124:125], v[124:125], v[168:169]
	v_pk_add_f32 v[150:151], v[120:121], v[170:171]
	v_lshl_add_u64 v[120:121], v[166:167], 2, s[84:85]
	v_pk_add_f32 v[152:153], v[122:123], v[152:153]
	global_store_dwordx4 v[120:121], v[124:127], off
	global_store_dwordx4 v[120:121], v[150:153], off offset:16
	v_lshlrev_b32_e32 v122, 16, v154
	v_and_b32_e32 v123, 0xffff0000, v154
	v_lshlrev_b32_e32 v124, 16, v155
	v_and_b32_e32 v125, 0xffff0000, v155
	v_lshlrev_b32_e32 v126, 16, v156
	v_and_b32_e32 v127, 0xffff0000, v156
	v_lshlrev_b32_e32 v150, 16, v157
	v_and_b32_e32 v151, 0xffff0000, v157
	v_pk_add_f32 v[118:119], v[118:119], v[124:125]
	v_pk_add_f32 v[116:117], v[116:117], v[122:123]
	v_pk_add_f32 v[114:115], v[114:115], v[150:151]
	v_pk_add_f32 v[112:113], v[112:113], v[126:127]
	global_store_dwordx4 v[120:121], v[116:119], off offset:512
	global_store_dwordx4 v[120:121], v[112:115], off offset:528
	s_nop 0
	v_add_co_u32_e32 v116, vcc, s27, v142
	s_nop 1
	v_addc_co_u32_e32 v117, vcc, 0, v143, vcc
	global_load_dwordx4 v[112:115], v[116:117], off
	s_nop 0
	global_load_dwordx4 v[116:119], v[116:117], off offset:256
	v_lshlrev_b32_e32 v122, 16, v158
	v_and_b32_e32 v123, 0xffff0000, v158
	v_lshlrev_b32_e32 v124, 16, v159
	v_and_b32_e32 v125, 0xffff0000, v159
	v_lshlrev_b32_e32 v126, 16, v160
	v_and_b32_e32 v127, 0xffff0000, v160
	v_lshlrev_b32_e32 v150, 16, v161
	v_and_b32_e32 v151, 0xffff0000, v161
	v_pk_add_f32 v[108:109], v[108:109], v[122:123]
	v_add_co_u32_e32 v122, vcc, s27, v120
	v_pk_add_f32 v[110:111], v[110:111], v[124:125]
	v_pk_add_f32 v[106:107], v[106:107], v[150:151]
	v_pk_add_f32 v[104:105], v[104:105], v[126:127]
	v_addc_co_u32_e32 v123, vcc, 0, v121, vcc
	global_store_dwordx4 v[122:123], v[108:111], off
	global_store_dwordx4 v[122:123], v[104:107], off offset:16
	s_nop 0
	v_lshlrev_b32_e32 v108, 16, v164
	v_lshlrev_b32_e32 v104, 16, v162
	v_and_b32_e32 v105, 0xffff0000, v162
	v_lshlrev_b32_e32 v106, 16, v163
	v_and_b32_e32 v107, 0xffff0000, v163
	v_and_b32_e32 v109, 0xffff0000, v164
	v_lshlrev_b32_e32 v110, 16, v165
	v_and_b32_e32 v111, 0xffff0000, v165
	v_pk_add_f32 v[102:103], v[102:103], v[106:107]
	v_pk_add_f32 v[100:101], v[100:101], v[104:105]
	v_pk_add_f32 v[98:99], v[98:99], v[110:111]
	v_pk_add_f32 v[96:97], v[96:97], v[108:109]
	global_store_dwordx4 v[122:123], v[100:103], off offset:512
	global_store_dwordx4 v[122:123], v[96:99], off offset:528
	s_nop 0
	v_add_co_u32_e32 v100, vcc, s30, v142
	s_nop 1
	v_addc_co_u32_e32 v101, vcc, 0, v143, vcc
	global_load_dwordx4 v[96:99], v[100:101], off
	s_nop 0
	global_load_dwordx4 v[100:103], v[100:101], off offset:256
	s_waitcnt vmcnt(7)
	v_lshlrev_b32_e32 v104, 16, v112
	v_and_b32_e32 v105, 0xffff0000, v112
	v_lshlrev_b32_e32 v106, 16, v113
	v_and_b32_e32 v107, 0xffff0000, v113
	v_lshlrev_b32_e32 v108, 16, v114
	v_and_b32_e32 v109, 0xffff0000, v114
	v_lshlrev_b32_e32 v110, 16, v115
	v_and_b32_e32 v111, 0xffff0000, v115
	v_pk_add_f32 v[92:93], v[92:93], v[104:105]
	v_add_co_u32_e32 v104, vcc, s35, v120
	v_pk_add_f32 v[94:95], v[94:95], v[106:107]
	v_pk_add_f32 v[90:91], v[90:91], v[110:111]
	v_pk_add_f32 v[88:89], v[88:89], v[108:109]
	v_addc_co_u32_e32 v105, vcc, 0, v121, vcc
	global_store_dwordx4 v[104:105], v[92:95], off
	global_store_dwordx4 v[104:105], v[88:91], off offset:16
	s_waitcnt vmcnt(8)
	v_lshlrev_b32_e32 v92, 16, v118
	v_lshlrev_b32_e32 v88, 16, v116
	v_and_b32_e32 v89, 0xffff0000, v116
	v_lshlrev_b32_e32 v90, 16, v117
	v_and_b32_e32 v91, 0xffff0000, v117
	v_and_b32_e32 v93, 0xffff0000, v118
	v_lshlrev_b32_e32 v94, 16, v119
	v_and_b32_e32 v95, 0xffff0000, v119
	v_pk_add_f32 v[86:87], v[86:87], v[90:91]
	v_pk_add_f32 v[84:85], v[84:85], v[88:89]
	v_pk_add_f32 v[82:83], v[82:83], v[94:95]
	v_pk_add_f32 v[80:81], v[80:81], v[92:93]
	global_store_dwordx4 v[104:105], v[84:87], off offset:512
	global_store_dwordx4 v[104:105], v[80:83], off offset:528
	s_nop 0
	v_add_co_u32_e32 v84, vcc, s36, v142
	s_nop 1
	v_addc_co_u32_e32 v85, vcc, 0, v143, vcc
	global_load_dwordx4 v[80:83], v[84:85], off
	s_nop 0
	global_load_dwordx4 v[84:87], v[84:85], off offset:256
	s_waitcnt vmcnt(7)
	v_lshlrev_b32_e32 v88, 16, v96
	v_and_b32_e32 v89, 0xffff0000, v96
	v_lshlrev_b32_e32 v90, 16, v97
	v_and_b32_e32 v91, 0xffff0000, v97
	v_lshlrev_b32_e32 v92, 16, v98
	v_and_b32_e32 v93, 0xffff0000, v98
	v_lshlrev_b32_e32 v94, 16, v99
	v_and_b32_e32 v95, 0xffff0000, v99
	v_pk_add_f32 v[76:77], v[76:77], v[88:89]
	v_add_co_u32_e32 v88, vcc, s37, v120
	v_pk_add_f32 v[78:79], v[78:79], v[90:91]
	v_pk_add_f32 v[74:75], v[74:75], v[94:95]
	v_pk_add_f32 v[72:73], v[72:73], v[92:93]
	v_addc_co_u32_e32 v89, vcc, 0, v121, vcc
	global_store_dwordx4 v[88:89], v[76:79], off
	global_store_dwordx4 v[88:89], v[72:75], off offset:16
	s_waitcnt vmcnt(8)
	v_lshlrev_b32_e32 v76, 16, v102
	v_lshlrev_b32_e32 v72, 16, v100
	v_and_b32_e32 v73, 0xffff0000, v100
	v_lshlrev_b32_e32 v74, 16, v101
	v_and_b32_e32 v75, 0xffff0000, v101
	v_and_b32_e32 v77, 0xffff0000, v102
	v_lshlrev_b32_e32 v78, 16, v103
	v_and_b32_e32 v79, 0xffff0000, v103
	v_pk_add_f32 v[70:71], v[70:71], v[74:75]
	v_pk_add_f32 v[68:69], v[68:69], v[72:73]
	v_pk_add_f32 v[66:67], v[66:67], v[78:79]
	v_pk_add_f32 v[64:65], v[64:65], v[76:77]
	global_store_dwordx4 v[88:89], v[68:71], off offset:512
	global_store_dwordx4 v[88:89], v[64:67], off offset:528
	s_nop 0
	v_add_co_u32_e32 v68, vcc, s38, v142
	s_nop 1
	v_addc_co_u32_e32 v69, vcc, 0, v143, vcc
	global_load_dwordx4 v[64:67], v[68:69], off
	s_nop 0
	global_load_dwordx4 v[68:71], v[68:69], off offset:256
	s_waitcnt vmcnt(7)
; DI unsigned pack2(float a, float b) { bf2_t v = __builtin_convertvector((f32x2){a, b}, bf2_t); return __builtin_bit_cast(unsigned, v); }
; #define PG8_BAR __builtin_amdgcn_s_barrier()
;   DI void operator()(const f32x4 (&acc)[2][2][4][2], const Unit& u, int wr, int wc, int fr, int fq) const {
;     ...
;     for (int i = 0; i < 8; ++i) {
;       const int ai = i >> 2, m = i & 3;
;       if (i + 1 < 8) RES_LD(i + 1)
;       __builtin_amdgcn_sched_barrier(0);
;       const size_t idx = base + (size_t)(ai * HALF + m * 16) * DM;
;       float ssum = 0.f;
; #pragma unroll
;       for (int bj = 0; bj < 2; ++bj) {
;         f32x4 x0, x1;
;         if (FIRST) { x0 = xv[i & 1][2 * bj]; x1 = xv[i & 1][2 * bj + 1]; }
;         else {
;           const u32x4 hw = xh[i & 1][bj];
;           x0 = (f32x4){__uint_as_float(hw.x << 16), __uint_as_float(hw.x & 0xffff0000u), __uint_as_float(hw.y << 16), __uint_as_float(hw.y & 0xffff0000u)};
;           x1 = (f32x4){__uint_as_float(hw.z << 16), __uint_as_float(hw.z & 0xffff0000u), __uint_as_float(hw.w << 16), __uint_as_float(hw.w & 0xffff0000u)};
;         }
;         const f32x4 v0 = x0 + acc[ai][bj][m][0], v1 = x1 + acc[ai][bj][m][1];
;         if (LAST) { *(f32x4*)(xout32 + idx + bj * HALF) = v0; *(f32x4*)(xout32 + idx + bj * HALF + 4) = v1; }
;         else {
;           ssum += (v0[0] * v0[0] + v0[1] * v0[1]) + (v0[2] * v0[2] + v0[3] * v0[3]) + (v1[0] * v1[0] + v1[1] * v1[1]) + (v1[2] * v1[2] + v1[3] * v1[3]);
;           u32x4 w; w.x = pack2(v0[0], v0[1]); w.y = pack2(v0[2], v0[3]); w.z = pack2(v1[0], v1[1]); w.w = pack2(v1[2], v1[3]);
;           *(u32x4*)(xb + idx + bj * HALF) = w;
;         }
;       }
;       if (!LAST) {
;         ssum += __shfl_xor(ssum, 16); ssum += __shfl_xor(ssum, 32);
;         if (fq == 0) ps_out[(size_t)(row0 + ai * HALF + m * 16) * 16 + u.pn * 4 + wc] = ssum;
;       }
;       __builtin_amdgcn_sched_barrier(0);
; template <class Epi, class Sched>
; DI void gemm_phase(PG8_LAS unsigned char* lds, const Gemm g, const Sched& S, const Epi& E) {
;     ...
;     if (!has_next) break;
; #pragma unroll
;     for (int a = 0; a < 2; ++a)
; #pragma unroll
;       for (int b = 0; b < 2; ++b)
; #pragma unroll
;         for (int m = 0; m < 4; ++m)
; #pragma unroll
;           for (int n = 0; n < 2; ++n) acc[a][b][m][n] = (f32x4){0.f, 0.f, 0.f, 0.f};
;     cur = nxt; cA = nA; cB = nB; ++ui;
;     if (wr == 1) PG8_BAR;
	v_lshlrev_b32_e32 v72, 16, v80
	v_and_b32_e32 v73, 0xffff0000, v80
	v_lshlrev_b32_e32 v74, 16, v81
	v_and_b32_e32 v75, 0xffff0000, v81
	v_lshlrev_b32_e32 v76, 16, v82
	v_and_b32_e32 v77, 0xffff0000, v82
	v_lshlrev_b32_e32 v78, 16, v83
	v_and_b32_e32 v79, 0xffff0000, v83
	v_pk_add_f32 v[60:61], v[60:61], v[72:73]
	v_add_co_u32_e32 v72, vcc, s39, v120
	v_pk_add_f32 v[62:63], v[62:63], v[74:75]
	v_pk_add_f32 v[58:59], v[58:59], v[78:79]
	v_pk_add_f32 v[56:57], v[56:57], v[76:77]
	v_addc_co_u32_e32 v73, vcc, 0, v121, vcc
	global_store_dwordx4 v[72:73], v[60:63], off
	global_store_dwordx4 v[72:73], v[56:59], off offset:16
	s_waitcnt vmcnt(8)
	v_lshlrev_b32_e32 v60, 16, v86
	v_lshlrev_b32_e32 v56, 16, v84
	v_and_b32_e32 v57, 0xffff0000, v84
	v_lshlrev_b32_e32 v58, 16, v85
	v_and_b32_e32 v59, 0xffff0000, v85
	v_and_b32_e32 v61, 0xffff0000, v86
	v_lshlrev_b32_e32 v62, 16, v87
	v_and_b32_e32 v63, 0xffff0000, v87
	v_pk_add_f32 v[54:55], v[54:55], v[58:59]
	v_pk_add_f32 v[52:53], v[52:53], v[56:57]
	v_pk_add_f32 v[50:51], v[50:51], v[62:63]
	v_pk_add_f32 v[48:49], v[48:49], v[60:61]
	global_store_dwordx4 v[72:73], v[52:55], off offset:512
	global_store_dwordx4 v[72:73], v[48:51], off offset:528
	s_nop 0
	v_add_co_u32_e32 v52, vcc, s40, v142
	s_nop 1
	v_addc_co_u32_e32 v53, vcc, 0, v143, vcc
	global_load_dwordx4 v[48:51], v[52:53], off
	s_nop 0
	global_load_dwordx4 v[52:55], v[52:53], off offset:256
	s_waitcnt vmcnt(7)
	v_lshlrev_b32_e32 v56, 16, v64
	v_and_b32_e32 v57, 0xffff0000, v64
	v_lshlrev_b32_e32 v58, 16, v65
	v_and_b32_e32 v59, 0xffff0000, v65
	v_lshlrev_b32_e32 v60, 16, v66
	v_and_b32_e32 v61, 0xffff0000, v66
	v_lshlrev_b32_e32 v62, 16, v67
	v_and_b32_e32 v63, 0xffff0000, v67
	v_pk_add_f32 v[44:45], v[44:45], v[56:57]
	v_add_co_u32_e32 v56, vcc, s41, v120
	v_pk_add_f32 v[46:47], v[46:47], v[58:59]
	v_pk_add_f32 v[42:43], v[42:43], v[62:63]
	v_pk_add_f32 v[40:41], v[40:41], v[60:61]
	v_addc_co_u32_e32 v57, vcc, 0, v121, vcc
	global_store_dwordx4 v[56:57], v[44:47], off
	global_store_dwordx4 v[56:57], v[40:43], off offset:16
	s_waitcnt vmcnt(8)
	v_lshlrev_b32_e32 v44, 16, v70
	v_lshlrev_b32_e32 v40, 16, v68
	v_and_b32_e32 v41, 0xffff0000, v68
	v_lshlrev_b32_e32 v42, 16, v69
	v_and_b32_e32 v43, 0xffff0000, v69
	v_and_b32_e32 v45, 0xffff0000, v70
	v_lshlrev_b32_e32 v46, 16, v71
	v_and_b32_e32 v47, 0xffff0000, v71
	v_pk_add_f32 v[38:39], v[38:39], v[42:43]
	v_pk_add_f32 v[36:37], v[36:37], v[40:41]
	v_pk_add_f32 v[34:35], v[34:35], v[46:47]
	v_pk_add_f32 v[32:33], v[32:33], v[44:45]
	global_store_dwordx4 v[56:57], v[36:39], off offset:512
	global_store_dwordx4 v[56:57], v[32:35], off offset:528
	s_nop 0
	v_add_co_u32_e32 v36, vcc, s44, v142
	s_nop 1
	v_addc_co_u32_e32 v37, vcc, 0, v143, vcc
	global_load_dwordx4 v[32:35], v[36:37], off
	s_nop 0
	global_load_dwordx4 v[36:39], v[36:37], off offset:256
	s_waitcnt vmcnt(7)
	v_lshlrev_b32_e32 v40, 16, v48
	v_and_b32_e32 v41, 0xffff0000, v48
	v_lshlrev_b32_e32 v42, 16, v49
	v_and_b32_e32 v43, 0xffff0000, v49
	v_lshlrev_b32_e32 v44, 16, v50
	v_and_b32_e32 v45, 0xffff0000, v50
	v_lshlrev_b32_e32 v46, 16, v51
	v_and_b32_e32 v47, 0xffff0000, v51
	v_pk_add_f32 v[28:29], v[28:29], v[40:41]
	v_add_co_u32_e32 v40, vcc, s45, v120
	v_pk_add_f32 v[30:31], v[30:31], v[42:43]
	v_pk_add_f32 v[26:27], v[26:27], v[46:47]
	v_pk_add_f32 v[24:25], v[24:25], v[44:45]
	v_addc_co_u32_e32 v41, vcc, 0, v121, vcc
	global_store_dwordx4 v[40:41], v[28:31], off
	global_store_dwordx4 v[40:41], v[24:27], off offset:16
	s_waitcnt vmcnt(8)
	v_lshlrev_b32_e32 v28, 16, v54
	v_lshlrev_b32_e32 v24, 16, v52
	v_and_b32_e32 v25, 0xffff0000, v52
	v_lshlrev_b32_e32 v26, 16, v53
	v_and_b32_e32 v27, 0xffff0000, v53
	v_and_b32_e32 v29, 0xffff0000, v54
	v_lshlrev_b32_e32 v30, 16, v55
	v_and_b32_e32 v31, 0xffff0000, v55
	v_pk_add_f32 v[22:23], v[22:23], v[26:27]
	v_pk_add_f32 v[20:21], v[20:21], v[24:25]
	v_pk_add_f32 v[14:15], v[14:15], v[30:31]
	v_pk_add_f32 v[12:13], v[12:13], v[28:29]
	global_store_dwordx4 v[40:41], v[20:23], off offset:512
	global_store_dwordx4 v[40:41], v[12:15], off offset:528
	s_waitcnt vmcnt(5)
	s_nop 0
	v_lshlrev_b32_e32 v12, 16, v32
	v_and_b32_e32 v13, 0xffff0000, v32
	v_lshlrev_b32_e32 v14, 16, v33
	v_and_b32_e32 v15, 0xffff0000, v33
	v_lshlrev_b32_e32 v20, 16, v34
	v_and_b32_e32 v21, 0xffff0000, v34
	v_lshlrev_b32_e32 v22, 16, v35
	v_and_b32_e32 v23, 0xffff0000, v35
	v_pk_add_f32 v[12:13], v[16:17], v[12:13]
	v_add_co_u32_e32 v16, vcc, s48, v120
	v_pk_add_f32 v[14:15], v[18:19], v[14:15]
	v_pk_add_f32 v[10:11], v[10:11], v[22:23]
	v_pk_add_f32 v[8:9], v[8:9], v[20:21]
	v_addc_co_u32_e32 v17, vcc, 0, v121, vcc
	global_store_dwordx4 v[16:17], v[12:15], off
	global_store_dwordx4 v[16:17], v[8:11], off offset:16
	s_waitcnt vmcnt(6)
	v_lshlrev_b32_e32 v12, 16, v38
	v_lshlrev_b32_e32 v8, 16, v36
	v_and_b32_e32 v9, 0xffff0000, v36
	v_lshlrev_b32_e32 v10, 16, v37
	v_and_b32_e32 v11, 0xffff0000, v37
	v_and_b32_e32 v13, 0xffff0000, v38
	v_lshlrev_b32_e32 v14, 16, v39
	v_and_b32_e32 v15, 0xffff0000, v39
	v_pk_add_f32 v[6:7], v[6:7], v[10:11]
	v_pk_add_f32 v[4:5], v[4:5], v[8:9]
	v_pk_add_f32 v[2:3], v[2:3], v[14:15]
	v_pk_add_f32 v[0:1], v[0:1], v[12:13]
	global_store_dwordx4 v[16:17], v[4:7], off offset:512
	global_store_dwordx4 v[16:17], v[0:3], off offset:528
	s_and_b64 vcc, exec, s[0:1]
	s_mov_b64 s[0:1], -1
	s_cbranch_vccnz .LBB0_1448
	s_andn2_b64 vcc, exec, s[2:3]
	s_cbranch_vccnz .LBB0_1447
	s_barrier
	s_branch .LBB0_1447
